# SSD prefetch hoist + counted waits; fast f32 division (rcp+mul); dma256 GEMM loops rescheduled (12 frag reads upfront, counted lgkmcnt, DMA interleaved)
# speedup vs baseline: 1.0292x; 1.0292x over previous
.LBB0_68:
	s_or_b64 exec, exec, s[6:7]
	global_load_dword v2, v[2:3], off
	v_add_u32_e32 v4, 0x200, v4
	s_waitcnt vmcnt(0)
	v_mul_f32_e32 v3, 0xbfb8aa3b, v2
	v_exp_f32_e32 v3, v3
	s_nop 0
	v_add_f32_e32 v3, 1.0, v3
	v_rcp_f32_e32 v8, v3
	s_movk_i32 s6, 0x8ff
	v_mul_f32_e32 v2, v2, v8
	ds_write_b32 v5, v2
	v_add_u32_e32 v2, 0x100, v6
	v_cmp_lt_i32_e32 vcc, s6, v6
	v_add_u32_e32 v5, 0x400, v5
	s_or_b64 s[4:5], vcc, s[4:5]
	v_mov_b32_e32 v6, v2
	s_andn2_b64 exec, exec, s[4:5]
	s_cbranch_execz .LBB0_73

.LBB0_206:
	s_mul_i32 s8, s6, 0x6000
	s_waitcnt vmcnt(6)
	s_add_i32 s10, s27, s8
	s_mul_i32 s98, s7, 0x6000
	v_lshl_add_u64 v[200:201], v[140:141], 0, s[0:1]
	v_lshl_add_u64 v[202:203], v[138:139], 0, s[0:1]
	s_add_i32 s99, s10, s28
	s_waitcnt lgkmcnt(0)
	s_barrier
	v_add_u32_e32 v182, s98, v142
	v_add_u32_e32 v183, s98, v144
	ds_read_b128 v[166:169], v183
	ds_read_b128 v[150:153], v182
	ds_read_b128 v[170:173], v183 offset:1024
	ds_read_b128 v[174:177], v183 offset:2048
	ds_read_b128 v[178:181], v183 offset:3072
	ds_read_b128 v[154:157], v182 offset:1024
	ds_read_b128 v[158:161], v182 offset:2048
	ds_read_b128 v[162:165], v182 offset:3072
	ds_read_b128 v[184:187], v182 offset:4096
	ds_read_b128 v[188:191], v182 offset:5120
	ds_read_b128 v[192:195], v182 offset:6144
	ds_read_b128 v[196:199], v182 offset:7168
	v_lshl_add_u64 v[204:205], v[200:201], 0, s[20:21]
	s_mov_b32 m0, s10
	s_waitcnt lgkmcnt(10)
	v_mfma_f32_16x16x32_bf16 v[84:87], v[150:153], v[166:169], v[84:87]
	global_load_lds_dwordx4 v[204:205], off
	s_waitcnt lgkmcnt(9)
	v_mfma_f32_16x16x32_bf16 v[76:79], v[150:153], v[170:173], v[76:79]
	v_lshl_add_u64 v[204:205], v[200:201], 0, s[22:23]
	s_add_i32 m0, s10, 0x400
	s_waitcnt lgkmcnt(8)
	v_mfma_f32_16x16x32_bf16 v[68:71], v[150:153], v[174:177], v[68:71]
	global_load_lds_dwordx4 v[204:205], off
	s_waitcnt lgkmcnt(7)
	v_mfma_f32_16x16x32_bf16 v[60:63], v[150:153], v[178:181], v[60:63]
	s_mov_b64 s[100:101], 0x10080
	v_lshl_add_u64 v[204:205], v[200:201], 0, s[100:101]
	s_add_i32 m0, s10, 0x800
	s_waitcnt lgkmcnt(6)
	v_mfma_f32_16x16x32_bf16 v[52:55], v[154:157], v[166:169], v[52:55]
	global_load_lds_dwordx4 v[204:205], off
	v_mfma_f32_16x16x32_bf16 v[44:47], v[154:157], v[170:173], v[44:47]
	v_mfma_f32_16x16x32_bf16 v[36:39], v[154:157], v[174:177], v[36:39]
	s_mov_b64 s[100:101], 0x18080
	v_lshl_add_u64 v[204:205], v[200:201], 0, s[100:101]
	s_add_i32 m0, s10, 0xc00
	v_mfma_f32_16x16x32_bf16 v[32:35], v[154:157], v[178:181], v[32:35]
	global_load_lds_dwordx4 v[204:205], off
	s_waitcnt lgkmcnt(5)
	v_mfma_f32_16x16x32_bf16 v[28:31], v[158:161], v[166:169], v[28:31]
	v_lshl_add_u64 v[204:205], v[202:203], 0, s[20:21]
	s_add_i32 m0, s99, 0x4000
	v_mfma_f32_16x16x32_bf16 v[24:27], v[158:161], v[170:173], v[24:27]
	global_load_lds_dwordx4 v[204:205], off
	v_mfma_f32_16x16x32_bf16 v[20:23], v[158:161], v[174:177], v[20:23]
	v_lshl_add_u64 v[204:205], v[202:203], 0, s[22:23]
	s_add_i32 m0, s99, 0x4400
	v_mfma_f32_16x16x32_bf16 v[16:19], v[158:161], v[178:181], v[16:19]
	global_load_lds_dwordx4 v[204:205], off
	s_waitcnt lgkmcnt(4)
	v_mfma_f32_16x16x32_bf16 v[12:15], v[162:165], v[166:169], v[12:15]
	v_mfma_f32_16x16x32_bf16 v[8:11], v[162:165], v[170:173], v[8:11]
	v_mfma_f32_16x16x32_bf16 v[4:7], v[162:165], v[174:177], v[4:7]
	v_mfma_f32_16x16x32_bf16 v[0:3], v[162:165], v[178:181], v[0:3]
	s_waitcnt lgkmcnt(3)
	v_mfma_f32_16x16x32_bf16 v[124:127], v[184:187], v[166:169], v[124:127]
	v_mfma_f32_16x16x32_bf16 v[120:123], v[184:187], v[170:173], v[120:123]
	v_mfma_f32_16x16x32_bf16 v[116:119], v[184:187], v[174:177], v[116:119]
	v_mfma_f32_16x16x32_bf16 v[112:115], v[184:187], v[178:181], v[112:115]
	s_waitcnt lgkmcnt(2)
	v_mfma_f32_16x16x32_bf16 v[108:111], v[188:191], v[166:169], v[108:111]
	v_mfma_f32_16x16x32_bf16 v[104:107], v[188:191], v[170:173], v[104:107]
	v_mfma_f32_16x16x32_bf16 v[100:103], v[188:191], v[174:177], v[100:103]
	v_mfma_f32_16x16x32_bf16 v[96:99], v[188:191], v[178:181], v[96:99]
	s_waitcnt lgkmcnt(1)
	v_mfma_f32_16x16x32_bf16 v[92:95], v[192:195], v[166:169], v[92:95]
	v_mfma_f32_16x16x32_bf16 v[88:91], v[192:195], v[170:173], v[88:91]
	v_mfma_f32_16x16x32_bf16 v[80:83], v[192:195], v[174:177], v[80:83]
	v_mfma_f32_16x16x32_bf16 v[72:75], v[192:195], v[178:181], v[72:75]
	s_waitcnt lgkmcnt(0)
	v_mfma_f32_16x16x32_bf16 v[64:67], v[196:199], v[166:169], v[64:67]
	v_mfma_f32_16x16x32_bf16 v[56:59], v[196:199], v[170:173], v[56:59]
	v_mfma_f32_16x16x32_bf16 v[48:51], v[196:199], v[174:177], v[48:51]
	v_mfma_f32_16x16x32_bf16 v[40:43], v[196:199], v[178:181], v[40:43]
	s_add_i32 s8, s7, 1
	s_cmp_lg_u32 s7, 2
	s_cselect_b32 s7, s8, 0
	s_add_i32 s8, s6, 1
	s_cmp_lg_u32 s6, 2
	s_cselect_b32 s6, s8, 0
	s_add_u32 s0, s0, 64
	s_addc_u32 s1, s1, 0
	s_cmpk_eq_i32 s0, 0x780
	s_cbranch_scc0 .LBB0_206
	s_waitcnt vmcnt(6)
	s_waitcnt lgkmcnt(0)
	s_barrier
	ds_read_b128 v[138:141], v142
	ds_read_b128 v[150:153], v142 offset:1024
	ds_read_b128 v[154:157], v142 offset:2048
	ds_read_b128 v[158:161], v142 offset:3072
	ds_read_b128 v[162:165], v144
	ds_read_b128 v[166:169], v144 offset:1024
	ds_read_b128 v[170:173], v144 offset:2048
	ds_read_b128 v[174:177], v144 offset:3072
	s_waitcnt lgkmcnt(0)
	s_nop 0
	v_mfma_f32_16x16x32_bf16 v[84:87], v[138:141], v[162:165], v[84:87]
	v_mfma_f32_16x16x32_bf16 v[76:79], v[138:141], v[166:169], v[76:79]
	v_mfma_f32_16x16x32_bf16 v[68:71], v[138:141], v[170:173], v[68:71]
	v_mfma_f32_16x16x32_bf16 v[60:63], v[138:141], v[174:177], v[60:63]
	v_mfma_f32_16x16x32_bf16 v[52:55], v[150:153], v[162:165], v[52:55]
	v_mfma_f32_16x16x32_bf16 v[44:47], v[150:153], v[166:169], v[44:47]
	v_mfma_f32_16x16x32_bf16 v[36:39], v[150:153], v[170:173], v[36:39]
	v_mfma_f32_16x16x32_bf16 v[32:35], v[150:153], v[174:177], v[32:35]
	v_mfma_f32_16x16x32_bf16 v[28:31], v[154:157], v[162:165], v[28:31]
	v_mfma_f32_16x16x32_bf16 v[24:27], v[154:157], v[166:169], v[24:27]
	v_mfma_f32_16x16x32_bf16 v[20:23], v[154:157], v[170:173], v[20:23]
	v_mfma_f32_16x16x32_bf16 v[16:19], v[154:157], v[174:177], v[16:19]
	v_mfma_f32_16x16x32_bf16 v[12:15], v[158:161], v[162:165], v[12:15]
	v_mfma_f32_16x16x32_bf16 v[8:11], v[158:161], v[166:169], v[8:11]
	v_mfma_f32_16x16x32_bf16 v[4:7], v[158:161], v[170:173], v[4:7]
	v_mfma_f32_16x16x32_bf16 v[0:3], v[158:161], v[174:177], v[0:3]
	ds_read_b128 v[138:141], v142 offset:4096
	ds_read_b128 v[150:153], v142 offset:5120
	ds_read_b128 v[154:157], v142 offset:6144
	ds_read_b128 v[158:161], v142 offset:7168
	s_waitcnt lgkmcnt(0)
	s_nop 0
	v_mfma_f32_16x16x32_bf16 v[178:181], v[138:141], v[162:165], v[124:127]
	v_mfma_f32_16x16x32_bf16 v[182:185], v[138:141], v[166:169], v[120:123]
	v_mfma_f32_16x16x32_bf16 v[186:189], v[138:141], v[170:173], v[116:119]
	v_mfma_f32_16x16x32_bf16 v[138:141], v[138:141], v[174:177], v[112:115]
	v_mfma_f32_16x16x32_bf16 v[190:193], v[150:153], v[162:165], v[108:111]
	v_mfma_f32_16x16x32_bf16 v[194:197], v[150:153], v[166:169], v[104:107]
	v_mfma_f32_16x16x32_bf16 v[198:201], v[150:153], v[170:173], v[100:103]
	v_mfma_f32_16x16x32_bf16 v[150:153], v[150:153], v[174:177], v[96:99]
	v_mfma_f32_16x16x32_bf16 v[202:205], v[154:157], v[162:165], v[92:95]
	v_mfma_f32_16x16x32_bf16 v[206:209], v[154:157], v[166:169], v[88:91]
	v_mfma_f32_16x16x32_bf16 v[210:213], v[154:157], v[170:173], v[80:83]
	v_mfma_f32_16x16x32_bf16 v[154:157], v[154:157], v[174:177], v[72:75]
	v_mfma_f32_16x16x32_bf16 v[162:165], v[158:161], v[162:165], v[64:67]
	v_mfma_f32_16x16x32_bf16 v[166:169], v[158:161], v[166:169], v[56:59]
	v_mfma_f32_16x16x32_bf16 v[170:173], v[158:161], v[170:173], v[48:51]
	v_mfma_f32_16x16x32_bf16 v[158:161], v[158:161], v[174:177], v[40:43]
	s_waitcnt vmcnt(0)
	s_waitcnt lgkmcnt(0)
	s_barrier
	ds_read_b128 v[40:43], v148
	ds_read_b128 v[48:51], v148 offset:1024
	ds_read_b128 v[56:59], v148 offset:2048
	ds_read_b128 v[174:177], v148 offset:3072
	ds_read_b128 v[214:217], v149
	ds_read_b128 v[218:221], v149 offset:1024
	ds_read_b128 v[222:225], v149 offset:2048
	ds_read_b128 v[228:231], v149 offset:3072
	s_waitcnt lgkmcnt(0)
	s_nop 0
	v_mfma_f32_16x16x32_bf16 v[116:119], v[40:43], v[218:221], v[76:79]
	v_mfma_f32_16x16x32_bf16 v[120:123], v[40:43], v[222:225], v[68:71]
	v_mfma_f32_16x16x32_bf16 v[64:67], v[174:177], v[214:217], v[12:15]
	v_mfma_f32_16x16x32_bf16 v[68:71], v[174:177], v[218:221], v[8:11]
	v_mfma_f32_16x16x32_bf16 v[72:75], v[174:177], v[222:225], v[4:7]
	v_mfma_f32_16x16x32_bf16 v[76:79], v[174:177], v[228:231], v[0:3]
	ds_read_b128 v[0:3], v148 offset:4096
	ds_read_b128 v[4:7], v148 offset:5120
	ds_read_b128 v[8:11], v148 offset:6144
	ds_read_b128 v[12:15], v148 offset:7168
	s_waitcnt lgkmcnt(0)
	v_mfma_f32_16x16x32_bf16 v[112:115], v[40:43], v[214:217], v[84:87]
	v_mfma_f32_16x16x32_bf16 v[124:127], v[40:43], v[228:231], v[60:63]
	v_mfma_f32_16x16x32_bf16 v[96:99], v[48:51], v[214:217], v[52:55]
	v_mfma_f32_16x16x32_bf16 v[100:103], v[48:51], v[218:221], v[44:47]
	v_mfma_f32_16x16x32_bf16 v[104:107], v[48:51], v[222:225], v[36:39]
	v_mfma_f32_16x16x32_bf16 v[108:111], v[48:51], v[228:231], v[32:35]
	v_mfma_f32_16x16x32_bf16 v[80:83], v[56:59], v[214:217], v[28:31]
	v_mfma_f32_16x16x32_bf16 v[84:87], v[56:59], v[218:221], v[24:27]
	v_mfma_f32_16x16x32_bf16 v[88:91], v[56:59], v[222:225], v[20:23]
	v_mfma_f32_16x16x32_bf16 v[92:95], v[56:59], v[228:231], v[16:19]
	v_mfma_f32_16x16x32_bf16 v[48:51], v[0:3], v[214:217], v[178:181]
	v_mfma_f32_16x16x32_bf16 v[52:55], v[0:3], v[218:221], v[182:185]
	v_mfma_f32_16x16x32_bf16 v[56:59], v[0:3], v[222:225], v[186:189]
	v_mfma_f32_16x16x32_bf16 v[60:63], v[0:3], v[228:231], v[138:141]
	v_mfma_f32_16x16x32_bf16 v[32:35], v[4:7], v[214:217], v[190:193]
	v_mfma_f32_16x16x32_bf16 v[36:39], v[4:7], v[218:221], v[194:197]
	v_mfma_f32_16x16x32_bf16 v[40:43], v[4:7], v[222:225], v[198:201]
	v_mfma_f32_16x16x32_bf16 v[44:47], v[4:7], v[228:231], v[150:153]
	v_mfma_f32_16x16x32_bf16 v[16:19], v[8:11], v[214:217], v[202:205]
	v_mfma_f32_16x16x32_bf16 v[20:23], v[8:11], v[218:221], v[206:209]
	v_mfma_f32_16x16x32_bf16 v[24:27], v[8:11], v[222:225], v[210:213]
	v_mfma_f32_16x16x32_bf16 v[28:31], v[8:11], v[228:231], v[154:157]
	v_mfma_f32_16x16x32_bf16 v[0:3], v[12:15], v[214:217], v[162:165]
	v_mfma_f32_16x16x32_bf16 v[4:7], v[12:15], v[218:221], v[166:169]
	v_mfma_f32_16x16x32_bf16 v[8:11], v[12:15], v[222:225], v[170:173]
	v_mfma_f32_16x16x32_bf16 v[12:15], v[12:15], v[228:231], v[158:161]
	v_add_u32_e32 v150, s4, v129
	v_or_b32_e32 v151, v150, v147
	v_or_b32_e32 v138, s5, v143
	v_mov_b32_e32 v153, v151
	v_mov_b64_e32 v[140:141], s[94:95]
	s_waitcnt lgkmcnt(0)
	s_barrier
	v_ashrrev_i32_e32 v139, 31, v138
	v_or_b32_e32 v152, v138, v128
	v_mad_i64_i32 v[140:141], s[0:1], v153, s43, v[140:141]
	v_lshl_add_u64 v[140:141], v[138:139], 1, v[140:141]
	v_lshl_add_u64 v[140:141], v[140:141], 0, v[130:131]
	v_cmp_gt_i32_e32 vcc, s44, v152
	s_and_saveexec_b64 s[0:1], vcc
	s_cbranch_execz .LBB0_209
	v_bfe_u32 v153, v112, 16, 1
	v_add3_u32 v153, v112, v153, s45
	global_store_short_d16_hi v[140:141], v153, off

.LBB0_523:
	s_movk_i32 s6, 0xfff
	v_cmp_lt_i32_e32 vcc, s6, v32
	v_lshl_add_u64 v[12:13], v[24:25], 0, v[20:21]
	s_nop 0
	v_cndmask_b32_e32 v8, v33, v34, vcc
	v_and_b32_e32 v9, v8, v32
	v_cmp_eq_u32_e32 vcc, 0, v9
	v_cmp_eq_u32_e64 s[6:7], v9, v8
	global_load_dwordx4 v[8:11], v[12:13], off offset:-8
	v_cndmask_b32_e64 v15, -1, 0, vcc
	v_cndmask_b32_e64 v14, v35, 0, vcc
	v_cndmask_b32_e64 v22, v36, 0, s[6:7]
	v_lshl_add_u64 v[14:15], v[12:13], 0, v[14:15]
	v_lshl_add_u64 v[12:13], v[12:13], 0, v[22:23]
	global_load_dwordx4 v[16:19], v[12:13], off offset:-8
	s_nop 0
	global_load_dwordx4 v[12:15], v[14:15], off offset:-8
	v_cndmask_b32_e64 v30, 0.5, 0, s[6:7]
	v_cndmask_b32_e64 v31, 0.5, 0, vcc
	s_waitcnt vmcnt(2)
	v_lshlrev_b32_e32 v28, 16, v8
	v_and_b32_e32 v29, 0xffff0000, v8
	s_waitcnt vmcnt(1)
	v_and_b32_e32 v42, 0xffff0000, v16
	s_waitcnt vmcnt(0)
	v_lshlrev_b32_e32 v43, 16, v12
	v_lshlrev_b32_e32 v40, 16, v16
	v_and_b32_e32 v41, 0xffff0000, v12
	v_pk_mul_f32 v[42:43], v[30:31], v[42:43]
	s_nop 0
	v_pk_fma_f32 v[40:41], v[30:31], v[40:41], v[42:43] op_sel:[0,0,1] op_sel_hi:[1,1,0]
	s_nop 0
	v_pk_add_f32 v[40:41], v[40:41], v[28:29] neg_lo:[0,1] neg_hi:[0,1]
	s_nop 0
	v_pk_fma_f32 v[28:29], v[4:5], v[40:41], v[28:29]
	s_and_saveexec_b64 s[6:7], s[0:1]
	s_xor_b64 s[6:7], exec, s[6:7]
	s_cbranch_execz .LBB0_527
	s_and_saveexec_b64 s[18:19], s[4:5]
	s_cbranch_execz .LBB0_526
	v_mul_f32_e32 v8, 0xbfb8aa3b, v28
	v_exp_f32_e32 v28, v8
	v_mul_f32_e32 v8, 0xbfb8aa3b, v29
	v_exp_f32_e32 v29, v8
	s_nop 0
	v_pk_add_f32 v[28:29], v[28:29], 1.0 op_sel_hi:[1,0]
	s_nop 0
	v_rcp_f32_e32 v12, v28
	s_nop 0
	v_mul_f32_e32 v28, 1.0, v12
	v_rcp_f32_e32 v12, v29
	s_nop 0
	v_mul_f32_e32 v29, 1.0, v12

.LBB0_537:
	s_or_b64 exec, exec, s[6:7]
	v_lshlrev_b32_e32 v40, 16, v13
	v_and_b32_e32 v41, 0xffff0000, v17
	v_lshlrev_b32_e32 v12, 16, v17
	v_and_b32_e32 v13, 0xffff0000, v13
	v_pk_mul_f32 v[16:17], v[30:31], v[40:41] op_sel:[1,0] op_sel_hi:[0,1]
	v_lshlrev_b32_e32 v8, 16, v9
	v_and_b32_e32 v9, 0xffff0000, v9
	v_pk_fma_f32 v[12:13], v[30:31], v[12:13], v[16:17]
	s_nop 0
	v_pk_add_f32 v[12:13], v[12:13], v[8:9] neg_lo:[0,1] neg_hi:[0,1]
	s_nop 0
	v_pk_fma_f32 v[8:9], v[6:7], v[12:13], v[8:9]
	s_and_saveexec_b64 s[6:7], s[0:1]
	s_xor_b64 s[6:7], exec, s[6:7]
	s_cbranch_execz .LBB0_541
	s_and_saveexec_b64 s[18:19], s[4:5]
	s_cbranch_execz .LBB0_540
	v_mul_f32_e32 v8, 0xbfb8aa3b, v8
	v_mul_f32_e32 v9, 0xbfb8aa3b, v9
	v_exp_f32_e32 v8, v8
	v_exp_f32_e32 v9, v9
	s_nop 0
	v_pk_add_f32 v[8:9], v[8:9], 1.0 op_sel_hi:[1,0]
	s_nop 0
	v_rcp_f32_e32 v13, v8
	s_nop 0
	v_mul_f32_e32 v8, 1.0, v13
	v_rcp_f32_e32 v13, v9
	s_nop 0
	v_mul_f32_e32 v9, 1.0, v13

.LBB0_551:
	s_or_b64 exec, exec, s[6:7]
	v_pk_mov_b32 v[16:17], v[30:31], v[30:31] op_sel:[1,0]
	v_lshlrev_b32_e32 v40, 16, v14
	v_and_b32_e32 v41, 0xffff0000, v18
	v_lshlrev_b32_e32 v42, 16, v18
	v_and_b32_e32 v43, 0xffff0000, v14
	v_pk_mul_f32 v[40:41], v[16:17], v[40:41]
	v_lshlrev_b32_e32 v12, 16, v10
	v_and_b32_e32 v13, 0xffff0000, v10
	v_pk_fma_f32 v[40:41], v[30:31], v[42:43], v[40:41]
	s_nop 0
	v_pk_add_f32 v[40:41], v[40:41], v[12:13] neg_lo:[0,1] neg_hi:[0,1]
	s_nop 0
	v_pk_fma_f32 v[12:13], v[0:1], v[40:41], v[12:13]
	s_and_saveexec_b64 s[6:7], s[0:1]
	s_xor_b64 s[6:7], exec, s[6:7]
	s_cbranch_execz .LBB0_555
	s_and_saveexec_b64 s[18:19], s[4:5]
	s_cbranch_execz .LBB0_554
	v_mul_f32_e32 v10, 0xbfb8aa3b, v12
	v_exp_f32_e32 v12, v10
	v_mul_f32_e32 v10, 0xbfb8aa3b, v13
	v_exp_f32_e32 v13, v10
	s_nop 0
	v_pk_add_f32 v[12:13], v[12:13], 1.0 op_sel_hi:[1,0]
	s_nop 0
	v_rcp_f32_e32 v14, v12
	s_nop 0
	v_mul_f32_e32 v12, 1.0, v14
	v_rcp_f32_e32 v14, v13
	s_nop 0
	v_mul_f32_e32 v13, 1.0, v14

.LBB0_565:
	s_or_b64 exec, exec, s[6:7]
	v_lshlrev_b32_e32 v40, 16, v15
	v_and_b32_e32 v41, 0xffff0000, v19
	v_lshlrev_b32_e32 v14, 16, v19
	v_and_b32_e32 v15, 0xffff0000, v15
	v_pk_mul_f32 v[16:17], v[16:17], v[40:41]
	v_lshlrev_b32_e32 v10, 16, v11
	v_and_b32_e32 v11, 0xffff0000, v11
	v_pk_fma_f32 v[14:15], v[30:31], v[14:15], v[16:17]
	s_nop 0
	v_pk_add_f32 v[14:15], v[14:15], v[10:11] neg_lo:[0,1] neg_hi:[0,1]
	s_nop 0
	v_pk_fma_f32 v[10:11], v[2:3], v[14:15], v[10:11]
	s_and_saveexec_b64 s[6:7], s[0:1]
	s_xor_b64 s[6:7], exec, s[6:7]
	s_cbranch_execz .LBB0_569
	s_and_saveexec_b64 s[18:19], s[4:5]
	s_cbranch_execz .LBB0_568
	v_mul_f32_e32 v10, 0xbfb8aa3b, v10
	v_mul_f32_e32 v11, 0xbfb8aa3b, v11
	v_exp_f32_e32 v10, v10
	v_exp_f32_e32 v11, v11
	s_nop 0
	v_pk_add_f32 v[10:11], v[10:11], 1.0 op_sel_hi:[1,0]
	s_nop 0
	v_rcp_f32_e32 v15, v10
	s_nop 0
	v_mul_f32_e32 v10, 1.0, v15
	v_rcp_f32_e32 v15, v11
	s_nop 0
	v_mul_f32_e32 v11, 1.0, v15

.LBB0_638:
	s_or_b64 exec, exec, s[34:35]
	v_add_u32_e32 v90, s54, v81
	v_mov_b32_e32 v54, v66
	v_mov_b32_e32 v55, v68
	v_mov_b32_e32 v68, v67
	v_mov_b32_e32 v70, v90
	v_pk_add_f32 v[54:55], v[54:55], v[52:53]
	v_pk_add_f32 v[66:67], v[68:69], v[56:57]
	s_and_saveexec_b64 s[34:35], s[30:31]
	s_cbranch_execz .LBB0_640
	v_mul_f32_e32 v54, 0xbfb8aa3b, v54
	v_mul_f32_e32 v55, 0xbfb8aa3b, v55
	v_exp_f32_e32 v54, v54
	v_exp_f32_e32 v55, v55
	v_mul_f32_e32 v66, 0xbfb8aa3b, v66
	v_mul_f32_e32 v67, 0xbfb8aa3b, v67
	v_exp_f32_e32 v66, v66
	v_pk_add_f32 v[54:55], v[54:55], 1.0 op_sel_hi:[1,0]
	v_exp_f32_e32 v67, v67
	v_rcp_f32_e32 v69, v55
	v_pk_add_f32 v[66:67], v[66:67], 1.0 op_sel_hi:[1,0]
	v_mul_f32_e32 v55, 1.0, v69
	v_rcp_f32_e32 v69, v54
	s_nop 0
	v_mul_f32_e32 v54, 1.0, v69
	v_rcp_f32_e32 v69, v67
	s_nop 0
	v_mul_f32_e32 v67, 1.0, v69
	v_rcp_f32_e32 v69, v66
	s_nop 0
	v_mul_f32_e32 v66, 1.0, v69
.LBB0_640:
	s_or_b64 exec, exec, s[34:35]
	v_mad_i64_i32 v[68:69], s[34:35], v70, s51, v[76:77]
	v_and_b32_sdwa v70, v55, v89 dst_sel:DWORD dst_unused:UNUSED_PAD src0_sel:WORD_1 src1_sel:DWORD
	v_and_b32_sdwa v91, v54, v89 dst_sel:DWORD dst_unused:UNUSED_PAD src0_sel:WORD_1 src1_sel:DWORD
	v_add3_u32 v54, v54, v91, s52
	v_add3_u32 v55, v55, v70, s52
	v_and_b32_sdwa v70, v67, v89 dst_sel:DWORD dst_unused:UNUSED_PAD src0_sel:WORD_1 src1_sel:DWORD
	v_and_b32_sdwa v91, v66, v89 dst_sel:DWORD dst_unused:UNUSED_PAD src0_sel:WORD_1 src1_sel:DWORD
	v_add3_u32 v67, v67, v70, s52
	v_add3_u32 v66, v66, v91, s52
	v_and_b32_e32 v67, 0xffff0000, v67
	v_and_b32_e32 v66, 0xffff0000, v66
	v_lshl_add_u64 v[68:69], v[78:79], 1, v[68:69]
	v_or_b32_sdwa v55, v67, v55 dst_sel:DWORD dst_unused:UNUSED_PAD src0_sel:DWORD src1_sel:WORD_1
	v_or_b32_sdwa v54, v66, v54 dst_sel:DWORD dst_unused:UNUSED_PAD src0_sel:DWORD src1_sel:WORD_1
	global_store_dwordx2 v[68:69], v[54:55], off
	v_or_b32_e32 v66, 16, v90
	v_mov_b32_e32 v54, v62
	v_mov_b32_e32 v55, v64
	v_mov_b32_e32 v64, v63
	v_mov_b32_e32 v67, v66
	v_pk_add_f32 v[54:55], v[54:55], v[52:53]
	v_pk_add_f32 v[62:63], v[64:65], v[56:57]
	s_and_saveexec_b64 s[34:35], s[30:31]
	s_cbranch_execz .LBB0_642
	v_mul_f32_e32 v54, 0xbfb8aa3b, v54
	v_mul_f32_e32 v55, 0xbfb8aa3b, v55
	v_exp_f32_e32 v54, v54
	v_exp_f32_e32 v55, v55
	v_mul_f32_e32 v62, 0xbfb8aa3b, v62
	v_mul_f32_e32 v63, 0xbfb8aa3b, v63
	v_exp_f32_e32 v62, v62
	v_pk_add_f32 v[54:55], v[54:55], 1.0 op_sel_hi:[1,0]
	v_exp_f32_e32 v63, v63
	v_rcp_f32_e32 v65, v55
	v_pk_add_f32 v[62:63], v[62:63], 1.0 op_sel_hi:[1,0]
	v_mul_f32_e32 v55, 1.0, v65
	v_rcp_f32_e32 v65, v54
	s_nop 0
	v_mul_f32_e32 v54, 1.0, v65
	v_rcp_f32_e32 v65, v63
	s_nop 0
	v_mul_f32_e32 v63, 1.0, v65
	v_rcp_f32_e32 v65, v62
	s_nop 0
	v_mul_f32_e32 v62, 1.0, v65
.LBB0_642:
	s_or_b64 exec, exec, s[34:35]
	v_mad_i64_i32 v[64:65], s[34:35], v67, s51, v[76:77]
	v_and_b32_sdwa v67, v55, v89 dst_sel:DWORD dst_unused:UNUSED_PAD src0_sel:WORD_1 src1_sel:DWORD
	v_and_b32_sdwa v68, v54, v89 dst_sel:DWORD dst_unused:UNUSED_PAD src0_sel:WORD_1 src1_sel:DWORD
	v_add3_u32 v54, v54, v68, s52
	v_add3_u32 v55, v55, v67, s52
	v_and_b32_sdwa v67, v63, v89 dst_sel:DWORD dst_unused:UNUSED_PAD src0_sel:WORD_1 src1_sel:DWORD
	v_and_b32_sdwa v68, v62, v89 dst_sel:DWORD dst_unused:UNUSED_PAD src0_sel:WORD_1 src1_sel:DWORD
	v_add3_u32 v63, v63, v67, s52
	v_add3_u32 v62, v62, v68, s52
	v_and_b32_e32 v63, 0xffff0000, v63
	v_and_b32_e32 v62, 0xffff0000, v62
	v_lshl_add_u64 v[64:65], v[78:79], 1, v[64:65]
	v_or_b32_sdwa v55, v63, v55 dst_sel:DWORD dst_unused:UNUSED_PAD src0_sel:DWORD src1_sel:WORD_1
	v_or_b32_sdwa v54, v62, v54 dst_sel:DWORD dst_unused:UNUSED_PAD src0_sel:DWORD src1_sel:WORD_1
	global_store_dwordx2 v[64:65], v[54:55], off
	v_or_b32_e32 v62, 32, v90
	v_mov_b32_e32 v54, v58
	v_mov_b32_e32 v55, v60
	v_mov_b32_e32 v60, v59
	v_mov_b32_e32 v63, v62
	v_pk_add_f32 v[54:55], v[54:55], v[52:53]
	v_pk_add_f32 v[58:59], v[60:61], v[56:57]
	s_and_saveexec_b64 s[34:35], s[30:31]
	s_cbranch_execz .LBB0_644
	v_mul_f32_e32 v54, 0xbfb8aa3b, v54
	v_mul_f32_e32 v55, 0xbfb8aa3b, v55
	v_exp_f32_e32 v54, v54
	v_exp_f32_e32 v55, v55
	v_mul_f32_e32 v58, 0xbfb8aa3b, v58
	v_mul_f32_e32 v59, 0xbfb8aa3b, v59
	v_exp_f32_e32 v58, v58
	v_pk_add_f32 v[54:55], v[54:55], 1.0 op_sel_hi:[1,0]
	v_exp_f32_e32 v59, v59
	v_rcp_f32_e32 v61, v55
	v_pk_add_f32 v[58:59], v[58:59], 1.0 op_sel_hi:[1,0]
	v_mul_f32_e32 v55, 1.0, v61
	v_rcp_f32_e32 v61, v54
	s_nop 0
	v_mul_f32_e32 v54, 1.0, v61
	v_rcp_f32_e32 v61, v59
	s_nop 0
	v_mul_f32_e32 v59, 1.0, v61
	v_rcp_f32_e32 v61, v58
	s_nop 0
	v_mul_f32_e32 v58, 1.0, v61
.LBB0_644:
	s_or_b64 exec, exec, s[34:35]
	v_readlane_b32 s56, v241, 17
	v_readlane_b32 s58, v241, 19
	v_readlane_b32 s59, v241, 20
	v_and_b32_sdwa v64, v54, v89 dst_sel:DWORD dst_unused:UNUSED_PAD src0_sel:WORD_1 src1_sel:DWORD
	v_add3_u32 v54, v54, v64, s52
	v_mov_b64_e32 v[60:61], s[58:59]
	v_mad_i64_i32 v[60:61], s[34:35], v63, s51, v[60:61]
	v_and_b32_sdwa v63, v55, v89 dst_sel:DWORD dst_unused:UNUSED_PAD src0_sel:WORD_1 src1_sel:DWORD
	v_add3_u32 v55, v55, v63, s52
	v_and_b32_sdwa v63, v59, v89 dst_sel:DWORD dst_unused:UNUSED_PAD src0_sel:WORD_1 src1_sel:DWORD
	v_and_b32_sdwa v64, v58, v89 dst_sel:DWORD dst_unused:UNUSED_PAD src0_sel:WORD_1 src1_sel:DWORD
	v_add3_u32 v59, v59, v63, s52
	v_add3_u32 v58, v58, v64, s52
	v_and_b32_e32 v59, 0xffff0000, v59
	v_and_b32_e32 v58, 0xffff0000, v58
	v_lshl_add_u64 v[60:61], v[78:79], 1, v[60:61]
	v_or_b32_sdwa v55, v59, v55 dst_sel:DWORD dst_unused:UNUSED_PAD src0_sel:DWORD src1_sel:WORD_1
	v_or_b32_sdwa v54, v58, v54 dst_sel:DWORD dst_unused:UNUSED_PAD src0_sel:DWORD src1_sel:WORD_1
	global_store_dwordx2 v[60:61], v[54:55], off
	v_or_b32_e32 v58, 48, v90
	v_mov_b32_e32 v60, v48
	v_mov_b32_e32 v61, v50
	v_mov_b32_e32 v50, v49
	v_mov_b32_e32 v54, v58
	v_pk_add_f32 v[52:53], v[60:61], v[52:53]
	v_pk_add_f32 v[48:49], v[50:51], v[56:57]
	v_readlane_b32 s57, v241, 18
	v_readlane_b32 s60, v241, 21
	v_readlane_b32 s61, v241, 22
	v_readlane_b32 s62, v241, 23
	v_readlane_b32 s63, v241, 24
	s_and_saveexec_b64 s[34:35], s[30:31]
	s_cbranch_execz .LBB0_646
	v_mul_f32_e32 v50, 0xbfb8aa3b, v52
	v_mul_f32_e32 v51, 0xbfb8aa3b, v53
	v_exp_f32_e32 v50, v50
	v_exp_f32_e32 v51, v51
	v_mul_f32_e32 v48, 0xbfb8aa3b, v48
	v_mul_f32_e32 v49, 0xbfb8aa3b, v49
	v_exp_f32_e32 v48, v48
	v_pk_add_f32 v[50:51], v[50:51], 1.0 op_sel_hi:[1,0]
	v_exp_f32_e32 v49, v49
	v_rcp_f32_e32 v53, v51
	v_pk_add_f32 v[48:49], v[48:49], 1.0 op_sel_hi:[1,0]
	v_mul_f32_e32 v53, 1.0, v53
	v_rcp_f32_e32 v52, v50
	s_nop 0
	v_mul_f32_e32 v52, 1.0, v52
	v_rcp_f32_e32 v51, v49
	s_nop 0
	v_mul_f32_e32 v49, 1.0, v51
	v_rcp_f32_e32 v51, v48
	s_nop 0
	v_mul_f32_e32 v48, 1.0, v51

.LBB0_653:
	s_or_b64 exec, exec, s[34:35]
	v_mov_b32_e32 v50, v44
	v_mov_b32_e32 v51, v46
	v_mov_b32_e32 v46, v45
	v_mov_b32_e32 v56, v90
	v_pk_add_f32 v[50:51], v[50:51], v[48:49]
	v_pk_add_f32 v[44:45], v[46:47], v[52:53]
	s_and_saveexec_b64 s[34:35], s[30:31]
	s_cbranch_execz .LBB0_655
	v_mul_f32_e32 v46, 0xbfb8aa3b, v50
	v_mul_f32_e32 v47, 0xbfb8aa3b, v51
	v_exp_f32_e32 v46, v46
	v_exp_f32_e32 v47, v47
	v_mul_f32_e32 v44, 0xbfb8aa3b, v44
	v_mul_f32_e32 v45, 0xbfb8aa3b, v45
	v_exp_f32_e32 v44, v44
	v_pk_add_f32 v[46:47], v[46:47], 1.0 op_sel_hi:[1,0]
	v_exp_f32_e32 v45, v45
	v_rcp_f32_e32 v51, v47
	v_pk_add_f32 v[44:45], v[44:45], 1.0 op_sel_hi:[1,0]
	v_mul_f32_e32 v51, 1.0, v51
	v_rcp_f32_e32 v50, v46
	s_nop 0
	v_mul_f32_e32 v50, 1.0, v50
	v_rcp_f32_e32 v47, v45
	s_nop 0
	v_mul_f32_e32 v45, 1.0, v47
	v_rcp_f32_e32 v47, v44
	s_nop 0
	v_mul_f32_e32 v44, 1.0, v47
.LBB0_655:
	s_or_b64 exec, exec, s[34:35]
	v_readlane_b32 s56, v241, 17
	v_readlane_b32 s58, v241, 19
	v_readlane_b32 s59, v241, 20
	v_and_b32_sdwa v57, v50, v89 dst_sel:DWORD dst_unused:UNUSED_PAD src0_sel:WORD_1 src1_sel:DWORD
	v_add3_u32 v50, v50, v57, s52
	v_mov_b64_e32 v[46:47], s[58:59]
	v_mad_i64_i32 v[46:47], s[34:35], v56, s51, v[46:47]
	v_and_b32_sdwa v56, v51, v89 dst_sel:DWORD dst_unused:UNUSED_PAD src0_sel:WORD_1 src1_sel:DWORD
	v_add3_u32 v51, v51, v56, s52
	v_and_b32_sdwa v56, v45, v89 dst_sel:DWORD dst_unused:UNUSED_PAD src0_sel:WORD_1 src1_sel:DWORD
	v_and_b32_sdwa v57, v44, v89 dst_sel:DWORD dst_unused:UNUSED_PAD src0_sel:WORD_1 src1_sel:DWORD
	v_add3_u32 v45, v45, v56, s52
	v_add3_u32 v44, v44, v57, s52
	v_and_b32_e32 v45, 0xffff0000, v45
	v_and_b32_e32 v44, 0xffff0000, v44
	v_lshl_add_u64 v[46:47], v[78:79], 1, v[46:47]
	v_or_b32_sdwa v45, v45, v51 dst_sel:DWORD dst_unused:UNUSED_PAD src0_sel:DWORD src1_sel:WORD_1
	v_or_b32_sdwa v44, v44, v50 dst_sel:DWORD dst_unused:UNUSED_PAD src0_sel:DWORD src1_sel:WORD_1
	global_store_dwordx2 v[46:47], v[44:45], off offset:32
	v_mov_b32_e32 v44, v40
	v_mov_b32_e32 v45, v42
	v_mov_b32_e32 v42, v41
	v_mov_b32_e32 v46, v66
	v_pk_add_f32 v[44:45], v[44:45], v[48:49]
	v_pk_add_f32 v[40:41], v[42:43], v[52:53]
	v_readlane_b32 s57, v241, 18
	v_readlane_b32 s60, v241, 21
	v_readlane_b32 s61, v241, 22
	v_readlane_b32 s62, v241, 23
	v_readlane_b32 s63, v241, 24
	s_and_saveexec_b64 s[34:35], s[30:31]
	s_cbranch_execz .LBB0_657
	v_mul_f32_e32 v42, 0xbfb8aa3b, v44
	v_mul_f32_e32 v43, 0xbfb8aa3b, v45
	v_exp_f32_e32 v42, v42
	v_exp_f32_e32 v43, v43
	v_mul_f32_e32 v40, 0xbfb8aa3b, v40
	v_mul_f32_e32 v41, 0xbfb8aa3b, v41
	v_exp_f32_e32 v40, v40
	v_pk_add_f32 v[42:43], v[42:43], 1.0 op_sel_hi:[1,0]
	v_exp_f32_e32 v41, v41
	v_rcp_f32_e32 v45, v43
	v_pk_add_f32 v[40:41], v[40:41], 1.0 op_sel_hi:[1,0]
	v_mul_f32_e32 v45, 1.0, v45
	v_rcp_f32_e32 v44, v42
	s_nop 0
	v_mul_f32_e32 v44, 1.0, v44
	v_rcp_f32_e32 v43, v41
	s_nop 0
	v_mul_f32_e32 v41, 1.0, v43
	v_rcp_f32_e32 v43, v40
	s_nop 0
	v_mul_f32_e32 v40, 1.0, v43
.LBB0_657:
	s_or_b64 exec, exec, s[34:35]
	v_readlane_b32 s56, v241, 17
	v_readlane_b32 s58, v241, 19
	v_readlane_b32 s59, v241, 20
	v_and_b32_sdwa v47, v44, v89 dst_sel:DWORD dst_unused:UNUSED_PAD src0_sel:WORD_1 src1_sel:DWORD
	v_add3_u32 v44, v44, v47, s52
	v_mov_b64_e32 v[42:43], s[58:59]
	v_mad_i64_i32 v[42:43], s[34:35], v46, s51, v[42:43]
	v_and_b32_sdwa v46, v45, v89 dst_sel:DWORD dst_unused:UNUSED_PAD src0_sel:WORD_1 src1_sel:DWORD
	v_add3_u32 v45, v45, v46, s52
	v_and_b32_sdwa v46, v41, v89 dst_sel:DWORD dst_unused:UNUSED_PAD src0_sel:WORD_1 src1_sel:DWORD
	v_and_b32_sdwa v47, v40, v89 dst_sel:DWORD dst_unused:UNUSED_PAD src0_sel:WORD_1 src1_sel:DWORD
	v_add3_u32 v41, v41, v46, s52
	v_add3_u32 v40, v40, v47, s52
	v_and_b32_e32 v41, 0xffff0000, v41
	v_and_b32_e32 v40, 0xffff0000, v40
	v_lshl_add_u64 v[42:43], v[78:79], 1, v[42:43]
	v_or_b32_sdwa v41, v41, v45 dst_sel:DWORD dst_unused:UNUSED_PAD src0_sel:DWORD src1_sel:WORD_1
	v_or_b32_sdwa v40, v40, v44 dst_sel:DWORD dst_unused:UNUSED_PAD src0_sel:DWORD src1_sel:WORD_1
	global_store_dwordx2 v[42:43], v[40:41], off offset:32
	v_mov_b32_e32 v40, v36
	v_mov_b32_e32 v41, v38
	v_mov_b32_e32 v38, v37
	v_mov_b32_e32 v42, v62
	v_pk_add_f32 v[40:41], v[40:41], v[48:49]
	v_pk_add_f32 v[36:37], v[38:39], v[52:53]
	v_readlane_b32 s57, v241, 18
	v_readlane_b32 s60, v241, 21
	v_readlane_b32 s61, v241, 22
	v_readlane_b32 s62, v241, 23
	v_readlane_b32 s63, v241, 24
	s_and_saveexec_b64 s[34:35], s[30:31]
	s_cbranch_execz .LBB0_659
	v_mul_f32_e32 v38, 0xbfb8aa3b, v40
	v_mul_f32_e32 v39, 0xbfb8aa3b, v41
	v_exp_f32_e32 v38, v38
	v_exp_f32_e32 v39, v39
	v_mul_f32_e32 v36, 0xbfb8aa3b, v36
	v_mul_f32_e32 v37, 0xbfb8aa3b, v37
	v_exp_f32_e32 v36, v36
	v_pk_add_f32 v[38:39], v[38:39], 1.0 op_sel_hi:[1,0]
	v_exp_f32_e32 v37, v37
	v_rcp_f32_e32 v41, v39
	v_pk_add_f32 v[36:37], v[36:37], 1.0 op_sel_hi:[1,0]
	v_mul_f32_e32 v41, 1.0, v41
	v_rcp_f32_e32 v40, v38
	s_nop 0
	v_mul_f32_e32 v40, 1.0, v40
	v_rcp_f32_e32 v39, v37
	s_nop 0
	v_mul_f32_e32 v37, 1.0, v39
	v_rcp_f32_e32 v39, v36
	s_nop 0
	v_mul_f32_e32 v36, 1.0, v39
.LBB0_659:
	s_or_b64 exec, exec, s[34:35]
	v_readlane_b32 s56, v241, 17
	v_readlane_b32 s58, v241, 19
	v_readlane_b32 s59, v241, 20
	v_and_b32_sdwa v43, v40, v89 dst_sel:DWORD dst_unused:UNUSED_PAD src0_sel:WORD_1 src1_sel:DWORD
	v_add3_u32 v40, v40, v43, s52
	v_mov_b64_e32 v[38:39], s[58:59]
	v_mad_i64_i32 v[38:39], s[34:35], v42, s51, v[38:39]
	v_and_b32_sdwa v42, v41, v89 dst_sel:DWORD dst_unused:UNUSED_PAD src0_sel:WORD_1 src1_sel:DWORD
	v_add3_u32 v41, v41, v42, s52
	v_and_b32_sdwa v42, v37, v89 dst_sel:DWORD dst_unused:UNUSED_PAD src0_sel:WORD_1 src1_sel:DWORD
	v_and_b32_sdwa v43, v36, v89 dst_sel:DWORD dst_unused:UNUSED_PAD src0_sel:WORD_1 src1_sel:DWORD
	v_add3_u32 v37, v37, v42, s52
	v_add3_u32 v36, v36, v43, s52
	v_and_b32_e32 v37, 0xffff0000, v37
	v_and_b32_e32 v36, 0xffff0000, v36
	v_lshl_add_u64 v[38:39], v[78:79], 1, v[38:39]
	v_or_b32_sdwa v37, v37, v41 dst_sel:DWORD dst_unused:UNUSED_PAD src0_sel:DWORD src1_sel:WORD_1
	v_or_b32_sdwa v36, v36, v40 dst_sel:DWORD dst_unused:UNUSED_PAD src0_sel:DWORD src1_sel:WORD_1
	global_store_dwordx2 v[38:39], v[36:37], off offset:32
	v_mov_b32_e32 v36, v32
	v_mov_b32_e32 v37, v34
	v_mov_b32_e32 v34, v33
	v_mov_b32_e32 v38, v58
	v_pk_add_f32 v[36:37], v[36:37], v[48:49]
	v_pk_add_f32 v[32:33], v[34:35], v[52:53]
	v_readlane_b32 s57, v241, 18
	v_readlane_b32 s60, v241, 21
	v_readlane_b32 s61, v241, 22
	v_readlane_b32 s62, v241, 23
	v_readlane_b32 s63, v241, 24
	s_and_saveexec_b64 s[34:35], s[30:31]
	s_cbranch_execz .LBB0_661
	v_mul_f32_e32 v34, 0xbfb8aa3b, v36
	v_mul_f32_e32 v35, 0xbfb8aa3b, v37
	v_exp_f32_e32 v34, v34
	v_exp_f32_e32 v35, v35
	v_mul_f32_e32 v32, 0xbfb8aa3b, v32
	v_mul_f32_e32 v33, 0xbfb8aa3b, v33
	v_exp_f32_e32 v32, v32
	v_pk_add_f32 v[34:35], v[34:35], 1.0 op_sel_hi:[1,0]
	v_exp_f32_e32 v33, v33
	v_rcp_f32_e32 v37, v35
	v_pk_add_f32 v[32:33], v[32:33], 1.0 op_sel_hi:[1,0]
	v_mul_f32_e32 v37, 1.0, v37
	v_rcp_f32_e32 v36, v34
	s_nop 0
	v_mul_f32_e32 v36, 1.0, v36
	v_rcp_f32_e32 v35, v33
	s_nop 0
	v_mul_f32_e32 v33, 1.0, v35
	v_rcp_f32_e32 v35, v32
	s_nop 0
	v_mul_f32_e32 v32, 1.0, v35

.LBB0_666:
	s_or_b64 exec, exec, s[34:35]
	v_mov_b32_e32 v34, v28
	v_mov_b32_e32 v35, v30
	v_mov_b32_e32 v30, v29
	v_mov_b32_e32 v38, v90
	v_pk_add_f32 v[34:35], v[34:35], v[32:33]
	v_pk_add_f32 v[28:29], v[30:31], v[36:37]
	s_and_saveexec_b64 s[34:35], s[30:31]
	s_cbranch_execz .LBB0_668
	v_mul_f32_e32 v30, 0xbfb8aa3b, v34
	v_mul_f32_e32 v31, 0xbfb8aa3b, v35
	v_exp_f32_e32 v30, v30
	v_exp_f32_e32 v31, v31
	v_mul_f32_e32 v28, 0xbfb8aa3b, v28
	v_mul_f32_e32 v29, 0xbfb8aa3b, v29
	v_exp_f32_e32 v28, v28
	v_pk_add_f32 v[30:31], v[30:31], 1.0 op_sel_hi:[1,0]
	v_exp_f32_e32 v29, v29
	v_rcp_f32_e32 v35, v31
	v_pk_add_f32 v[28:29], v[28:29], 1.0 op_sel_hi:[1,0]
	v_mul_f32_e32 v35, 1.0, v35
	v_rcp_f32_e32 v34, v30
	s_nop 0
	v_mul_f32_e32 v34, 1.0, v34
	v_rcp_f32_e32 v31, v29
	s_nop 0
	v_mul_f32_e32 v29, 1.0, v31
	v_rcp_f32_e32 v31, v28
	s_nop 0
	v_mul_f32_e32 v28, 1.0, v31
.LBB0_668:
	s_or_b64 exec, exec, s[34:35]
	v_readlane_b32 s56, v241, 17
	v_readlane_b32 s58, v241, 19
	v_readlane_b32 s59, v241, 20
	v_and_b32_sdwa v39, v34, v89 dst_sel:DWORD dst_unused:UNUSED_PAD src0_sel:WORD_1 src1_sel:DWORD
	v_add3_u32 v34, v34, v39, s52
	v_mov_b64_e32 v[30:31], s[58:59]
	v_mad_i64_i32 v[30:31], s[34:35], v38, s51, v[30:31]
	v_and_b32_sdwa v38, v35, v89 dst_sel:DWORD dst_unused:UNUSED_PAD src0_sel:WORD_1 src1_sel:DWORD
	v_add3_u32 v35, v35, v38, s52
	v_and_b32_sdwa v38, v29, v89 dst_sel:DWORD dst_unused:UNUSED_PAD src0_sel:WORD_1 src1_sel:DWORD
	v_and_b32_sdwa v39, v28, v89 dst_sel:DWORD dst_unused:UNUSED_PAD src0_sel:WORD_1 src1_sel:DWORD
	v_add3_u32 v29, v29, v38, s52
	v_add3_u32 v28, v28, v39, s52
	v_and_b32_e32 v29, 0xffff0000, v29
	v_and_b32_e32 v28, 0xffff0000, v28
	v_lshl_add_u64 v[30:31], v[78:79], 1, v[30:31]
	v_or_b32_sdwa v29, v29, v35 dst_sel:DWORD dst_unused:UNUSED_PAD src0_sel:DWORD src1_sel:WORD_1
	v_or_b32_sdwa v28, v28, v34 dst_sel:DWORD dst_unused:UNUSED_PAD src0_sel:DWORD src1_sel:WORD_1
	global_store_dwordx2 v[30:31], v[28:29], off offset:64
	v_mov_b32_e32 v28, v24
	v_mov_b32_e32 v29, v26
	v_mov_b32_e32 v26, v25
	v_mov_b32_e32 v30, v66
	v_pk_add_f32 v[28:29], v[28:29], v[32:33]
	v_pk_add_f32 v[24:25], v[26:27], v[36:37]
	v_readlane_b32 s57, v241, 18
	v_readlane_b32 s60, v241, 21
	v_readlane_b32 s61, v241, 22
	v_readlane_b32 s62, v241, 23
	v_readlane_b32 s63, v241, 24
	s_and_saveexec_b64 s[34:35], s[30:31]
	s_cbranch_execz .LBB0_670
	v_mul_f32_e32 v26, 0xbfb8aa3b, v28
	v_mul_f32_e32 v27, 0xbfb8aa3b, v29
	v_exp_f32_e32 v26, v26
	v_exp_f32_e32 v27, v27
	v_mul_f32_e32 v24, 0xbfb8aa3b, v24
	v_mul_f32_e32 v25, 0xbfb8aa3b, v25
	v_exp_f32_e32 v24, v24
	v_pk_add_f32 v[26:27], v[26:27], 1.0 op_sel_hi:[1,0]
	v_exp_f32_e32 v25, v25
	v_rcp_f32_e32 v29, v27
	v_pk_add_f32 v[24:25], v[24:25], 1.0 op_sel_hi:[1,0]
	v_mul_f32_e32 v29, 1.0, v29
	v_rcp_f32_e32 v28, v26
	s_nop 0
	v_mul_f32_e32 v28, 1.0, v28
	v_rcp_f32_e32 v27, v25
	s_nop 0
	v_mul_f32_e32 v25, 1.0, v27
	v_rcp_f32_e32 v27, v24
	s_nop 0
	v_mul_f32_e32 v24, 1.0, v27
.LBB0_670:
	s_or_b64 exec, exec, s[34:35]
	v_readlane_b32 s56, v241, 17
	v_readlane_b32 s58, v241, 19
	v_readlane_b32 s59, v241, 20
	v_and_b32_sdwa v31, v28, v89 dst_sel:DWORD dst_unused:UNUSED_PAD src0_sel:WORD_1 src1_sel:DWORD
	v_add3_u32 v28, v28, v31, s52
	v_mov_b64_e32 v[26:27], s[58:59]
	v_mad_i64_i32 v[26:27], s[34:35], v30, s51, v[26:27]
	v_and_b32_sdwa v30, v29, v89 dst_sel:DWORD dst_unused:UNUSED_PAD src0_sel:WORD_1 src1_sel:DWORD
	v_add3_u32 v29, v29, v30, s52
	v_and_b32_sdwa v30, v25, v89 dst_sel:DWORD dst_unused:UNUSED_PAD src0_sel:WORD_1 src1_sel:DWORD
	v_and_b32_sdwa v31, v24, v89 dst_sel:DWORD dst_unused:UNUSED_PAD src0_sel:WORD_1 src1_sel:DWORD
	v_add3_u32 v25, v25, v30, s52
	v_add3_u32 v24, v24, v31, s52
	v_and_b32_e32 v25, 0xffff0000, v25
	v_and_b32_e32 v24, 0xffff0000, v24
	v_lshl_add_u64 v[26:27], v[78:79], 1, v[26:27]
	v_or_b32_sdwa v25, v25, v29 dst_sel:DWORD dst_unused:UNUSED_PAD src0_sel:DWORD src1_sel:WORD_1
	v_or_b32_sdwa v24, v24, v28 dst_sel:DWORD dst_unused:UNUSED_PAD src0_sel:DWORD src1_sel:WORD_1
	global_store_dwordx2 v[26:27], v[24:25], off offset:64
	v_mov_b32_e32 v24, v20
	v_mov_b32_e32 v25, v22
	v_mov_b32_e32 v22, v21
	v_mov_b32_e32 v26, v62
	v_pk_add_f32 v[24:25], v[24:25], v[32:33]
	v_pk_add_f32 v[20:21], v[22:23], v[36:37]
	v_readlane_b32 s57, v241, 18
	v_readlane_b32 s60, v241, 21
	v_readlane_b32 s61, v241, 22
	v_readlane_b32 s62, v241, 23
	v_readlane_b32 s63, v241, 24
	s_and_saveexec_b64 s[34:35], s[30:31]
	s_cbranch_execz .LBB0_672
	v_mul_f32_e32 v22, 0xbfb8aa3b, v24
	v_mul_f32_e32 v23, 0xbfb8aa3b, v25
	v_exp_f32_e32 v22, v22
	v_exp_f32_e32 v23, v23
	v_mul_f32_e32 v20, 0xbfb8aa3b, v20
	v_mul_f32_e32 v21, 0xbfb8aa3b, v21
	v_exp_f32_e32 v20, v20
	v_pk_add_f32 v[22:23], v[22:23], 1.0 op_sel_hi:[1,0]
	v_exp_f32_e32 v21, v21
	v_rcp_f32_e32 v25, v23
	v_pk_add_f32 v[20:21], v[20:21], 1.0 op_sel_hi:[1,0]
	v_mul_f32_e32 v25, 1.0, v25
	v_rcp_f32_e32 v24, v22
	s_nop 0
	v_mul_f32_e32 v24, 1.0, v24
	v_rcp_f32_e32 v23, v21
	s_nop 0
	v_mul_f32_e32 v21, 1.0, v23
	v_rcp_f32_e32 v23, v20
	s_nop 0
	v_mul_f32_e32 v20, 1.0, v23
.LBB0_672:
	s_or_b64 exec, exec, s[34:35]
	v_readlane_b32 s56, v241, 17
	v_readlane_b32 s58, v241, 19
	v_readlane_b32 s59, v241, 20
	v_and_b32_sdwa v27, v24, v89 dst_sel:DWORD dst_unused:UNUSED_PAD src0_sel:WORD_1 src1_sel:DWORD
	v_add3_u32 v24, v24, v27, s52
	v_mov_b64_e32 v[22:23], s[58:59]
	v_mad_i64_i32 v[22:23], s[34:35], v26, s51, v[22:23]
	v_and_b32_sdwa v26, v25, v89 dst_sel:DWORD dst_unused:UNUSED_PAD src0_sel:WORD_1 src1_sel:DWORD
	v_add3_u32 v25, v25, v26, s52
	v_and_b32_sdwa v26, v21, v89 dst_sel:DWORD dst_unused:UNUSED_PAD src0_sel:WORD_1 src1_sel:DWORD
	v_and_b32_sdwa v27, v20, v89 dst_sel:DWORD dst_unused:UNUSED_PAD src0_sel:WORD_1 src1_sel:DWORD
	v_add3_u32 v21, v21, v26, s52
	v_add3_u32 v20, v20, v27, s52
	v_and_b32_e32 v21, 0xffff0000, v21
	v_and_b32_e32 v20, 0xffff0000, v20
	v_lshl_add_u64 v[22:23], v[78:79], 1, v[22:23]
	v_or_b32_sdwa v21, v21, v25 dst_sel:DWORD dst_unused:UNUSED_PAD src0_sel:DWORD src1_sel:WORD_1
	v_or_b32_sdwa v20, v20, v24 dst_sel:DWORD dst_unused:UNUSED_PAD src0_sel:DWORD src1_sel:WORD_1
	global_store_dwordx2 v[22:23], v[20:21], off offset:64
	v_mov_b32_e32 v20, v16
	v_mov_b32_e32 v21, v18
	v_mov_b32_e32 v18, v17
	v_mov_b32_e32 v22, v58
	v_pk_add_f32 v[20:21], v[20:21], v[32:33]
	v_pk_add_f32 v[16:17], v[18:19], v[36:37]
	v_readlane_b32 s57, v241, 18
	v_readlane_b32 s60, v241, 21
	v_readlane_b32 s61, v241, 22
	v_readlane_b32 s62, v241, 23
	v_readlane_b32 s63, v241, 24
	s_and_saveexec_b64 s[34:35], s[30:31]
	s_cbranch_execz .LBB0_674
	v_mul_f32_e32 v18, 0xbfb8aa3b, v20
	v_mul_f32_e32 v19, 0xbfb8aa3b, v21
	v_exp_f32_e32 v18, v18
	v_exp_f32_e32 v19, v19
	v_mul_f32_e32 v16, 0xbfb8aa3b, v16
	v_mul_f32_e32 v17, 0xbfb8aa3b, v17
	v_exp_f32_e32 v16, v16
	v_pk_add_f32 v[18:19], v[18:19], 1.0 op_sel_hi:[1,0]
	v_exp_f32_e32 v17, v17
	v_rcp_f32_e32 v21, v19
	v_pk_add_f32 v[16:17], v[16:17], 1.0 op_sel_hi:[1,0]
	v_mul_f32_e32 v21, 1.0, v21
	v_rcp_f32_e32 v20, v18
	s_nop 0
	v_mul_f32_e32 v20, 1.0, v20
	v_rcp_f32_e32 v19, v17
	s_nop 0
	v_mul_f32_e32 v17, 1.0, v19
	v_rcp_f32_e32 v19, v16
	s_nop 0
	v_mul_f32_e32 v16, 1.0, v19

.LBB0_679:
	s_or_b64 exec, exec, s[34:35]
	v_mov_b32_e32 v18, v12
	v_mov_b32_e32 v19, v14
	v_mov_b32_e32 v14, v13
	v_pk_add_f32 v[18:19], v[18:19], v[16:17]
	v_pk_add_f32 v[12:13], v[14:15], v[20:21]
	s_and_saveexec_b64 s[34:35], s[30:31]
	s_cbranch_execz .LBB0_681
	v_mul_f32_e32 v14, 0xbfb8aa3b, v18
	v_mul_f32_e32 v15, 0xbfb8aa3b, v19
	v_exp_f32_e32 v14, v14
	v_exp_f32_e32 v15, v15
	v_mul_f32_e32 v12, 0xbfb8aa3b, v12
	v_mul_f32_e32 v13, 0xbfb8aa3b, v13
	v_exp_f32_e32 v12, v12
	v_pk_add_f32 v[14:15], v[14:15], 1.0 op_sel_hi:[1,0]
	v_exp_f32_e32 v13, v13
	v_rcp_f32_e32 v19, v15
	v_pk_add_f32 v[12:13], v[12:13], 1.0 op_sel_hi:[1,0]
	v_mul_f32_e32 v19, 1.0, v19
	v_rcp_f32_e32 v18, v14
	s_nop 0
	v_mul_f32_e32 v18, 1.0, v18
	v_rcp_f32_e32 v15, v13
	s_nop 0
	v_mul_f32_e32 v13, 1.0, v15
	v_rcp_f32_e32 v15, v12
	s_nop 0
	v_mul_f32_e32 v12, 1.0, v15
.LBB0_681:
	s_or_b64 exec, exec, s[34:35]
	v_readlane_b32 s56, v241, 17
	v_and_b32_sdwa v22, v19, v89 dst_sel:DWORD dst_unused:UNUSED_PAD src0_sel:WORD_1 src1_sel:DWORD
	v_and_b32_sdwa v23, v18, v89 dst_sel:DWORD dst_unused:UNUSED_PAD src0_sel:WORD_1 src1_sel:DWORD
	v_readlane_b32 s58, v241, 19
	v_readlane_b32 s59, v241, 20
	v_add3_u32 v18, v18, v23, s52
	v_add3_u32 v19, v19, v22, s52
	v_and_b32_sdwa v22, v13, v89 dst_sel:DWORD dst_unused:UNUSED_PAD src0_sel:WORD_1 src1_sel:DWORD
	v_and_b32_sdwa v23, v12, v89 dst_sel:DWORD dst_unused:UNUSED_PAD src0_sel:WORD_1 src1_sel:DWORD
	v_mov_b64_e32 v[14:15], s[58:59]
	v_add3_u32 v13, v13, v22, s52
	v_add3_u32 v12, v12, v23, s52
	v_mad_i64_i32 v[14:15], s[34:35], v90, s51, v[14:15]
	v_and_b32_e32 v13, 0xffff0000, v13
	v_and_b32_e32 v12, 0xffff0000, v12
	v_lshl_add_u64 v[14:15], v[78:79], 1, v[14:15]
	v_or_b32_sdwa v13, v13, v19 dst_sel:DWORD dst_unused:UNUSED_PAD src0_sel:DWORD src1_sel:WORD_1
	v_or_b32_sdwa v12, v12, v18 dst_sel:DWORD dst_unused:UNUSED_PAD src0_sel:DWORD src1_sel:WORD_1
	global_store_dwordx2 v[14:15], v[12:13], off offset:96
	v_mov_b32_e32 v12, v8
	v_mov_b32_e32 v13, v10
	v_mov_b32_e32 v10, v9
	v_pk_add_f32 v[12:13], v[12:13], v[16:17]
	v_pk_add_f32 v[8:9], v[10:11], v[20:21]
	v_readlane_b32 s57, v241, 18
	v_readlane_b32 s60, v241, 21
	v_readlane_b32 s61, v241, 22
	v_readlane_b32 s62, v241, 23
	v_readlane_b32 s63, v241, 24
	s_and_saveexec_b64 s[34:35], s[30:31]
	s_cbranch_execz .LBB0_683
	v_mul_f32_e32 v10, 0xbfb8aa3b, v12
	v_mul_f32_e32 v11, 0xbfb8aa3b, v13
	v_exp_f32_e32 v10, v10
	v_exp_f32_e32 v11, v11
	v_mul_f32_e32 v8, 0xbfb8aa3b, v8
	v_mul_f32_e32 v9, 0xbfb8aa3b, v9
	v_exp_f32_e32 v8, v8
	v_pk_add_f32 v[10:11], v[10:11], 1.0 op_sel_hi:[1,0]
	v_exp_f32_e32 v9, v9
	v_rcp_f32_e32 v13, v11
	v_pk_add_f32 v[8:9], v[8:9], 1.0 op_sel_hi:[1,0]
	v_mul_f32_e32 v13, 1.0, v13
	v_rcp_f32_e32 v12, v10
	s_nop 0
	v_mul_f32_e32 v12, 1.0, v12
	v_rcp_f32_e32 v11, v9
	s_nop 0
	v_mul_f32_e32 v9, 1.0, v11
	v_rcp_f32_e32 v11, v8
	s_nop 0
	v_mul_f32_e32 v8, 1.0, v11
.LBB0_683:
	s_or_b64 exec, exec, s[34:35]
	v_readlane_b32 s56, v241, 17
	v_and_b32_sdwa v14, v13, v89 dst_sel:DWORD dst_unused:UNUSED_PAD src0_sel:WORD_1 src1_sel:DWORD
	v_and_b32_sdwa v15, v12, v89 dst_sel:DWORD dst_unused:UNUSED_PAD src0_sel:WORD_1 src1_sel:DWORD
	v_readlane_b32 s58, v241, 19
	v_readlane_b32 s59, v241, 20
	v_add3_u32 v12, v12, v15, s52
	v_add3_u32 v13, v13, v14, s52
	v_and_b32_sdwa v14, v9, v89 dst_sel:DWORD dst_unused:UNUSED_PAD src0_sel:WORD_1 src1_sel:DWORD
	v_and_b32_sdwa v15, v8, v89 dst_sel:DWORD dst_unused:UNUSED_PAD src0_sel:WORD_1 src1_sel:DWORD
	v_mov_b64_e32 v[10:11], s[58:59]
	v_add3_u32 v9, v9, v14, s52
	v_add3_u32 v8, v8, v15, s52
	v_mad_i64_i32 v[10:11], s[34:35], v66, s51, v[10:11]
	v_and_b32_e32 v9, 0xffff0000, v9
	v_and_b32_e32 v8, 0xffff0000, v8
	v_lshl_add_u64 v[10:11], v[78:79], 1, v[10:11]
	v_or_b32_sdwa v9, v9, v13 dst_sel:DWORD dst_unused:UNUSED_PAD src0_sel:DWORD src1_sel:WORD_1
	v_or_b32_sdwa v8, v8, v12 dst_sel:DWORD dst_unused:UNUSED_PAD src0_sel:DWORD src1_sel:WORD_1
	global_store_dwordx2 v[10:11], v[8:9], off offset:96
	v_mov_b32_e32 v8, v4
	v_mov_b32_e32 v9, v6
	v_mov_b32_e32 v6, v5
	v_pk_add_f32 v[8:9], v[8:9], v[16:17]
	v_pk_add_f32 v[4:5], v[6:7], v[20:21]
	v_readlane_b32 s57, v241, 18
	v_readlane_b32 s60, v241, 21
	v_readlane_b32 s61, v241, 22
	v_readlane_b32 s62, v241, 23
	v_readlane_b32 s63, v241, 24
	s_and_saveexec_b64 s[34:35], s[30:31]
	s_cbranch_execz .LBB0_685
	v_mul_f32_e32 v6, 0xbfb8aa3b, v8
	v_mul_f32_e32 v7, 0xbfb8aa3b, v9
	v_exp_f32_e32 v6, v6
	v_exp_f32_e32 v7, v7
	v_mul_f32_e32 v4, 0xbfb8aa3b, v4
	v_mul_f32_e32 v5, 0xbfb8aa3b, v5
	v_exp_f32_e32 v4, v4
	v_pk_add_f32 v[6:7], v[6:7], 1.0 op_sel_hi:[1,0]
	v_exp_f32_e32 v5, v5
	v_rcp_f32_e32 v9, v7
	v_pk_add_f32 v[4:5], v[4:5], 1.0 op_sel_hi:[1,0]
	v_mul_f32_e32 v9, 1.0, v9
	v_rcp_f32_e32 v8, v6
	s_nop 0
	v_mul_f32_e32 v8, 1.0, v8
	v_rcp_f32_e32 v7, v5
	s_nop 0
	v_mul_f32_e32 v5, 1.0, v7
	v_rcp_f32_e32 v7, v4
	s_nop 0
	v_mul_f32_e32 v4, 1.0, v7
.LBB0_685:
	s_or_b64 exec, exec, s[34:35]
	v_readlane_b32 s56, v241, 17
	v_and_b32_sdwa v10, v9, v89 dst_sel:DWORD dst_unused:UNUSED_PAD src0_sel:WORD_1 src1_sel:DWORD
	v_and_b32_sdwa v11, v8, v89 dst_sel:DWORD dst_unused:UNUSED_PAD src0_sel:WORD_1 src1_sel:DWORD
	v_readlane_b32 s58, v241, 19
	v_readlane_b32 s59, v241, 20
	v_add3_u32 v8, v8, v11, s52
	v_add3_u32 v9, v9, v10, s52
	v_and_b32_sdwa v10, v5, v89 dst_sel:DWORD dst_unused:UNUSED_PAD src0_sel:WORD_1 src1_sel:DWORD
	v_and_b32_sdwa v11, v4, v89 dst_sel:DWORD dst_unused:UNUSED_PAD src0_sel:WORD_1 src1_sel:DWORD
	v_mov_b64_e32 v[6:7], s[58:59]
	v_add3_u32 v5, v5, v10, s52
	v_add3_u32 v4, v4, v11, s52
	v_mad_i64_i32 v[6:7], s[34:35], v62, s51, v[6:7]
	v_and_b32_e32 v5, 0xffff0000, v5
	v_and_b32_e32 v4, 0xffff0000, v4
	v_lshl_add_u64 v[6:7], v[78:79], 1, v[6:7]
	v_or_b32_sdwa v5, v5, v9 dst_sel:DWORD dst_unused:UNUSED_PAD src0_sel:DWORD src1_sel:WORD_1
	v_or_b32_sdwa v4, v4, v8 dst_sel:DWORD dst_unused:UNUSED_PAD src0_sel:DWORD src1_sel:WORD_1
	global_store_dwordx2 v[6:7], v[4:5], off offset:96
	v_mov_b32_e32 v4, v0
	v_mov_b32_e32 v5, v2
	v_mov_b32_e32 v2, v1
	v_pk_add_f32 v[4:5], v[4:5], v[16:17]
	v_pk_add_f32 v[0:1], v[2:3], v[20:21]
	v_readlane_b32 s57, v241, 18
	v_readlane_b32 s60, v241, 21
	v_readlane_b32 s61, v241, 22
	v_readlane_b32 s62, v241, 23
	v_readlane_b32 s63, v241, 24
	s_and_saveexec_b64 s[34:35], s[30:31]
	s_cbranch_execz .LBB0_632
	v_mul_f32_e32 v2, 0xbfb8aa3b, v4
	v_mul_f32_e32 v3, 0xbfb8aa3b, v5
	v_exp_f32_e32 v2, v2
	v_exp_f32_e32 v3, v3
	v_mul_f32_e32 v0, 0xbfb8aa3b, v0
	v_mul_f32_e32 v1, 0xbfb8aa3b, v1
	v_exp_f32_e32 v0, v0
	v_pk_add_f32 v[2:3], v[2:3], 1.0 op_sel_hi:[1,0]
	v_exp_f32_e32 v1, v1
	v_rcp_f32_e32 v5, v3
	v_pk_add_f32 v[0:1], v[0:1], 1.0 op_sel_hi:[1,0]
	v_mul_f32_e32 v5, 1.0, v5
	v_rcp_f32_e32 v4, v2
	s_nop 0
	v_mul_f32_e32 v4, 1.0, v4
	v_rcp_f32_e32 v3, v1
	s_nop 0
	v_mul_f32_e32 v1, 1.0, v3
	v_rcp_f32_e32 v3, v0
	s_nop 0
	v_mul_f32_e32 v0, 1.0, v3
	s_branch .LBB0_632

.LBB0_981:
	v_writelane_b32 v240, s34, 52
	v_writelane_b32 v240, s56, 54
	s_nop 1
	v_writelane_b32 v240, s57, 55
	s_or_b64 exec, exec, s[10:11]
	s_lshl_b64 s[0:1], s[12:13], 12
	v_writelane_b32 v240, s0, 56
	v_mul_f32_e32 v1, 0x3fb8aa3b, v69
	v_and_b32_e32 v114, 48, v66
	v_writelane_b32 v240, s1, 57
	v_cmp_gt_u32_e64 s[0:1], 16, v70
	v_exp_f32_e32 v112, v1
	v_or_b32_e32 v1, v67, v77
	v_cndmask_b32_e64 v66, v120, v121, s[0:1]
	s_movk_i32 s0, 0x480
	s_movk_i32 s24, 0x90
	s_cmp_eq_u32 s79, 0
	v_cmp_lt_i32_e64 s[8:9], 7, v70
	v_cmp_gt_i32_e64 s[10:11], 16, v70
	v_mul_lo_u32 v69, v70, s0
	v_or_b32_e32 v70, 2, v80
	v_mul_lo_u32 v113, v1, s24
	s_cselect_b64 s[6:7], -1, 0
	s_lshl_b32 s68, s58, 6
	v_mul_lo_u32 v70, v70, s24
	v_readlane_b32 s60, v241, 17
	s_ashr_i32 s69, s68, 31
	v_lshl_add_u32 v115, v78, 4, v113
	v_lshlrev_b32_e32 v127, 5, v78
	v_lshlrev_b32_e32 v129, 1, v80
	v_mul_lo_u32 v78, v110, s24
	v_add_u32_e32 v80, 0x4920, v69
	v_add_u32_e32 v81, 0x4800, v70
	v_mul_u32_u24_e32 v85, 0x90, v77
	v_or_b32_e32 v89, 16, v77
	v_or_b32_e32 v100, 32, v77
	v_or_b32_e32 v101, 48, v77
	v_cmp_gt_i32_e64 s[24:25], v77, v90
	v_cmp_gt_i32_e64 s[26:27], v77, v94
	v_cmp_gt_i32_e64 s[28:29], v77, v96
	v_cmp_gt_i32_e64 s[30:31], v77, v98
	v_lshlrev_b32_e32 v77, 1, v110
	s_movk_i32 s0, 0x4800
	s_mulk_i32 s79, 0x300
	v_readlane_b32 s66, v241, 23
	v_add_u32_e32 v82, 0x4a40, v69
	v_add_u32_e32 v83, 0x4920, v70
	v_add_u32_e32 v84, 0x4b60, v69
	v_add3_u32 v130, v69, v77, s0
	v_cndmask_b32_e32 v69, v80, v81, vcc
	v_readlane_b32 s67, v241, 24
	s_add_u32 s76, s66, s79
	v_add_u32_e32 v70, 0x4a40, v70
	v_add_u32_e32 v131, v69, v77
	v_cndmask_b32_e32 v69, v82, v83, vcc
	s_addc_u32 s79, s67, 0
	s_lshl_b64 s[0:1], s[68:69], 1
	v_add_u32_e32 v132, v69, v77
	v_cndmask_b32_e32 v69, v84, v70, vcc
	s_add_u32 s0, s76, s0
	v_add_u32_e32 v133, v69, v77
	s_addc_u32 s1, s79, s1
	v_mov_b32_e32 v69, v0
	v_lshlrev_b32_e32 v1, 2, v67
	v_add_u32_e32 v66, v129, v66
	v_ashrrev_i32_e32 v73, 31, v72
	v_lshl_add_u64 v[102:103], s[0:1], 0, v[68:69]
	v_lshl_add_u64 v[68:69], v[74:75], 1, s[94:95]
	v_add_u32_e32 v137, v67, v76
	s_waitcnt lgkmcnt(0)
	s_barrier
	s_mov_b32 s78, 0
	v_lshlrev_b32_e32 v128, 2, v71
	v_cmp_eq_u32_e64 s[12:13], 0, v71
	v_cmp_gt_u32_e64 s[14:15], 2, v71
	v_cmp_gt_u32_e64 s[16:17], 4, v71
	v_cmp_gt_u32_e64 s[18:19], 8, v71
	v_cmp_gt_u32_e64 s[20:21], 16, v71
	v_cmp_gt_u32_e64 s[22:23], 32, v71
	v_cmp_gt_i32_e64 s[34:35], v89, v90
	v_cmp_gt_i32_e64 s[36:37], v89, v94
	v_cmp_gt_i32_e64 s[38:39], v89, v96
	v_cmp_gt_i32_e64 s[40:41], v89, v98
	v_cmp_gt_i32_e64 s[42:43], v100, v90
	v_cmp_gt_i32_e64 s[44:45], v100, v94
	v_cmp_gt_i32_e64 s[46:47], v100, v96
	v_cmp_gt_i32_e64 s[48:49], v100, v98
	v_cmp_gt_i32_e64 s[50:51], v101, v90
	v_cmp_gt_i32_e64 s[52:53], v101, v94
	v_cmp_gt_i32_e64 s[54:55], v101, v96
	v_cmp_gt_i32_e64 s[56:57], v101, v98
	v_lshl_add_u64 v[100:101], v[72:73], 1, s[94:95]
	v_readlane_b32 s61, v241, 18
	v_readlane_b32 s62, v241, 19
	v_readlane_b32 s63, v241, 20
	v_readlane_b32 s64, v241, 21
	v_readlane_b32 s65, v241, 22
	v_lshl_add_u64 v[104:105], s[58:59], 1, v[68:69]
	v_sub_u32_e32 v134, 0, v79
	v_or_b32_e32 v135, 64, v71
	v_xor_b32_e32 v136, 0xffffffbf, v71
	v_not_b32_e32 v138, v137
	v_add_u32_e32 v139, v1, v114
	v_add_u32_e32 v140, v66, v78
	v_add_u32_e32 v141, v114, v85
	s_mov_b32 s76, s75
	s_waitcnt vmcnt(0)
	s_and_saveexec_b64 s[0:1], s[4:5]
	s_xor_b64 s[0:1], exec, s[0:1]
	s_cbranch_execz .LBB0_985

.LBB0_985:
	s_andn2_saveexec_b64 s[0:1], s[0:1]
	s_cbranch_execz .LBB0_1003
	v_add_u32_e32 v74, v129, v129
	v_add_u32_e32 v1, 0xb400, v74
	v_add_u32_e32 v142, 0xc000, v74
	ds_read2_b64 v[66:69], v1 offset0:96 offset1:192
	v_add_u32_e32 v89, 0xbc00, v74
	ds_read2_b64 v[74:77], v142 offset0:96 offset1:192
	ds_read2_b64 v[70:73], v89 offset0:32 offset1:128
	s_waitcnt vmcnt(16)
	v_lshlrev_b32_e32 v144, 16, v26
	v_lshlrev_b32_e32 v80, 16, v18
	v_lshlrev_b32_e32 v146, 16, v30
	v_mov_b32_e32 v81, v144
	v_lshlrev_b32_e32 v84, 16, v14
	s_waitcnt lgkmcnt(1)
	v_pk_fma_f32 v[80:81], v[66:67], v[80:81], v[76:77] op_sel_hi:[0,1,0]
	v_mov_b32_e32 v85, v146
	v_lshlrev_b32_e32 v145, 16, v34
	v_pk_fma_f32 v[80:81], v[68:69], v[84:85], v[80:81] op_sel_hi:[0,1,1]
	v_lshlrev_b32_e32 v147, 16, v38
	s_waitcnt lgkmcnt(0)
	v_pk_fma_f32 v[80:81], v[70:71], v[144:145], v[80:81] op_sel_hi:[0,1,1]
	v_lshlrev_b32_e32 v83, 16, v42
	v_mov_b32_e32 v82, v145
	v_pk_fma_f32 v[80:81], v[72:73], v[146:147], v[80:81] op_sel_hi:[0,1,1]
	v_pk_fma_f32 v[80:81], v[74:75], v[82:83], v[80:81] op_sel_hi:[0,1,1]
	v_mul_f32_e32 v107, 0xbfb8aa3b, v80
	v_pk_fma_f32 v[84:85], v[66:67], v[84:85], v[76:77] op_sel_hi:[0,1,0]
	v_exp_f32_e32 v154, v107
	v_mul_f32_e32 v107, 0xbfb8aa3b, v81
	v_pk_fma_f32 v[84:85], v[68:69], v[144:145], v[84:85] op_sel_hi:[0,1,1]
	v_exp_f32_e32 v155, v107
	v_pk_fma_f32 v[84:85], v[70:71], v[146:147], v[84:85] op_sel_hi:[0,1,1]
	v_lshlrev_b32_e32 v79, 16, v46
	v_mov_b32_e32 v78, v147
	v_pk_fma_f32 v[84:85], v[72:73], v[82:83], v[84:85] op_sel_hi:[0,1,1]
	v_pk_fma_f32 v[84:85], v[74:75], v[78:79], v[84:85] op_sel_hi:[0,1,1]
	v_mul_f32_e32 v107, 0xbfb8aa3b, v84
	v_pk_add_f32 v[154:155], v[154:155], 1.0 op_sel_hi:[1,0]
	v_exp_f32_e32 v144, v107
	v_mul_f32_e32 v107, 0xbfb8aa3b, v85
	v_exp_f32_e32 v145, v107
	v_rcp_f32_e32 v143, v155
	v_pk_add_f32 v[146:147], v[144:145], 1.0 op_sel_hi:[1,0]
	v_and_b32_e32 v150, 0xffff0000, v26
	v_and_b32_e32 v148, 0xffff0000, v18
	v_mul_f32_e32 v143, v81, v143
	v_rcp_f32_e32 v107, v154
	v_and_b32_e32 v152, 0xffff0000, v30
	v_and_b32_e32 v106, 0xffff0000, v14
	v_mul_f32_e32 v144, v80, v107
	v_rcp_f32_e32 v81, v147
	s_nop 0
	v_mul_f32_e32 v145, v85, v81
	v_rcp_f32_e32 v81, v146
	v_mov_b32_e32 v149, v150
	v_pk_fma_f32 v[148:149], v[66:67], v[148:149], v[76:77] op_sel:[1,0,1]
	v_mul_f32_e32 v146, v84, v81
	v_and_b32_e32 v84, 0xffff0000, v34
	v_mov_b32_e32 v107, v152
	v_mov_b32_e32 v151, v84
	v_and_b32_e32 v80, 0xffff0000, v38
	v_pk_fma_f32 v[148:149], v[68:69], v[106:107], v[148:149] op_sel:[1,0,0]
	v_mov_b32_e32 v153, v80
	v_pk_fma_f32 v[148:149], v[70:71], v[150:151], v[148:149] op_sel:[1,0,0]
	v_pk_fma_f32 v[106:107], v[66:67], v[106:107], v[76:77] op_sel:[1,0,1]
	v_and_b32_e32 v85, 0xffff0000, v42
	v_pk_fma_f32 v[148:149], v[72:73], v[152:153], v[148:149] op_sel:[1,0,0]
	v_pk_fma_f32 v[106:107], v[68:69], v[150:151], v[106:107] op_sel:[1,0,0]
	v_pk_fma_f32 v[148:149], v[74:75], v[84:85], v[148:149] op_sel:[1,0,0]
	v_pk_fma_f32 v[106:107], v[70:71], v[152:153], v[106:107] op_sel:[1,0,0]
	v_and_b32_e32 v81, 0xffff0000, v46
	v_mul_f32_e32 v147, 0xbfb8aa3b, v148
	v_pk_fma_f32 v[106:107], v[72:73], v[84:85], v[106:107] op_sel:[1,0,0]
	v_exp_f32_e32 v154, v147
	v_mul_f32_e32 v147, 0xbfb8aa3b, v149
	v_pk_fma_f32 v[150:151], v[74:75], v[80:81], v[106:107] op_sel:[1,0,0]
	v_exp_f32_e32 v155, v147
	v_mul_f32_e32 v106, 0xbfb8aa3b, v150
	v_mul_f32_e32 v107, 0xbfb8aa3b, v151
	v_exp_f32_e32 v106, v106
	v_exp_f32_e32 v107, v107
	v_pk_add_f32 v[154:155], v[154:155], 1.0 op_sel_hi:[1,0]
	v_pk_add_f32 v[152:153], v[106:107], 1.0 op_sel_hi:[1,0]
	v_rcp_f32_e32 v107, v155
	s_nop 0
	v_mul_f32_e32 v106, v149, v107
	v_rcp_f32_e32 v147, v154
	s_nop 0
	v_mul_f32_e32 v107, v148, v147
	v_rcp_f32_e32 v148, v153
	s_nop 0
	v_mul_f32_e32 v147, v151, v148
	v_rcp_f32_e32 v149, v152
	s_nop 0
	v_mul_f32_e32 v148, v150, v149
	v_lshlrev_b32_e32 v150, 16, v50
	v_lshlrev_b32_e32 v151, 16, v58
	v_pk_fma_f32 v[154:155], v[66:67], v[82:83], v[76:77] op_sel_hi:[0,1,0]
	v_lshlrev_b32_e32 v152, 16, v54
	v_lshlrev_b32_e32 v153, 16, v62
	v_pk_fma_f32 v[154:155], v[68:69], v[78:79], v[154:155] op_sel_hi:[0,1,1]
	v_pk_mov_b32 v[82:83], v[82:83], v[150:151] op_sel:[1,0]
	v_pk_mov_b32 v[156:157], v[78:79], v[152:153] op_sel:[1,0]
	v_pk_fma_f32 v[154:155], v[70:71], v[82:83], v[154:155] op_sel_hi:[0,1,1]
	v_pk_fma_f32 v[78:79], v[66:67], v[78:79], v[76:77] op_sel_hi:[0,1,0]
	v_pk_fma_f32 v[154:155], v[72:73], v[156:157], v[154:155] op_sel_hi:[0,1,1]
	v_pk_fma_f32 v[78:79], v[68:69], v[82:83], v[78:79] op_sel_hi:[0,1,1]
	v_pk_fma_f32 v[154:155], v[74:75], v[150:151], v[154:155] op_sel_hi:[0,1,1]
	v_pk_fma_f32 v[78:79], v[70:71], v[156:157], v[78:79] op_sel_hi:[0,1,1]
	v_mul_f32_e32 v149, 0xbfb8aa3b, v154
	v_pk_fma_f32 v[78:79], v[72:73], v[150:151], v[78:79] op_sel_hi:[0,1,1]
	v_exp_f32_e32 v158, v149
	v_mul_f32_e32 v149, 0xbfb8aa3b, v155
	v_pk_fma_f32 v[150:151], v[74:75], v[152:153], v[78:79] op_sel_hi:[0,1,1]
	v_exp_f32_e32 v159, v149
	v_mul_f32_e32 v78, 0xbfb8aa3b, v150
	v_mul_f32_e32 v79, 0xbfb8aa3b, v151
	v_exp_f32_e32 v78, v78
	v_exp_f32_e32 v79, v79
	v_pk_add_f32 v[158:159], v[158:159], 1.0 op_sel_hi:[1,0]
	v_pk_add_f32 v[152:153], v[78:79], 1.0 op_sel_hi:[1,0]
	v_rcp_f32_e32 v79, v159
	s_nop 0
	v_mul_f32_e32 v78, v155, v79
	v_rcp_f32_e32 v82, v158
	s_nop 0
	v_mul_f32_e32 v79, v154, v82
	v_rcp_f32_e32 v83, v153
	s_nop 0
	v_mul_f32_e32 v82, v151, v83
	v_rcp_f32_e32 v149, v152
	s_nop 0
	v_mul_f32_e32 v83, v150, v149
	v_and_b32_e32 v151, 0xffff0000, v58
	v_and_b32_e32 v150, 0xffff0000, v50
	v_pk_fma_f32 v[154:155], v[66:67], v[84:85], v[76:77] op_sel:[1,0,1]
	v_and_b32_e32 v153, 0xffff0000, v62
	v_and_b32_e32 v152, 0xffff0000, v54
	v_pk_fma_f32 v[154:155], v[68:69], v[80:81], v[154:155] op_sel:[1,0,0]
	v_pk_mov_b32 v[84:85], v[84:85], v[150:151] op_sel:[1,0]
	v_pk_mov_b32 v[156:157], v[80:81], v[152:153] op_sel:[1,0]
	v_pk_fma_f32 v[154:155], v[70:71], v[84:85], v[154:155] op_sel:[1,0,0]
	v_pk_fma_f32 v[66:67], v[66:67], v[80:81], v[76:77] op_sel:[1,0,1]
	v_pk_fma_f32 v[154:155], v[72:73], v[156:157], v[154:155] op_sel:[1,0,0]
	v_pk_fma_f32 v[66:67], v[68:69], v[84:85], v[66:67] op_sel:[1,0,0]
	v_pk_fma_f32 v[154:155], v[74:75], v[150:151], v[154:155] op_sel:[1,0,0]
	v_pk_fma_f32 v[66:67], v[70:71], v[156:157], v[66:67] op_sel:[1,0,0]
	v_mul_f32_e32 v149, 0xbfb8aa3b, v154
	v_pk_fma_f32 v[66:67], v[72:73], v[150:151], v[66:67] op_sel:[1,0,0]
	v_exp_f32_e32 v158, v149
	v_mul_f32_e32 v149, 0xbfb8aa3b, v155
	v_pk_fma_f32 v[70:71], v[74:75], v[152:153], v[66:67] op_sel:[1,0,0]
	v_exp_f32_e32 v159, v149
	v_mul_f32_e32 v66, 0xbfb8aa3b, v70
	v_mul_f32_e32 v67, 0xbfb8aa3b, v71
	v_exp_f32_e32 v66, v66
	v_exp_f32_e32 v67, v67
	v_pk_add_f32 v[158:159], v[158:159], 1.0 op_sel_hi:[1,0]
	v_pk_add_f32 v[72:73], v[66:67], 1.0 op_sel_hi:[1,0]
	v_rcp_f32_e32 v67, v159
	s_nop 0
	v_mul_f32_e32 v66, v155, v67
	v_rcp_f32_e32 v68, v158
	s_nop 0
	v_mul_f32_e32 v67, v154, v68
	v_rcp_f32_e32 v69, v73
	s_nop 0
	v_mul_f32_e32 v68, v71, v69
	v_rcp_f32_e32 v71, v72
	s_nop 0
	v_mul_f32_e32 v69, v70, v71
	s_and_saveexec_b64 s[58:59], s[8:9]
	s_cbranch_execz .LBB0_988
	v_bfe_u32 v70, v144, 16, 1
	v_add3_u32 v70, v144, v70, s33
	v_bfe_u32 v71, v107, 16, 1
	v_lshrrev_b32_e32 v70, 16, v70
	v_add3_u32 v71, v107, v71, s33
	v_and_or_b32 v70, v71, s71, v70
	v_bfe_u32 v71, v146, 16, 1
	v_add3_u32 v71, v146, v71, s33
	v_bfe_u32 v72, v148, 16, 1
	v_lshrrev_b32_e32 v71, 16, v71
	v_add3_u32 v72, v148, v72, s33
	v_and_or_b32 v71, v72, s71, v71
	ds_write2_b32 v140, v70, v71 offset1:36
	v_bfe_u32 v70, v143, 16, 1
	v_add3_u32 v70, v143, v70, s33
	v_bfe_u32 v71, v106, 16, 1
	v_lshrrev_b32_e32 v70, 16, v70
	v_add3_u32 v71, v106, v71, s33
	v_and_or_b32 v70, v71, s71, v70
	v_bfe_u32 v71, v145, 16, 1
	v_add3_u32 v71, v145, v71, s33
	v_bfe_u32 v72, v147, 16, 1
	v_lshrrev_b32_e32 v71, 16, v71
	v_add3_u32 v72, v147, v72, s33
	v_and_or_b32 v71, v72, s71, v71
	ds_write2_b32 v140, v70, v71 offset0:72 offset1:108
	v_bfe_u32 v70, v79, 16, 1
	v_add3_u32 v70, v79, v70, s33
	v_bfe_u32 v71, v67, 16, 1
	v_lshrrev_b32_e32 v70, 16, v70
	v_add3_u32 v71, v67, v71, s33
	v_and_or_b32 v70, v71, s71, v70
	v_bfe_u32 v71, v83, 16, 1
	v_add3_u32 v71, v83, v71, s33
	v_bfe_u32 v72, v69, 16, 1
	v_lshrrev_b32_e32 v71, 16, v71
	v_add3_u32 v72, v69, v72, s33
	v_and_or_b32 v71, v72, s71, v71
	ds_write2_b32 v140, v70, v71 offset0:144 offset1:180
	v_bfe_u32 v70, v78, 16, 1
	v_add3_u32 v70, v78, v70, s33
	v_bfe_u32 v71, v66, 16, 1
	v_lshrrev_b32_e32 v70, 16, v70
	v_add3_u32 v71, v66, v71, s33
	v_and_or_b32 v70, v71, s71, v70
	v_bfe_u32 v71, v82, 16, 1
	v_add3_u32 v71, v82, v71, s33
	v_bfe_u32 v72, v68, 16, 1
	v_lshrrev_b32_e32 v71, 16, v71
	v_add3_u32 v72, v68, v72, s33
	v_and_or_b32 v71, v72, s71, v71
	ds_write2_b32 v140, v70, v71 offset0:216 offset1:252

.LBB0_990:
	s_or_b64 exec, exec, s[58:59]
	ds_read2_b64 v[74:77], v1 offset0:97 offset1:193
	ds_read2_b64 v[66:69], v89 offset0:33 offset1:129
	ds_read2_b64 v[70:73], v142 offset0:97 offset1:193
	v_lshlrev_b32_e32 v106, 16, v27
	v_lshlrev_b32_e32 v80, 16, v19
	v_lshlrev_b32_e32 v144, 16, v31
	v_mov_b32_e32 v81, v106
	v_lshlrev_b32_e32 v84, 16, v15
	s_waitcnt lgkmcnt(0)
	v_pk_fma_f32 v[80:81], v[74:75], v[80:81], v[72:73] op_sel_hi:[0,1,0]
	v_mov_b32_e32 v85, v144
	v_lshlrev_b32_e32 v107, 16, v35
	v_pk_fma_f32 v[80:81], v[76:77], v[84:85], v[80:81] op_sel_hi:[0,1,1]
	v_lshlrev_b32_e32 v145, 16, v39
	v_pk_fma_f32 v[80:81], v[66:67], v[106:107], v[80:81] op_sel_hi:[0,1,1]
	v_pk_fma_f32 v[84:85], v[74:75], v[84:85], v[72:73] op_sel_hi:[0,1,0]
	v_lshlrev_b32_e32 v83, 16, v43
	v_mov_b32_e32 v82, v107
	v_pk_fma_f32 v[80:81], v[68:69], v[144:145], v[80:81] op_sel_hi:[0,1,1]
	v_pk_fma_f32 v[84:85], v[76:77], v[106:107], v[84:85] op_sel_hi:[0,1,1]
	v_pk_fma_f32 v[80:81], v[70:71], v[82:83], v[80:81] op_sel_hi:[0,1,1]
	v_pk_fma_f32 v[84:85], v[66:67], v[144:145], v[84:85] op_sel_hi:[0,1,1]
	v_lshlrev_b32_e32 v79, 16, v47
	v_mov_b32_e32 v78, v145
	v_mul_f32_e32 v143, 0xbfb8aa3b, v80
	v_pk_fma_f32 v[84:85], v[68:69], v[82:83], v[84:85] op_sel_hi:[0,1,1]
	v_exp_f32_e32 v154, v143
	v_mul_f32_e32 v143, 0xbfb8aa3b, v81
	v_pk_fma_f32 v[84:85], v[70:71], v[78:79], v[84:85] op_sel_hi:[0,1,1]
	v_exp_f32_e32 v155, v143
	v_mul_f32_e32 v106, 0xbfb8aa3b, v84
	v_mul_f32_e32 v107, 0xbfb8aa3b, v85
	v_exp_f32_e32 v106, v106
	v_exp_f32_e32 v107, v107
	v_pk_add_f32 v[154:155], v[154:155], 1.0 op_sel_hi:[1,0]
	v_and_b32_e32 v150, 0xffff0000, v27
	v_and_b32_e32 v146, 0xffff0000, v19
	v_pk_add_f32 v[144:145], v[106:107], 1.0 op_sel_hi:[1,0]
	v_rcp_f32_e32 v107, v155
	v_and_b32_e32 v152, 0xffff0000, v31
	v_and_b32_e32 v148, 0xffff0000, v15
	v_mul_f32_e32 v106, v81, v107
	v_rcp_f32_e32 v107, v154
	s_nop 0
	v_mul_f32_e32 v107, v80, v107
	v_rcp_f32_e32 v81, v145
	s_nop 0
	v_mul_f32_e32 v143, v85, v81
	v_rcp_f32_e32 v81, v144
	v_mov_b32_e32 v149, v152
	v_mul_f32_e32 v144, v84, v81
	v_mov_b32_e32 v147, v150
	v_and_b32_e32 v84, 0xffff0000, v35
	v_pk_fma_f32 v[146:147], v[74:75], v[146:147], v[72:73] op_sel:[1,0,1]
	v_mov_b32_e32 v151, v84
	v_and_b32_e32 v80, 0xffff0000, v39
	v_pk_fma_f32 v[146:147], v[76:77], v[148:149], v[146:147] op_sel:[1,0,0]
	v_mov_b32_e32 v153, v80
	v_pk_fma_f32 v[146:147], v[66:67], v[150:151], v[146:147] op_sel:[1,0,0]
	v_and_b32_e32 v85, 0xffff0000, v43
	v_pk_fma_f32 v[146:147], v[68:69], v[152:153], v[146:147] op_sel:[1,0,0]
	v_pk_fma_f32 v[148:149], v[74:75], v[148:149], v[72:73] op_sel:[1,0,1]
	v_pk_fma_f32 v[146:147], v[70:71], v[84:85], v[146:147] op_sel:[1,0,0]
	v_pk_fma_f32 v[148:149], v[76:77], v[150:151], v[148:149] op_sel:[1,0,0]
	v_mul_f32_e32 v145, 0xbfb8aa3b, v146
	v_exp_f32_e32 v154, v145
	v_mul_f32_e32 v145, 0xbfb8aa3b, v147
	v_exp_f32_e32 v155, v145
	v_pk_fma_f32 v[148:149], v[66:67], v[152:153], v[148:149] op_sel:[1,0,0]
	v_and_b32_e32 v81, 0xffff0000, v47
	v_pk_fma_f32 v[148:149], v[68:69], v[84:85], v[148:149] op_sel:[1,0,0]
	v_pk_add_f32 v[154:155], v[154:155], 1.0 op_sel_hi:[1,0]
	v_pk_fma_f32 v[148:149], v[70:71], v[80:81], v[148:149] op_sel:[1,0,0]
	s_nop 0
	v_mul_f32_e32 v145, 0xbfb8aa3b, v148
	v_exp_f32_e32 v150, v145
	v_mul_f32_e32 v145, 0xbfb8aa3b, v149
	v_exp_f32_e32 v151, v145
	v_rcp_f32_e32 v152, v155
	v_pk_add_f32 v[150:151], v[150:151], 1.0 op_sel_hi:[1,0]
	v_mul_f32_e32 v145, v147, v152
	v_rcp_f32_e32 v152, v154
	s_nop 0
	v_mul_f32_e32 v146, v146, v152
	v_rcp_f32_e32 v152, v151
	s_nop 0
	v_mul_f32_e32 v147, v149, v152
	v_rcp_f32_e32 v151, v150
	s_nop 0
	v_mul_f32_e32 v148, v148, v151
	v_lshlrev_b32_e32 v150, 16, v51
	v_lshlrev_b32_e32 v151, 16, v59
	v_pk_fma_f32 v[154:155], v[74:75], v[82:83], v[72:73] op_sel_hi:[0,1,0]
	v_lshlrev_b32_e32 v152, 16, v55
	v_lshlrev_b32_e32 v153, 16, v63
	v_pk_fma_f32 v[154:155], v[76:77], v[78:79], v[154:155] op_sel_hi:[0,1,1]
	v_pk_mov_b32 v[82:83], v[82:83], v[150:151] op_sel:[1,0]
	v_pk_mov_b32 v[156:157], v[78:79], v[152:153] op_sel:[1,0]
	v_pk_fma_f32 v[154:155], v[66:67], v[82:83], v[154:155] op_sel_hi:[0,1,1]
	v_pk_fma_f32 v[78:79], v[74:75], v[78:79], v[72:73] op_sel_hi:[0,1,0]
	v_pk_fma_f32 v[154:155], v[68:69], v[156:157], v[154:155] op_sel_hi:[0,1,1]
	v_pk_fma_f32 v[78:79], v[76:77], v[82:83], v[78:79] op_sel_hi:[0,1,1]
	v_pk_fma_f32 v[154:155], v[70:71], v[150:151], v[154:155] op_sel_hi:[0,1,1]
	v_pk_fma_f32 v[78:79], v[66:67], v[156:157], v[78:79] op_sel_hi:[0,1,1]
	v_mul_f32_e32 v149, 0xbfb8aa3b, v154
	v_pk_fma_f32 v[78:79], v[68:69], v[150:151], v[78:79] op_sel_hi:[0,1,1]
	v_exp_f32_e32 v158, v149
	v_mul_f32_e32 v149, 0xbfb8aa3b, v155
	v_pk_fma_f32 v[150:151], v[70:71], v[152:153], v[78:79] op_sel_hi:[0,1,1]
	v_exp_f32_e32 v159, v149
	v_mul_f32_e32 v78, 0xbfb8aa3b, v150
	v_mul_f32_e32 v79, 0xbfb8aa3b, v151
	v_exp_f32_e32 v78, v78
	v_exp_f32_e32 v79, v79
	v_pk_add_f32 v[158:159], v[158:159], 1.0 op_sel_hi:[1,0]
	v_pk_add_f32 v[152:153], v[78:79], 1.0 op_sel_hi:[1,0]
	v_rcp_f32_e32 v79, v159
	s_nop 0
	v_mul_f32_e32 v78, v155, v79
	v_rcp_f32_e32 v82, v158
	s_nop 0
	v_mul_f32_e32 v79, v154, v82
	v_rcp_f32_e32 v83, v153
	s_nop 0
	v_mul_f32_e32 v82, v151, v83
	v_rcp_f32_e32 v149, v152
	s_nop 0
	v_mul_f32_e32 v83, v150, v149
	v_and_b32_e32 v151, 0xffff0000, v59
	v_and_b32_e32 v150, 0xffff0000, v51
	v_pk_fma_f32 v[154:155], v[74:75], v[84:85], v[72:73] op_sel:[1,0,1]
	v_and_b32_e32 v153, 0xffff0000, v63
	v_and_b32_e32 v152, 0xffff0000, v55
	v_pk_fma_f32 v[154:155], v[76:77], v[80:81], v[154:155] op_sel:[1,0,0]
	v_pk_mov_b32 v[84:85], v[84:85], v[150:151] op_sel:[1,0]
	v_pk_mov_b32 v[156:157], v[80:81], v[152:153] op_sel:[1,0]
	v_pk_fma_f32 v[154:155], v[66:67], v[84:85], v[154:155] op_sel:[1,0,0]
	v_pk_fma_f32 v[72:73], v[74:75], v[80:81], v[72:73] op_sel:[1,0,1]
	v_pk_fma_f32 v[154:155], v[68:69], v[156:157], v[154:155] op_sel:[1,0,0]
	v_pk_fma_f32 v[72:73], v[76:77], v[84:85], v[72:73] op_sel:[1,0,0]
	v_pk_fma_f32 v[154:155], v[70:71], v[150:151], v[154:155] op_sel:[1,0,0]
	v_pk_fma_f32 v[66:67], v[66:67], v[156:157], v[72:73] op_sel:[1,0,0]
	v_mul_f32_e32 v149, 0xbfb8aa3b, v154
	v_pk_fma_f32 v[66:67], v[68:69], v[150:151], v[66:67] op_sel:[1,0,0]
	v_exp_f32_e32 v158, v149
	v_mul_f32_e32 v149, 0xbfb8aa3b, v155
	v_pk_fma_f32 v[70:71], v[70:71], v[152:153], v[66:67] op_sel:[1,0,0]
	v_exp_f32_e32 v159, v149
	v_mul_f32_e32 v66, 0xbfb8aa3b, v70
	v_mul_f32_e32 v67, 0xbfb8aa3b, v71
	v_exp_f32_e32 v66, v66
	v_exp_f32_e32 v67, v67
	v_pk_add_f32 v[158:159], v[158:159], 1.0 op_sel_hi:[1,0]
	v_pk_add_f32 v[72:73], v[66:67], 1.0 op_sel_hi:[1,0]
	v_rcp_f32_e32 v67, v159
	s_nop 0
	v_mul_f32_e32 v66, v155, v67
	v_rcp_f32_e32 v68, v158
	s_nop 0
	v_mul_f32_e32 v67, v154, v68
	v_rcp_f32_e32 v69, v73
	s_nop 0
	v_mul_f32_e32 v68, v71, v69
	v_rcp_f32_e32 v71, v72
	s_nop 0
	v_mul_f32_e32 v69, v70, v71
	s_and_saveexec_b64 s[58:59], s[8:9]
	s_cbranch_execz .LBB0_992
	v_bfe_u32 v70, v107, 16, 1
	v_add3_u32 v70, v107, v70, s33
	v_bfe_u32 v71, v146, 16, 1
	v_lshrrev_b32_e32 v70, 16, v70
	v_add3_u32 v71, v146, v71, s33
	v_and_or_b32 v70, v71, s71, v70
	v_bfe_u32 v71, v144, 16, 1
	v_add3_u32 v71, v144, v71, s33
	v_bfe_u32 v72, v148, 16, 1
	v_lshrrev_b32_e32 v71, 16, v71
	v_add3_u32 v72, v148, v72, s33
	v_and_or_b32 v71, v72, s71, v71
	ds_write2_b32 v140, v70, v71 offset0:1 offset1:37
	v_bfe_u32 v70, v106, 16, 1
	v_add3_u32 v70, v106, v70, s33
	v_bfe_u32 v71, v145, 16, 1
	v_lshrrev_b32_e32 v70, 16, v70
	v_add3_u32 v71, v145, v71, s33
	v_and_or_b32 v70, v71, s71, v70
	v_bfe_u32 v71, v143, 16, 1
	v_add3_u32 v71, v143, v71, s33
	v_bfe_u32 v72, v147, 16, 1
	v_lshrrev_b32_e32 v71, 16, v71
	v_add3_u32 v72, v147, v72, s33
	v_and_or_b32 v71, v72, s71, v71
	ds_write2_b32 v140, v70, v71 offset0:73 offset1:109
	v_bfe_u32 v70, v79, 16, 1
	v_add3_u32 v70, v79, v70, s33
	v_bfe_u32 v71, v67, 16, 1
	v_lshrrev_b32_e32 v70, 16, v70
	v_add3_u32 v71, v67, v71, s33
	v_and_or_b32 v70, v71, s71, v70
	v_bfe_u32 v71, v83, 16, 1
	v_add3_u32 v71, v83, v71, s33
	v_bfe_u32 v72, v69, 16, 1
	v_lshrrev_b32_e32 v71, 16, v71
	v_add3_u32 v72, v69, v72, s33
	v_and_or_b32 v71, v72, s71, v71
	ds_write2_b32 v140, v70, v71 offset0:145 offset1:181
	v_bfe_u32 v70, v78, 16, 1
	v_add3_u32 v70, v78, v70, s33
	v_bfe_u32 v71, v66, 16, 1
	v_lshrrev_b32_e32 v70, 16, v70
	v_add3_u32 v71, v66, v71, s33
	v_and_or_b32 v70, v71, s71, v70
	v_bfe_u32 v71, v82, 16, 1
	v_add3_u32 v71, v82, v71, s33
	v_bfe_u32 v72, v68, 16, 1
	v_lshrrev_b32_e32 v71, 16, v71
	v_add3_u32 v72, v68, v72, s33
	v_and_or_b32 v71, v72, s71, v71
	ds_write2_b32 v140, v70, v71 offset0:217 offset1:253

.LBB0_994:
	s_or_b64 exec, exec, s[58:59]
	ds_read2_b64 v[74:77], v1 offset0:98 offset1:194
	ds_read2_b64 v[66:69], v89 offset0:34 offset1:130
	ds_read2_b64 v[70:73], v142 offset0:98 offset1:194
	v_lshlrev_b32_e32 v106, 16, v28
	v_lshlrev_b32_e32 v80, 16, v20
	v_lshlrev_b32_e32 v144, 16, v32
	v_mov_b32_e32 v81, v106
	v_lshlrev_b32_e32 v84, 16, v16
	s_waitcnt lgkmcnt(0)
	v_pk_fma_f32 v[80:81], v[74:75], v[80:81], v[72:73] op_sel_hi:[0,1,0]
	v_mov_b32_e32 v85, v144
	v_lshlrev_b32_e32 v107, 16, v36
	v_pk_fma_f32 v[80:81], v[76:77], v[84:85], v[80:81] op_sel_hi:[0,1,1]
	v_lshlrev_b32_e32 v145, 16, v40
	v_pk_fma_f32 v[80:81], v[66:67], v[106:107], v[80:81] op_sel_hi:[0,1,1]
	v_pk_fma_f32 v[84:85], v[74:75], v[84:85], v[72:73] op_sel_hi:[0,1,0]
	v_lshlrev_b32_e32 v83, 16, v44
	v_mov_b32_e32 v82, v107
	v_pk_fma_f32 v[80:81], v[68:69], v[144:145], v[80:81] op_sel_hi:[0,1,1]
	v_pk_fma_f32 v[84:85], v[76:77], v[106:107], v[84:85] op_sel_hi:[0,1,1]
	v_pk_fma_f32 v[80:81], v[70:71], v[82:83], v[80:81] op_sel_hi:[0,1,1]
	v_pk_fma_f32 v[84:85], v[66:67], v[144:145], v[84:85] op_sel_hi:[0,1,1]
	v_lshlrev_b32_e32 v79, 16, v48
	v_mov_b32_e32 v78, v145
	v_mul_f32_e32 v143, 0xbfb8aa3b, v80
	v_pk_fma_f32 v[84:85], v[68:69], v[82:83], v[84:85] op_sel_hi:[0,1,1]
	v_exp_f32_e32 v154, v143
	v_mul_f32_e32 v143, 0xbfb8aa3b, v81
	v_pk_fma_f32 v[84:85], v[70:71], v[78:79], v[84:85] op_sel_hi:[0,1,1]
	v_exp_f32_e32 v155, v143
	v_mul_f32_e32 v106, 0xbfb8aa3b, v84
	v_mul_f32_e32 v107, 0xbfb8aa3b, v85
	v_exp_f32_e32 v106, v106
	v_exp_f32_e32 v107, v107
	v_pk_add_f32 v[154:155], v[154:155], 1.0 op_sel_hi:[1,0]
	v_and_b32_e32 v150, 0xffff0000, v28
	v_and_b32_e32 v146, 0xffff0000, v20
	v_pk_add_f32 v[144:145], v[106:107], 1.0 op_sel_hi:[1,0]
	v_rcp_f32_e32 v107, v155
	v_and_b32_e32 v152, 0xffff0000, v32
	v_and_b32_e32 v148, 0xffff0000, v16
	v_mul_f32_e32 v106, v81, v107
	v_rcp_f32_e32 v107, v154
	s_nop 0
	v_mul_f32_e32 v107, v80, v107
	v_rcp_f32_e32 v81, v145
	s_nop 0
	v_mul_f32_e32 v143, v85, v81
	v_rcp_f32_e32 v81, v144
	v_mov_b32_e32 v149, v152
	v_mul_f32_e32 v144, v84, v81
	v_mov_b32_e32 v147, v150
	v_and_b32_e32 v84, 0xffff0000, v36
	v_pk_fma_f32 v[146:147], v[74:75], v[146:147], v[72:73] op_sel:[1,0,1]
	v_mov_b32_e32 v151, v84
	v_and_b32_e32 v80, 0xffff0000, v40
	v_pk_fma_f32 v[146:147], v[76:77], v[148:149], v[146:147] op_sel:[1,0,0]
	v_mov_b32_e32 v153, v80
	v_pk_fma_f32 v[146:147], v[66:67], v[150:151], v[146:147] op_sel:[1,0,0]
	v_and_b32_e32 v85, 0xffff0000, v44
	v_pk_fma_f32 v[146:147], v[68:69], v[152:153], v[146:147] op_sel:[1,0,0]
	v_pk_fma_f32 v[148:149], v[74:75], v[148:149], v[72:73] op_sel:[1,0,1]
	v_pk_fma_f32 v[146:147], v[70:71], v[84:85], v[146:147] op_sel:[1,0,0]
	v_pk_fma_f32 v[148:149], v[76:77], v[150:151], v[148:149] op_sel:[1,0,0]
	v_mul_f32_e32 v145, 0xbfb8aa3b, v146
	v_exp_f32_e32 v154, v145
	v_mul_f32_e32 v145, 0xbfb8aa3b, v147
	v_exp_f32_e32 v155, v145
	v_pk_fma_f32 v[148:149], v[66:67], v[152:153], v[148:149] op_sel:[1,0,0]
	v_and_b32_e32 v81, 0xffff0000, v48
	v_pk_fma_f32 v[148:149], v[68:69], v[84:85], v[148:149] op_sel:[1,0,0]
	v_pk_add_f32 v[154:155], v[154:155], 1.0 op_sel_hi:[1,0]
	v_pk_fma_f32 v[148:149], v[70:71], v[80:81], v[148:149] op_sel:[1,0,0]
	s_nop 0
	v_mul_f32_e32 v145, 0xbfb8aa3b, v148
	v_exp_f32_e32 v150, v145
	v_mul_f32_e32 v145, 0xbfb8aa3b, v149
	v_exp_f32_e32 v151, v145
	v_rcp_f32_e32 v152, v155
	v_pk_add_f32 v[150:151], v[150:151], 1.0 op_sel_hi:[1,0]
	v_mul_f32_e32 v145, v147, v152
	v_rcp_f32_e32 v152, v154
	s_nop 0
	v_mul_f32_e32 v146, v146, v152
	v_rcp_f32_e32 v152, v151
	s_nop 0
	v_mul_f32_e32 v147, v149, v152
	v_rcp_f32_e32 v151, v150
	s_nop 0
	v_mul_f32_e32 v148, v148, v151
	v_lshlrev_b32_e32 v150, 16, v52
	v_lshlrev_b32_e32 v151, 16, v60
	v_pk_fma_f32 v[154:155], v[74:75], v[82:83], v[72:73] op_sel_hi:[0,1,0]
	v_lshlrev_b32_e32 v152, 16, v56
	v_lshlrev_b32_e32 v153, 16, v64
	v_pk_fma_f32 v[154:155], v[76:77], v[78:79], v[154:155] op_sel_hi:[0,1,1]
	v_pk_mov_b32 v[82:83], v[82:83], v[150:151] op_sel:[1,0]
	v_pk_mov_b32 v[156:157], v[78:79], v[152:153] op_sel:[1,0]
	v_pk_fma_f32 v[154:155], v[66:67], v[82:83], v[154:155] op_sel_hi:[0,1,1]
	v_pk_fma_f32 v[78:79], v[74:75], v[78:79], v[72:73] op_sel_hi:[0,1,0]
	v_pk_fma_f32 v[154:155], v[68:69], v[156:157], v[154:155] op_sel_hi:[0,1,1]
	v_pk_fma_f32 v[78:79], v[76:77], v[82:83], v[78:79] op_sel_hi:[0,1,1]
	v_pk_fma_f32 v[154:155], v[70:71], v[150:151], v[154:155] op_sel_hi:[0,1,1]
	v_pk_fma_f32 v[78:79], v[66:67], v[156:157], v[78:79] op_sel_hi:[0,1,1]
	v_mul_f32_e32 v149, 0xbfb8aa3b, v154
	v_pk_fma_f32 v[78:79], v[68:69], v[150:151], v[78:79] op_sel_hi:[0,1,1]
	v_exp_f32_e32 v158, v149
	v_mul_f32_e32 v149, 0xbfb8aa3b, v155
	v_pk_fma_f32 v[150:151], v[70:71], v[152:153], v[78:79] op_sel_hi:[0,1,1]
	v_exp_f32_e32 v159, v149
	v_mul_f32_e32 v78, 0xbfb8aa3b, v150
	v_mul_f32_e32 v79, 0xbfb8aa3b, v151
	v_exp_f32_e32 v78, v78
	v_exp_f32_e32 v79, v79
	v_pk_add_f32 v[158:159], v[158:159], 1.0 op_sel_hi:[1,0]
	v_pk_add_f32 v[152:153], v[78:79], 1.0 op_sel_hi:[1,0]
	v_rcp_f32_e32 v79, v159
	s_nop 0
	v_mul_f32_e32 v78, v155, v79
	v_rcp_f32_e32 v82, v158
	s_nop 0
	v_mul_f32_e32 v79, v154, v82
	v_rcp_f32_e32 v83, v153
	s_nop 0
	v_mul_f32_e32 v82, v151, v83
	v_rcp_f32_e32 v149, v152
	s_nop 0
	v_mul_f32_e32 v83, v150, v149
	v_and_b32_e32 v151, 0xffff0000, v60
	v_and_b32_e32 v150, 0xffff0000, v52
	v_pk_fma_f32 v[154:155], v[74:75], v[84:85], v[72:73] op_sel:[1,0,1]
	v_and_b32_e32 v153, 0xffff0000, v64
	v_and_b32_e32 v152, 0xffff0000, v56
	v_pk_fma_f32 v[154:155], v[76:77], v[80:81], v[154:155] op_sel:[1,0,0]
	v_pk_mov_b32 v[84:85], v[84:85], v[150:151] op_sel:[1,0]
	v_pk_mov_b32 v[156:157], v[80:81], v[152:153] op_sel:[1,0]
	v_pk_fma_f32 v[154:155], v[66:67], v[84:85], v[154:155] op_sel:[1,0,0]
	v_pk_fma_f32 v[72:73], v[74:75], v[80:81], v[72:73] op_sel:[1,0,1]
	v_pk_fma_f32 v[154:155], v[68:69], v[156:157], v[154:155] op_sel:[1,0,0]
	v_pk_fma_f32 v[72:73], v[76:77], v[84:85], v[72:73] op_sel:[1,0,0]
	v_pk_fma_f32 v[154:155], v[70:71], v[150:151], v[154:155] op_sel:[1,0,0]
	v_pk_fma_f32 v[66:67], v[66:67], v[156:157], v[72:73] op_sel:[1,0,0]
	v_mul_f32_e32 v149, 0xbfb8aa3b, v154
	v_pk_fma_f32 v[66:67], v[68:69], v[150:151], v[66:67] op_sel:[1,0,0]
	v_exp_f32_e32 v158, v149
	v_mul_f32_e32 v149, 0xbfb8aa3b, v155
	v_pk_fma_f32 v[70:71], v[70:71], v[152:153], v[66:67] op_sel:[1,0,0]
	v_exp_f32_e32 v159, v149
	v_mul_f32_e32 v66, 0xbfb8aa3b, v70
	v_mul_f32_e32 v67, 0xbfb8aa3b, v71
	v_exp_f32_e32 v66, v66
	v_exp_f32_e32 v67, v67
	v_pk_add_f32 v[158:159], v[158:159], 1.0 op_sel_hi:[1,0]
	v_pk_add_f32 v[72:73], v[66:67], 1.0 op_sel_hi:[1,0]
	v_rcp_f32_e32 v67, v159
	s_nop 0
	v_mul_f32_e32 v66, v155, v67
	v_rcp_f32_e32 v68, v158
	s_nop 0
	v_mul_f32_e32 v67, v154, v68
	v_rcp_f32_e32 v69, v73
	s_nop 0
	v_mul_f32_e32 v68, v71, v69
	v_rcp_f32_e32 v71, v72
	s_nop 0
	v_mul_f32_e32 v69, v70, v71
	s_and_saveexec_b64 s[58:59], s[8:9]
	s_cbranch_execz .LBB0_996
	v_bfe_u32 v70, v107, 16, 1
	v_add3_u32 v70, v107, v70, s33
	v_bfe_u32 v71, v146, 16, 1
	v_lshrrev_b32_e32 v70, 16, v70
	v_add3_u32 v71, v146, v71, s33
	v_and_or_b32 v70, v71, s71, v70
	v_bfe_u32 v71, v144, 16, 1
	v_add3_u32 v71, v144, v71, s33
	v_bfe_u32 v72, v148, 16, 1
	v_lshrrev_b32_e32 v71, 16, v71
	v_add3_u32 v72, v148, v72, s33
	v_and_or_b32 v71, v72, s71, v71
	ds_write2_b32 v140, v70, v71 offset0:2 offset1:38
	v_bfe_u32 v70, v106, 16, 1
	v_add3_u32 v70, v106, v70, s33
	v_bfe_u32 v71, v145, 16, 1
	v_lshrrev_b32_e32 v70, 16, v70
	v_add3_u32 v71, v145, v71, s33
	v_and_or_b32 v70, v71, s71, v70
	v_bfe_u32 v71, v143, 16, 1
	v_add3_u32 v71, v143, v71, s33
	v_bfe_u32 v72, v147, 16, 1
	v_lshrrev_b32_e32 v71, 16, v71
	v_add3_u32 v72, v147, v72, s33
	v_and_or_b32 v71, v72, s71, v71
	ds_write2_b32 v140, v70, v71 offset0:74 offset1:110
	v_bfe_u32 v70, v79, 16, 1
	v_add3_u32 v70, v79, v70, s33
	v_bfe_u32 v71, v67, 16, 1
	v_lshrrev_b32_e32 v70, 16, v70
	v_add3_u32 v71, v67, v71, s33
	v_and_or_b32 v70, v71, s71, v70
	v_bfe_u32 v71, v83, 16, 1
	v_add3_u32 v71, v83, v71, s33
	v_bfe_u32 v72, v69, 16, 1
	v_lshrrev_b32_e32 v71, 16, v71
	v_add3_u32 v72, v69, v72, s33
	v_and_or_b32 v71, v72, s71, v71
	ds_write2_b32 v140, v70, v71 offset0:146 offset1:182
	v_bfe_u32 v70, v78, 16, 1
	v_add3_u32 v70, v78, v70, s33
	v_bfe_u32 v71, v66, 16, 1
	v_lshrrev_b32_e32 v70, 16, v70
	v_add3_u32 v71, v66, v71, s33
	v_and_or_b32 v70, v71, s71, v70
	v_bfe_u32 v71, v82, 16, 1
	v_add3_u32 v71, v82, v71, s33
	v_bfe_u32 v72, v68, 16, 1
	v_lshrrev_b32_e32 v71, 16, v71
	v_add3_u32 v72, v68, v72, s33
	v_and_or_b32 v71, v72, s71, v71
	ds_write2_b32 v140, v70, v71 offset0:218 offset1:254

.LBB0_998:
	s_or_b64 exec, exec, s[58:59]
	ds_read2_b64 v[74:77], v1 offset0:99 offset1:195
	ds_read2_b64 v[66:69], v89 offset0:35 offset1:131
	ds_read2_b64 v[70:73], v142 offset0:99 offset1:195
	v_lshlrev_b32_e32 v106, 16, v29
	v_lshlrev_b32_e32 v80, 16, v21
	v_lshlrev_b32_e32 v150, 16, v33
	v_mov_b32_e32 v81, v106
	v_lshlrev_b32_e32 v84, 16, v17
	s_waitcnt lgkmcnt(0)
	v_pk_fma_f32 v[80:81], v[74:75], v[80:81], v[72:73] op_sel_hi:[0,1,0]
	v_mov_b32_e32 v85, v150
	v_lshlrev_b32_e32 v107, 16, v37
	v_pk_fma_f32 v[80:81], v[76:77], v[84:85], v[80:81] op_sel_hi:[0,1,1]
	v_lshlrev_b32_e32 v151, 16, v41
	v_pk_fma_f32 v[80:81], v[66:67], v[106:107], v[80:81] op_sel_hi:[0,1,1]
	v_lshlrev_b32_e32 v83, 16, v45
	v_mov_b32_e32 v82, v107
	v_pk_fma_f32 v[80:81], v[68:69], v[150:151], v[80:81] op_sel_hi:[0,1,1]
	v_pk_fma_f32 v[80:81], v[70:71], v[82:83], v[80:81] op_sel_hi:[0,1,1]
	v_mul_f32_e32 v1, 0xbfb8aa3b, v80
	v_pk_fma_f32 v[84:85], v[74:75], v[84:85], v[72:73] op_sel_hi:[0,1,0]
	v_exp_f32_e32 v142, v1
	v_mul_f32_e32 v1, 0xbfb8aa3b, v81
	v_pk_fma_f32 v[84:85], v[76:77], v[106:107], v[84:85] op_sel_hi:[0,1,1]
	v_exp_f32_e32 v143, v1
	v_pk_fma_f32 v[84:85], v[66:67], v[150:151], v[84:85] op_sel_hi:[0,1,1]
	v_lshlrev_b32_e32 v79, 16, v49
	v_mov_b32_e32 v78, v151
	v_pk_fma_f32 v[84:85], v[68:69], v[82:83], v[84:85] op_sel_hi:[0,1,1]
	v_pk_fma_f32 v[84:85], v[70:71], v[78:79], v[84:85] op_sel_hi:[0,1,1]
	v_mul_f32_e32 v1, 0xbfb8aa3b, v84
	v_pk_add_f32 v[142:143], v[142:143], 1.0 op_sel_hi:[1,0]
	v_exp_f32_e32 v106, v1
	v_mul_f32_e32 v1, 0xbfb8aa3b, v85
	v_exp_f32_e32 v107, v1
	v_rcp_f32_e32 v89, v143
	v_pk_add_f32 v[150:151], v[106:107], 1.0 op_sel_hi:[1,0]
	v_and_b32_e32 v148, 0xffff0000, v29
	v_and_b32_e32 v144, 0xffff0000, v21
	v_mul_f32_e32 v1, v81, v89
	v_rcp_f32_e32 v89, v142
	v_and_b32_e32 v152, 0xffff0000, v33
	v_mov_b32_e32 v145, v148
	v_and_b32_e32 v146, 0xffff0000, v17
	v_mul_f32_e32 v89, v80, v89
	v_rcp_f32_e32 v81, v151
	v_mov_b32_e32 v147, v152
	v_mul_f32_e32 v106, v85, v81
	v_rcp_f32_e32 v81, v150
	s_nop 0
	v_mul_f32_e32 v107, v84, v81
	v_and_b32_e32 v84, 0xffff0000, v37
	v_pk_fma_f32 v[142:143], v[74:75], v[144:145], v[72:73] op_sel:[1,0,1]
	v_mov_b32_e32 v149, v84
	v_and_b32_e32 v80, 0xffff0000, v41
	v_pk_fma_f32 v[142:143], v[76:77], v[146:147], v[142:143] op_sel:[1,0,0]
	v_mov_b32_e32 v153, v80
	v_pk_fma_f32 v[142:143], v[66:67], v[148:149], v[142:143] op_sel:[1,0,0]
	v_and_b32_e32 v85, 0xffff0000, v45
	v_pk_fma_f32 v[142:143], v[68:69], v[152:153], v[142:143] op_sel:[1,0,0]
	v_and_b32_e32 v81, 0xffff0000, v49
	v_pk_fma_f32 v[144:145], v[70:71], v[84:85], v[142:143] op_sel:[1,0,0]
	s_nop 0
	v_mul_f32_e32 v142, 0xbfb8aa3b, v144
	v_mul_f32_e32 v143, 0xbfb8aa3b, v145
	v_exp_f32_e32 v142, v142
	v_exp_f32_e32 v143, v143
	s_nop 0
	v_pk_add_f32 v[150:151], v[142:143], 1.0 op_sel_hi:[1,0]
	v_pk_fma_f32 v[142:143], v[74:75], v[146:147], v[72:73] op_sel:[1,0,1]
	s_nop 0
	v_pk_fma_f32 v[142:143], v[76:77], v[148:149], v[142:143] op_sel:[1,0,0]
	s_nop 0
	v_pk_fma_f32 v[142:143], v[66:67], v[152:153], v[142:143] op_sel:[1,0,0]
	s_nop 0
	v_pk_fma_f32 v[142:143], v[68:69], v[84:85], v[142:143] op_sel:[1,0,0]
	s_nop 0
	v_pk_fma_f32 v[146:147], v[70:71], v[80:81], v[142:143] op_sel:[1,0,0]
	s_nop 0
	v_mul_f32_e32 v142, 0xbfb8aa3b, v146
	v_mul_f32_e32 v143, 0xbfb8aa3b, v147
	v_exp_f32_e32 v142, v142
	v_exp_f32_e32 v143, v143
	s_nop 0
	v_pk_add_f32 v[148:149], v[142:143], 1.0 op_sel_hi:[1,0]
	v_rcp_f32_e32 v143, v151
	s_nop 0
	v_mul_f32_e32 v142, v145, v143
	v_rcp_f32_e32 v145, v150
	s_nop 0
	v_mul_f32_e32 v143, v144, v145
	v_rcp_f32_e32 v145, v149
	s_nop 0
	v_mul_f32_e32 v144, v147, v145
	v_rcp_f32_e32 v147, v148
	s_nop 0
	v_mul_f32_e32 v145, v146, v147
	v_lshlrev_b32_e32 v146, 16, v53
	v_lshlrev_b32_e32 v147, 16, v61
	v_lshlrev_b32_e32 v148, 16, v57
	v_lshlrev_b32_e32 v149, 16, v65
	v_pk_fma_f32 v[150:151], v[74:75], v[82:83], v[72:73] op_sel_hi:[0,1,0]
	v_pk_fma_f32 v[150:151], v[76:77], v[78:79], v[150:151] op_sel_hi:[0,1,1]
	v_pk_mov_b32 v[82:83], v[82:83], v[146:147] op_sel:[1,0]
	v_pk_mov_b32 v[152:153], v[78:79], v[148:149] op_sel:[1,0]
	v_pk_fma_f32 v[78:79], v[74:75], v[78:79], v[72:73] op_sel_hi:[0,1,0]
	v_pk_fma_f32 v[150:151], v[66:67], v[82:83], v[150:151] op_sel_hi:[0,1,1]
	v_pk_fma_f32 v[78:79], v[76:77], v[82:83], v[78:79] op_sel_hi:[0,1,1]
	v_pk_fma_f32 v[150:151], v[68:69], v[152:153], v[150:151] op_sel_hi:[0,1,1]
	v_pk_fma_f32 v[78:79], v[66:67], v[152:153], v[78:79] op_sel_hi:[0,1,1]
	v_pk_fma_f32 v[150:151], v[70:71], v[146:147], v[150:151] op_sel_hi:[0,1,1]
	v_pk_fma_f32 v[78:79], v[68:69], v[146:147], v[78:79] op_sel_hi:[0,1,1]
	v_mul_f32_e32 v154, 0xbfb8aa3b, v150
	v_mul_f32_e32 v155, 0xbfb8aa3b, v151
	v_pk_fma_f32 v[146:147], v[70:71], v[148:149], v[78:79] op_sel_hi:[0,1,1]
	v_exp_f32_e32 v154, v154
	v_exp_f32_e32 v155, v155
	v_mul_f32_e32 v78, 0xbfb8aa3b, v146
	v_mul_f32_e32 v79, 0xbfb8aa3b, v147
	v_exp_f32_e32 v78, v78
	v_exp_f32_e32 v79, v79
	v_pk_add_f32 v[154:155], v[154:155], 1.0 op_sel_hi:[1,0]
	v_pk_add_f32 v[148:149], v[78:79], 1.0 op_sel_hi:[1,0]
	v_rcp_f32_e32 v79, v155
	s_nop 0
	v_mul_f32_e32 v78, v151, v79
	v_rcp_f32_e32 v82, v154
	s_nop 0
	v_mul_f32_e32 v79, v150, v82
	v_rcp_f32_e32 v83, v149
	s_nop 0
	v_mul_f32_e32 v82, v147, v83
	v_rcp_f32_e32 v147, v148
	s_nop 0
	v_mul_f32_e32 v83, v146, v147
	v_and_b32_e32 v147, 0xffff0000, v61
	v_and_b32_e32 v146, 0xffff0000, v53
	v_pk_fma_f32 v[150:151], v[74:75], v[84:85], v[72:73] op_sel:[1,0,1]
	v_and_b32_e32 v149, 0xffff0000, v65
	v_and_b32_e32 v148, 0xffff0000, v57
	v_pk_fma_f32 v[150:151], v[76:77], v[80:81], v[150:151] op_sel:[1,0,0]
	v_pk_mov_b32 v[84:85], v[84:85], v[146:147] op_sel:[1,0]
	v_pk_fma_f32 v[72:73], v[74:75], v[80:81], v[72:73] op_sel:[1,0,1]
	v_pk_fma_f32 v[150:151], v[66:67], v[84:85], v[150:151] op_sel:[1,0,0]
	v_pk_mov_b32 v[152:153], v[80:81], v[148:149] op_sel:[1,0]
	v_pk_fma_f32 v[72:73], v[76:77], v[84:85], v[72:73] op_sel:[1,0,0]
	v_pk_fma_f32 v[150:151], v[68:69], v[152:153], v[150:151] op_sel:[1,0,0]
	v_pk_fma_f32 v[66:67], v[66:67], v[152:153], v[72:73] op_sel:[1,0,0]
	v_pk_fma_f32 v[150:151], v[70:71], v[146:147], v[150:151] op_sel:[1,0,0]
	v_pk_fma_f32 v[66:67], v[68:69], v[146:147], v[66:67] op_sel:[1,0,0]
	v_mul_f32_e32 v154, 0xbfb8aa3b, v150
	v_mul_f32_e32 v155, 0xbfb8aa3b, v151
	v_pk_fma_f32 v[70:71], v[70:71], v[148:149], v[66:67] op_sel:[1,0,0]
	v_exp_f32_e32 v154, v154
	v_exp_f32_e32 v155, v155
	v_mul_f32_e32 v66, 0xbfb8aa3b, v70
	v_mul_f32_e32 v67, 0xbfb8aa3b, v71
	v_exp_f32_e32 v66, v66
	v_exp_f32_e32 v67, v67
	v_pk_add_f32 v[154:155], v[154:155], 1.0 op_sel_hi:[1,0]
	v_pk_add_f32 v[72:73], v[66:67], 1.0 op_sel_hi:[1,0]
	v_rcp_f32_e32 v67, v155
	s_nop 0
	v_mul_f32_e32 v66, v151, v67
	v_rcp_f32_e32 v68, v154
	s_nop 0
	v_mul_f32_e32 v67, v150, v68
	v_rcp_f32_e32 v69, v73
	s_nop 0
	v_mul_f32_e32 v68, v71, v69
	v_rcp_f32_e32 v71, v72
	s_nop 0
	v_mul_f32_e32 v69, v70, v71
	s_and_saveexec_b64 s[58:59], s[8:9]
	s_cbranch_execz .LBB0_1000
	v_bfe_u32 v70, v89, 16, 1
	v_add3_u32 v70, v89, v70, s33
	v_bfe_u32 v71, v143, 16, 1
	v_lshrrev_b32_e32 v70, 16, v70
	v_add3_u32 v71, v143, v71, s33
	v_and_or_b32 v70, v71, s71, v70
	v_bfe_u32 v71, v107, 16, 1
	v_add3_u32 v71, v107, v71, s33
	v_bfe_u32 v72, v145, 16, 1
	v_lshrrev_b32_e32 v71, 16, v71
	v_add3_u32 v72, v145, v72, s33
	v_and_or_b32 v71, v72, s71, v71
	ds_write2_b32 v140, v70, v71 offset0:3 offset1:39
	v_bfe_u32 v70, v1, 16, 1
	v_add3_u32 v70, v1, v70, s33
	v_bfe_u32 v71, v142, 16, 1
	v_lshrrev_b32_e32 v70, 16, v70
	v_add3_u32 v71, v142, v71, s33
	v_and_or_b32 v70, v71, s71, v70
	v_bfe_u32 v71, v106, 16, 1
	v_add3_u32 v71, v106, v71, s33
	v_bfe_u32 v72, v144, 16, 1
	v_lshrrev_b32_e32 v71, 16, v71
	v_add3_u32 v72, v144, v72, s33
	v_and_or_b32 v71, v72, s71, v71
	ds_write2_b32 v140, v70, v71 offset0:75 offset1:111
	v_bfe_u32 v70, v79, 16, 1
	v_add3_u32 v70, v79, v70, s33
	v_bfe_u32 v71, v67, 16, 1
	v_lshrrev_b32_e32 v70, 16, v70
	v_add3_u32 v71, v67, v71, s33
	v_and_or_b32 v70, v71, s71, v70
	v_bfe_u32 v71, v83, 16, 1
	v_add3_u32 v71, v83, v71, s33
	v_bfe_u32 v72, v69, 16, 1
	v_lshrrev_b32_e32 v71, 16, v71
	v_add3_u32 v72, v69, v72, s33
	v_and_or_b32 v71, v72, s71, v71
	ds_write2_b32 v140, v70, v71 offset0:147 offset1:183
	v_bfe_u32 v70, v78, 16, 1
	v_add3_u32 v70, v78, v70, s33
	v_bfe_u32 v71, v66, 16, 1
	v_lshrrev_b32_e32 v70, 16, v70
	v_add3_u32 v71, v66, v71, s33
	v_and_or_b32 v70, v71, s71, v70
	v_bfe_u32 v71, v82, 16, 1
	v_add3_u32 v71, v82, v71, s33
	v_bfe_u32 v72, v68, 16, 1
	v_lshrrev_b32_e32 v71, 16, v71
	v_add3_u32 v72, v68, v72, s33
	v_and_or_b32 v71, v72, s71, v71
	ds_write2_b32 v140, v70, v71 offset0:219 offset1:255

.LBB0_1003:
	s_or_b64 exec, exec, s[0:1]
	v_add_u32_e32 v1, v113, v114
	s_waitcnt lgkmcnt(0)
	s_barrier
	s_add_i32 s98, s78, 64
	s_cmp_ge_u32 s98, s75
	s_cbranch_scc1 .Lssd0_pf_done
	s_and_saveexec_b64 s[100:101], s[4:5]
	s_xor_b64 s[100:101], exec, s[100:101]
	s_cbranch_execz .Lssd0_pf_conv
	v_add_u32_e32 v242, s78, v135
	v_add_u32_e32 v243, s76, v136
	v_cndmask_b32_e64 v242, v243, v242, s[6:7]
	v_add_u32_e32 v242, s96, v242
	v_mad_i64_i32 v[242:243], vcc, v242, s70, v[104:105]
	global_load_ushort v62, v[242:243], off offset:3328
.Lssd0_pf_conv:
	s_andn2_saveexec_b64 s[100:101], s[100:101]
	s_cbranch_execz .Lssd0_pf_end
	v_add_u32_e32 v242, s78, v110
	v_add_u32_e32 v243, s76, v134
	v_add_u32_e32 v244, 62, v242
	v_cmp_gt_u32_e32 vcc, s75, v244
	v_mov_b32_e32 v18, 0
	v_mov_b32_e32 v19, 0
	v_mov_b32_e32 v20, 0
	v_mov_b32_e32 v21, 0
	s_and_saveexec_b64 s[98:99], vcc
	s_cbranch_execz .Lssd0_pf_0
	v_subrev_u32_e32 v245, 63, v243
	v_cndmask_b32_e64 v244, v245, v244, s[6:7]
	v_add_u32_e32 v244, s96, v244
	v_mad_i64_i32 v[18:19], vcc, v244, s70, v[100:101]
	global_load_dwordx4 v[18:21], v[18:19], off
.Lssd0_pf_0:
	s_or_b64 exec, exec, s[98:99]
	v_add_u32_e32 v244, 63, v242
	v_cmp_gt_u32_e32 vcc, s75, v244
	v_mov_b32_e32 v14, 0
	v_mov_b32_e32 v15, 0
	v_mov_b32_e32 v16, 0
	v_mov_b32_e32 v17, 0
	s_and_saveexec_b64 s[98:99], vcc
	s_cbranch_execz .Lssd0_pf_1
	v_subrev_u32_e32 v245, 64, v243
	v_cndmask_b32_e64 v244, v245, v244, s[6:7]
	v_add_u32_e32 v244, s96, v244
	v_mad_i64_i32 v[14:15], vcc, v244, s70, v[100:101]
	global_load_dwordx4 v[14:17], v[14:15], off
.Lssd0_pf_1:
	s_or_b64 exec, exec, s[98:99]
	v_add_u32_e32 v244, 64, v242
	v_cmp_gt_u32_e32 vcc, s75, v244
	v_mov_b32_e32 v26, 0
	v_mov_b32_e32 v27, 0
	v_mov_b32_e32 v28, 0
	v_mov_b32_e32 v29, 0
	s_and_saveexec_b64 s[98:99], vcc
	s_cbranch_execz .Lssd0_pf_2
	v_subrev_u32_e32 v245, 65, v243
	v_cndmask_b32_e64 v244, v245, v244, s[6:7]
	v_add_u32_e32 v244, s96, v244
	v_mad_i64_i32 v[26:27], vcc, v244, s70, v[100:101]
	global_load_dwordx4 v[26:29], v[26:27], off
.Lssd0_pf_2:
	s_or_b64 exec, exec, s[98:99]
	v_add_u32_e32 v244, 65, v242
	v_cmp_gt_u32_e32 vcc, s75, v244
	v_mov_b32_e32 v30, 0
	v_mov_b32_e32 v31, 0
	v_mov_b32_e32 v32, 0
	v_mov_b32_e32 v33, 0
	s_and_saveexec_b64 s[98:99], vcc
	s_cbranch_execz .Lssd0_pf_3
	v_subrev_u32_e32 v245, 66, v243
	v_cndmask_b32_e64 v244, v245, v244, s[6:7]
	v_add_u32_e32 v244, s96, v244
	v_mad_i64_i32 v[30:31], vcc, v244, s70, v[100:101]
	global_load_dwordx4 v[30:33], v[30:31], off
.Lssd0_pf_3:
	s_or_b64 exec, exec, s[98:99]
	v_add_u32_e32 v244, 66, v242
	v_cmp_gt_u32_e32 vcc, s75, v244
	v_mov_b32_e32 v34, 0
	v_mov_b32_e32 v35, 0
	v_mov_b32_e32 v36, 0
	v_mov_b32_e32 v37, 0
	s_and_saveexec_b64 s[98:99], vcc
	s_cbranch_execz .Lssd0_pf_4
	v_subrev_u32_e32 v245, 67, v243
	v_cndmask_b32_e64 v244, v245, v244, s[6:7]
	v_add_u32_e32 v244, s96, v244
	v_mad_i64_i32 v[34:35], vcc, v244, s70, v[100:101]
	global_load_dwordx4 v[34:37], v[34:35], off
.Lssd0_pf_4:
	s_or_b64 exec, exec, s[98:99]
	v_add_u32_e32 v244, 67, v242
	v_cmp_gt_u32_e32 vcc, s75, v244
	v_mov_b32_e32 v38, 0
	v_mov_b32_e32 v39, 0
	v_mov_b32_e32 v40, 0
	v_mov_b32_e32 v41, 0
	s_and_saveexec_b64 s[98:99], vcc
	s_cbranch_execz .Lssd0_pf_5
	v_subrev_u32_e32 v245, 68, v243
	v_cndmask_b32_e64 v244, v245, v244, s[6:7]
	v_add_u32_e32 v244, s96, v244
	v_mad_i64_i32 v[38:39], vcc, v244, s70, v[100:101]
	global_load_dwordx4 v[38:41], v[38:39], off
.Lssd0_pf_5:
	s_or_b64 exec, exec, s[98:99]
	v_add_u32_e32 v244, 68, v242
	v_cmp_gt_u32_e32 vcc, s75, v244
	v_mov_b32_e32 v42, 0
	v_mov_b32_e32 v43, 0
	v_mov_b32_e32 v44, 0
	v_mov_b32_e32 v45, 0
	s_and_saveexec_b64 s[98:99], vcc
	s_cbranch_execz .Lssd0_pf_6
	v_subrev_u32_e32 v245, 69, v243
	v_cndmask_b32_e64 v244, v245, v244, s[6:7]
	v_add_u32_e32 v244, s96, v244
	v_mad_i64_i32 v[42:43], vcc, v244, s70, v[100:101]
	global_load_dwordx4 v[42:45], v[42:43], off
.Lssd0_pf_6:
	s_or_b64 exec, exec, s[98:99]
	v_add_u32_e32 v244, 69, v242
	v_cmp_gt_u32_e32 vcc, s75, v244
	v_mov_b32_e32 v46, 0
	v_mov_b32_e32 v47, 0
	v_mov_b32_e32 v48, 0
	v_mov_b32_e32 v49, 0
	s_and_saveexec_b64 s[98:99], vcc
	s_cbranch_execz .Lssd0_pf_7
	v_subrev_u32_e32 v245, 70, v243
	v_cndmask_b32_e64 v244, v245, v244, s[6:7]
	v_add_u32_e32 v244, s96, v244
	v_mad_i64_i32 v[46:47], vcc, v244, s70, v[100:101]
	global_load_dwordx4 v[46:49], v[46:47], off
.Lssd0_pf_7:
	s_or_b64 exec, exec, s[98:99]
	v_add_u32_e32 v244, 70, v242
	v_cmp_gt_u32_e32 vcc, s75, v244
	v_mov_b32_e32 v50, 0
	v_mov_b32_e32 v51, 0
	v_mov_b32_e32 v52, 0
	v_mov_b32_e32 v53, 0
	s_and_saveexec_b64 s[98:99], vcc
	s_cbranch_execz .Lssd0_pf_8
	v_subrev_u32_e32 v245, 71, v243
	v_cndmask_b32_e64 v244, v245, v244, s[6:7]
	v_add_u32_e32 v244, s96, v244
	v_mad_i64_i32 v[50:51], vcc, v244, s70, v[100:101]
	global_load_dwordx4 v[50:53], v[50:51], off
.Lssd0_pf_8:
	s_or_b64 exec, exec, s[98:99]
	v_add_u32_e32 v244, 71, v242
	v_cmp_gt_u32_e32 vcc, s75, v244
	v_mov_b32_e32 v54, 0
	v_mov_b32_e32 v55, 0
	v_mov_b32_e32 v56, 0
	v_mov_b32_e32 v57, 0
	s_and_saveexec_b64 s[98:99], vcc
	s_cbranch_execz .Lssd0_pf_9
	v_subrev_u32_e32 v245, 72, v243
	v_cndmask_b32_e64 v244, v245, v244, s[6:7]
	v_add_u32_e32 v244, s96, v244
	v_mad_i64_i32 v[54:55], vcc, v244, s70, v[100:101]
	global_load_dwordx4 v[54:57], v[54:55], off
.Lssd0_pf_9:
	s_or_b64 exec, exec, s[98:99]
	v_add_u32_e32 v244, 72, v242
	v_cmp_gt_u32_e32 vcc, s75, v244
	v_mov_b32_e32 v58, 0
	v_mov_b32_e32 v59, 0
	v_mov_b32_e32 v60, 0
	v_mov_b32_e32 v61, 0
	s_and_saveexec_b64 s[98:99], vcc
	s_cbranch_execz .Lssd0_pf_10
	v_subrev_u32_e32 v245, 73, v243
	v_cndmask_b32_e64 v244, v245, v244, s[6:7]
	v_add_u32_e32 v244, s96, v244
	v_mad_i64_i32 v[58:59], vcc, v244, s70, v[100:101]
	global_load_dwordx4 v[58:61], v[58:59], off
.Lssd0_pf_10:
	s_or_b64 exec, exec, s[98:99]
	v_add_u32_e32 v244, 73, v242
	v_cmp_gt_u32_e32 vcc, s75, v244
	v_mov_b32_e32 v62, 0
	v_mov_b32_e32 v63, 0
	v_mov_b32_e32 v64, 0
	v_mov_b32_e32 v65, 0
	s_and_saveexec_b64 s[98:99], vcc
	s_cbranch_execz .Lssd0_pf_11
	v_subrev_u32_e32 v245, 74, v243
	v_cndmask_b32_e64 v244, v245, v244, s[6:7]
	v_add_u32_e32 v244, s96, v244
	v_mad_i64_i32 v[62:63], vcc, v244, s70, v[100:101]
	global_load_dwordx4 v[62:65], v[62:63], off
.Lssd0_pf_11:
	s_or_b64 exec, exec, s[98:99]
.Lssd0_pf_end:
	s_or_b64 exec, exec, s[100:101]
.Lssd0_pf_done:
	ds_read_b128 v[70:73], v1
	ds_read_b128 v[66:69], v1 offset:64
	ds_read_b128 v[74:77], v141 offset:9216
	ds_read_b128 v[78:81], v141 offset:9280
	s_waitcnt lgkmcnt(1)
	v_mfma_f32_16x16x32_bf16 v[74:77], v[70:73], v[74:77], 0
	v_add_u32_e32 v89, 0xb400, v92
	s_add_i32 s97, s78, 64
	s_cmp_ge_u32 s97, s75
	s_waitcnt lgkmcnt(0)
	v_mfma_f32_16x16x32_bf16 v[142:145], v[66:69], v[78:81], v[74:77]
	ds_read_b128 v[78:81], v141 offset:11584
	s_nop 1
	ds_read_b128 v[74:77], v141 offset:11520
	s_waitcnt lgkmcnt(0)
	v_mfma_f32_16x16x32_bf16 v[74:77], v[70:73], v[74:77], 0
	v_mfma_f32_16x16x32_bf16 v[146:149], v[66:69], v[78:81], v[74:77]
	ds_read_b128 v[78:81], v141 offset:13888
	s_nop 5
	ds_read_b128 v[74:77], v141 offset:13824
	s_waitcnt lgkmcnt(0)
	v_mfma_f32_16x16x32_bf16 v[74:77], v[70:73], v[74:77], 0
	v_mfma_f32_16x16x32_bf16 v[82:85], v[66:69], v[78:81], v[74:77]
	ds_read_b128 v[78:81], v141 offset:16192
	s_nop 5
	ds_read_b128 v[74:77], v141 offset:16128
	s_waitcnt lgkmcnt(0)
	v_mfma_f32_16x16x32_bf16 v[74:77], v[70:73], v[74:77], 0
	v_mfma_f32_16x16x32_bf16 v[78:81], v[66:69], v[78:81], v[74:77]
	s_nop 6
	ds_read_b128 v[74:77], v139 offset:46080
	ds_read2_b32 v[106:107], v89 offset1:16
	ds_read2_b32 v[150:151], v89 offset0:64 offset1:80
	s_waitcnt lgkmcnt(1)
	v_sub_f32_e32 v152, v74, v106
	v_mul_f32_e32 v152, 0x3fb8aa3b, v152
	v_exp_f32_e32 v152, v152
	s_waitcnt lgkmcnt(0)
	v_mul_f32_e32 v152, v150, v152
	v_cndmask_b32_e64 v152, v152, 0, s[24:25]
	v_mul_f32_e32 v142, v142, v152
	v_bfe_u32 v152, v142, 16, 1
	v_add3_u32 v142, v142, v152, s33
	ds_write_b16_d16_hi v93, v142
	v_sub_f32_e32 v142, v75, v106
	v_mul_f32_e32 v142, 0x3fb8aa3b, v142
	v_exp_f32_e32 v142, v142
	s_nop 0
	v_mul_f32_e32 v142, v150, v142
	v_cndmask_b32_e64 v142, v142, 0, s[26:27]
	v_mul_f32_e32 v142, v143, v142
	v_bfe_u32 v143, v142, 16, 1
	v_add3_u32 v142, v142, v143, s33
	ds_write_b16_d16_hi v93, v142 offset:144
	v_sub_f32_e32 v142, v76, v106
	v_mul_f32_e32 v142, 0x3fb8aa3b, v142
	v_exp_f32_e32 v142, v142
	v_sub_f32_e32 v106, v77, v106
	v_mul_f32_e32 v106, 0x3fb8aa3b, v106
	v_exp_f32_e32 v106, v106
	v_mul_f32_e32 v142, v150, v142
	v_cndmask_b32_e64 v142, v142, 0, s[28:29]
	v_mul_f32_e32 v142, v144, v142
	v_mul_f32_e32 v106, v150, v106
	v_bfe_u32 v143, v142, 16, 1
	v_cndmask_b32_e64 v106, v106, 0, s[30:31]
	v_add3_u32 v142, v142, v143, s33
	v_mul_f32_e32 v106, v145, v106
	ds_write_b16_d16_hi v93, v142 offset:288
	v_bfe_u32 v142, v106, 16, 1
	v_add3_u32 v106, v106, v142, s33
	ds_write_b16_d16_hi v93, v106 offset:432
	v_sub_f32_e32 v106, v74, v107
	v_mul_f32_e32 v106, 0x3fb8aa3b, v106
	v_exp_f32_e32 v106, v106
	s_nop 0
	v_mul_f32_e32 v106, v151, v106
	v_cndmask_b32_e64 v106, v106, 0, s[34:35]
	v_mul_f32_e32 v106, v146, v106
	v_bfe_u32 v142, v106, 16, 1
	v_add3_u32 v106, v106, v142, s33
	ds_write_b16_d16_hi v93, v106 offset:32
	v_sub_f32_e32 v106, v75, v107
	v_mul_f32_e32 v106, 0x3fb8aa3b, v106
	v_exp_f32_e32 v106, v106
	s_nop 0
	v_mul_f32_e32 v106, v151, v106
	v_cndmask_b32_e64 v106, v106, 0, s[36:37]
	v_mul_f32_e32 v106, v147, v106
	v_bfe_u32 v142, v106, 16, 1
	v_add3_u32 v106, v106, v142, s33
	ds_write_b16_d16_hi v93, v106 offset:176
	v_sub_f32_e32 v106, v76, v107
	v_mul_f32_e32 v106, 0x3fb8aa3b, v106
	v_exp_f32_e32 v106, v106
	s_nop 0
	v_mul_f32_e32 v106, v151, v106
	v_cndmask_b32_e64 v106, v106, 0, s[38:39]
	v_mul_f32_e32 v106, v148, v106
	v_bfe_u32 v142, v106, 16, 1
	v_add3_u32 v106, v106, v142, s33
	ds_write_b16_d16_hi v93, v106 offset:320
	v_sub_f32_e32 v106, v77, v107
	v_mul_f32_e32 v106, 0x3fb8aa3b, v106
	v_exp_f32_e32 v106, v106
	s_nop 0
	v_mul_f32_e32 v106, v151, v106
	v_cndmask_b32_e64 v106, v106, 0, s[40:41]
	v_mul_f32_e32 v106, v149, v106
	v_bfe_u32 v107, v106, 16, 1
	v_add3_u32 v106, v106, v107, s33
	ds_write_b16_d16_hi v93, v106 offset:464
	ds_read2_b32 v[106:107], v89 offset0:32 offset1:48
	ds_read2_b32 v[142:143], v89 offset0:96 offset1:112
	s_waitcnt lgkmcnt(1)
	v_sub_f32_e32 v89, v74, v106
	v_mul_f32_e32 v89, 0x3fb8aa3b, v89
	v_exp_f32_e32 v89, v89
	s_waitcnt lgkmcnt(0)
	v_mul_f32_e32 v89, v142, v89
	v_cndmask_b32_e64 v89, v89, 0, s[42:43]
	v_mul_f32_e32 v82, v82, v89
	v_bfe_u32 v89, v82, 16, 1
	v_add3_u32 v82, v82, v89, s33
	ds_write_b16_d16_hi v93, v82 offset:64
	v_sub_f32_e32 v82, v75, v106
	v_mul_f32_e32 v82, 0x3fb8aa3b, v82
	v_exp_f32_e32 v82, v82
	s_nop 0
	v_mul_f32_e32 v82, v142, v82
	v_cndmask_b32_e64 v82, v82, 0, s[44:45]
	v_mul_f32_e32 v82, v83, v82
	v_bfe_u32 v83, v82, 16, 1
	v_add3_u32 v82, v82, v83, s33
	ds_write_b16_d16_hi v93, v82 offset:208
	v_sub_f32_e32 v82, v76, v106
	v_mul_f32_e32 v82, 0x3fb8aa3b, v82
	v_exp_f32_e32 v82, v82
	s_nop 0
	v_mul_f32_e32 v82, v142, v82
	v_cndmask_b32_e64 v82, v82, 0, s[46:47]
	v_mul_f32_e32 v82, v84, v82
	v_bfe_u32 v83, v82, 16, 1
	v_add3_u32 v82, v82, v83, s33
	ds_write_b16_d16_hi v93, v82 offset:352
	v_sub_f32_e32 v82, v77, v106
	v_mul_f32_e32 v82, 0x3fb8aa3b, v82
	v_exp_f32_e32 v82, v82
	s_nop 0
	v_mul_f32_e32 v82, v142, v82
	v_cndmask_b32_e64 v82, v82, 0, s[48:49]
	v_mul_f32_e32 v82, v85, v82
	v_bfe_u32 v83, v82, 16, 1
	v_add3_u32 v82, v82, v83, s33
	ds_write_b16_d16_hi v93, v82 offset:496
	v_sub_f32_e32 v82, v74, v107
	v_mul_f32_e32 v82, 0x3fb8aa3b, v82
	v_exp_f32_e32 v82, v82
	s_nop 0
	v_mul_f32_e32 v82, v143, v82
	v_cndmask_b32_e64 v82, v82, 0, s[50:51]
	v_mul_f32_e32 v78, v78, v82
	v_bfe_u32 v82, v78, 16, 1
	v_add3_u32 v78, v78, v82, s33
	ds_write_b16_d16_hi v93, v78 offset:96
	v_sub_f32_e32 v78, v75, v107
	v_mul_f32_e32 v78, 0x3fb8aa3b, v78
	v_exp_f32_e32 v78, v78
	s_nop 0
	v_mul_f32_e32 v78, v143, v78
	v_cndmask_b32_e64 v78, v78, 0, s[52:53]
	v_mul_f32_e32 v78, v79, v78
	v_bfe_u32 v79, v78, 16, 1
	v_add3_u32 v78, v78, v79, s33
	ds_write_b16_d16_hi v93, v78 offset:240
	v_sub_f32_e32 v78, v76, v107
	v_mul_f32_e32 v78, 0x3fb8aa3b, v78
	v_exp_f32_e32 v78, v78
	s_nop 0
	v_mul_f32_e32 v78, v143, v78
	v_cndmask_b32_e64 v78, v78, 0, s[54:55]
	v_mul_f32_e32 v78, v80, v78
	v_bfe_u32 v79, v78, 16, 1
	v_add3_u32 v78, v78, v79, s33
	ds_write_b16_d16_hi v93, v78 offset:384
	v_sub_f32_e32 v78, v77, v107
	v_mul_f32_e32 v78, 0x3fb8aa3b, v78
	v_exp_f32_e32 v78, v78
	s_nop 0
	v_mul_f32_e32 v78, v143, v78
	v_cndmask_b32_e64 v78, v78, 0, s[56:57]
	v_mul_f32_e32 v78, v81, v78
	v_bfe_u32 v79, v78, 16, 1
	v_add3_u32 v78, v78, v79, s33
	ds_write_b16_d16_hi v93, v78 offset:528
	ds_read_b128 v[78:81], v1
	ds_read_b128 v[82:85], v1 offset:64
	ds_read_b128 v[142:145], v141 offset:36864
	ds_read_b128 v[146:149], v141 offset:36928
	ds_read_b128 v[150:153], v141 offset:41536
	s_waitcnt lgkmcnt(2)
	v_mfma_f32_16x16x32_bf16 v[142:145], v[70:73], v[142:145], 0
	v_mul_f32_e32 v1, 0x3fb8aa3b, v74
	v_exp_f32_e32 v106, v1
	v_mul_f32_e32 v1, 0x3fb8aa3b, v75
	v_exp_f32_e32 v107, v1
	v_mul_f32_e32 v1, 0x3fb8aa3b, v76
	v_exp_f32_e32 v154, v1
	v_mul_f32_e32 v1, 0x3fb8aa3b, v77
	s_waitcnt lgkmcnt(1)
	v_mfma_f32_16x16x32_bf16 v[142:145], v[66:69], v[146:149], v[142:145]
	v_exp_f32_e32 v155, v1
	ds_read_b128 v[74:77], v141 offset:18432
	ds_read_b128 v[146:149], v141 offset:39232
	v_add_u32_e32 v1, s78, v137
	s_nop 3
	v_pk_mul_f32 v[142:143], v[106:107], v[142:143]
	v_pk_mul_f32 v[144:145], v[154:155], v[144:145]
	s_waitcnt lgkmcnt(1)
	s_nop 0
	v_mfma_f32_16x16x32_bf16 v[74:77], v[78:81], v[74:77], v[142:145]
	s_nop 2
	ds_read_b128 v[142:145], v141 offset:18496
	s_waitcnt lgkmcnt(0)
	v_mfma_f32_16x16x32_bf16 v[74:77], v[82:85], v[142:145], v[74:77]
	ds_read_b128 v[142:145], v141 offset:39168
	s_waitcnt lgkmcnt(0)
	v_mfma_f32_16x16x32_bf16 v[142:145], v[70:73], v[142:145], 0
	v_mfma_f32_16x16x32_bf16 v[142:145], v[66:69], v[146:149], v[142:145]
	ds_read_b128 v[146:149], v141 offset:20736
	s_nop 6
	v_pk_mul_f32 v[142:143], v[106:107], v[142:143]
	v_pk_mul_f32 v[144:145], v[154:155], v[144:145]
	s_waitcnt lgkmcnt(0)
	s_nop 0
	v_mfma_f32_16x16x32_bf16 v[142:145], v[78:81], v[146:149], v[142:145]
	ds_read_b128 v[146:149], v141 offset:20800
	s_waitcnt lgkmcnt(0)
	v_mfma_f32_16x16x32_bf16 v[142:145], v[82:85], v[146:149], v[142:145]
	ds_read_b128 v[146:149], v141 offset:41472
	s_waitcnt lgkmcnt(0)
	v_mfma_f32_16x16x32_bf16 v[146:149], v[70:73], v[146:149], 0
	v_mfma_f32_16x16x32_bf16 v[146:149], v[66:69], v[150:153], v[146:149]
	ds_read_b128 v[150:153], v141 offset:23040
	s_nop 6
	v_pk_mul_f32 v[146:147], v[106:107], v[146:147]
	v_pk_mul_f32 v[148:149], v[154:155], v[148:149]
	s_waitcnt lgkmcnt(0)
	s_nop 0
	v_mfma_f32_16x16x32_bf16 v[146:149], v[78:81], v[150:153], v[146:149]
	ds_read_b128 v[150:153], v141 offset:23104
	s_waitcnt lgkmcnt(0)
	v_mfma_f32_16x16x32_bf16 v[146:149], v[82:85], v[150:153], v[146:149]
	ds_read_b128 v[150:153], v141 offset:43776
	s_waitcnt lgkmcnt(0)
	v_mfma_f32_16x16x32_bf16 v[70:73], v[70:73], v[150:153], 0
	ds_read_b128 v[150:153], v141 offset:43840
	s_waitcnt lgkmcnt(0)
	v_mfma_f32_16x16x32_bf16 v[66:69], v[66:69], v[150:153], v[70:73]
	s_nop 4
	ds_read_b128 v[70:73], v141 offset:25344
	s_nop 1
	v_pk_mul_f32 v[66:67], v[106:107], v[66:67]
	v_pk_mul_f32 v[68:69], v[154:155], v[68:69]
	s_waitcnt lgkmcnt(0)
	s_nop 0
	v_mfma_f32_16x16x32_bf16 v[66:69], v[78:81], v[70:73], v[66:69]
	ds_read_b128 v[70:73], v141 offset:25408
	s_waitcnt lgkmcnt(0)
	v_mfma_f32_16x16x32_bf16 v[66:69], v[82:85], v[70:73], v[66:69]
	v_add_u32_e32 v70, s76, v138
	v_cndmask_b32_e64 v70, v70, v1, s[6:7]
	v_add_u32_e32 v70, s96, v70
	v_bfe_u32 v72, v74, 16, 1
	v_mad_i64_i32 v[70:71], s[0:1], v70, s72, v[102:103]
	v_add3_u32 v72, v74, v72, s33
	global_store_short_d16_hi v[70:71], v72, off offset:1024
	v_bfe_u32 v72, v142, 16, 1
	v_add3_u32 v72, v142, v72, s33
	global_store_short_d16_hi v[70:71], v72, off offset:1056
	v_bfe_u32 v72, v146, 16, 1
	v_add3_u32 v72, v146, v72, s33
	global_store_short_d16_hi v[70:71], v72, off offset:1088
	v_bfe_u32 v72, v66, 16, 1
	v_add3_u32 v66, v66, v72, s33
	global_store_short_d16_hi v[70:71], v66, off offset:1120
	v_add_u32_e32 v66, 1, v1
	v_xad_u32 v70, v1, -2, s75
	v_cndmask_b32_e64 v66, v70, v66, s[6:7]
	v_add_u32_e32 v66, s96, v66
	v_mad_i64_i32 v[70:71], s[0:1], v66, s72, v[102:103]
	v_bfe_u32 v66, v75, 16, 1
	v_add3_u32 v66, v75, v66, s33
	global_store_short_d16_hi v[70:71], v66, off offset:1024
	v_bfe_u32 v66, v143, 16, 1
	v_add3_u32 v66, v143, v66, s33
	global_store_short_d16_hi v[70:71], v66, off offset:1056
	v_bfe_u32 v66, v147, 16, 1
	v_add3_u32 v66, v147, v66, s33
	global_store_short_d16_hi v[70:71], v66, off offset:1088
	v_bfe_u32 v66, v67, 16, 1
	v_add3_u32 v66, v67, v66, s33
	global_store_short_d16_hi v[70:71], v66, off offset:1120
	v_add_u32_e32 v66, 2, v1
	v_xad_u32 v67, v1, -3, s75
	v_cndmask_b32_e64 v66, v67, v66, s[6:7]
	v_add_u32_e32 v66, s96, v66
	v_bfe_u32 v70, v76, 16, 1
	v_mad_i64_i32 v[66:67], s[0:1], v66, s72, v[102:103]
	v_add3_u32 v70, v76, v70, s33
	global_store_short_d16_hi v[66:67], v70, off offset:1024
	v_bfe_u32 v70, v144, 16, 1
	v_add3_u32 v70, v144, v70, s33
	global_store_short_d16_hi v[66:67], v70, off offset:1056
	v_bfe_u32 v70, v148, 16, 1
	v_add3_u32 v70, v148, v70, s33
	global_store_short_d16_hi v[66:67], v70, off offset:1088
	v_bfe_u32 v70, v68, 16, 1
	v_add3_u32 v68, v68, v70, s33
	global_store_short_d16_hi v[66:67], v68, off offset:1120
	v_add_u32_e32 v66, 3, v1
	v_xad_u32 v1, v1, -4, s75
	v_cndmask_b32_e64 v1, v1, v66, s[6:7]
	v_add_u32_e32 v1, s96, v1
	v_mad_i64_i32 v[66:67], s[0:1], v1, s72, v[102:103]
	v_bfe_u32 v1, v77, 16, 1
	v_add3_u32 v1, v77, v1, s33
	global_store_short_d16_hi v[66:67], v1, off offset:1024
	v_bfe_u32 v1, v145, 16, 1
	v_add3_u32 v1, v145, v1, s33
	global_store_short_d16_hi v[66:67], v1, off offset:1056
	v_bfe_u32 v1, v149, 16, 1
	v_add3_u32 v1, v149, v1, s33
	global_store_short_d16_hi v[66:67], v1, off offset:1088
	v_bfe_u32 v1, v69, 16, 1
	s_cselect_b64 s[0:1], -1, 0
	v_add3_u32 v1, v69, v1, s33
	s_and_b64 vcc, exec, s[0:1]
	global_store_short_d16_hi v[66:67], v1, off offset:1120

.Lssd0_w3back:
	s_waitcnt vmcnt(16)
	v_lshlrev_b32_e32 v108, 16, v62
	s_branch .LBB0_982

.LBB0_1046:
	s_lshl_b64 s[0:1], s[8:9], 1
	v_readlane_b32 s4, v241, 17
	v_readlane_b32 s5, v241, 18
	v_rcp_f32_e32 v7, v55
	s_add_i32 s19, s19, s17
	v_readlane_b32 s8, v241, 21
	v_readlane_b32 s9, v241, 22
	v_mul_f32_e32 v8, 1.0, v7
	s_add_u32 s0, s8, s0
	v_or_b32_e32 v1, v68, v47
	s_addc_u32 s1, s9, s1
	v_lshlrev_b32_e32 v4, 1, v45
	v_mov_b32_e32 v5, v0
	v_mul_f32_e32 v9, v8, v12
	v_add_u32_e32 v1, s19, v1
	v_lshl_add_u64 v[4:5], s[0:1], 0, v[4:5]
	s_movk_i32 s4, 0x300
	v_bfe_u32 v10, v9, 16, 1
	v_mad_i64_i32 v[6:7], s[0:1], v1, s4, v[4:5]
	v_add3_u32 v9, v9, v10, s33
	global_store_short_d16_hi v[6:7], v9, off
	v_mul_f32_e32 v9, v8, v16
	v_bfe_u32 v10, v9, 16, 1
	v_add3_u32 v9, v9, v10, s33
	global_store_short_d16_hi v[6:7], v9, off offset:32
	v_mul_f32_e32 v9, v8, v20
	v_bfe_u32 v10, v9, 16, 1
	v_add3_u32 v9, v9, v10, s33
	global_store_short_d16_hi v[6:7], v9, off offset:64
	v_rcp_f32_e32 v10, v54
	v_mul_f32_e32 v8, v8, v24
	v_bfe_u32 v11, v8, 16, 1
	v_add3_u32 v8, v8, v11, s33
	global_store_short_d16_hi v[6:7], v8, off offset:96
	v_mul_f32_e32 v8, 1.0, v10
	v_mul_f32_e32 v9, v8, v13
	v_add_u32_e32 v6, 1, v1
	v_bfe_u32 v10, v9, 16, 1
	v_mad_i64_i32 v[6:7], s[0:1], v6, s4, v[4:5]
	v_add3_u32 v9, v9, v10, s33
	global_store_short_d16_hi v[6:7], v9, off
	v_mul_f32_e32 v9, v8, v17
	v_bfe_u32 v10, v9, 16, 1
	v_add3_u32 v9, v9, v10, s33
	global_store_short_d16_hi v[6:7], v9, off offset:32
	v_mul_f32_e32 v9, v8, v21
	v_bfe_u32 v10, v9, 16, 1
	v_add3_u32 v9, v9, v10, s33
	global_store_short_d16_hi v[6:7], v9, off offset:64
	v_rcp_f32_e32 v10, v3
	v_mul_f32_e32 v8, v8, v25
	v_bfe_u32 v11, v8, 16, 1
	v_add3_u32 v8, v8, v11, s33
	global_store_short_d16_hi v[6:7], v8, off offset:96
	v_mul_f32_e32 v3, 1.0, v10
	v_mul_f32_e32 v8, v3, v14
	v_add_u32_e32 v6, 2, v1
	v_bfe_u32 v9, v8, 16, 1
	v_mad_i64_i32 v[6:7], s[0:1], v6, s4, v[4:5]
	v_add3_u32 v8, v8, v9, s33
	global_store_short_d16_hi v[6:7], v8, off
	v_mul_f32_e32 v8, v3, v18
	v_bfe_u32 v9, v8, 16, 1
	v_add3_u32 v8, v8, v9, s33
	global_store_short_d16_hi v[6:7], v8, off offset:32
	v_mul_f32_e32 v8, v3, v22
	v_bfe_u32 v9, v8, 16, 1
	v_add3_u32 v8, v8, v9, s33
	global_store_short_d16_hi v[6:7], v8, off offset:64
	v_rcp_f32_e32 v9, v2
	v_mul_f32_e32 v3, v3, v26
	v_bfe_u32 v10, v3, 16, 1
	v_add3_u32 v3, v3, v10, s33
	global_store_short_d16_hi v[6:7], v3, off offset:96
	v_mul_f32_e32 v6, 1.0, v9
	v_add_u32_e32 v1, 3, v1
	v_mad_i64_i32 v[2:3], s[0:1], v1, s4, v[4:5]
	v_mul_f32_e32 v1, v6, v15
	v_bfe_u32 v4, v1, 16, 1
	v_add3_u32 v1, v1, v4, s33
	global_store_short_d16_hi v[2:3], v1, off
	v_mul_f32_e32 v1, v6, v19
	v_bfe_u32 v4, v1, 16, 1
	v_add3_u32 v1, v1, v4, s33
	global_store_short_d16_hi v[2:3], v1, off offset:32
	v_mul_f32_e32 v1, v6, v23
	v_bfe_u32 v4, v1, 16, 1
	v_add3_u32 v1, v1, v4, s33
	global_store_short_d16_hi v[2:3], v1, off offset:64
	v_mul_f32_e32 v1, v6, v27
	v_bfe_u32 v4, v1, 16, 1
	v_add3_u32 v1, v1, v4, s33
	v_readlane_b32 s6, v241, 19
	v_readlane_b32 s7, v241, 20
	v_readlane_b32 s10, v241, 23
	v_readlane_b32 s11, v241, 24
	global_store_short_d16_hi v[2:3], v1, off offset:96
	s_barrier
	s_mov_b32 s23, s27
	s_cbranch_execz .LBB0_893
	s_branch .LBB0_1038

.LBB0_1347:
	v_lshl_add_u64 v[116:117], v[166:167], 0, v[168:169]
	global_load_dwordx4 v[112:115], v[116:117], off offset:2048
	v_lshl_add_u64 v[174:175], v[172:173], 0, v[168:169]
	v_cmp_gt_i32_e64 s[6:7], s2, v197
	v_lshl_add_u64 v[180:181], v[166:167], 0, v[164:165]
	v_lshl_add_u64 v[178:179], v[170:171], 0, v[164:165]
	s_waitcnt vmcnt(0)
	v_lshlrev_b32_e32 v61, 16, v113
	v_and_b32_e32 v119, 0xffff0000, v113
	v_and_b32_e32 v118, 0xffff0000, v112
	v_lshlrev_b32_e32 v63, 16, v112
	v_and_b32_e32 v113, 0xffff0000, v115
	v_and_b32_e32 v112, 0xffff0000, v114
	v_mul_f32_e32 v69, v70, v61
	v_lshlrev_b32_e32 v61, 16, v114
	v_lshlrev_b32_e32 v65, 16, v115
	v_pk_mul_f32 v[128:129], v[146:147], v[112:113]
	global_load_dwordx4 v[112:115], v[174:175], off offset:1024
	v_pk_mul_f32 v[120:121], v[158:159], v[118:119]
	s_waitcnt lgkmcnt(0)
	v_mul_f32_e32 v71, v68, v63
	v_mul_f32_e32 v63, v44, v61
	v_mul_f32_e32 v61, v46, v65
	s_waitcnt vmcnt(0)
	v_lshlrev_b32_e32 v130, 16, v112
	v_lshlrev_b32_e32 v131, 16, v113
	v_and_b32_e32 v135, 0xffff0000, v113
	v_and_b32_e32 v134, 0xffff0000, v112
	v_lshlrev_b32_e32 v124, 16, v114
	v_lshlrev_b32_e32 v125, 16, v115
	v_and_b32_e32 v119, 0xffff0000, v115
	v_and_b32_e32 v118, 0xffff0000, v114
	global_load_dwordx4 v[112:115], v[174:175], off offset:1792
	s_waitcnt vmcnt(0)
	v_lshlrev_b32_e32 v132, 16, v112
	v_lshlrev_b32_e32 v133, 16, v113
	v_and_b32_e32 v177, 0xffff0000, v113
	v_and_b32_e32 v176, 0xffff0000, v112
	v_lshlrev_b32_e32 v126, 16, v114
	v_lshlrev_b32_e32 v127, 16, v115
	v_and_b32_e32 v123, 0xffff0000, v115
	v_and_b32_e32 v122, 0xffff0000, v114
	global_load_dwordx4 v[112:115], v[116:117], off offset:1280
	v_pk_add_f32 v[130:131], v[130:131], v[132:133]
	v_pk_add_f32 v[186:187], v[124:125], v[126:127]
	v_pk_add_f32 v[188:189], v[118:119], v[122:123]
	v_pk_add_f32 v[134:135], v[134:135], v[176:177]
	v_lshl_add_u64 v[176:177], v[172:173], 0, v[164:165]
	s_waitcnt vmcnt(0)
	v_lshlrev_b32_e32 v67, 16, v112
	v_lshlrev_b32_e32 v65, 16, v113
	v_mul_f32_e32 v77, 0xbfb8aa3b, v67
	v_and_b32_e32 v75, 0xffff0000, v112
	v_exp_f32_e32 v112, v77
	v_mul_f32_e32 v77, 0xbfb8aa3b, v65
	v_and_b32_e32 v73, 0xffff0000, v113
	v_exp_f32_e32 v113, v77
	s_nop 0
	v_pk_add_f32 v[112:113], v[112:113], 1.0 op_sel_hi:[1,0]
	s_nop 0
	v_rcp_f32_e32 v79, v113
	s_nop 0
	v_mul_f32_e32 v133, v65, v79
	v_rcp_f32_e32 v77, v112
	s_nop 0
	v_mul_f32_e32 v132, v67, v77
	v_mul_f32_e32 v65, 0xbfb8aa3b, v75
	v_exp_f32_e32 v112, v65
	v_mul_f32_e32 v65, 0xbfb8aa3b, v73
	v_exp_f32_e32 v113, v65
	s_nop 0
	v_pk_add_f32 v[112:113], v[112:113], 1.0 op_sel_hi:[1,0]
	s_nop 0
	v_rcp_f32_e32 v67, v113
	s_nop 0
	v_mul_f32_e32 v185, v73, v67
	v_rcp_f32_e32 v67, v112
	s_nop 0
	v_mul_f32_e32 v184, v75, v67
	v_lshlrev_b32_e32 v67, 16, v114
	v_lshlrev_b32_e32 v65, 16, v115
	v_mul_f32_e32 v77, 0xbfb8aa3b, v67
	v_exp_f32_e32 v112, v77
	v_mul_f32_e32 v77, 0xbfb8aa3b, v65
	v_exp_f32_e32 v113, v77
	v_and_b32_e32 v75, 0xffff0000, v114
	v_and_b32_e32 v73, 0xffff0000, v115
	v_pk_add_f32 v[112:113], v[112:113], 1.0 op_sel_hi:[1,0]
	s_nop 0
	v_rcp_f32_e32 v79, v113
	s_nop 0
	v_mul_f32_e32 v191, v65, v79
	v_rcp_f32_e32 v77, v112
	s_nop 0
	v_mul_f32_e32 v190, v67, v77
	v_mul_f32_e32 v65, 0xbfb8aa3b, v75
	v_exp_f32_e32 v112, v65
	v_mul_f32_e32 v65, 0xbfb8aa3b, v73
	v_exp_f32_e32 v113, v65
	s_nop 0
	v_pk_add_f32 v[112:113], v[112:113], 1.0 op_sel_hi:[1,0]
	s_nop 0
	v_rcp_f32_e32 v67, v113
	s_nop 0
	v_mul_f32_e32 v193, v73, v67
	v_rcp_f32_e32 v67, v112
	s_nop 0
	v_mul_f32_e32 v192, v75, v67
	v_cndmask_b32_e64 v67, v37, v39, s[6:7]
	v_cndmask_b32_e64 v73, v41, v43, s[6:7]
	v_or_b32_e32 v75, 2, v73
	v_and_b32_e32 v67, v67, v197
	v_cmp_lt_u32_e32 vcc, 1, v67
	v_cmp_lt_u32_e64 s[6:7], v67, v75
	v_add_u32_e32 v77, 1, v67
	s_and_b64 s[12:13], vcc, s[6:7]
	v_cmp_ne_u32_e32 vcc, 0, v67
	v_cmp_lt_u32_e64 s[6:7], v77, v75
	v_cndmask_b32_e64 v113, 0, -1, s[12:13]
	v_cndmask_b32_e64 v112, 0, v45, s[12:13]
	s_and_b64 s[10:11], vcc, s[6:7]
	v_lshl_add_u64 v[112:113], v[116:117], 0, v[112:113]
	v_cndmask_b32_e64 v115, 0, -1, s[10:11]
	v_cndmask_b32_e64 v114, 0, v47, s[10:11]
	v_lshl_add_u64 v[118:119], v[116:117], 0, v[114:115]
	global_load_dwordx4 v[112:115], v[112:113], off offset:2048
	v_add_u32_e32 v65, -1, v73
	v_cmp_lt_u32_e64 s[8:9], v67, v73
	v_add_u32_e32 v73, 3, v67
	v_cmp_lt_u32_e64 s[6:7], v73, v75
	v_add_u32_e32 v73, 4, v67
	v_cmp_lt_u32_e32 vcc, v73, v75
	v_cndmask_b32_e64 v136, 0, v49, s[6:7]
	v_lshl_add_u64 v[122:123], v[116:117], 0, v[136:137]
	v_cndmask_b32_e32 v136, 0, v51, vcc
	v_lshl_add_u64 v[124:125], v[116:117], 0, v[136:137]
	v_cndmask_b32_e64 v69, 0, v69, s[8:9]
	v_cndmask_b32_e64 v71, 0, v71, s[8:9]
	v_cndmask_b32_e64 v63, 0, v63, s[8:9]
	v_cndmask_b32_e64 v61, 0, v61, s[8:9]
	s_waitcnt vmcnt(0)
	v_and_b32_e32 v117, 0xffff0000, v113
	v_and_b32_e32 v116, 0xffff0000, v112
	v_lshlrev_b32_e32 v73, 16, v113
	v_lshlrev_b32_e32 v75, 16, v112
	v_pk_mul_f32 v[112:113], v[154:155], v[116:117]
	global_load_dwordx4 v[116:119], v[118:119], off offset:2048
	v_cndmask_b32_e64 v113, 0, v113, s[12:13]
	v_cndmask_b32_e64 v112, 0, v112, s[12:13]
	v_pk_add_f32 v[112:113], v[152:153], v[112:113]
	v_mul_f32_e32 v73, v62, v73
	v_cndmask_b32_e64 v73, 0, v73, s[12:13]
	v_mul_f32_e32 v75, v60, v75
	v_add_f32_e32 v73, v58, v73
	v_cndmask_b32_e64 v75, 0, v75, s[12:13]
	v_add_f32_e32 v75, v56, v75
	s_waitcnt vmcnt(0)
	v_and_b32_e32 v127, 0xffff0000, v117
	v_and_b32_e32 v126, 0xffff0000, v116
	v_lshlrev_b32_e32 v77, 16, v117
	v_lshlrev_b32_e32 v79, 16, v116
	v_pk_mul_f32 v[116:117], v[156:157], v[126:127]
	global_load_dwordx4 v[124:127], v[124:125], off offset:2048
	v_cndmask_b32_e64 v117, 0, v117, s[10:11]
	v_cndmask_b32_e64 v116, 0, v116, s[10:11]
	v_pk_add_f32 v[112:113], v[112:113], v[116:117]
	v_cndmask_b32_e64 v117, 0, v121, s[8:9]
	v_cndmask_b32_e64 v116, 0, v120, s[8:9]
	global_load_dwordx4 v[120:123], v[122:123], off offset:2048
	v_mul_f32_e32 v77, v66, v77
	v_cndmask_b32_e64 v77, 0, v77, s[10:11]
	v_mul_f32_e32 v79, v64, v79
	v_add_f32_e32 v73, v73, v77
	v_cndmask_b32_e64 v79, 0, v79, s[10:11]
	v_add_f32_e32 v69, v73, v69
	v_add_f32_e32 v75, v75, v79
	v_add_f32_e32 v71, v75, v71
	v_pk_add_f32 v[112:113], v[112:113], v[116:117]
	v_lshlrev_b32_e32 v77, 16, v118
	v_mul_f32_e32 v77, v32, v77
	v_lshlrev_b32_e32 v79, 16, v119
	v_cndmask_b32_e64 v77, 0, v77, s[10:11]
	s_waitcnt vmcnt(0)
	v_lshlrev_b32_e32 v73, 16, v121
	v_mul_f32_e32 v73, v74, v73
	v_lshlrev_b32_e32 v75, 16, v120
	v_cndmask_b32_e64 v73, 0, v73, s[6:7]
	v_mul_f32_e32 v75, v72, v75
	v_add_f32_e32 v69, v69, v73
	v_lshlrev_b32_e32 v73, 16, v125
	v_cndmask_b32_e64 v75, 0, v75, s[6:7]
	v_mul_f32_e32 v73, v78, v73
	v_and_b32_e32 v117, 0xffff0000, v121
	v_and_b32_e32 v116, 0xffff0000, v120
	v_add_f32_e32 v71, v71, v75
	v_lshlrev_b32_e32 v75, 16, v124
	v_cndmask_b32_e32 v73, 0, v73, vcc
	v_pk_mul_f32 v[116:117], v[160:161], v[116:117]
	v_mul_f32_e32 v75, v76, v75
	v_add_f32_e32 v69, v69, v73
	v_lshlrev_b32_e32 v73, 16, v114
	v_cndmask_b32_e64 v117, 0, v117, s[6:7]
	v_cndmask_b32_e64 v116, 0, v116, s[6:7]
	v_cndmask_b32_e32 v75, 0, v75, vcc
	v_mul_f32_e32 v73, v36, v73
	v_pk_add_f32 v[112:113], v[112:113], v[116:117]
	v_and_b32_e32 v117, 0xffff0000, v125
	v_and_b32_e32 v116, 0xffff0000, v124
	v_add_f32_e32 v71, v71, v75
	v_lshlrev_b32_e32 v75, 16, v115
	v_cndmask_b32_e64 v73, 0, v73, s[12:13]
	v_pk_mul_f32 v[116:117], v[162:163], v[116:117]
	v_add_f32_e32 v73, v40, v73
	v_mul_f32_e32 v75, v38, v75
	v_cndmask_b32_e32 v117, 0, v117, vcc
	v_cndmask_b32_e32 v116, 0, v116, vcc
	v_cndmask_b32_e64 v75, 0, v75, s[12:13]
	v_add_f32_e32 v73, v73, v77
	v_mul_f32_e32 v77, v34, v79
	v_pk_add_f32 v[116:117], v[112:113], v[116:117]
	v_and_b32_e32 v113, 0xffff0000, v115
	v_and_b32_e32 v112, 0xffff0000, v114
	v_add_f32_e32 v75, v42, v75
	v_cndmask_b32_e64 v77, 0, v77, s[10:11]
	v_add_f32_e32 v63, v73, v63
	v_lshlrev_b32_e32 v73, 16, v122
	v_pk_mul_f32 v[112:113], v[26:27], v[112:113]
	v_and_b32_e32 v115, 0xffff0000, v119
	v_and_b32_e32 v114, 0xffff0000, v118
	v_add_f32_e32 v75, v75, v77
	v_mul_f32_e32 v73, v48, v73
	v_cndmask_b32_e64 v113, 0, v113, s[12:13]
	v_cndmask_b32_e64 v112, 0, v112, s[12:13]
	v_pk_mul_f32 v[114:115], v[30:31], v[114:115]
	v_add_f32_e32 v61, v75, v61
	v_lshlrev_b32_e32 v75, 16, v123
	v_cndmask_b32_e64 v73, 0, v73, s[6:7]
	v_pk_add_f32 v[112:113], v[22:23], v[112:113]
	v_cndmask_b32_e64 v115, 0, v115, s[10:11]
	v_cndmask_b32_e64 v114, 0, v114, s[10:11]
	v_add_f32_e32 v63, v63, v73
	v_mul_f32_e32 v73, v50, v75
	v_pk_add_f32 v[112:113], v[112:113], v[114:115]
	v_cndmask_b32_e64 v115, 0, v129, s[8:9]
	v_cndmask_b32_e64 v114, 0, v128, s[8:9]
	v_cndmask_b32_e64 v73, 0, v73, s[6:7]
	v_pk_add_f32 v[112:113], v[112:113], v[114:115]
	v_and_b32_e32 v115, 0xffff0000, v123
	v_and_b32_e32 v114, 0xffff0000, v122
	v_add_f32_e32 v61, v61, v73
	v_lshlrev_b32_e32 v73, 16, v126
	v_pk_mul_f32 v[114:115], v[148:149], v[114:115]
	v_mul_f32_e32 v73, v52, v73
	v_cndmask_b32_e64 v115, 0, v115, s[6:7]
	v_cndmask_b32_e64 v114, 0, v114, s[6:7]
	v_lshlrev_b32_e32 v75, 16, v127
	v_cndmask_b32_e32 v73, 0, v73, vcc
	v_pk_add_f32 v[112:113], v[112:113], v[114:115]
	v_and_b32_e32 v115, 0xffff0000, v127
	v_and_b32_e32 v114, 0xffff0000, v126
	v_add_f32_e32 v63, v63, v73
	v_mul_f32_e32 v73, v54, v75
	v_cndmask_b32_e32 v73, 0, v73, vcc
	v_pk_mul_f32 v[114:115], v[150:151], v[114:115]
	v_add_f32_e32 v73, v61, v73
	v_cndmask_b32_e32 v115, 0, v115, vcc
	v_cndmask_b32_e32 v114, 0, v114, vcc
	v_mul_f32_e32 v61, 0xbfb8aa3b, v71
	v_pk_add_f32 v[112:113], v[112:113], v[114:115]
	v_exp_f32_e32 v114, v61
	v_mul_f32_e32 v61, 0xbfb8aa3b, v116
	v_exp_f32_e32 v118, v61
	v_mul_f32_e32 v61, 0xbfb8aa3b, v69
	v_exp_f32_e32 v115, v61
	v_mul_f32_e32 v61, 0xbfb8aa3b, v117
	v_exp_f32_e32 v119, v61
	v_pk_add_f32 v[114:115], v[114:115], 1.0 op_sel_hi:[1,0]
	s_nop 0
	v_rcp_f32_e32 v75, v115
	v_pk_add_f32 v[118:119], v[118:119], 1.0 op_sel_hi:[1,0]
	v_mul_f32_e32 v115, v69, v75
	v_rcp_f32_e32 v69, v114
	s_nop 0
	v_mul_f32_e32 v114, v71, v69
	v_rcp_f32_e32 v71, v119
	v_pk_fma_f32 v[114:115], v[138:139], v[114:115], v[130:131]
	v_mul_f32_e32 v61, v117, v71
	v_pk_mul_f32 v[182:183], v[114:115], v[132:133]
	v_mov_b32_e32 v115, v61
	v_rcp_f32_e32 v71, v118
	v_cndmask_b32_e64 v69, 0, v182, s[4:5]
	v_mul_f32_e32 v114, v116, v71
	v_pk_fma_f32 v[114:115], v[138:139], v[114:115], v[134:135]
	v_mul_f32_e32 v77, 0xbfb8aa3b, v63
	v_pk_mul_f32 v[184:185], v[114:115], v[184:185]
	v_exp_f32_e32 v114, v77
	v_mul_f32_e32 v77, 0xbfb8aa3b, v112
	v_exp_f32_e32 v116, v77
	v_mul_f32_e32 v77, 0xbfb8aa3b, v73
	v_exp_f32_e32 v115, v77
	v_mul_f32_e32 v77, 0xbfb8aa3b, v113
	v_exp_f32_e32 v117, v77
	v_cndmask_b32_e64 v61, 0, v184, s[4:5]
	v_pk_add_f32 v[114:115], v[114:115], 1.0 op_sel_hi:[1,0]
	v_mul_f32_e32 v61, v61, v61
	v_rcp_f32_e32 v79, v115
	v_pk_add_f32 v[116:117], v[116:117], 1.0 op_sel_hi:[1,0]
	v_fmac_f32_e32 v61, v69, v69
	v_cndmask_b32_e64 v71, 0, v183, s[4:5]
	v_mul_f32_e32 v115, v73, v79
	v_rcp_f32_e32 v77, v114
	v_cndmask_b32_e64 v75, 0, v185, s[4:5]
	v_fmac_f32_e32 v61, v71, v71
	v_fmac_f32_e32 v61, v75, v75
	v_mul_f32_e32 v114, v63, v77
	v_rcp_f32_e32 v77, v117
	v_pk_fma_f32 v[114:115], v[138:139], v[114:115], v[186:187]
	v_pk_mul_f32 v[186:187], v[114:115], v[190:191]
	v_mul_f32_e32 v113, v113, v77
	v_rcp_f32_e32 v77, v116
	v_cmp_eq_u32_e64 s[6:7], 0, v67
	v_cndmask_b32_e64 v73, 0, v186, s[4:5]
	v_fmac_f32_e32 v61, v73, v73
	v_mul_f32_e32 v112, v112, v77
	v_pk_fma_f32 v[112:113], v[138:139], v[112:113], v[188:189]
	global_load_dwordx4 v[116:119], v[176:177], off offset:512
	v_pk_mul_f32 v[188:189], v[112:113], v[192:193]
	global_load_dwordx4 v[112:115], v[176:177], off
	v_cmp_lt_u32_e32 vcc, v67, v65
	v_cndmask_b32_e64 v190, 0.5, 0, s[6:7]
	v_cndmask_b32_e64 v77, 0, v188, s[4:5]
	v_cndmask_b32_e32 v136, 0, v49, vcc
	v_cndmask_b32_e64 v191, 0, 0.5, vcc
	v_cndmask_b32_e64 v79, 0, v187, s[4:5]
	v_fmac_f32_e32 v61, v77, v77
	v_cndmask_b32_e64 v63, 0, v189, s[4:5]
	v_fmac_f32_e32 v61, v79, v79
	v_fmac_f32_e32 v61, v63, v63
	v_mov_b32_e32 v65, 0
	s_waitcnt vmcnt(1)
	v_and_b32_e32 v123, 0xffff0000, v117
	v_and_b32_e32 v122, 0xffff0000, v116
	s_waitcnt vmcnt(0)
	v_and_b32_e32 v121, 0xffff0000, v113
	v_and_b32_e32 v120, 0xffff0000, v112
	v_lshlrev_b32_e32 v113, 16, v113
	v_lshlrev_b32_e32 v112, 16, v112
	v_lshlrev_b32_e32 v117, 16, v117
	v_lshlrev_b32_e32 v116, 16, v116
	v_pk_add_f32 v[200:201], v[112:113], v[116:117]
	v_pk_add_f32 v[198:199], v[120:121], v[122:123]
	v_add_f32_e32 v112, 0, v200
	v_add_f32_e32 v112, v198, v112
	v_add_f32_e32 v112, v201, v112
	v_add_f32_e32 v120, v199, v112
	v_and_b32_e32 v113, 0xffff0000, v115
	v_and_b32_e32 v112, 0xffff0000, v114
	v_and_b32_e32 v117, 0xffff0000, v119
	v_and_b32_e32 v116, 0xffff0000, v118
	v_pk_add_f32 v[192:193], v[112:113], v[116:117]
	v_lshlrev_b32_e32 v113, 16, v115
	v_lshlrev_b32_e32 v112, 16, v114
	v_lshlrev_b32_e32 v115, 16, v119
	v_lshlrev_b32_e32 v114, 16, v118
	v_pk_add_f32 v[194:195], v[112:113], v[114:115]
	global_load_dwordx4 v[114:117], v[180:181], off offset:3360
	v_add_f32_e32 v112, v194, v120
	v_add_f32_e32 v112, v192, v112
	v_add_f32_e32 v112, v195, v112
	v_add_f32_e32 v112, v193, v112
	v_cndmask_b32_e64 v113, -1, 0, s[6:7]
	v_lshl_add_u64 v[118:119], v[180:181], 0, v[136:137]
	v_add_f32_dpp v69, v112, v112 quad_perm:[1,0,3,2] row_mask:0xf bank_mask:0xf bound_ctrl:1
	v_cndmask_b32_e64 v112, v47, 0, s[6:7]
	global_load_dwordx4 v[124:127], v[118:119], off offset:3360
	v_add_f32_dpp v69, v69, v69 quad_perm:[2,3,0,1] row_mask:0xf bank_mask:0xf bound_ctrl:1
	v_add_f32_dpp v61, v61, v61 row_ror:8 row_mask:0xf bank_mask:0xf bound_ctrl:1
	s_waitcnt vmcnt(1)
	v_lshlrev_b32_e32 v208, 16, v114
	v_and_b32_e32 v209, 0xffff0000, v114
	v_lshlrev_b32_e32 v206, 16, v115
	v_and_b32_e32 v207, 0xffff0000, v115
	v_lshlrev_b32_e32 v202, 16, v116
	v_and_b32_e32 v203, 0xffff0000, v116
	v_lshlrev_b32_e32 v114, 16, v117
	v_and_b32_e32 v115, 0xffff0000, v117
	v_lshl_add_u64 v[116:117], v[180:181], 0, v[112:113]
	global_load_dwordx4 v[120:123], v[116:117], off offset:3360
	s_waitcnt vmcnt(1)
	v_lshlrev_b32_e32 v113, 16, v127
	v_and_b32_e32 v129, 0xffff0000, v127
	v_lshlrev_b32_e32 v237, 16, v124
	v_and_b32_e32 v239, 0xffff0000, v124
	v_add_f32_dpp v69, v69, v69 row_half_mirror row_mask:0xf bank_mask:0xf bound_ctrl:1
	v_mul_f32_e32 v196, 0x3c800000, v69
	v_add_f32_dpp v61, v61, v61 row_ror:4 row_mask:0xf bank_mask:0xf bound_ctrl:1
	v_mov_b32_e32 v69, 0
	s_waitcnt vmcnt(0)
	v_and_b32_e32 v112, 0xffff0000, v123
	v_lshlrev_b32_e32 v128, 16, v123
	v_pk_mul_f32 v[112:113], v[190:191], v[112:113]
	v_and_b32_e32 v236, 0xffff0000, v120
	v_pk_fma_f32 v[112:113], v[190:191], v[128:129], v[112:113] op_sel:[0,0,1] op_sel_hi:[1,1,0]
	v_lshlrev_b32_e32 v238, 16, v120
	v_pk_add_f32 v[112:113], v[112:113], v[114:115] neg_lo:[0,1] neg_hi:[0,1]
	v_pk_mul_f32 v[236:237], v[190:191], v[236:237]
	v_pk_fma_f32 v[204:205], v[82:83], v[112:113], v[114:115]
	global_load_dwordx4 v[112:115], v[180:181], off offset:3872
	global_load_dwordx4 v[128:131], v[116:117], off offset:3872
	global_load_dwordx4 v[132:135], v[118:119], off offset:3872
	v_pk_fma_f32 v[236:237], v[190:191], v[238:239], v[236:237] op_sel:[0,0,1] op_sel_hi:[1,1,0]
	v_lshlrev_b32_e32 v124, 16, v121
	v_pk_add_f32 v[236:237], v[236:237], v[208:209] neg_lo:[0,1] neg_hi:[0,1]
	v_and_b32_e32 v123, 0xffff0000, v126
	v_pk_fma_f32 v[208:209], v[84:85], v[236:237], v[208:209]
	v_add_f32_dpp v61, v61, v61 row_ror:2 row_mask:0xf bank_mask:0xf bound_ctrl:1
	s_waitcnt vmcnt(2)
	v_lshlrev_b32_e32 v216, 16, v112
	v_and_b32_e32 v217, 0xffff0000, v112
	v_lshlrev_b32_e32 v212, 16, v113
	v_and_b32_e32 v213, 0xffff0000, v113
	v_lshlrev_b32_e32 v210, 16, v114
	v_and_b32_e32 v211, 0xffff0000, v114
	v_lshlrev_b32_e32 v112, 16, v115
	v_and_b32_e32 v113, 0xffff0000, v115
	s_waitcnt vmcnt(1)
	v_and_b32_e32 v114, 0xffff0000, v131
	s_waitcnt vmcnt(0)
	v_lshlrev_b32_e32 v115, 16, v135
	v_and_b32_e32 v215, 0xffff0000, v135
	v_lshlrev_b32_e32 v214, 16, v131
	v_pk_mul_f32 v[114:115], v[190:191], v[114:115]
	v_and_b32_e32 v236, 0xffff0000, v128
	v_pk_fma_f32 v[114:115], v[190:191], v[214:215], v[114:115] op_sel:[0,0,1] op_sel_hi:[1,1,0]
	v_lshlrev_b32_e32 v237, 16, v132
	v_pk_add_f32 v[114:115], v[114:115], v[112:113] neg_lo:[0,1] neg_hi:[0,1]
	v_and_b32_e32 v239, 0xffff0000, v132
	v_pk_fma_f32 v[214:215], v[90:91], v[114:115], v[112:113]
	v_add_co_u32_e32 v112, vcc, s2, v116
	v_lshlrev_b32_e32 v238, 16, v128
	s_nop 0
	v_addc_co_u32_e32 v113, vcc, 0, v117, vcc
	v_add_co_u32_e32 v116, vcc, s2, v118
	global_load_dwordx4 v[112:115], v[112:113], off offset:288
	s_nop 0
	v_addc_co_u32_e32 v117, vcc, 0, v119, vcc
	global_load_dwordx4 v[116:119], v[116:117], off offset:288
	s_nop 0
	global_load_dwordx4 v[228:231], v[178:179], off offset:1024
	v_pk_mul_f32 v[236:237], v[190:191], v[236:237]
	v_lshlrev_b32_e32 v132, 16, v129
	v_pk_fma_f32 v[236:237], v[190:191], v[238:239], v[236:237] op_sel:[0,0,1] op_sel_hi:[1,1,0]
	v_add_f32_dpp v61, v61, v61 row_ror:1 row_mask:0xf bank_mask:0xf bound_ctrl:1
	v_pk_add_f32 v[236:237], v[236:237], v[216:217] neg_lo:[0,1] neg_hi:[0,1]
	s_waitcnt vmcnt(0)
	v_lshlrev_b32_e32 v224, 16, v228
	v_and_b32_e32 v225, 0xffff0000, v228
	v_lshlrev_b32_e32 v222, 16, v229
	v_and_b32_e32 v223, 0xffff0000, v229
	v_lshlrev_b32_e32 v220, 16, v230
	v_and_b32_e32 v221, 0xffff0000, v230
	v_lshlrev_b32_e32 v218, 16, v231
	v_and_b32_e32 v219, 0xffff0000, v231
	global_load_dwordx4 v[228:231], v[178:179], off offset:1536
	v_pk_fma_f32 v[216:217], v[92:93], v[236:237], v[216:217]
	v_pk_add_f32 v[224:225], v[224:225], -1.0 op_sel_hi:[1,0]
	s_waitcnt vmcnt(0)
	v_lshlrev_b32_e32 v232, 16, v228
	v_and_b32_e32 v233, 0xffff0000, v228
	v_pk_add_f32 v[232:233], v[232:233], -1.0 op_sel_hi:[1,0]
	v_pk_fma_f32 v[224:225], v[104:105], v[224:225], 1.0 op_sel_hi:[1,1,0]
	v_pk_fma_f32 v[232:233], v[104:105], v[232:233], 1.0 op_sel_hi:[1,1,0]
	v_lshlrev_b32_e32 v228, 16, v229
	v_pk_mul_f32 v[232:233], v[216:217], v[232:233]
	v_and_b32_e32 v229, 0xffff0000, v229
	v_pk_fma_f32 v[216:217], v[216:217], v[224:225], v[232:233]
	v_lshlrev_b32_e32 v234, 16, v230
	v_pk_mul_f32 v[208:209], v[208:209], v[216:217]
	v_and_b32_e32 v235, 0xffff0000, v230
	v_pk_mul_f32 v[208:209], v[108:109], v[208:209]
	v_lshlrev_b32_e32 v230, 16, v231
	v_add_f32_e32 v63, 0, v208
	v_add_f32_e32 v63, v209, v63
	v_and_b32_e32 v208, 0xffff0000, v121
	v_lshlrev_b32_e32 v209, 16, v125
	v_and_b32_e32 v125, 0xffff0000, v125
	v_pk_mul_f32 v[120:121], v[190:191], v[208:209]
	v_and_b32_e32 v231, 0xffff0000, v231
	v_pk_fma_f32 v[120:121], v[190:191], v[124:125], v[120:121] op_sel:[0,0,1] op_sel_hi:[1,1,0]
	v_and_b32_e32 v124, 0xffff0000, v129
	v_lshlrev_b32_e32 v125, 16, v133
	v_and_b32_e32 v133, 0xffff0000, v133
	v_pk_mul_f32 v[124:125], v[190:191], v[124:125]
	v_pk_add_f32 v[128:129], v[222:223], -1.0 op_sel_hi:[1,0]
	v_pk_fma_f32 v[124:125], v[190:191], v[132:133], v[124:125] op_sel:[0,0,1] op_sel_hi:[1,1,0]
	v_pk_add_f32 v[132:133], v[228:229], -1.0 op_sel_hi:[1,0]
	v_pk_add_f32 v[124:125], v[124:125], v[212:213] neg_lo:[0,1] neg_hi:[0,1]
	v_pk_fma_f32 v[132:133], v[106:107], v[132:133], 1.0 op_sel_hi:[1,1,0]
	v_pk_fma_f32 v[124:125], v[94:95], v[124:125], v[212:213]
	v_pk_add_f32 v[120:121], v[120:121], v[206:207] neg_lo:[0,1] neg_hi:[0,1]
	v_pk_fma_f32 v[128:129], v[106:107], v[128:129], 1.0 op_sel_hi:[1,1,0]
	v_pk_mul_f32 v[132:133], v[124:125], v[132:133]
	v_pk_fma_f32 v[120:121], v[86:87], v[120:121], v[206:207]
	v_pk_fma_f32 v[124:125], v[124:125], v[128:129], v[132:133]
	v_pk_add_f32 v[128:129], v[198:199], v[196:197] op_sel_hi:[1,0] neg_lo:[0,1] neg_hi:[0,1]
	v_pk_mul_f32 v[120:121], v[120:121], v[124:125]
	v_and_b32_e32 v125, 0xffff0000, v134
	v_pk_mul_f32 v[120:121], v[110:111], v[120:121]
	v_lshlrev_b32_e32 v124, 16, v130
	v_add_f32_e32 v63, v120, v63
	v_add_f32_e32 v63, v121, v63
	v_and_b32_e32 v120, 0xffff0000, v122
	v_lshlrev_b32_e32 v121, 16, v126
	v_lshlrev_b32_e32 v122, 16, v122
	v_pk_mul_f32 v[120:121], v[190:191], v[120:121]
	v_pk_add_f32 v[126:127], v[234:235], -1.0 op_sel_hi:[1,0]
	v_pk_fma_f32 v[120:121], v[190:191], v[122:123], v[120:121] op_sel:[0,0,1] op_sel_hi:[1,1,0]
	v_and_b32_e32 v122, 0xffff0000, v130
	v_lshlrev_b32_e32 v123, 16, v134
	v_pk_mul_f32 v[122:123], v[190:191], v[122:123]
	v_pk_fma_f32 v[126:127], v[96:97], v[126:127], 1.0 op_sel_hi:[1,1,0]
	v_pk_fma_f32 v[122:123], v[190:191], v[124:125], v[122:123] op_sel:[0,0,1] op_sel_hi:[1,1,0]
	v_pk_add_f32 v[124:125], v[220:221], -1.0 op_sel_hi:[1,0]
	v_pk_add_f32 v[122:123], v[122:123], v[210:211] neg_lo:[0,1] neg_hi:[0,1]
	v_pk_add_f32 v[120:121], v[120:121], v[202:203] neg_lo:[0,1] neg_hi:[0,1]
	v_pk_fma_f32 v[122:123], v[88:89], v[122:123], v[210:211]
	v_pk_fma_f32 v[124:125], v[96:97], v[124:125], 1.0 op_sel_hi:[1,1,0]
	v_pk_mul_f32 v[126:127], v[122:123], v[126:127]
	v_pk_fma_f32 v[120:121], v[80:81], v[120:121], v[202:203]
	v_pk_fma_f32 v[122:123], v[122:123], v[124:125], v[126:127]
	v_pk_add_f32 v[130:131], v[200:201], v[196:197] op_sel_hi:[1,0] neg_lo:[0,1] neg_hi:[0,1]
	v_pk_mul_f32 v[120:121], v[120:121], v[122:123]
	v_pk_add_f32 v[122:123], v[230:231], -1.0 op_sel_hi:[1,0]
	v_pk_mul_f32 v[120:121], v[100:101], v[120:121]
	v_pk_fma_f32 v[122:123], v[98:99], v[122:123], 1.0 op_sel_hi:[1,1,0]
	v_add_f32_e32 v63, v120, v63
	v_add_f32_e32 v63, v121, v63
	v_pk_add_f32 v[120:121], v[218:219], -1.0 op_sel_hi:[1,0]
	v_pk_mul_f32 v[122:123], v[214:215], v[122:123]
	v_pk_fma_f32 v[120:121], v[98:99], v[120:121], 1.0 op_sel_hi:[1,1,0]
	s_nop 0
	v_pk_fma_f32 v[120:121], v[214:215], v[120:121], v[122:123]
	s_nop 0
	v_pk_mul_f32 v[120:121], v[204:205], v[120:121]
	s_nop 0
	v_pk_mul_f32 v[120:121], v[102:103], v[120:121]
	s_nop 0
	v_add_f32_e32 v63, v120, v63
	v_add_f32_e32 v63, v121, v63
	v_mov_b32_e32 v120, v130
	v_mov_b32_e32 v121, v128
	v_pk_mul_f32 v[132:133], v[120:121], v[120:121]
	v_mov_b32_e32 v120, v129
	v_mov_b32_e32 v121, v131
	v_pk_mul_f32 v[134:135], v[120:121], v[120:121]
	v_add_co_u32_e32 v120, vcc, s2, v180
	v_add_f32_e32 v67, v132, v133
	s_nop 0
	v_addc_co_u32_e32 v121, vcc, 0, v181, vcc
	global_load_dwordx4 v[124:127], v[120:121], off offset:288
	s_nop 0
	global_load_dwordx4 v[120:123], v[178:179], off offset:2048
	v_cmp_lt_i32_e32 vcc, v53, v55
	v_pk_add_f32 v[180:181], v[194:195], v[196:197] op_sel_hi:[1,0] neg_lo:[0,1] neg_hi:[0,1]
	v_pk_add_f32 v[178:179], v[192:193], v[196:197] op_sel_hi:[1,0] neg_lo:[0,1] neg_hi:[0,1]
	v_cndmask_b32_e32 v71, v227, v53, vcc
	v_lshlrev_b32_e32 v71, 2, v71
	ds_bpermute_b32 v71, v71, v61
	v_mov_b32_e32 v192, v178
	v_mov_b32_e32 v193, v180
	v_add_f32_e32 v67, v135, v67
	v_pk_mul_f32 v[192:193], v[192:193], v[192:193]
	v_add_f32_e32 v67, v134, v67
	v_cmp_lt_i32_e32 vcc, v57, v55
	v_mov_b32_e32 v194, v179
	v_mov_b32_e32 v195, v181
	v_add_f32_e32 v67, v193, v67
	s_waitcnt lgkmcnt(0)
	v_add_f32_e32 v61, v61, v71
	v_cndmask_b32_e32 v71, v227, v57, vcc
	v_pk_mul_f32 v[194:195], v[194:195], v[194:195]
	v_add_f32_e32 v67, v192, v67
	v_lshlrev_b32_e32 v71, 2, v71
	v_add_f32_e32 v67, v195, v67
	ds_bpermute_b32 v71, v71, v61
	v_add_f32_e32 v67, v194, v67
	v_add_f32_dpp v63, v63, v63 quad_perm:[1,0,3,2] row_mask:0xf bank_mask:0xf bound_ctrl:1
	s_nop 0
	v_add_f32_dpp v67, v67, v67 quad_perm:[1,0,3,2] row_mask:0xf bank_mask:0xf bound_ctrl:1
	v_add_f32_dpp v63, v63, v63 quad_perm:[2,3,0,1] row_mask:0xf bank_mask:0xf bound_ctrl:1
	s_nop 0
	v_add_f32_dpp v67, v67, v67 quad_perm:[2,3,0,1] row_mask:0xf bank_mask:0xf bound_ctrl:1
	v_mov_b32_dpp v65, v63 row_half_mirror row_mask:0xf bank_mask:0xf
	s_nop 0
	v_mov_b32_dpp v69, v67 row_half_mirror row_mask:0xf bank_mask:0xf
	s_and_saveexec_b64 s[6:7], s[4:5]
	s_cbranch_execz .LBB0_1349
	s_waitcnt lgkmcnt(0)
	v_add_f32_e32 v61, v61, v71
	v_fmamk_f32 v61, v61, 0x3b2aaaab, v33
	v_mul_f32_e32 v71, 0x4b800000, v61
	v_cmp_gt_f32_e32 vcc, s22, v61
	s_nop 1
	v_cndmask_b32_e32 v61, v61, v71, vcc
	v_rsq_f32_e32 v61, v61
	s_nop 0
	v_mul_f32_e32 v71, 0x45800000, v61
	v_cndmask_b32_e32 v134, v61, v71, vcc
	v_pk_mul_f32 v[132:133], v[182:183], v[134:135] op_sel_hi:[1,0]
	v_pk_mul_f32 v[182:183], v[184:185], v[134:135] op_sel_hi:[1,0]
	v_pk_mul_f32 v[132:133], v[28:29], v[132:133]
	v_pk_mul_f32 v[182:183], v[14:15], v[182:183]
	v_and_b32_sdwa v61, v133, v59 dst_sel:DWORD dst_unused:UNUSED_PAD src0_sel:WORD_1 src1_sel:DWORD
	v_and_b32_sdwa v73, v183, v59 dst_sel:DWORD dst_unused:UNUSED_PAD src0_sel:WORD_1 src1_sel:DWORD
	v_and_b32_sdwa v75, v182, v59 dst_sel:DWORD dst_unused:UNUSED_PAD src0_sel:WORD_1 src1_sel:DWORD
	v_and_b32_sdwa v71, v132, v59 dst_sel:DWORD dst_unused:UNUSED_PAD src0_sel:WORD_1 src1_sel:DWORD
	v_add3_u32 v73, v183, v73, s23
	v_add3_u32 v75, v182, v75, s23
	v_pk_mul_f32 v[182:183], v[186:187], v[134:135] op_sel_hi:[1,0]
	v_pk_mul_f32 v[134:135], v[188:189], v[134:135] op_sel_hi:[1,0]
	v_add3_u32 v71, v132, v71, s23
	v_add3_u32 v61, v133, v61, s23
	v_and_b32_e32 v73, 0xffff0000, v73
	v_and_b32_e32 v75, 0xffff0000, v75
	v_pk_mul_f32 v[134:135], v[18:19], v[134:135]
	v_or_b32_sdwa v133, v73, v61 dst_sel:DWORD dst_unused:UNUSED_PAD src0_sel:DWORD src1_sel:WORD_1
	v_or_b32_sdwa v132, v75, v71 dst_sel:DWORD dst_unused:UNUSED_PAD src0_sel:DWORD src1_sel:WORD_1
	v_pk_mul_f32 v[182:183], v[24:25], v[182:183]
	v_and_b32_sdwa v73, v135, v59 dst_sel:DWORD dst_unused:UNUSED_PAD src0_sel:WORD_1 src1_sel:DWORD
	v_and_b32_sdwa v75, v134, v59 dst_sel:DWORD dst_unused:UNUSED_PAD src0_sel:WORD_1 src1_sel:DWORD
	v_and_b32_sdwa v61, v183, v59 dst_sel:DWORD dst_unused:UNUSED_PAD src0_sel:WORD_1 src1_sel:DWORD
	v_and_b32_sdwa v71, v182, v59 dst_sel:DWORD dst_unused:UNUSED_PAD src0_sel:WORD_1 src1_sel:DWORD
	v_add3_u32 v73, v135, v73, s23
	v_add3_u32 v75, v134, v75, s23
	v_add3_u32 v71, v182, v71, s23
	v_add3_u32 v61, v183, v61, s23
	v_and_b32_e32 v73, 0xffff0000, v73
	v_and_b32_e32 v75, 0xffff0000, v75
	v_or_b32_sdwa v135, v73, v61 dst_sel:DWORD dst_unused:UNUSED_PAD src0_sel:DWORD src1_sel:WORD_1
	v_or_b32_sdwa v134, v75, v71 dst_sel:DWORD dst_unused:UNUSED_PAD src0_sel:DWORD src1_sel:WORD_1
	global_store_dwordx4 v[174:175], v[132:135], off

.LBB0_1520:
	s_mul_i32 s39, s37, 0x6000
	s_waitcnt vmcnt(6)
	s_add_i32 s39, s17, s39
	s_mul_i32 s98, s38, 0x6000
	v_lshl_add_u64 v[196:197], v[136:137], 0, s[14:15]
	v_lshl_add_u64 v[198:199], v[134:135], 0, s[14:15]
	s_add_i32 s99, s39, s18
	s_waitcnt lgkmcnt(0)
	s_barrier
	v_add_u32_e32 v178, s98, v139
	v_add_u32_e32 v179, s98, v141
	ds_read_b128 v[162:165], v179
	ds_read_b128 v[146:149], v178
	ds_read_b128 v[166:169], v179 offset:1024
	ds_read_b128 v[170:173], v179 offset:2048
	ds_read_b128 v[174:177], v179 offset:3072
	ds_read_b128 v[150:153], v178 offset:1024
	ds_read_b128 v[154:157], v178 offset:2048
	ds_read_b128 v[158:161], v178 offset:3072
	ds_read_b128 v[180:183], v178 offset:4096
	ds_read_b128 v[184:187], v178 offset:5120
	ds_read_b128 v[188:191], v178 offset:6144
	ds_read_b128 v[192:195], v178 offset:7168
	v_lshl_add_u64 v[200:201], v[196:197], 0, s[10:11]
	s_mov_b32 m0, s39
	s_waitcnt lgkmcnt(10)
	v_mfma_f32_16x16x32_bf16 v[84:87], v[146:149], v[162:165], v[84:87]
	global_load_lds_dwordx4 v[200:201], off
	s_waitcnt lgkmcnt(9)
	v_mfma_f32_16x16x32_bf16 v[76:79], v[146:149], v[166:169], v[76:79]
	v_lshl_add_u64 v[200:201], v[196:197], 0, s[12:13]
	s_add_i32 m0, s39, 0x400
	s_waitcnt lgkmcnt(8)
	v_mfma_f32_16x16x32_bf16 v[68:71], v[146:149], v[170:173], v[68:71]
	global_load_lds_dwordx4 v[200:201], off
	s_waitcnt lgkmcnt(7)
	v_mfma_f32_16x16x32_bf16 v[60:63], v[146:149], v[174:177], v[60:63]
	s_mov_b64 s[100:101], 0x10080
	v_lshl_add_u64 v[200:201], v[196:197], 0, s[100:101]
	s_add_i32 m0, s39, 0x800
	s_waitcnt lgkmcnt(6)
	v_mfma_f32_16x16x32_bf16 v[52:55], v[150:153], v[162:165], v[52:55]
	global_load_lds_dwordx4 v[200:201], off
	v_mfma_f32_16x16x32_bf16 v[44:47], v[150:153], v[166:169], v[44:47]
	v_mfma_f32_16x16x32_bf16 v[36:39], v[150:153], v[170:173], v[36:39]
	s_mov_b64 s[100:101], 0x18080
	v_lshl_add_u64 v[200:201], v[196:197], 0, s[100:101]
	s_add_i32 m0, s39, 0xc00
	v_mfma_f32_16x16x32_bf16 v[32:35], v[150:153], v[174:177], v[32:35]
	global_load_lds_dwordx4 v[200:201], off
	s_waitcnt lgkmcnt(5)
	v_mfma_f32_16x16x32_bf16 v[28:31], v[154:157], v[162:165], v[28:31]
	v_lshl_add_u64 v[200:201], v[198:199], 0, s[10:11]
	s_add_i32 m0, s99, 0x4000
	v_mfma_f32_16x16x32_bf16 v[24:27], v[154:157], v[166:169], v[24:27]
	global_load_lds_dwordx4 v[200:201], off
	v_mfma_f32_16x16x32_bf16 v[20:23], v[154:157], v[170:173], v[20:23]
	v_lshl_add_u64 v[200:201], v[198:199], 0, s[12:13]
	s_add_i32 m0, s99, 0x4400
	v_mfma_f32_16x16x32_bf16 v[16:19], v[154:157], v[174:177], v[16:19]
	global_load_lds_dwordx4 v[200:201], off
	s_waitcnt lgkmcnt(4)
	v_mfma_f32_16x16x32_bf16 v[12:15], v[158:161], v[162:165], v[12:15]
	v_mfma_f32_16x16x32_bf16 v[8:11], v[158:161], v[166:169], v[8:11]
	v_mfma_f32_16x16x32_bf16 v[4:7], v[158:161], v[170:173], v[4:7]
	v_mfma_f32_16x16x32_bf16 v[0:3], v[158:161], v[174:177], v[0:3]
	s_waitcnt lgkmcnt(3)
	v_mfma_f32_16x16x32_bf16 v[124:127], v[180:183], v[162:165], v[124:127]
	v_mfma_f32_16x16x32_bf16 v[120:123], v[180:183], v[166:169], v[120:123]
	v_mfma_f32_16x16x32_bf16 v[116:119], v[180:183], v[170:173], v[116:119]
	v_mfma_f32_16x16x32_bf16 v[112:115], v[180:183], v[174:177], v[112:115]
	s_waitcnt lgkmcnt(2)
	v_mfma_f32_16x16x32_bf16 v[108:111], v[184:187], v[162:165], v[108:111]
	v_mfma_f32_16x16x32_bf16 v[104:107], v[184:187], v[166:169], v[104:107]
	v_mfma_f32_16x16x32_bf16 v[100:103], v[184:187], v[170:173], v[100:103]
	v_mfma_f32_16x16x32_bf16 v[96:99], v[184:187], v[174:177], v[96:99]
	s_waitcnt lgkmcnt(1)
	v_mfma_f32_16x16x32_bf16 v[92:95], v[188:191], v[162:165], v[92:95]
	v_mfma_f32_16x16x32_bf16 v[88:91], v[188:191], v[166:169], v[88:91]
	v_mfma_f32_16x16x32_bf16 v[80:83], v[188:191], v[170:173], v[80:83]
	v_mfma_f32_16x16x32_bf16 v[72:75], v[188:191], v[174:177], v[72:75]
	s_waitcnt lgkmcnt(0)
	v_mfma_f32_16x16x32_bf16 v[64:67], v[192:195], v[162:165], v[64:67]
	v_mfma_f32_16x16x32_bf16 v[56:59], v[192:195], v[166:169], v[56:59]
	v_mfma_f32_16x16x32_bf16 v[48:51], v[192:195], v[170:173], v[48:51]
	v_mfma_f32_16x16x32_bf16 v[40:43], v[192:195], v[174:177], v[40:43]
	s_add_i32 s39, s38, 1
	s_cmp_lg_u32 s38, 2
	s_cselect_b32 s38, s39, 0
	s_add_i32 s39, s37, 1
	s_cmp_lg_u32 s37, 2
	s_cselect_b32 s37, s39, 0
	s_add_u32 s14, s14, 64
	s_addc_u32 s15, s15, 0
	s_cmpk_eq_i32 s14, 0x780
	s_cbranch_scc0 .LBB0_1520
	s_waitcnt vmcnt(6)
	s_waitcnt lgkmcnt(0)
	s_barrier
	ds_read_b128 v[134:137], v139
	ds_read_b128 v[146:149], v139 offset:1024
	ds_read_b128 v[150:153], v139 offset:2048
	ds_read_b128 v[154:157], v139 offset:3072
	ds_read_b128 v[158:161], v141
	ds_read_b128 v[162:165], v141 offset:1024
	ds_read_b128 v[166:169], v141 offset:2048
	ds_read_b128 v[170:173], v141 offset:3072
	s_waitcnt lgkmcnt(0)
	s_nop 0
	v_mfma_f32_16x16x32_bf16 v[84:87], v[134:137], v[158:161], v[84:87]
	v_mfma_f32_16x16x32_bf16 v[76:79], v[134:137], v[162:165], v[76:79]
	v_mfma_f32_16x16x32_bf16 v[68:71], v[134:137], v[166:169], v[68:71]
	v_mfma_f32_16x16x32_bf16 v[60:63], v[134:137], v[170:173], v[60:63]
	v_mfma_f32_16x16x32_bf16 v[52:55], v[146:149], v[158:161], v[52:55]
	v_mfma_f32_16x16x32_bf16 v[44:47], v[146:149], v[162:165], v[44:47]
	v_mfma_f32_16x16x32_bf16 v[36:39], v[146:149], v[166:169], v[36:39]
	v_mfma_f32_16x16x32_bf16 v[32:35], v[146:149], v[170:173], v[32:35]
	v_mfma_f32_16x16x32_bf16 v[28:31], v[150:153], v[158:161], v[28:31]
	v_mfma_f32_16x16x32_bf16 v[24:27], v[150:153], v[162:165], v[24:27]
	v_mfma_f32_16x16x32_bf16 v[20:23], v[150:153], v[166:169], v[20:23]
	v_mfma_f32_16x16x32_bf16 v[16:19], v[150:153], v[170:173], v[16:19]
	v_mfma_f32_16x16x32_bf16 v[12:15], v[154:157], v[158:161], v[12:15]
	v_mfma_f32_16x16x32_bf16 v[8:11], v[154:157], v[162:165], v[8:11]
	v_mfma_f32_16x16x32_bf16 v[4:7], v[154:157], v[166:169], v[4:7]
	v_mfma_f32_16x16x32_bf16 v[0:3], v[154:157], v[170:173], v[0:3]
	ds_read_b128 v[134:137], v139 offset:4096
	ds_read_b128 v[146:149], v139 offset:5120
	ds_read_b128 v[150:153], v139 offset:6144
	ds_read_b128 v[154:157], v139 offset:7168
	s_waitcnt lgkmcnt(0)
	s_nop 0
	v_mfma_f32_16x16x32_bf16 v[124:127], v[134:137], v[158:161], v[124:127]
	v_mfma_f32_16x16x32_bf16 v[120:123], v[134:137], v[162:165], v[120:123]
	v_mfma_f32_16x16x32_bf16 v[174:177], v[134:137], v[166:169], v[116:119]
	v_mfma_f32_16x16x32_bf16 v[134:137], v[134:137], v[170:173], v[112:115]
	v_mfma_f32_16x16x32_bf16 v[178:181], v[146:149], v[158:161], v[108:111]
	v_mfma_f32_16x16x32_bf16 v[182:185], v[146:149], v[162:165], v[104:107]
	v_mfma_f32_16x16x32_bf16 v[186:189], v[146:149], v[166:169], v[100:103]
	v_mfma_f32_16x16x32_bf16 v[146:149], v[146:149], v[170:173], v[96:99]
	v_mfma_f32_16x16x32_bf16 v[190:193], v[150:153], v[158:161], v[92:95]
	v_mfma_f32_16x16x32_bf16 v[194:197], v[150:153], v[162:165], v[88:91]
	v_mfma_f32_16x16x32_bf16 v[198:201], v[150:153], v[166:169], v[80:83]
	v_mfma_f32_16x16x32_bf16 v[150:153], v[150:153], v[170:173], v[72:75]
	v_mfma_f32_16x16x32_bf16 v[158:161], v[154:157], v[158:161], v[64:67]
	v_mfma_f32_16x16x32_bf16 v[162:165], v[154:157], v[162:165], v[56:59]
	v_mfma_f32_16x16x32_bf16 v[166:169], v[154:157], v[166:169], v[48:51]
	v_mfma_f32_16x16x32_bf16 v[154:157], v[154:157], v[170:173], v[40:43]
	s_waitcnt vmcnt(0)
	s_waitcnt lgkmcnt(0)
	s_barrier
	ds_read_b128 v[40:43], v128
	ds_read_b128 v[48:51], v128 offset:1024
	ds_read_b128 v[56:59], v128 offset:2048
	ds_read_b128 v[170:173], v128 offset:3072
	ds_read_b128 v[202:205], v144
	ds_read_b128 v[206:209], v144 offset:1024
	ds_read_b128 v[210:213], v144 offset:2048
	ds_read_b128 v[214:217], v144 offset:3072
	s_waitcnt lgkmcnt(0)
	s_nop 0
	v_mfma_f32_16x16x32_bf16 v[222:225], v[40:43], v[206:209], v[76:79]
	v_mfma_f32_16x16x32_bf16 v[112:115], v[40:43], v[210:213], v[68:71]
	v_mfma_f32_16x16x32_bf16 v[72:75], v[170:173], v[202:205], v[12:15]
	v_mfma_f32_16x16x32_bf16 v[76:79], v[170:173], v[206:209], v[8:11]
	v_mfma_f32_16x16x32_bf16 v[64:67], v[170:173], v[210:213], v[4:7]
	v_mfma_f32_16x16x32_bf16 v[68:71], v[170:173], v[214:217], v[0:3]
	ds_read_b128 v[0:3], v128 offset:4096
	ds_read_b128 v[4:7], v128 offset:5120
	ds_read_b128 v[8:11], v128 offset:6144
	ds_read_b128 v[170:173], v128 offset:7168
	s_waitcnt lgkmcnt(0)
	v_mfma_f32_16x16x32_bf16 v[218:221], v[40:43], v[202:205], v[84:87]
	v_mfma_f32_16x16x32_bf16 v[116:119], v[40:43], v[214:217], v[60:63]
	v_mfma_f32_16x16x32_bf16 v[104:107], v[48:51], v[202:205], v[52:55]
	v_mfma_f32_16x16x32_bf16 v[108:111], v[48:51], v[206:209], v[44:47]
	v_mfma_f32_16x16x32_bf16 v[96:99], v[48:51], v[210:213], v[36:39]
	v_mfma_f32_16x16x32_bf16 v[100:103], v[48:51], v[214:217], v[32:35]
	v_mfma_f32_16x16x32_bf16 v[88:91], v[56:59], v[202:205], v[28:31]
	v_mfma_f32_16x16x32_bf16 v[92:95], v[56:59], v[206:209], v[24:27]
	v_mfma_f32_16x16x32_bf16 v[80:83], v[56:59], v[210:213], v[20:23]
	v_mfma_f32_16x16x32_bf16 v[84:87], v[56:59], v[214:217], v[16:19]
	v_mfma_f32_16x16x32_bf16 v[56:59], v[0:3], v[202:205], v[124:127]
	v_mfma_f32_16x16x32_bf16 v[60:63], v[0:3], v[206:209], v[120:123]
	v_mfma_f32_16x16x32_bf16 v[48:51], v[0:3], v[210:213], v[174:177]
	v_mfma_f32_16x16x32_bf16 v[52:55], v[0:3], v[214:217], v[134:137]
	v_mfma_f32_16x16x32_bf16 v[40:43], v[4:7], v[202:205], v[178:181]
	v_mfma_f32_16x16x32_bf16 v[44:47], v[4:7], v[206:209], v[182:185]
	v_mfma_f32_16x16x32_bf16 v[32:35], v[4:7], v[210:213], v[186:189]
	v_mfma_f32_16x16x32_bf16 v[36:39], v[4:7], v[214:217], v[146:149]
	v_mfma_f32_16x16x32_bf16 v[24:27], v[8:11], v[202:205], v[190:193]
	v_mfma_f32_16x16x32_bf16 v[28:31], v[8:11], v[206:209], v[194:197]
	v_mfma_f32_16x16x32_bf16 v[16:19], v[8:11], v[210:213], v[198:201]
	v_mfma_f32_16x16x32_bf16 v[20:23], v[8:11], v[214:217], v[150:153]
	v_mfma_f32_16x16x32_bf16 v[8:11], v[170:173], v[202:205], v[158:161]
	v_mfma_f32_16x16x32_bf16 v[12:15], v[170:173], v[206:209], v[162:165]
	v_mfma_f32_16x16x32_bf16 v[0:3], v[170:173], v[210:213], v[166:169]
	v_mfma_f32_16x16x32_bf16 v[4:7], v[170:173], v[214:217], v[154:157]
	v_mul_f32_e32 v121, 0xbfb8aa3b, v218
	v_exp_f32_e32 v121, v121
	v_or_b32_e32 v120, s36, v140
	v_ashrrev_i32_e32 v120, 1, v120
	v_or_b32_e32 v122, v120, v138
	v_add_f32_e32 v120, 1.0, v121
	v_rcp_f32_e32 v125, v120
	v_add_u32_e32 v124, s35, v145
	v_readlane_b32 s36, v241, 17
	v_mov_b32_e32 v126, v124
	v_mul_f32_e32 v120, v218, v125
	v_mul_f32_e32 v120, v222, v120
	v_mul_f32_e32 v134, 0xbfb8aa3b, v219
	v_bfe_u32 v121, v120, 16, 1
	v_readlane_b32 s37, v241, 18
	v_exp_f32_e32 v134, v134
	s_waitcnt lgkmcnt(0)
	s_barrier
	v_ashrrev_i32_e32 v123, 31, v122
	v_add3_u32 v125, v120, v121, s34
	v_mov_b64_e32 v[120:121], s[36:37]
	v_mad_i64_i32 v[126:127], s[14:15], v126, s33, v[120:121]
	v_lshlrev_b64 v[122:123], 1, v[122:123]
	v_lshl_add_u64 v[126:127], v[126:127], 0, v[122:123]
	global_store_short_d16_hi v[126:127], v125, off
	v_add_f32_e32 v125, 1.0, v134
	v_rcp_f32_e32 v127, v125
	v_or_b32_e32 v134, 1, v124
	v_mov_b32_e32 v135, v134
	v_mul_f32_e32 v125, v219, v127
	v_mul_f32_e32 v125, v223, v125
	v_bfe_u32 v126, v125, 16, 1
	v_add3_u32 v125, v125, v126, s34
	v_mul_f32_e32 v126, 0xbfb8aa3b, v220
	v_exp_f32_e32 v136, v126
	v_mad_i64_i32 v[126:127], s[14:15], v135, s33, v[120:121]
	v_lshl_add_u64 v[126:127], v[126:127], 0, v[122:123]
	global_store_short_d16_hi v[126:127], v125, off
	v_add_f32_e32 v125, 1.0, v136
	v_rcp_f32_e32 v127, v125
	v_or_b32_e32 v135, 2, v124
	v_mov_b32_e32 v136, v135
	v_mul_f32_e32 v125, v220, v127
	v_mul_f32_e32 v125, v224, v125
	v_bfe_u32 v126, v125, 16, 1
	v_add3_u32 v125, v125, v126, s34
	v_mul_f32_e32 v126, 0xbfb8aa3b, v221
	v_exp_f32_e32 v137, v126
	v_mad_i64_i32 v[126:127], s[14:15], v136, s33, v[120:121]
	v_lshl_add_u64 v[126:127], v[126:127], 0, v[122:123]
	global_store_short_d16_hi v[126:127], v125, off
	v_add_f32_e32 v125, 1.0, v137
	v_rcp_f32_e32 v127, v125
	v_or_b32_e32 v136, 3, v124
	v_mov_b32_e32 v137, v136
	v_mul_f32_e32 v125, v221, v127
	v_mul_f32_e32 v125, v225, v125
	v_bfe_u32 v126, v125, 16, 1
	v_add3_u32 v125, v125, v126, s34
	v_mul_f32_e32 v126, 0xbfb8aa3b, v112
	v_exp_f32_e32 v146, v126
	v_mad_i64_i32 v[126:127], s[14:15], v137, s33, v[120:121]
	v_lshl_add_u64 v[126:127], v[126:127], 0, v[122:123]
	v_add_f32_e32 v137, 1.0, v146
	v_rcp_f32_e32 v147, v137
	global_store_short_d16_hi v[126:127], v125, off
	v_mov_b32_e32 v125, v124
	v_mul_f32_e32 v112, v112, v147
	v_mul_f32_e32 v126, 0xbfb8aa3b, v113
	v_exp_f32_e32 v137, v126
	v_mul_f32_e32 v112, v116, v112
	v_bfe_u32 v116, v112, 16, 1
	v_add3_u32 v112, v112, v116, s34
	v_add_f32_e32 v116, 1.0, v137
	v_mad_i64_i32 v[126:127], s[14:15], v125, s33, v[120:121]
	v_rcp_f32_e32 v137, v116
	v_lshl_add_u64 v[126:127], v[126:127], 0, v[122:123]
	global_store_short_d16_hi v[126:127], v112, off offset:32
	v_mul_f32_e32 v112, v113, v137
	v_mul_f32_e32 v116, 0xbfb8aa3b, v114
	v_exp_f32_e32 v116, v116
	v_mul_f32_e32 v112, v117, v112
	v_bfe_u32 v113, v112, 16, 1
	v_add3_u32 v117, v112, v113, s34
	v_add_f32_e32 v116, 1.0, v116
	v_rcp_f32_e32 v126, v116
	v_mad_i64_i32 v[112:113], s[14:15], v134, s33, v[120:121]
	v_lshl_add_u64 v[112:113], v[112:113], 0, v[122:123]
	global_store_short_d16_hi v[112:113], v117, off offset:32
	v_mul_f32_e32 v112, v114, v126
	v_mul_f32_e32 v114, 0xbfb8aa3b, v115
	v_exp_f32_e32 v114, v114
	v_mul_f32_e32 v112, v118, v112
	v_bfe_u32 v113, v112, 16, 1
	v_add_f32_e32 v114, 1.0, v114
	v_rcp_f32_e32 v118, v114
	v_add3_u32 v116, v112, v113, s34
	v_mad_i64_i32 v[112:113], s[14:15], v135, s33, v[120:121]
	v_lshl_add_u64 v[112:113], v[112:113], 0, v[122:123]
	global_store_short_d16_hi v[112:113], v116, off offset:32
	v_mul_f32_e32 v112, v115, v118
	v_mul_f32_e32 v112, v119, v112
	v_bfe_u32 v113, v112, 16, 1
	v_add3_u32 v114, v112, v113, s34
	v_mul_f32_e32 v112, 0xbfb8aa3b, v104
	v_exp_f32_e32 v115, v112
	v_readlane_b32 s38, v241, 19
	v_mad_i64_i32 v[112:113], s[14:15], v136, s33, v[120:121]
	v_lshl_add_u64 v[112:113], v[112:113], 0, v[122:123]
	global_store_short_d16_hi v[112:113], v114, off offset:32
	v_add_f32_e32 v112, 1.0, v115
	v_rcp_f32_e32 v114, v112
	v_or_b32_e32 v115, 16, v124
	v_mov_b32_e32 v116, v115
	v_mul_f32_e32 v104, v104, v114
	v_mul_f32_e32 v104, v108, v104
	v_bfe_u32 v108, v104, 16, 1
	v_add3_u32 v104, v104, v108, s34
	v_mul_f32_e32 v108, 0xbfb8aa3b, v105
	v_exp_f32_e32 v108, v108
	v_mad_i64_i32 v[112:113], s[14:15], v116, s33, v[120:121]
	v_lshl_add_u64 v[112:113], v[112:113], 0, v[122:123]
	global_store_short_d16_hi v[112:113], v104, off
	v_add_f32_e32 v104, 1.0, v108
	v_rcp_f32_e32 v112, v104
	v_or_b32_e32 v113, 17, v124
	v_mov_b32_e32 v114, v113
	v_mul_f32_e32 v104, v105, v112
	v_mul_f32_e32 v104, v109, v104
	v_bfe_u32 v105, v104, 16, 1
	v_add3_u32 v108, v104, v105, s34
	v_mul_f32_e32 v104, 0xbfb8aa3b, v106
	v_exp_f32_e32 v109, v104
	v_mad_i64_i32 v[104:105], s[14:15], v114, s33, v[120:121]
	v_lshl_add_u64 v[104:105], v[104:105], 0, v[122:123]
	global_store_short_d16_hi v[104:105], v108, off
	v_add_f32_e32 v104, 1.0, v109
	v_rcp_f32_e32 v108, v104
	v_or_b32_e32 v109, 18, v124
	v_mov_b32_e32 v112, v109
	v_mul_f32_e32 v104, v106, v108
	v_mul_f32_e32 v104, v110, v104
	v_bfe_u32 v105, v104, 16, 1
	v_add3_u32 v106, v104, v105, s34
	v_mul_f32_e32 v104, 0xbfb8aa3b, v107
	v_exp_f32_e32 v108, v104
	v_mad_i64_i32 v[104:105], s[14:15], v112, s33, v[120:121]
	v_lshl_add_u64 v[104:105], v[104:105], 0, v[122:123]
	global_store_short_d16_hi v[104:105], v106, off
	v_add_f32_e32 v104, 1.0, v108
	v_rcp_f32_e32 v106, v104
	v_or_b32_e32 v108, 19, v124
	v_mov_b32_e32 v110, v108
	v_mul_f32_e32 v104, v107, v106
	v_mul_f32_e32 v106, 0xbfb8aa3b, v96
	v_exp_f32_e32 v106, v106
	v_mul_f32_e32 v104, v111, v104
	v_bfe_u32 v105, v104, 16, 1
	v_add_f32_e32 v106, 1.0, v106
	v_add3_u32 v107, v104, v105, s34
	v_mad_i64_i32 v[104:105], s[14:15], v110, s33, v[120:121]
	v_rcp_f32_e32 v111, v106
	v_lshl_add_u64 v[104:105], v[104:105], 0, v[122:123]
	global_store_short_d16_hi v[104:105], v107, off
	v_mul_f32_e32 v96, v96, v111
	v_mul_f32_e32 v104, 0xbfb8aa3b, v97
	v_exp_f32_e32 v106, v104
	v_mul_f32_e32 v96, v100, v96
	v_bfe_u32 v100, v96, 16, 1
	v_add3_u32 v96, v96, v100, s34
	v_add_f32_e32 v100, 1.0, v106
	v_rcp_f32_e32 v107, v100
	v_mad_i64_i32 v[104:105], s[14:15], v115, s33, v[120:121]
	v_lshl_add_u64 v[104:105], v[104:105], 0, v[122:123]
	global_store_short_d16_hi v[104:105], v96, off offset:32
	v_mul_f32_e32 v96, v97, v107
	v_mul_f32_e32 v100, 0xbfb8aa3b, v98
	v_exp_f32_e32 v100, v100
	v_mul_f32_e32 v96, v101, v96
	v_bfe_u32 v97, v96, 16, 1
	v_add_f32_e32 v100, 1.0, v100
	v_rcp_f32_e32 v105, v100
	v_add3_u32 v101, v96, v97, s34
	v_mad_i64_i32 v[96:97], s[14:15], v113, s33, v[120:121]
	v_lshl_add_u64 v[96:97], v[96:97], 0, v[122:123]
	global_store_short_d16_hi v[96:97], v101, off offset:32
	v_mul_f32_e32 v96, v98, v105
	v_mul_f32_e32 v98, 0xbfb8aa3b, v99
	v_exp_f32_e32 v98, v98
	v_mul_f32_e32 v96, v102, v96
	v_bfe_u32 v97, v96, 16, 1
	v_add_f32_e32 v98, 1.0, v98
	v_rcp_f32_e32 v102, v98
	v_add3_u32 v100, v96, v97, s34
	v_mad_i64_i32 v[96:97], s[14:15], v109, s33, v[120:121]
	v_lshl_add_u64 v[96:97], v[96:97], 0, v[122:123]
	global_store_short_d16_hi v[96:97], v100, off offset:32
	v_mul_f32_e32 v96, v99, v102
	v_mul_f32_e32 v96, v103, v96
	v_bfe_u32 v97, v96, 16, 1
	v_add3_u32 v98, v96, v97, s34
	v_mul_f32_e32 v96, 0xbfb8aa3b, v88
	v_exp_f32_e32 v99, v96
	v_readlane_b32 s39, v241, 20
	v_mad_i64_i32 v[96:97], s[14:15], v108, s33, v[120:121]
	v_lshl_add_u64 v[96:97], v[96:97], 0, v[122:123]
	global_store_short_d16_hi v[96:97], v98, off offset:32
	v_add_f32_e32 v96, 1.0, v99
	v_rcp_f32_e32 v98, v96
	v_or_b32_e32 v99, 32, v124
	v_mov_b32_e32 v100, v99
	v_mul_f32_e32 v88, v88, v98
	v_mul_f32_e32 v88, v92, v88
	v_bfe_u32 v92, v88, 16, 1
	v_add3_u32 v88, v88, v92, s34
	v_mul_f32_e32 v92, 0xbfb8aa3b, v89
	v_exp_f32_e32 v92, v92
	v_mad_i64_i32 v[96:97], s[14:15], v100, s33, v[120:121]
	v_lshl_add_u64 v[96:97], v[96:97], 0, v[122:123]
	global_store_short_d16_hi v[96:97], v88, off
	v_add_f32_e32 v88, 1.0, v92
	v_rcp_f32_e32 v96, v88
	v_or_b32_e32 v97, 33, v124
	v_mov_b32_e32 v98, v97
	v_mul_f32_e32 v88, v89, v96
	v_mul_f32_e32 v88, v93, v88
	v_bfe_u32 v89, v88, 16, 1
	v_add3_u32 v92, v88, v89, s34
	v_mul_f32_e32 v88, 0xbfb8aa3b, v90
	v_exp_f32_e32 v93, v88
	v_mad_i64_i32 v[88:89], s[14:15], v98, s33, v[120:121]
	v_lshl_add_u64 v[88:89], v[88:89], 0, v[122:123]
	global_store_short_d16_hi v[88:89], v92, off
	v_add_f32_e32 v88, 1.0, v93
	v_rcp_f32_e32 v92, v88
	v_or_b32_e32 v93, 34, v124
	v_mov_b32_e32 v96, v93
	v_mul_f32_e32 v88, v90, v92
	v_mul_f32_e32 v88, v94, v88
	v_bfe_u32 v89, v88, 16, 1
	v_add3_u32 v90, v88, v89, s34
	v_mul_f32_e32 v88, 0xbfb8aa3b, v91
	v_exp_f32_e32 v92, v88
	v_mad_i64_i32 v[88:89], s[14:15], v96, s33, v[120:121]
	v_lshl_add_u64 v[88:89], v[88:89], 0, v[122:123]
	global_store_short_d16_hi v[88:89], v90, off
	v_add_f32_e32 v88, 1.0, v92
	v_rcp_f32_e32 v90, v88
	v_or_b32_e32 v92, 35, v124
	v_mov_b32_e32 v94, v92
	v_mul_f32_e32 v88, v91, v90
	v_mul_f32_e32 v90, 0xbfb8aa3b, v80
	v_exp_f32_e32 v90, v90
	v_mul_f32_e32 v88, v95, v88
	v_bfe_u32 v89, v88, 16, 1
	v_add_f32_e32 v90, 1.0, v90
	v_add3_u32 v91, v88, v89, s34
	v_mad_i64_i32 v[88:89], s[14:15], v94, s33, v[120:121]
	v_rcp_f32_e32 v95, v90
	v_lshl_add_u64 v[88:89], v[88:89], 0, v[122:123]
	global_store_short_d16_hi v[88:89], v91, off
	v_mul_f32_e32 v80, v80, v95
	v_mul_f32_e32 v88, 0xbfb8aa3b, v81
	v_exp_f32_e32 v90, v88
	v_mul_f32_e32 v80, v84, v80
	v_bfe_u32 v84, v80, 16, 1
	v_add3_u32 v80, v80, v84, s34
	v_add_f32_e32 v84, 1.0, v90
	v_rcp_f32_e32 v91, v84
	v_mad_i64_i32 v[88:89], s[14:15], v99, s33, v[120:121]
	v_lshl_add_u64 v[88:89], v[88:89], 0, v[122:123]
	global_store_short_d16_hi v[88:89], v80, off offset:32
	v_mul_f32_e32 v80, v81, v91
	v_mul_f32_e32 v84, 0xbfb8aa3b, v82
	v_exp_f32_e32 v84, v84
	v_mul_f32_e32 v80, v85, v80
	v_bfe_u32 v81, v80, 16, 1
	v_add_f32_e32 v84, 1.0, v84
	v_rcp_f32_e32 v89, v84
	v_add3_u32 v85, v80, v81, s34
	v_mad_i64_i32 v[80:81], s[14:15], v97, s33, v[120:121]
	v_lshl_add_u64 v[80:81], v[80:81], 0, v[122:123]
	global_store_short_d16_hi v[80:81], v85, off offset:32
	v_mul_f32_e32 v80, v82, v89
	v_mul_f32_e32 v82, 0xbfb8aa3b, v83
	v_exp_f32_e32 v82, v82
	v_mul_f32_e32 v80, v86, v80
	v_bfe_u32 v81, v80, 16, 1
	v_add_f32_e32 v82, 1.0, v82
	v_rcp_f32_e32 v86, v82
	v_add3_u32 v84, v80, v81, s34
	v_mad_i64_i32 v[80:81], s[14:15], v93, s33, v[120:121]
	v_lshl_add_u64 v[80:81], v[80:81], 0, v[122:123]
	global_store_short_d16_hi v[80:81], v84, off offset:32
	v_mul_f32_e32 v80, v83, v86
	v_mul_f32_e32 v80, v87, v80
	v_bfe_u32 v81, v80, 16, 1
	v_add3_u32 v82, v80, v81, s34
	v_mul_f32_e32 v80, 0xbfb8aa3b, v72
	v_exp_f32_e32 v83, v80
	v_readlane_b32 s40, v241, 21
	v_mad_i64_i32 v[80:81], s[14:15], v92, s33, v[120:121]
	v_lshl_add_u64 v[80:81], v[80:81], 0, v[122:123]
	global_store_short_d16_hi v[80:81], v82, off offset:32
	v_add_f32_e32 v80, 1.0, v83
	v_rcp_f32_e32 v82, v80
	v_or_b32_e32 v83, 48, v124
	v_mov_b32_e32 v84, v83
	v_mul_f32_e32 v72, v72, v82
	v_mul_f32_e32 v72, v76, v72
	v_bfe_u32 v76, v72, 16, 1
	v_add3_u32 v72, v72, v76, s34
	v_mul_f32_e32 v76, 0xbfb8aa3b, v73
	v_exp_f32_e32 v76, v76
	v_mad_i64_i32 v[80:81], s[14:15], v84, s33, v[120:121]
	v_lshl_add_u64 v[80:81], v[80:81], 0, v[122:123]
	global_store_short_d16_hi v[80:81], v72, off
	v_add_f32_e32 v72, 1.0, v76
	v_rcp_f32_e32 v80, v72
	v_or_b32_e32 v81, 49, v124
	v_mov_b32_e32 v82, v81
	v_mul_f32_e32 v72, v73, v80
	v_mul_f32_e32 v72, v77, v72
	v_bfe_u32 v73, v72, 16, 1
	v_add3_u32 v76, v72, v73, s34
	v_mul_f32_e32 v72, 0xbfb8aa3b, v74
	v_exp_f32_e32 v77, v72
	v_mad_i64_i32 v[72:73], s[14:15], v82, s33, v[120:121]
	v_lshl_add_u64 v[72:73], v[72:73], 0, v[122:123]
	global_store_short_d16_hi v[72:73], v76, off
	v_add_f32_e32 v72, 1.0, v77
	v_rcp_f32_e32 v76, v72
	v_or_b32_e32 v77, 50, v124
	v_mov_b32_e32 v80, v77
	v_mul_f32_e32 v72, v74, v76
	v_mul_f32_e32 v72, v78, v72
	v_bfe_u32 v73, v72, 16, 1
	v_add3_u32 v74, v72, v73, s34
	v_mul_f32_e32 v72, 0xbfb8aa3b, v75
	v_exp_f32_e32 v76, v72
	v_mad_i64_i32 v[72:73], s[14:15], v80, s33, v[120:121]
	v_lshl_add_u64 v[72:73], v[72:73], 0, v[122:123]
	global_store_short_d16_hi v[72:73], v74, off
	v_add_f32_e32 v72, 1.0, v76
	v_rcp_f32_e32 v74, v72
	v_or_b32_e32 v76, 51, v124
	v_mov_b32_e32 v78, v76
	v_mul_f32_e32 v72, v75, v74
	v_mul_f32_e32 v74, 0xbfb8aa3b, v64
	v_exp_f32_e32 v74, v74
	v_mul_f32_e32 v72, v79, v72
	v_bfe_u32 v73, v72, 16, 1
	v_add_f32_e32 v74, 1.0, v74
	v_add3_u32 v75, v72, v73, s34
	v_mad_i64_i32 v[72:73], s[14:15], v78, s33, v[120:121]
	v_rcp_f32_e32 v79, v74
	v_lshl_add_u64 v[72:73], v[72:73], 0, v[122:123]
	global_store_short_d16_hi v[72:73], v75, off
	v_mul_f32_e32 v64, v64, v79
	v_mul_f32_e32 v72, 0xbfb8aa3b, v65
	v_exp_f32_e32 v74, v72
	v_mul_f32_e32 v64, v68, v64
	v_bfe_u32 v68, v64, 16, 1
	v_add3_u32 v64, v64, v68, s34
	v_add_f32_e32 v68, 1.0, v74
	v_rcp_f32_e32 v75, v68
	v_mad_i64_i32 v[72:73], s[14:15], v83, s33, v[120:121]
	v_lshl_add_u64 v[72:73], v[72:73], 0, v[122:123]
	global_store_short_d16_hi v[72:73], v64, off offset:32
	v_mul_f32_e32 v64, v65, v75
	v_mul_f32_e32 v68, 0xbfb8aa3b, v66
	v_exp_f32_e32 v68, v68
	v_mul_f32_e32 v64, v69, v64
	v_bfe_u32 v65, v64, 16, 1
	v_add_f32_e32 v68, 1.0, v68
	v_rcp_f32_e32 v73, v68
	v_add3_u32 v69, v64, v65, s34
	v_mad_i64_i32 v[64:65], s[14:15], v81, s33, v[120:121]
	v_lshl_add_u64 v[64:65], v[64:65], 0, v[122:123]
	global_store_short_d16_hi v[64:65], v69, off offset:32
	v_mul_f32_e32 v64, v66, v73
	v_mul_f32_e32 v66, 0xbfb8aa3b, v67
	v_exp_f32_e32 v66, v66
	v_mul_f32_e32 v64, v70, v64
	v_bfe_u32 v65, v64, 16, 1
	v_add_f32_e32 v66, 1.0, v66
	v_rcp_f32_e32 v70, v66
	v_add3_u32 v68, v64, v65, s34
	v_mad_i64_i32 v[64:65], s[14:15], v77, s33, v[120:121]
	v_lshl_add_u64 v[64:65], v[64:65], 0, v[122:123]
	global_store_short_d16_hi v[64:65], v68, off offset:32
	v_mul_f32_e32 v64, v67, v70
	v_mul_f32_e32 v64, v71, v64
	v_bfe_u32 v65, v64, 16, 1
	v_add3_u32 v66, v64, v65, s34
	v_mad_i64_i32 v[64:65], s[14:15], v76, s33, v[120:121]
	v_lshl_add_u64 v[64:65], v[64:65], 0, v[122:123]
	global_store_short_d16_hi v[64:65], v66, off offset:32
	v_readlane_b32 s41, v241, 22
	v_readlane_b32 s42, v241, 23
	v_readlane_b32 s43, v241, 24
	v_mul_f32_e32 v64, 0xbfb8aa3b, v56
	v_exp_f32_e32 v64, v64
	v_or_b32_e32 v66, 64, v124
	v_mov_b32_e32 v65, v66
	v_add_f32_e32 v64, 1.0, v64
	v_rcp_f32_e32 v68, v64
	s_add_i32 s2, s2, s3
	v_mul_f32_e32 v56, v56, v68
	v_mul_f32_e32 v56, v60, v56
	v_bfe_u32 v60, v56, 16, 1
	v_add3_u32 v56, v56, v60, s34
	v_mul_f32_e32 v60, 0xbfb8aa3b, v57
	v_exp_f32_e32 v60, v60
	v_mad_i64_i32 v[64:65], s[14:15], v65, s33, v[120:121]
	v_lshl_add_u64 v[64:65], v[64:65], 0, v[122:123]
	global_store_short_d16_hi v[64:65], v56, off
	v_add_f32_e32 v56, 1.0, v60
	v_rcp_f32_e32 v64, v56
	v_or_b32_e32 v65, 0x41, v124
	v_mov_b32_e32 v67, v65
	v_mul_f32_e32 v56, v57, v64
	v_mul_f32_e32 v56, v61, v56
	v_bfe_u32 v57, v56, 16, 1
	v_add3_u32 v60, v56, v57, s34
	v_mul_f32_e32 v56, 0xbfb8aa3b, v58
	v_exp_f32_e32 v61, v56
	v_mad_i64_i32 v[56:57], s[14:15], v67, s33, v[120:121]
	v_lshl_add_u64 v[56:57], v[56:57], 0, v[122:123]
	global_store_short_d16_hi v[56:57], v60, off
	v_add_f32_e32 v56, 1.0, v61
	v_rcp_f32_e32 v60, v56
	v_or_b32_e32 v61, 0x42, v124
	v_mov_b32_e32 v64, v61
	v_mul_f32_e32 v56, v58, v60
	v_mul_f32_e32 v56, v62, v56
	v_bfe_u32 v57, v56, 16, 1
	v_add3_u32 v58, v56, v57, s34
	v_mul_f32_e32 v56, 0xbfb8aa3b, v59
	v_exp_f32_e32 v60, v56
	v_mad_i64_i32 v[56:57], s[14:15], v64, s33, v[120:121]
	v_lshl_add_u64 v[56:57], v[56:57], 0, v[122:123]
	global_store_short_d16_hi v[56:57], v58, off
	v_add_f32_e32 v56, 1.0, v60
	v_rcp_f32_e32 v58, v56
	v_or_b32_e32 v60, 0x43, v124
	v_mov_b32_e32 v62, v60
	v_mul_f32_e32 v56, v59, v58
	v_mul_f32_e32 v58, 0xbfb8aa3b, v48
	v_exp_f32_e32 v58, v58
	v_mul_f32_e32 v56, v63, v56
	v_bfe_u32 v57, v56, 16, 1
	v_add_f32_e32 v58, 1.0, v58
	v_add3_u32 v59, v56, v57, s34
	v_mad_i64_i32 v[56:57], s[14:15], v62, s33, v[120:121]
	v_rcp_f32_e32 v63, v58
	v_lshl_add_u64 v[56:57], v[56:57], 0, v[122:123]
	global_store_short_d16_hi v[56:57], v59, off
	v_mul_f32_e32 v48, v48, v63
	v_mul_f32_e32 v56, 0xbfb8aa3b, v49
	v_exp_f32_e32 v58, v56
	v_mul_f32_e32 v48, v52, v48
	v_bfe_u32 v52, v48, 16, 1
	v_add3_u32 v48, v48, v52, s34
	v_add_f32_e32 v52, 1.0, v58
	v_rcp_f32_e32 v59, v52
	v_mad_i64_i32 v[56:57], s[14:15], v66, s33, v[120:121]
	v_lshl_add_u64 v[56:57], v[56:57], 0, v[122:123]
	global_store_short_d16_hi v[56:57], v48, off offset:32
	v_mul_f32_e32 v48, v49, v59
	v_mul_f32_e32 v52, 0xbfb8aa3b, v50
	v_exp_f32_e32 v52, v52
	v_mul_f32_e32 v48, v53, v48
	v_bfe_u32 v49, v48, 16, 1
	v_add_f32_e32 v52, 1.0, v52
	v_rcp_f32_e32 v57, v52
	v_add3_u32 v53, v48, v49, s34
	v_mad_i64_i32 v[48:49], s[14:15], v65, s33, v[120:121]
	v_lshl_add_u64 v[48:49], v[48:49], 0, v[122:123]
	global_store_short_d16_hi v[48:49], v53, off offset:32
	v_mul_f32_e32 v48, v50, v57
	v_mul_f32_e32 v50, 0xbfb8aa3b, v51
	v_exp_f32_e32 v50, v50
	v_mul_f32_e32 v48, v54, v48
	v_bfe_u32 v49, v48, 16, 1
	v_add_f32_e32 v50, 1.0, v50
	v_rcp_f32_e32 v54, v50
	v_add3_u32 v52, v48, v49, s34
	v_mad_i64_i32 v[48:49], s[14:15], v61, s33, v[120:121]
	v_lshl_add_u64 v[48:49], v[48:49], 0, v[122:123]
	global_store_short_d16_hi v[48:49], v52, off offset:32
	v_mul_f32_e32 v48, v51, v54
	v_mul_f32_e32 v48, v55, v48
	v_bfe_u32 v49, v48, 16, 1
	v_add3_u32 v50, v48, v49, s34
	v_mul_f32_e32 v48, 0xbfb8aa3b, v40
	v_exp_f32_e32 v51, v48
	s_add_i32 s19, s19, s20
	v_mad_i64_i32 v[48:49], s[14:15], v60, s33, v[120:121]
	v_lshl_add_u64 v[48:49], v[48:49], 0, v[122:123]
	global_store_short_d16_hi v[48:49], v50, off offset:32
	v_add_f32_e32 v48, 1.0, v51
	v_rcp_f32_e32 v50, v48
	v_or_b32_e32 v51, 0x50, v124
	v_mov_b32_e32 v52, v51
	v_mul_f32_e32 v40, v40, v50
	v_mul_f32_e32 v40, v44, v40
	v_bfe_u32 v44, v40, 16, 1
	v_add3_u32 v40, v40, v44, s34
	v_mul_f32_e32 v44, 0xbfb8aa3b, v41
	v_exp_f32_e32 v44, v44
	v_mad_i64_i32 v[48:49], s[14:15], v52, s33, v[120:121]
	v_lshl_add_u64 v[48:49], v[48:49], 0, v[122:123]
	global_store_short_d16_hi v[48:49], v40, off
	v_add_f32_e32 v40, 1.0, v44
	v_rcp_f32_e32 v48, v40
	v_or_b32_e32 v49, 0x51, v124
	v_mov_b32_e32 v50, v49
	v_mul_f32_e32 v40, v41, v48
	v_mul_f32_e32 v40, v45, v40
	v_bfe_u32 v41, v40, 16, 1
	v_add3_u32 v44, v40, v41, s34
	v_mul_f32_e32 v40, 0xbfb8aa3b, v42
	v_exp_f32_e32 v45, v40
	v_mad_i64_i32 v[40:41], s[14:15], v50, s33, v[120:121]
	v_lshl_add_u64 v[40:41], v[40:41], 0, v[122:123]
	global_store_short_d16_hi v[40:41], v44, off
	v_add_f32_e32 v40, 1.0, v45
	v_rcp_f32_e32 v44, v40
	v_or_b32_e32 v45, 0x52, v124
	v_mov_b32_e32 v48, v45
	v_mul_f32_e32 v40, v42, v44
	v_mul_f32_e32 v40, v46, v40
	v_bfe_u32 v41, v40, 16, 1
	v_add3_u32 v42, v40, v41, s34
	v_mul_f32_e32 v40, 0xbfb8aa3b, v43
	v_exp_f32_e32 v44, v40
	v_mad_i64_i32 v[40:41], s[14:15], v48, s33, v[120:121]
	v_lshl_add_u64 v[40:41], v[40:41], 0, v[122:123]
	global_store_short_d16_hi v[40:41], v42, off
	v_add_f32_e32 v40, 1.0, v44
	v_rcp_f32_e32 v42, v40
	v_or_b32_e32 v44, 0x53, v124
	v_mov_b32_e32 v46, v44
	v_mul_f32_e32 v40, v43, v42
	v_mul_f32_e32 v42, 0xbfb8aa3b, v32
	v_exp_f32_e32 v42, v42
	v_mul_f32_e32 v40, v47, v40
	v_bfe_u32 v41, v40, 16, 1
	v_add_f32_e32 v42, 1.0, v42
	v_add3_u32 v43, v40, v41, s34
	v_mad_i64_i32 v[40:41], s[14:15], v46, s33, v[120:121]
	v_rcp_f32_e32 v47, v42
	v_lshl_add_u64 v[40:41], v[40:41], 0, v[122:123]
	global_store_short_d16_hi v[40:41], v43, off
	v_mul_f32_e32 v32, v32, v47
	v_mul_f32_e32 v40, 0xbfb8aa3b, v33
	v_exp_f32_e32 v42, v40
	v_mul_f32_e32 v32, v36, v32
	v_bfe_u32 v36, v32, 16, 1
	v_add3_u32 v32, v32, v36, s34
	v_add_f32_e32 v36, 1.0, v42
	v_rcp_f32_e32 v43, v36
	v_mad_i64_i32 v[40:41], s[14:15], v51, s33, v[120:121]
	v_lshl_add_u64 v[40:41], v[40:41], 0, v[122:123]
	global_store_short_d16_hi v[40:41], v32, off offset:32
	v_mul_f32_e32 v32, v33, v43
	v_mul_f32_e32 v36, 0xbfb8aa3b, v34
	v_exp_f32_e32 v36, v36
	v_mul_f32_e32 v32, v37, v32
	v_bfe_u32 v33, v32, 16, 1
	v_add_f32_e32 v36, 1.0, v36
	v_rcp_f32_e32 v41, v36
	v_add3_u32 v37, v32, v33, s34
	v_mad_i64_i32 v[32:33], s[14:15], v49, s33, v[120:121]
	v_lshl_add_u64 v[32:33], v[32:33], 0, v[122:123]
	global_store_short_d16_hi v[32:33], v37, off offset:32
	v_mul_f32_e32 v32, v34, v41
	v_mul_f32_e32 v34, 0xbfb8aa3b, v35
	v_exp_f32_e32 v34, v34
	v_mul_f32_e32 v32, v38, v32
	v_bfe_u32 v33, v32, 16, 1
	v_add_f32_e32 v34, 1.0, v34
	v_rcp_f32_e32 v38, v34
	v_add3_u32 v36, v32, v33, s34
	v_mad_i64_i32 v[32:33], s[14:15], v45, s33, v[120:121]
	v_lshl_add_u64 v[32:33], v[32:33], 0, v[122:123]
	global_store_short_d16_hi v[32:33], v36, off offset:32
	v_mul_f32_e32 v32, v35, v38
	v_mul_f32_e32 v32, v39, v32
	v_bfe_u32 v33, v32, 16, 1
	v_add3_u32 v34, v32, v33, s34
	v_mul_f32_e32 v32, 0xbfb8aa3b, v24
	v_exp_f32_e32 v35, v32
	s_xor_b64 s[0:1], s[0:1], s[4:5]
	v_mad_i64_i32 v[32:33], s[14:15], v44, s33, v[120:121]
	v_lshl_add_u64 v[32:33], v[32:33], 0, v[122:123]
	global_store_short_d16_hi v[32:33], v34, off offset:32
	v_add_f32_e32 v32, 1.0, v35
	v_rcp_f32_e32 v34, v32
	v_or_b32_e32 v35, 0x60, v124
	v_mov_b32_e32 v36, v35
	v_mul_f32_e32 v24, v24, v34
	v_mul_f32_e32 v24, v28, v24
	v_bfe_u32 v28, v24, 16, 1
	v_add3_u32 v24, v24, v28, s34
	v_mul_f32_e32 v28, 0xbfb8aa3b, v25
	v_exp_f32_e32 v28, v28
	v_mad_i64_i32 v[32:33], s[14:15], v36, s33, v[120:121]
	v_lshl_add_u64 v[32:33], v[32:33], 0, v[122:123]
	global_store_short_d16_hi v[32:33], v24, off
	v_add_f32_e32 v24, 1.0, v28
	v_rcp_f32_e32 v32, v24
	v_or_b32_e32 v33, 0x61, v124
	v_mov_b32_e32 v34, v33
	v_mul_f32_e32 v24, v25, v32
	v_mul_f32_e32 v24, v29, v24
	v_bfe_u32 v25, v24, 16, 1
	v_add3_u32 v28, v24, v25, s34
	v_mul_f32_e32 v24, 0xbfb8aa3b, v26
	v_exp_f32_e32 v29, v24
	v_mad_i64_i32 v[24:25], s[14:15], v34, s33, v[120:121]
	v_lshl_add_u64 v[24:25], v[24:25], 0, v[122:123]
	global_store_short_d16_hi v[24:25], v28, off
	v_add_f32_e32 v24, 1.0, v29
	v_rcp_f32_e32 v28, v24
	v_or_b32_e32 v29, 0x62, v124
	v_mov_b32_e32 v32, v29
	v_mul_f32_e32 v24, v26, v28
	v_mul_f32_e32 v24, v30, v24
	v_bfe_u32 v25, v24, 16, 1
	v_add3_u32 v26, v24, v25, s34
	v_mul_f32_e32 v24, 0xbfb8aa3b, v27
	v_exp_f32_e32 v28, v24
	v_mad_i64_i32 v[24:25], s[14:15], v32, s33, v[120:121]
	v_lshl_add_u64 v[24:25], v[24:25], 0, v[122:123]
	global_store_short_d16_hi v[24:25], v26, off
	v_add_f32_e32 v24, 1.0, v28
	v_rcp_f32_e32 v26, v24
	v_or_b32_e32 v28, 0x63, v124
	v_mov_b32_e32 v30, v28
	v_mul_f32_e32 v24, v27, v26
	v_mul_f32_e32 v26, 0xbfb8aa3b, v16
	v_exp_f32_e32 v26, v26
	v_mul_f32_e32 v24, v31, v24
	v_bfe_u32 v25, v24, 16, 1
	v_add_f32_e32 v26, 1.0, v26
	v_add3_u32 v27, v24, v25, s34
	v_mad_i64_i32 v[24:25], s[14:15], v30, s33, v[120:121]
	v_rcp_f32_e32 v31, v26
	v_lshl_add_u64 v[24:25], v[24:25], 0, v[122:123]
	global_store_short_d16_hi v[24:25], v27, off
	v_mul_f32_e32 v16, v16, v31
	v_mul_f32_e32 v24, 0xbfb8aa3b, v17
	v_exp_f32_e32 v26, v24
	v_mul_f32_e32 v16, v20, v16
	v_bfe_u32 v20, v16, 16, 1
	v_add3_u32 v16, v16, v20, s34
	v_add_f32_e32 v20, 1.0, v26
	v_rcp_f32_e32 v27, v20
	v_mad_i64_i32 v[24:25], s[14:15], v35, s33, v[120:121]
	v_lshl_add_u64 v[24:25], v[24:25], 0, v[122:123]
	global_store_short_d16_hi v[24:25], v16, off offset:32
	v_mul_f32_e32 v16, v17, v27
	v_mul_f32_e32 v20, 0xbfb8aa3b, v18
	v_exp_f32_e32 v20, v20
	v_mul_f32_e32 v16, v21, v16
	v_bfe_u32 v17, v16, 16, 1
	v_add_f32_e32 v20, 1.0, v20
	v_rcp_f32_e32 v25, v20
	v_add3_u32 v21, v16, v17, s34
	v_mad_i64_i32 v[16:17], s[14:15], v33, s33, v[120:121]
	v_lshl_add_u64 v[16:17], v[16:17], 0, v[122:123]
	global_store_short_d16_hi v[16:17], v21, off offset:32
	v_mul_f32_e32 v16, v18, v25
	v_mul_f32_e32 v18, 0xbfb8aa3b, v19
	v_exp_f32_e32 v18, v18
	v_mul_f32_e32 v16, v22, v16
	v_bfe_u32 v17, v16, 16, 1
	v_add_f32_e32 v18, 1.0, v18
	v_rcp_f32_e32 v22, v18
	v_add3_u32 v20, v16, v17, s34
	v_mad_i64_i32 v[16:17], s[14:15], v29, s33, v[120:121]
	v_lshl_add_u64 v[16:17], v[16:17], 0, v[122:123]
	global_store_short_d16_hi v[16:17], v20, off offset:32
	v_mul_f32_e32 v16, v19, v22
	v_mul_f32_e32 v16, v23, v16
	v_bfe_u32 v17, v16, 16, 1
	v_add3_u32 v18, v16, v17, s34
	v_mul_f32_e32 v16, 0xbfb8aa3b, v8
	v_exp_f32_e32 v19, v16
	s_cmpk_gt_i32 s2, 0x1b7
	v_mad_i64_i32 v[16:17], s[14:15], v28, s33, v[120:121]
	v_lshl_add_u64 v[16:17], v[16:17], 0, v[122:123]
	global_store_short_d16_hi v[16:17], v18, off offset:32
	v_add_f32_e32 v16, 1.0, v19
	v_rcp_f32_e32 v18, v16
	v_or_b32_e32 v19, 0x70, v124
	v_mov_b32_e32 v20, v19
	v_mul_f32_e32 v8, v8, v18
	v_mul_f32_e32 v8, v12, v8
	v_bfe_u32 v12, v8, 16, 1
	v_add3_u32 v8, v8, v12, s34
	v_mul_f32_e32 v12, 0xbfb8aa3b, v9
	v_exp_f32_e32 v12, v12
	v_mad_i64_i32 v[16:17], s[14:15], v20, s33, v[120:121]
	v_lshl_add_u64 v[16:17], v[16:17], 0, v[122:123]
	global_store_short_d16_hi v[16:17], v8, off
	v_add_f32_e32 v8, 1.0, v12
	v_rcp_f32_e32 v16, v8
	v_or_b32_e32 v17, 0x71, v124
	v_mov_b32_e32 v18, v17
	v_mul_f32_e32 v8, v9, v16
	v_mul_f32_e32 v8, v13, v8
	v_bfe_u32 v9, v8, 16, 1
	v_add3_u32 v12, v8, v9, s34
	v_mul_f32_e32 v8, 0xbfb8aa3b, v10
	v_exp_f32_e32 v13, v8
	v_mad_i64_i32 v[8:9], s[14:15], v18, s33, v[120:121]
	v_lshl_add_u64 v[8:9], v[8:9], 0, v[122:123]
	global_store_short_d16_hi v[8:9], v12, off
	v_add_f32_e32 v8, 1.0, v13
	v_rcp_f32_e32 v12, v8
	v_or_b32_e32 v13, 0x72, v124
	v_mov_b32_e32 v16, v13
	v_mul_f32_e32 v8, v10, v12
	v_mul_f32_e32 v8, v14, v8
	v_bfe_u32 v9, v8, 16, 1
	v_add3_u32 v10, v8, v9, s34
	v_mul_f32_e32 v8, 0xbfb8aa3b, v11
	v_exp_f32_e32 v12, v8
	v_mad_i64_i32 v[8:9], s[14:15], v16, s33, v[120:121]
	v_lshl_add_u64 v[8:9], v[8:9], 0, v[122:123]
	global_store_short_d16_hi v[8:9], v10, off
	v_add_f32_e32 v8, 1.0, v12
	v_rcp_f32_e32 v10, v8
	v_or_b32_e32 v12, 0x73, v124
	v_mov_b32_e32 v14, v12
	v_mul_f32_e32 v8, v11, v10
	v_mul_f32_e32 v10, 0xbfb8aa3b, v0
	v_exp_f32_e32 v10, v10
	v_mul_f32_e32 v8, v15, v8
	v_bfe_u32 v9, v8, 16, 1
	v_add_f32_e32 v10, 1.0, v10
	v_add3_u32 v11, v8, v9, s34
	v_mad_i64_i32 v[8:9], s[14:15], v14, s33, v[120:121]
	v_rcp_f32_e32 v15, v10
	v_lshl_add_u64 v[8:9], v[8:9], 0, v[122:123]
	global_store_short_d16_hi v[8:9], v11, off
	v_mul_f32_e32 v0, v0, v15
	v_mul_f32_e32 v8, 0xbfb8aa3b, v1
	v_exp_f32_e32 v10, v8
	v_mul_f32_e32 v0, v4, v0
	v_bfe_u32 v4, v0, 16, 1
	v_add3_u32 v0, v0, v4, s34
	v_add_f32_e32 v4, 1.0, v10
	v_rcp_f32_e32 v11, v4
	v_mad_i64_i32 v[8:9], s[14:15], v19, s33, v[120:121]
	v_lshl_add_u64 v[8:9], v[8:9], 0, v[122:123]
	global_store_short_d16_hi v[8:9], v0, off offset:32
	v_mul_f32_e32 v0, v1, v11
	v_mul_f32_e32 v4, 0xbfb8aa3b, v2
	v_exp_f32_e32 v4, v4
	v_mul_f32_e32 v0, v5, v0
	v_bfe_u32 v1, v0, 16, 1
	v_add_f32_e32 v4, 1.0, v4
	v_rcp_f32_e32 v9, v4
	v_add3_u32 v5, v0, v1, s34
	v_mad_i64_i32 v[0:1], s[14:15], v17, s33, v[120:121]
	v_lshl_add_u64 v[0:1], v[0:1], 0, v[122:123]
	global_store_short_d16_hi v[0:1], v5, off offset:32
	v_mul_f32_e32 v0, v2, v9
	v_mul_f32_e32 v2, 0xbfb8aa3b, v3
	v_exp_f32_e32 v2, v2
	v_mul_f32_e32 v0, v6, v0
	v_bfe_u32 v1, v0, 16, 1
	v_add_f32_e32 v2, 1.0, v2
	v_rcp_f32_e32 v6, v2
	v_add3_u32 v4, v0, v1, s34
	v_mad_i64_i32 v[0:1], s[14:15], v13, s33, v[120:121]
	v_lshl_add_u64 v[0:1], v[0:1], 0, v[122:123]
	global_store_short_d16_hi v[0:1], v4, off offset:32
	v_mul_f32_e32 v0, v3, v6
	v_mul_f32_e32 v0, v7, v0
	v_bfe_u32 v1, v0, 16, 1
	v_add3_u32 v2, v0, v1, s34
	v_mad_i64_i32 v[0:1], s[14:15], v12, s33, v[120:121]
	v_lshl_add_u64 v[0:1], v[0:1], 0, v[122:123]
	global_store_short_d16_hi v[0:1], v2, off offset:32
	s_cbranch_scc0 .LBB0_1519

.LBB0_1692:
	s_mul_i32 s8, s6, 0x6000
	s_waitcnt vmcnt(6)
	s_add_i32 s10, s23, s8
	s_mul_i32 s98, s7, 0x6000
	v_lshl_add_u64 v[186:187], v[142:143], 0, s[0:1]
	v_lshl_add_u64 v[204:205], v[140:141], 0, s[0:1]
	s_add_i32 s99, s10, s24
	s_waitcnt lgkmcnt(0)
	s_barrier
	v_add_u32_e32 v184, s98, v144
	v_add_u32_e32 v185, s98, v146
	ds_read_b128 v[168:171], v185
	ds_read_b128 v[152:155], v184
	ds_read_b128 v[172:175], v185 offset:1024
	ds_read_b128 v[176:179], v185 offset:2048
	ds_read_b128 v[180:183], v185 offset:3072
	ds_read_b128 v[156:159], v184 offset:1024
	ds_read_b128 v[160:163], v184 offset:2048
	ds_read_b128 v[164:167], v184 offset:3072
	ds_read_b128 v[188:191], v184 offset:4096
	ds_read_b128 v[192:195], v184 offset:5120
	ds_read_b128 v[196:199], v184 offset:6144
	ds_read_b128 v[200:203], v184 offset:7168
	s_mov_b64 s[100:101], 0x80
	v_lshl_add_u64 v[206:207], v[186:187], 0, s[100:101]
	s_mov_b32 m0, s10
	s_waitcnt lgkmcnt(10)
	v_mfma_f32_16x16x32_bf16 v[84:87], v[152:155], v[168:171], v[84:87]
	global_load_lds_dwordx4 v[206:207], off
	s_waitcnt lgkmcnt(9)
	v_mfma_f32_16x16x32_bf16 v[76:79], v[152:155], v[172:175], v[76:79]
	s_mov_b64 s[100:101], 0x8080
	v_lshl_add_u64 v[206:207], v[186:187], 0, s[100:101]
	s_add_i32 m0, s10, 0x400
	s_waitcnt lgkmcnt(8)
	v_mfma_f32_16x16x32_bf16 v[68:71], v[152:155], v[176:179], v[68:71]
	global_load_lds_dwordx4 v[206:207], off
	s_waitcnt lgkmcnt(7)
	v_mfma_f32_16x16x32_bf16 v[60:63], v[152:155], v[180:183], v[60:63]
	s_mov_b64 s[100:101], 0x10080
	v_lshl_add_u64 v[206:207], v[186:187], 0, s[100:101]
	s_add_i32 m0, s10, 0x800
	s_waitcnt lgkmcnt(6)
	v_mfma_f32_16x16x32_bf16 v[52:55], v[156:159], v[168:171], v[52:55]
	global_load_lds_dwordx4 v[206:207], off
	v_mfma_f32_16x16x32_bf16 v[44:47], v[156:159], v[172:175], v[44:47]
	v_mfma_f32_16x16x32_bf16 v[36:39], v[156:159], v[176:179], v[36:39]
	s_mov_b64 s[100:101], 0x18080
	v_lshl_add_u64 v[206:207], v[186:187], 0, s[100:101]
	s_add_i32 m0, s10, 0xc00
	v_mfma_f32_16x16x32_bf16 v[32:35], v[156:159], v[180:183], v[32:35]
	global_load_lds_dwordx4 v[206:207], off
	s_waitcnt lgkmcnt(5)
	v_mfma_f32_16x16x32_bf16 v[28:31], v[160:163], v[168:171], v[28:31]
	s_mov_b64 s[100:101], 0x580080
	v_lshl_add_u64 v[206:207], v[204:205], 0, s[100:101]
	s_add_i32 m0, s99, 0x4000
	v_mfma_f32_16x16x32_bf16 v[24:27], v[160:163], v[172:175], v[24:27]
	global_load_lds_dwordx4 v[206:207], off
	v_mfma_f32_16x16x32_bf16 v[20:23], v[160:163], v[176:179], v[20:23]
	s_mov_b64 s[100:101], 0x588080
	v_lshl_add_u64 v[206:207], v[204:205], 0, s[100:101]
	s_add_i32 m0, s99, 0x4400
	v_mfma_f32_16x16x32_bf16 v[16:19], v[160:163], v[180:183], v[16:19]
	global_load_lds_dwordx4 v[206:207], off
	s_waitcnt lgkmcnt(4)
	v_mfma_f32_16x16x32_bf16 v[12:15], v[164:167], v[168:171], v[12:15]
	v_mfma_f32_16x16x32_bf16 v[8:11], v[164:167], v[172:175], v[8:11]
	v_mfma_f32_16x16x32_bf16 v[4:7], v[164:167], v[176:179], v[4:7]
	v_mfma_f32_16x16x32_bf16 v[0:3], v[164:167], v[180:183], v[0:3]
	s_waitcnt lgkmcnt(3)
	v_mfma_f32_16x16x32_bf16 v[124:127], v[188:191], v[168:171], v[124:127]
	v_mfma_f32_16x16x32_bf16 v[120:123], v[188:191], v[172:175], v[120:123]
	v_mfma_f32_16x16x32_bf16 v[116:119], v[188:191], v[176:179], v[116:119]
	v_mfma_f32_16x16x32_bf16 v[112:115], v[188:191], v[180:183], v[112:115]
	s_waitcnt lgkmcnt(2)
	v_mfma_f32_16x16x32_bf16 v[108:111], v[192:195], v[168:171], v[108:111]
	v_mfma_f32_16x16x32_bf16 v[104:107], v[192:195], v[172:175], v[104:107]
	v_mfma_f32_16x16x32_bf16 v[100:103], v[192:195], v[176:179], v[100:103]
	v_mfma_f32_16x16x32_bf16 v[96:99], v[192:195], v[180:183], v[96:99]
	s_waitcnt lgkmcnt(1)
	v_mfma_f32_16x16x32_bf16 v[92:95], v[196:199], v[168:171], v[92:95]
	v_mfma_f32_16x16x32_bf16 v[88:91], v[196:199], v[172:175], v[88:91]
	v_mfma_f32_16x16x32_bf16 v[80:83], v[196:199], v[176:179], v[80:83]
	v_mfma_f32_16x16x32_bf16 v[72:75], v[196:199], v[180:183], v[72:75]
	s_waitcnt lgkmcnt(0)
	v_mfma_f32_16x16x32_bf16 v[64:67], v[200:203], v[168:171], v[64:67]
	v_mfma_f32_16x16x32_bf16 v[56:59], v[200:203], v[172:175], v[56:59]
	v_mfma_f32_16x16x32_bf16 v[48:51], v[200:203], v[176:179], v[48:51]
	v_mfma_f32_16x16x32_bf16 v[40:43], v[200:203], v[180:183], v[40:43]
	s_add_i32 s8, s7, 1
	s_cmp_lg_u32 s7, 2
	s_cselect_b32 s7, s8, 0
	s_add_i32 s8, s6, 1
	s_cmp_lg_u32 s6, 2
	s_cselect_b32 s6, s8, 0
	s_add_u32 s0, s0, 64
	s_addc_u32 s1, s1, 0
	s_cmpk_eq_i32 s0, 0x780
	s_cbranch_scc0 .LBB0_1692
	s_waitcnt vmcnt(6)
	s_waitcnt lgkmcnt(0)
	s_barrier
	ds_read_b128 v[140:143], v144
	ds_read_b128 v[152:155], v144 offset:1024
	ds_read_b128 v[156:159], v144 offset:2048
	ds_read_b128 v[160:163], v144 offset:3072
	ds_read_b128 v[164:167], v146
	ds_read_b128 v[168:171], v146 offset:1024
	ds_read_b128 v[172:175], v146 offset:2048
	ds_read_b128 v[176:179], v146 offset:3072
	s_waitcnt lgkmcnt(0)
	s_nop 0
	v_mfma_f32_16x16x32_bf16 v[84:87], v[140:143], v[164:167], v[84:87]
	v_mfma_f32_16x16x32_bf16 v[76:79], v[140:143], v[168:171], v[76:79]
	v_mfma_f32_16x16x32_bf16 v[68:71], v[140:143], v[172:175], v[68:71]
	v_mfma_f32_16x16x32_bf16 v[60:63], v[140:143], v[176:179], v[60:63]
	v_mfma_f32_16x16x32_bf16 v[52:55], v[152:155], v[164:167], v[52:55]
	v_mfma_f32_16x16x32_bf16 v[44:47], v[152:155], v[168:171], v[44:47]
	v_mfma_f32_16x16x32_bf16 v[36:39], v[152:155], v[172:175], v[36:39]
	v_mfma_f32_16x16x32_bf16 v[32:35], v[152:155], v[176:179], v[32:35]
	v_mfma_f32_16x16x32_bf16 v[28:31], v[156:159], v[164:167], v[28:31]
	v_mfma_f32_16x16x32_bf16 v[24:27], v[156:159], v[168:171], v[24:27]
	v_mfma_f32_16x16x32_bf16 v[20:23], v[156:159], v[172:175], v[20:23]
	v_mfma_f32_16x16x32_bf16 v[16:19], v[156:159], v[176:179], v[16:19]
	v_mfma_f32_16x16x32_bf16 v[12:15], v[160:163], v[164:167], v[12:15]
	v_mfma_f32_16x16x32_bf16 v[8:11], v[160:163], v[168:171], v[8:11]
	v_mfma_f32_16x16x32_bf16 v[4:7], v[160:163], v[172:175], v[4:7]
	v_mfma_f32_16x16x32_bf16 v[0:3], v[160:163], v[176:179], v[0:3]
	ds_read_b128 v[140:143], v144 offset:4096
	ds_read_b128 v[152:155], v144 offset:5120
	ds_read_b128 v[156:159], v144 offset:6144
	ds_read_b128 v[160:163], v144 offset:7168
	s_waitcnt lgkmcnt(0)
	s_nop 0
	v_mfma_f32_16x16x32_bf16 v[180:183], v[140:143], v[164:167], v[124:127]
	v_mfma_f32_16x16x32_bf16 v[184:187], v[140:143], v[168:171], v[120:123]
	v_mfma_f32_16x16x32_bf16 v[188:191], v[140:143], v[172:175], v[116:119]
	v_mfma_f32_16x16x32_bf16 v[140:143], v[140:143], v[176:179], v[112:115]
	v_mfma_f32_16x16x32_bf16 v[192:195], v[152:155], v[164:167], v[108:111]
	v_mfma_f32_16x16x32_bf16 v[196:199], v[152:155], v[168:171], v[104:107]
	v_mfma_f32_16x16x32_bf16 v[200:203], v[152:155], v[172:175], v[100:103]
	v_mfma_f32_16x16x32_bf16 v[152:155], v[152:155], v[176:179], v[96:99]
	v_mfma_f32_16x16x32_bf16 v[204:207], v[156:159], v[164:167], v[92:95]
	v_mfma_f32_16x16x32_bf16 v[208:211], v[156:159], v[168:171], v[88:91]
	v_mfma_f32_16x16x32_bf16 v[212:215], v[156:159], v[172:175], v[80:83]
	v_mfma_f32_16x16x32_bf16 v[156:159], v[156:159], v[176:179], v[72:75]
	v_mfma_f32_16x16x32_bf16 v[164:167], v[160:163], v[164:167], v[64:67]
	v_mfma_f32_16x16x32_bf16 v[168:171], v[160:163], v[168:171], v[56:59]
	v_mfma_f32_16x16x32_bf16 v[172:175], v[160:163], v[172:175], v[48:51]
	v_mfma_f32_16x16x32_bf16 v[160:163], v[160:163], v[176:179], v[40:43]
	s_waitcnt vmcnt(0)
	s_waitcnt lgkmcnt(0)
	s_barrier
	ds_read_b128 v[40:43], v150
	ds_read_b128 v[48:51], v150 offset:1024
	ds_read_b128 v[56:59], v150 offset:2048
	ds_read_b128 v[176:179], v150 offset:3072
	ds_read_b128 v[216:219], v151
	ds_read_b128 v[220:223], v151 offset:1024
	ds_read_b128 v[228:231], v151 offset:2048
	ds_read_b128 v[232:235], v151 offset:3072
	s_waitcnt lgkmcnt(0)
	s_nop 0
	v_mfma_f32_16x16x32_bf16 v[116:119], v[40:43], v[220:223], v[76:79]
	v_mfma_f32_16x16x32_bf16 v[120:123], v[40:43], v[228:231], v[68:71]
	v_mfma_f32_16x16x32_bf16 v[64:67], v[176:179], v[216:219], v[12:15]
	v_mfma_f32_16x16x32_bf16 v[68:71], v[176:179], v[220:223], v[8:11]
	v_mfma_f32_16x16x32_bf16 v[72:75], v[176:179], v[228:231], v[4:7]
	v_mfma_f32_16x16x32_bf16 v[76:79], v[176:179], v[232:235], v[0:3]
	ds_read_b128 v[0:3], v150 offset:4096
	ds_read_b128 v[4:7], v150 offset:5120
	ds_read_b128 v[8:11], v150 offset:6144
	ds_read_b128 v[12:15], v150 offset:7168
	s_waitcnt lgkmcnt(0)
	v_mfma_f32_16x16x32_bf16 v[112:115], v[40:43], v[216:219], v[84:87]
	v_mfma_f32_16x16x32_bf16 v[124:127], v[40:43], v[232:235], v[60:63]
	v_mfma_f32_16x16x32_bf16 v[96:99], v[48:51], v[216:219], v[52:55]
	v_mfma_f32_16x16x32_bf16 v[100:103], v[48:51], v[220:223], v[44:47]
	v_mfma_f32_16x16x32_bf16 v[104:107], v[48:51], v[228:231], v[36:39]
	v_mfma_f32_16x16x32_bf16 v[108:111], v[48:51], v[232:235], v[32:35]
	v_mfma_f32_16x16x32_bf16 v[80:83], v[56:59], v[216:219], v[28:31]
	v_mfma_f32_16x16x32_bf16 v[84:87], v[56:59], v[220:223], v[24:27]
	v_mfma_f32_16x16x32_bf16 v[88:91], v[56:59], v[228:231], v[20:23]
	v_mfma_f32_16x16x32_bf16 v[92:95], v[56:59], v[232:235], v[16:19]
	v_mfma_f32_16x16x32_bf16 v[48:51], v[0:3], v[216:219], v[180:183]
	v_mfma_f32_16x16x32_bf16 v[52:55], v[0:3], v[220:223], v[184:187]
	v_mfma_f32_16x16x32_bf16 v[56:59], v[0:3], v[228:231], v[188:191]
	v_mfma_f32_16x16x32_bf16 v[60:63], v[0:3], v[232:235], v[140:143]
	v_mfma_f32_16x16x32_bf16 v[32:35], v[4:7], v[216:219], v[192:195]
	v_mfma_f32_16x16x32_bf16 v[36:39], v[4:7], v[220:223], v[196:199]
	v_mfma_f32_16x16x32_bf16 v[40:43], v[4:7], v[228:231], v[200:203]
	v_mfma_f32_16x16x32_bf16 v[44:47], v[4:7], v[232:235], v[152:155]
	v_mfma_f32_16x16x32_bf16 v[16:19], v[8:11], v[216:219], v[204:207]
	v_mfma_f32_16x16x32_bf16 v[20:23], v[8:11], v[220:223], v[208:211]
	v_mfma_f32_16x16x32_bf16 v[24:27], v[8:11], v[228:231], v[212:215]
	v_mfma_f32_16x16x32_bf16 v[28:31], v[8:11], v[232:235], v[156:159]
	v_mfma_f32_16x16x32_bf16 v[0:3], v[12:15], v[216:219], v[164:167]
	v_mfma_f32_16x16x32_bf16 v[4:7], v[12:15], v[220:223], v[168:171]
	v_mfma_f32_16x16x32_bf16 v[8:11], v[12:15], v[228:231], v[172:175]
	v_mfma_f32_16x16x32_bf16 v[12:15], v[12:15], v[232:235], v[160:163]
	v_add_u32_e32 v152, s4, v129
	v_or_b32_e32 v153, v152, v149
	v_or_b32_e32 v140, s5, v145
	v_mov_b32_e32 v155, v153
	v_mov_b64_e32 v[142:143], s[94:95]
	s_waitcnt lgkmcnt(0)
	s_barrier
	v_ashrrev_i32_e32 v141, 31, v140
	v_or_b32_e32 v154, v140, v128
	v_mad_i64_i32 v[142:143], s[0:1], v155, s39, v[142:143]
	v_lshl_add_u64 v[142:143], v[140:141], 1, v[142:143]
	v_lshl_add_u64 v[142:143], v[142:143], 0, v[130:131]
	v_cmp_gt_i32_e32 vcc, s40, v154
	s_and_saveexec_b64 s[0:1], vcc
	s_cbranch_execz .LBB0_1695
	v_bfe_u32 v155, v112, 16, 1
	v_add3_u32 v155, v112, v155, s41
	global_store_short_d16_hi v[142:143], v155, off

.LBB0_2009:
	s_movk_i32 s6, 0xfff
	v_cmp_lt_i32_e32 vcc, s6, v32
	v_lshl_add_u64 v[12:13], v[24:25], 0, v[22:23]
	s_nop 0
	v_cndmask_b32_e32 v8, v33, v34, vcc
	v_and_b32_e32 v9, v8, v32
	v_cmp_eq_u32_e32 vcc, 0, v9
	v_cmp_eq_u32_e64 s[6:7], v9, v8
	global_load_dwordx4 v[8:11], v[12:13], off offset:-8
	v_cndmask_b32_e64 v15, -1, 0, vcc
	v_cndmask_b32_e64 v14, v35, 0, vcc
	v_cndmask_b32_e64 v20, v36, 0, s[6:7]
	v_lshl_add_u64 v[14:15], v[12:13], 0, v[14:15]
	v_lshl_add_u64 v[12:13], v[12:13], 0, v[20:21]
	global_load_dwordx4 v[16:19], v[12:13], off offset:-8
	s_nop 0
	global_load_dwordx4 v[12:15], v[14:15], off offset:-8
	v_cndmask_b32_e64 v30, 0.5, 0, s[6:7]
	v_cndmask_b32_e64 v31, 0.5, 0, vcc
	s_waitcnt vmcnt(2)
	v_lshlrev_b32_e32 v28, 16, v8
	v_and_b32_e32 v29, 0xffff0000, v8
	s_waitcnt vmcnt(1)
	v_and_b32_e32 v42, 0xffff0000, v16
	s_waitcnt vmcnt(0)
	v_lshlrev_b32_e32 v43, 16, v12
	v_lshlrev_b32_e32 v40, 16, v16
	v_and_b32_e32 v41, 0xffff0000, v12
	v_pk_mul_f32 v[42:43], v[30:31], v[42:43]
	s_nop 0
	v_pk_fma_f32 v[40:41], v[30:31], v[40:41], v[42:43] op_sel:[0,0,1] op_sel_hi:[1,1,0]
	s_nop 0
	v_pk_add_f32 v[40:41], v[40:41], v[28:29] neg_lo:[0,1] neg_hi:[0,1]
	s_nop 0
	v_pk_fma_f32 v[28:29], v[0:1], v[40:41], v[28:29]
	s_and_saveexec_b64 s[6:7], s[0:1]
	s_xor_b64 s[6:7], exec, s[6:7]
	s_cbranch_execz .LBB0_2013
	s_and_saveexec_b64 s[18:19], s[4:5]
	s_cbranch_execz .LBB0_2012
	v_mul_f32_e32 v8, 0xbfb8aa3b, v28
	v_exp_f32_e32 v28, v8
	v_mul_f32_e32 v8, 0xbfb8aa3b, v29
	v_exp_f32_e32 v29, v8
	s_nop 0
	v_pk_add_f32 v[28:29], v[28:29], 1.0 op_sel_hi:[1,0]
	s_nop 0
	v_rcp_f32_e32 v12, v28
	s_nop 0
	v_mul_f32_e32 v28, 1.0, v12
	v_rcp_f32_e32 v12, v29
	s_nop 0
	v_mul_f32_e32 v29, 1.0, v12

.LBB0_2023:
	s_or_b64 exec, exec, s[6:7]
	v_lshlrev_b32_e32 v40, 16, v13
	v_and_b32_e32 v41, 0xffff0000, v17
	v_lshlrev_b32_e32 v12, 16, v17
	v_and_b32_e32 v13, 0xffff0000, v13
	v_pk_mul_f32 v[16:17], v[30:31], v[40:41] op_sel:[1,0] op_sel_hi:[0,1]
	v_lshlrev_b32_e32 v8, 16, v9
	v_and_b32_e32 v9, 0xffff0000, v9
	v_pk_fma_f32 v[12:13], v[30:31], v[12:13], v[16:17]
	s_nop 0
	v_pk_add_f32 v[12:13], v[12:13], v[8:9] neg_lo:[0,1] neg_hi:[0,1]
	s_nop 0
	v_pk_fma_f32 v[8:9], v[2:3], v[12:13], v[8:9]
	s_and_saveexec_b64 s[6:7], s[0:1]
	s_xor_b64 s[6:7], exec, s[6:7]
	s_cbranch_execz .LBB0_2027
	s_and_saveexec_b64 s[18:19], s[4:5]
	s_cbranch_execz .LBB0_2026
	v_mul_f32_e32 v8, 0xbfb8aa3b, v8
	v_mul_f32_e32 v9, 0xbfb8aa3b, v9
	v_exp_f32_e32 v8, v8
	v_exp_f32_e32 v9, v9
	s_nop 0
	v_pk_add_f32 v[8:9], v[8:9], 1.0 op_sel_hi:[1,0]
	s_nop 0
	v_rcp_f32_e32 v13, v8
	s_nop 0
	v_mul_f32_e32 v8, 1.0, v13
	v_rcp_f32_e32 v13, v9
	s_nop 0
	v_mul_f32_e32 v9, 1.0, v13

.LBB0_2037:
	s_or_b64 exec, exec, s[6:7]
	v_pk_mov_b32 v[16:17], v[30:31], v[30:31] op_sel:[1,0]
	v_lshlrev_b32_e32 v40, 16, v14
	v_and_b32_e32 v41, 0xffff0000, v18
	v_lshlrev_b32_e32 v42, 16, v18
	v_and_b32_e32 v43, 0xffff0000, v14
	v_pk_mul_f32 v[40:41], v[16:17], v[40:41]
	v_lshlrev_b32_e32 v12, 16, v10
	v_and_b32_e32 v13, 0xffff0000, v10
	v_pk_fma_f32 v[40:41], v[30:31], v[42:43], v[40:41]
	s_nop 0
	v_pk_add_f32 v[40:41], v[40:41], v[12:13] neg_lo:[0,1] neg_hi:[0,1]
	s_nop 0
	v_pk_fma_f32 v[12:13], v[4:5], v[40:41], v[12:13]
	s_and_saveexec_b64 s[6:7], s[0:1]
	s_xor_b64 s[6:7], exec, s[6:7]
	s_cbranch_execz .LBB0_2041
	s_and_saveexec_b64 s[18:19], s[4:5]
	s_cbranch_execz .LBB0_2040
	v_mul_f32_e32 v10, 0xbfb8aa3b, v12
	v_exp_f32_e32 v12, v10
	v_mul_f32_e32 v10, 0xbfb8aa3b, v13
	v_exp_f32_e32 v13, v10
	s_nop 0
	v_pk_add_f32 v[12:13], v[12:13], 1.0 op_sel_hi:[1,0]
	s_nop 0
	v_rcp_f32_e32 v14, v12
	s_nop 0
	v_mul_f32_e32 v12, 1.0, v14
	v_rcp_f32_e32 v14, v13
	s_nop 0
	v_mul_f32_e32 v13, 1.0, v14

.LBB0_2051:
	s_or_b64 exec, exec, s[6:7]
	v_lshlrev_b32_e32 v40, 16, v15
	v_and_b32_e32 v41, 0xffff0000, v19
	v_lshlrev_b32_e32 v14, 16, v19
	v_and_b32_e32 v15, 0xffff0000, v15
	v_pk_mul_f32 v[16:17], v[16:17], v[40:41]
	v_lshlrev_b32_e32 v10, 16, v11
	v_and_b32_e32 v11, 0xffff0000, v11
	v_pk_fma_f32 v[14:15], v[30:31], v[14:15], v[16:17]
	s_nop 0
	v_pk_add_f32 v[14:15], v[14:15], v[10:11] neg_lo:[0,1] neg_hi:[0,1]
	s_nop 0
	v_pk_fma_f32 v[10:11], v[6:7], v[14:15], v[10:11]
	s_and_saveexec_b64 s[6:7], s[0:1]
	s_xor_b64 s[6:7], exec, s[6:7]
	s_cbranch_execz .LBB0_2055
	s_and_saveexec_b64 s[18:19], s[4:5]
	s_cbranch_execz .LBB0_2054
	v_mul_f32_e32 v10, 0xbfb8aa3b, v10
	v_mul_f32_e32 v11, 0xbfb8aa3b, v11
	v_exp_f32_e32 v10, v10
	v_exp_f32_e32 v11, v11
	s_nop 0
	v_pk_add_f32 v[10:11], v[10:11], 1.0 op_sel_hi:[1,0]
	s_nop 0
	v_rcp_f32_e32 v15, v10
	s_nop 0
	v_mul_f32_e32 v10, 1.0, v15
	v_rcp_f32_e32 v15, v11
	s_nop 0
	v_mul_f32_e32 v11, 1.0, v15

.LBB0_2467:
	v_writelane_b32 v240, s35, 47
	s_or_b64 exec, exec, s[12:13]
	s_lshl_b64 s[0:1], s[14:15], 12
	v_mul_f32_e32 v1, 0x3fb8aa3b, v69
	v_writelane_b32 v240, s0, 52
	v_exp_f32_e32 v112, v1
	v_or_b32_e32 v1, v67, v77
	v_writelane_b32 v240, s1, 53
	v_mul_lo_u32 v113, v1, s63
	s_cmp_eq_u32 s58, 0
	v_cmp_lt_i32_e64 s[8:9], 7, v70
	v_cmp_gt_i32_e64 s[10:11], 16, v70
	v_cmp_gt_u32_e64 s[0:1], 16, v70
	v_mul_lo_u32 v69, v70, s64
	v_or_b32_e32 v70, 2, v80
	s_cselect_b64 s[6:7], -1, 0
	s_lshl_b32 s96, s76, 6
	v_lshl_add_u32 v115, v78, 4, v113
	v_lshlrev_b32_e32 v128, 5, v78
	v_mul_lo_u32 v78, v110, s63
	v_mul_lo_u32 v70, v70, s63
	v_readlane_b32 s60, v241, 17
	v_and_b32_e32 v114, 48, v66
	s_ashr_i32 s97, s96, 31
	v_lshlrev_b32_e32 v130, 1, v80
	v_cndmask_b32_e64 v66, v121, v122, s[0:1]
	v_add_u32_e32 v80, 0x4920, v69
	v_add_u32_e32 v81, 0x4800, v70
	v_mul_u32_u24_e32 v85, 0x90, v77
	v_or_b32_e32 v89, 16, v77
	v_or_b32_e32 v100, 32, v77
	v_or_b32_e32 v101, 48, v77
	v_cmp_gt_i32_e64 s[24:25], v77, v90
	v_cmp_gt_i32_e64 s[26:27], v77, v94
	v_cmp_gt_i32_e64 s[28:29], v77, v96
	v_cmp_gt_i32_e64 s[30:31], v77, v98
	v_lshlrev_b32_e32 v77, 1, v110
	s_movk_i32 s0, 0x4800
	s_mulk_i32 s58, 0x300
	v_readlane_b32 s66, v241, 23
	v_add_u32_e32 v82, 0x4a40, v69
	v_add_u32_e32 v83, 0x4920, v70
	v_add_u32_e32 v84, 0x4b60, v69
	v_add3_u32 v131, v69, v77, s0
	v_cndmask_b32_e32 v69, v80, v81, vcc
	v_readlane_b32 s67, v241, 24
	s_add_u32 s58, s66, s58
	v_add_u32_e32 v70, 0x4a40, v70
	v_add_u32_e32 v132, v69, v77
	v_cndmask_b32_e32 v69, v82, v83, vcc
	s_addc_u32 s59, s67, 0
	s_lshl_b64 s[0:1], s[96:97], 1
	v_add_u32_e32 v133, v69, v77
	v_cndmask_b32_e32 v69, v84, v70, vcc
	s_add_u32 s0, s58, s0
	v_add_u32_e32 v134, v69, v77
	s_addc_u32 s1, s59, s1
	v_mov_b32_e32 v69, v0
	v_lshlrev_b32_e32 v1, 2, v67
	v_add_u32_e32 v66, v130, v66
	v_ashrrev_i32_e32 v73, 31, v72
	v_readlane_b32 s61, v241, 18
	v_readlane_b32 s62, v241, 19
	v_readlane_b32 s63, v241, 20
	v_readlane_b32 s64, v241, 21
	v_readlane_b32 s65, v241, 22
	v_lshl_add_u64 v[102:103], s[0:1], 0, v[68:69]
	v_lshl_add_u64 v[68:69], v[74:75], 1, s[94:95]
	v_add_u32_e32 v138, v67, v76
	s_waitcnt lgkmcnt(0)
	s_barrier
	s_mov_b32 s71, 0
	v_lshlrev_b32_e32 v129, 2, v71
	v_cmp_eq_u32_e64 s[12:13], 0, v71
	v_cmp_gt_u32_e64 s[14:15], 2, v71
	v_cmp_gt_u32_e64 s[16:17], 4, v71
	v_cmp_gt_u32_e64 s[18:19], 8, v71
	v_cmp_gt_u32_e64 s[20:21], 16, v71
	v_cmp_gt_u32_e64 s[22:23], 32, v71
	v_cmp_gt_i32_e64 s[34:35], v89, v90
	v_cmp_gt_i32_e64 s[36:37], v89, v94
	v_cmp_gt_i32_e64 s[38:39], v89, v96
	v_cmp_gt_i32_e64 s[40:41], v89, v98
	v_cmp_gt_i32_e64 s[42:43], v100, v90
	v_cmp_gt_i32_e64 s[44:45], v100, v94
	v_cmp_gt_i32_e64 s[46:47], v100, v96
	v_cmp_gt_i32_e64 s[48:49], v100, v98
	v_cmp_gt_i32_e64 s[50:51], v101, v90
	v_cmp_gt_i32_e64 s[52:53], v101, v94
	v_cmp_gt_i32_e64 s[54:55], v101, v96
	v_cmp_gt_i32_e64 s[56:57], v101, v98
	v_lshl_add_u64 v[100:101], v[72:73], 1, s[94:95]
	s_movk_i32 s64, 0x480
	s_movk_i32 s63, 0x90
	v_lshl_add_u64 v[104:105], s[76:77], 1, v[68:69]
	v_sub_u32_e32 v135, 0, v79
	v_or_b32_e32 v136, 64, v71
	v_xor_b32_e32 v137, 0xffffffbf, v71
	v_not_b32_e32 v139, v138
	v_add_u32_e32 v140, v1, v114
	v_add_u32_e32 v141, v66, v78
	v_add_u32_e32 v142, v114, v85
	s_mov_b32 s84, s2
	s_movk_i32 s60, 0x104
	s_movk_i32 s61, 0x1600
	s_movk_i32 s62, 0x5800
	s_movk_i32 s65, 0xff40
	s_movk_i32 s66, 0x3c0
	s_movk_i32 s67, 0x280
	s_waitcnt vmcnt(0)
	s_and_saveexec_b64 s[0:1], s[4:5]
	s_xor_b64 s[0:1], exec, s[0:1]
	s_cbranch_execz .LBB0_2471

.LBB0_2471:
	s_andn2_saveexec_b64 s[0:1], s[0:1]
	s_cbranch_execz .LBB0_2489
	v_add_u32_e32 v74, v130, v130
	v_add_u32_e32 v1, 0xb400, v74
	v_add_u32_e32 v143, 0xc000, v74
	ds_read2_b64 v[66:69], v1 offset0:96 offset1:192
	v_add_u32_e32 v89, 0xbc00, v74
	ds_read2_b64 v[74:77], v143 offset0:96 offset1:192
	ds_read2_b64 v[70:73], v89 offset0:32 offset1:128
	s_waitcnt vmcnt(16)
	v_lshlrev_b32_e32 v144, 16, v22
	v_lshlrev_b32_e32 v80, 16, v18
	v_lshlrev_b32_e32 v146, 16, v30
	v_mov_b32_e32 v81, v144
	v_lshlrev_b32_e32 v84, 16, v14
	s_waitcnt lgkmcnt(1)
	v_pk_fma_f32 v[80:81], v[66:67], v[80:81], v[76:77] op_sel_hi:[0,1,0]
	v_mov_b32_e32 v85, v146
	v_lshlrev_b32_e32 v145, 16, v34
	v_pk_fma_f32 v[80:81], v[68:69], v[84:85], v[80:81] op_sel_hi:[0,1,1]
	v_lshlrev_b32_e32 v147, 16, v38
	s_waitcnt lgkmcnt(0)
	v_pk_fma_f32 v[80:81], v[70:71], v[144:145], v[80:81] op_sel_hi:[0,1,1]
	v_pk_fma_f32 v[84:85], v[66:67], v[84:85], v[76:77] op_sel_hi:[0,1,0]
	v_lshlrev_b32_e32 v83, 16, v42
	v_mov_b32_e32 v82, v145
	v_pk_fma_f32 v[80:81], v[72:73], v[146:147], v[80:81] op_sel_hi:[0,1,1]
	v_pk_fma_f32 v[84:85], v[68:69], v[144:145], v[84:85] op_sel_hi:[0,1,1]
	v_pk_fma_f32 v[80:81], v[74:75], v[82:83], v[80:81] op_sel_hi:[0,1,1]
	v_pk_fma_f32 v[84:85], v[70:71], v[146:147], v[84:85] op_sel_hi:[0,1,1]
	v_lshlrev_b32_e32 v79, 16, v46
	v_mov_b32_e32 v78, v147
	v_mul_f32_e32 v107, 0xbfb8aa3b, v80
	v_pk_fma_f32 v[84:85], v[72:73], v[82:83], v[84:85] op_sel_hi:[0,1,1]
	v_exp_f32_e32 v154, v107
	v_mul_f32_e32 v107, 0xbfb8aa3b, v81
	v_pk_fma_f32 v[84:85], v[74:75], v[78:79], v[84:85] op_sel_hi:[0,1,1]
	v_exp_f32_e32 v155, v107
	v_mul_f32_e32 v107, 0xbfb8aa3b, v84
	v_exp_f32_e32 v144, v107
	v_mul_f32_e32 v107, 0xbfb8aa3b, v85
	v_exp_f32_e32 v145, v107
	v_pk_add_f32 v[154:155], v[154:155], 1.0 op_sel_hi:[1,0]
	v_and_b32_e32 v150, 0xffff0000, v22
	v_pk_add_f32 v[156:157], v[144:145], 1.0 op_sel_hi:[1,0]
	v_rcp_f32_e32 v144, v155
	v_and_b32_e32 v148, 0xffff0000, v18
	v_and_b32_e32 v152, 0xffff0000, v30
	v_mov_b32_e32 v149, v150
	v_mul_f32_e32 v144, v81, v144
	v_rcp_f32_e32 v107, v154
	v_and_b32_e32 v106, 0xffff0000, v14
	v_pk_fma_f32 v[148:149], v[66:67], v[148:149], v[76:77] op_sel:[1,0,1]
	v_mul_f32_e32 v145, v80, v107
	v_rcp_f32_e32 v81, v157
	s_nop 0
	v_mul_f32_e32 v146, v85, v81
	v_rcp_f32_e32 v81, v156
	s_nop 0
	v_mul_f32_e32 v147, v84, v81
	v_and_b32_e32 v84, 0xffff0000, v34
	v_mov_b32_e32 v107, v152
	v_mov_b32_e32 v151, v84
	v_and_b32_e32 v80, 0xffff0000, v38
	v_pk_fma_f32 v[148:149], v[68:69], v[106:107], v[148:149] op_sel:[1,0,0]
	v_pk_fma_f32 v[106:107], v[66:67], v[106:107], v[76:77] op_sel:[1,0,1]
	v_mov_b32_e32 v153, v80
	v_pk_fma_f32 v[148:149], v[70:71], v[150:151], v[148:149] op_sel:[1,0,0]
	v_pk_fma_f32 v[106:107], v[68:69], v[150:151], v[106:107] op_sel:[1,0,0]
	v_and_b32_e32 v85, 0xffff0000, v42
	v_pk_fma_f32 v[148:149], v[72:73], v[152:153], v[148:149] op_sel:[1,0,0]
	v_pk_fma_f32 v[106:107], v[70:71], v[152:153], v[106:107] op_sel:[1,0,0]
	v_and_b32_e32 v81, 0xffff0000, v46
	v_pk_fma_f32 v[148:149], v[74:75], v[84:85], v[148:149] op_sel:[1,0,0]
	v_pk_fma_f32 v[106:107], v[72:73], v[84:85], v[106:107] op_sel:[1,0,0]
	v_mul_f32_e32 v154, 0xbfb8aa3b, v148
	v_mul_f32_e32 v155, 0xbfb8aa3b, v149
	v_pk_fma_f32 v[150:151], v[74:75], v[80:81], v[106:107] op_sel:[1,0,0]
	v_exp_f32_e32 v154, v154
	v_exp_f32_e32 v155, v155
	v_mul_f32_e32 v106, 0xbfb8aa3b, v150
	v_mul_f32_e32 v107, 0xbfb8aa3b, v151
	v_exp_f32_e32 v106, v106
	v_exp_f32_e32 v107, v107
	v_pk_add_f32 v[154:155], v[154:155], 1.0 op_sel_hi:[1,0]
	v_pk_add_f32 v[152:153], v[106:107], 1.0 op_sel_hi:[1,0]
	v_rcp_f32_e32 v107, v155
	s_nop 0
	v_mul_f32_e32 v106, v149, v107
	v_rcp_f32_e32 v149, v154
	s_nop 0
	v_mul_f32_e32 v107, v148, v149
	v_rcp_f32_e32 v149, v153
	s_nop 0
	v_mul_f32_e32 v148, v151, v149
	v_rcp_f32_e32 v151, v152
	s_nop 0
	v_mul_f32_e32 v149, v150, v151
	v_lshlrev_b32_e32 v150, 16, v50
	v_lshlrev_b32_e32 v151, 16, v58
	v_lshlrev_b32_e32 v152, 16, v54
	v_lshlrev_b32_e32 v153, 16, v62
	v_pk_fma_f32 v[154:155], v[66:67], v[82:83], v[76:77] op_sel_hi:[0,1,0]
	v_pk_fma_f32 v[154:155], v[68:69], v[78:79], v[154:155] op_sel_hi:[0,1,1]
	v_pk_mov_b32 v[82:83], v[82:83], v[150:151] op_sel:[1,0]
	v_pk_mov_b32 v[156:157], v[78:79], v[152:153] op_sel:[1,0]
	v_pk_fma_f32 v[78:79], v[66:67], v[78:79], v[76:77] op_sel_hi:[0,1,0]
	v_pk_fma_f32 v[154:155], v[70:71], v[82:83], v[154:155] op_sel_hi:[0,1,1]
	v_pk_fma_f32 v[78:79], v[68:69], v[82:83], v[78:79] op_sel_hi:[0,1,1]
	v_pk_fma_f32 v[154:155], v[72:73], v[156:157], v[154:155] op_sel_hi:[0,1,1]
	v_pk_fma_f32 v[78:79], v[70:71], v[156:157], v[78:79] op_sel_hi:[0,1,1]
	v_pk_fma_f32 v[154:155], v[74:75], v[150:151], v[154:155] op_sel_hi:[0,1,1]
	v_pk_fma_f32 v[78:79], v[72:73], v[150:151], v[78:79] op_sel_hi:[0,1,1]
	v_mul_f32_e32 v158, 0xbfb8aa3b, v154
	v_mul_f32_e32 v159, 0xbfb8aa3b, v155
	v_pk_fma_f32 v[150:151], v[74:75], v[152:153], v[78:79] op_sel_hi:[0,1,1]
	v_exp_f32_e32 v158, v158
	v_exp_f32_e32 v159, v159
	v_mul_f32_e32 v78, 0xbfb8aa3b, v150
	v_mul_f32_e32 v79, 0xbfb8aa3b, v151
	v_exp_f32_e32 v78, v78
	v_exp_f32_e32 v79, v79
	v_pk_add_f32 v[158:159], v[158:159], 1.0 op_sel_hi:[1,0]
	v_pk_add_f32 v[152:153], v[78:79], 1.0 op_sel_hi:[1,0]
	v_rcp_f32_e32 v79, v159
	s_nop 0
	v_mul_f32_e32 v78, v155, v79
	v_rcp_f32_e32 v82, v158
	s_nop 0
	v_mul_f32_e32 v79, v154, v82
	v_rcp_f32_e32 v83, v153
	s_nop 0
	v_mul_f32_e32 v82, v151, v83
	v_rcp_f32_e32 v151, v152
	s_nop 0
	v_mul_f32_e32 v83, v150, v151
	v_and_b32_e32 v151, 0xffff0000, v58
	v_and_b32_e32 v150, 0xffff0000, v50
	v_pk_fma_f32 v[154:155], v[66:67], v[84:85], v[76:77] op_sel:[1,0,1]
	v_and_b32_e32 v153, 0xffff0000, v62
	v_and_b32_e32 v152, 0xffff0000, v54
	v_pk_fma_f32 v[154:155], v[68:69], v[80:81], v[154:155] op_sel:[1,0,0]
	v_pk_mov_b32 v[84:85], v[84:85], v[150:151] op_sel:[1,0]
	v_pk_fma_f32 v[66:67], v[66:67], v[80:81], v[76:77] op_sel:[1,0,1]
	v_pk_fma_f32 v[154:155], v[70:71], v[84:85], v[154:155] op_sel:[1,0,0]
	v_pk_mov_b32 v[156:157], v[80:81], v[152:153] op_sel:[1,0]
	v_pk_fma_f32 v[66:67], v[68:69], v[84:85], v[66:67] op_sel:[1,0,0]
	v_pk_fma_f32 v[154:155], v[72:73], v[156:157], v[154:155] op_sel:[1,0,0]
	v_pk_fma_f32 v[66:67], v[70:71], v[156:157], v[66:67] op_sel:[1,0,0]
	v_pk_fma_f32 v[154:155], v[74:75], v[150:151], v[154:155] op_sel:[1,0,0]
	v_pk_fma_f32 v[66:67], v[72:73], v[150:151], v[66:67] op_sel:[1,0,0]
	v_mul_f32_e32 v158, 0xbfb8aa3b, v154
	v_mul_f32_e32 v159, 0xbfb8aa3b, v155
	v_pk_fma_f32 v[70:71], v[74:75], v[152:153], v[66:67] op_sel:[1,0,0]
	v_exp_f32_e32 v158, v158
	v_exp_f32_e32 v159, v159
	v_mul_f32_e32 v66, 0xbfb8aa3b, v70
	v_mul_f32_e32 v67, 0xbfb8aa3b, v71
	v_exp_f32_e32 v66, v66
	v_exp_f32_e32 v67, v67
	v_pk_add_f32 v[158:159], v[158:159], 1.0 op_sel_hi:[1,0]
	v_pk_add_f32 v[72:73], v[66:67], 1.0 op_sel_hi:[1,0]
	v_rcp_f32_e32 v67, v159
	s_nop 0
	v_mul_f32_e32 v66, v155, v67
	v_rcp_f32_e32 v68, v158
	s_nop 0
	v_mul_f32_e32 v67, v154, v68
	v_rcp_f32_e32 v69, v73
	s_nop 0
	v_mul_f32_e32 v68, v71, v69
	v_rcp_f32_e32 v71, v72
	s_nop 0
	v_mul_f32_e32 v69, v70, v71
	s_and_saveexec_b64 s[58:59], s[8:9]
	s_cbranch_execz .LBB0_2474
	v_bfe_u32 v70, v145, 16, 1
	v_add3_u32 v70, v145, v70, s78
	v_bfe_u32 v71, v107, 16, 1
	v_lshrrev_b32_e32 v70, 16, v70
	v_add3_u32 v71, v107, v71, s78
	v_and_or_b32 v70, v71, s87, v70
	v_bfe_u32 v71, v147, 16, 1
	v_add3_u32 v71, v147, v71, s78
	v_bfe_u32 v72, v149, 16, 1
	v_lshrrev_b32_e32 v71, 16, v71
	v_add3_u32 v72, v149, v72, s78
	v_and_or_b32 v71, v72, s87, v71
	ds_write2_b32 v141, v70, v71 offset1:36
	v_bfe_u32 v70, v144, 16, 1
	v_add3_u32 v70, v144, v70, s78
	v_bfe_u32 v71, v106, 16, 1
	v_lshrrev_b32_e32 v70, 16, v70
	v_add3_u32 v71, v106, v71, s78
	v_and_or_b32 v70, v71, s87, v70
	v_bfe_u32 v71, v146, 16, 1
	v_add3_u32 v71, v146, v71, s78
	v_bfe_u32 v72, v148, 16, 1
	v_lshrrev_b32_e32 v71, 16, v71
	v_add3_u32 v72, v148, v72, s78
	v_and_or_b32 v71, v72, s87, v71
	ds_write2_b32 v141, v70, v71 offset0:72 offset1:108
	v_bfe_u32 v70, v79, 16, 1
	v_add3_u32 v70, v79, v70, s78
	v_bfe_u32 v71, v67, 16, 1
	v_lshrrev_b32_e32 v70, 16, v70
	v_add3_u32 v71, v67, v71, s78
	v_and_or_b32 v70, v71, s87, v70
	v_bfe_u32 v71, v83, 16, 1
	v_add3_u32 v71, v83, v71, s78
	v_bfe_u32 v72, v69, 16, 1
	v_lshrrev_b32_e32 v71, 16, v71
	v_add3_u32 v72, v69, v72, s78
	v_and_or_b32 v71, v72, s87, v71
	ds_write2_b32 v141, v70, v71 offset0:144 offset1:180
	v_bfe_u32 v70, v78, 16, 1
	v_add3_u32 v70, v78, v70, s78
	v_bfe_u32 v71, v66, 16, 1
	v_lshrrev_b32_e32 v70, 16, v70
	v_add3_u32 v71, v66, v71, s78
	v_and_or_b32 v70, v71, s87, v70
	v_bfe_u32 v71, v82, 16, 1
	v_add3_u32 v71, v82, v71, s78
	v_bfe_u32 v72, v68, 16, 1
	v_lshrrev_b32_e32 v71, 16, v71
	v_add3_u32 v72, v68, v72, s78
	v_and_or_b32 v71, v72, s87, v71
	ds_write2_b32 v141, v70, v71 offset0:216 offset1:252

.LBB0_2476:
	s_or_b64 exec, exec, s[58:59]
	ds_read2_b64 v[74:77], v1 offset0:97 offset1:193
	ds_read2_b64 v[66:69], v89 offset0:33 offset1:129
	ds_read2_b64 v[70:73], v143 offset0:97 offset1:193
	v_lshlrev_b32_e32 v106, 16, v23
	v_lshlrev_b32_e32 v80, 16, v19
	v_lshlrev_b32_e32 v144, 16, v31
	v_mov_b32_e32 v81, v106
	v_lshlrev_b32_e32 v84, 16, v15
	s_waitcnt lgkmcnt(0)
	v_pk_fma_f32 v[80:81], v[74:75], v[80:81], v[72:73] op_sel_hi:[0,1,0]
	v_mov_b32_e32 v85, v144
	v_lshlrev_b32_e32 v107, 16, v35
	v_pk_fma_f32 v[80:81], v[76:77], v[84:85], v[80:81] op_sel_hi:[0,1,1]
	v_lshlrev_b32_e32 v145, 16, v39
	v_pk_fma_f32 v[80:81], v[66:67], v[106:107], v[80:81] op_sel_hi:[0,1,1]
	v_pk_fma_f32 v[84:85], v[74:75], v[84:85], v[72:73] op_sel_hi:[0,1,0]
	v_lshlrev_b32_e32 v83, 16, v43
	v_mov_b32_e32 v82, v107
	v_pk_fma_f32 v[80:81], v[68:69], v[144:145], v[80:81] op_sel_hi:[0,1,1]
	v_pk_fma_f32 v[84:85], v[76:77], v[106:107], v[84:85] op_sel_hi:[0,1,1]
	v_pk_fma_f32 v[80:81], v[70:71], v[82:83], v[80:81] op_sel_hi:[0,1,1]
	v_pk_fma_f32 v[84:85], v[66:67], v[144:145], v[84:85] op_sel_hi:[0,1,1]
	v_lshlrev_b32_e32 v79, 16, v47
	v_mov_b32_e32 v78, v145
	v_mul_f32_e32 v147, 0xbfb8aa3b, v80
	v_pk_fma_f32 v[84:85], v[68:69], v[82:83], v[84:85] op_sel_hi:[0,1,1]
	v_exp_f32_e32 v154, v147
	v_mul_f32_e32 v147, 0xbfb8aa3b, v81
	v_pk_fma_f32 v[84:85], v[70:71], v[78:79], v[84:85] op_sel_hi:[0,1,1]
	v_exp_f32_e32 v155, v147
	v_mul_f32_e32 v106, 0xbfb8aa3b, v84
	v_mul_f32_e32 v107, 0xbfb8aa3b, v85
	v_exp_f32_e32 v106, v106
	v_exp_f32_e32 v107, v107
	v_pk_add_f32 v[154:155], v[154:155], 1.0 op_sel_hi:[1,0]
	v_and_b32_e32 v150, 0xffff0000, v23
	v_and_b32_e32 v146, 0xffff0000, v19
	v_pk_add_f32 v[156:157], v[106:107], 1.0 op_sel_hi:[1,0]
	v_rcp_f32_e32 v107, v155
	v_and_b32_e32 v152, 0xffff0000, v31
	v_and_b32_e32 v148, 0xffff0000, v15
	v_mov_b32_e32 v149, v152
	v_mul_f32_e32 v106, v81, v107
	v_rcp_f32_e32 v107, v154
	s_nop 0
	v_mul_f32_e32 v107, v80, v107
	v_rcp_f32_e32 v81, v157
	s_nop 0
	v_mul_f32_e32 v144, v85, v81
	v_rcp_f32_e32 v81, v156
	s_nop 0
	v_mul_f32_e32 v145, v84, v81
	v_mov_b32_e32 v147, v150
	v_and_b32_e32 v84, 0xffff0000, v35
	v_pk_fma_f32 v[146:147], v[74:75], v[146:147], v[72:73] op_sel:[1,0,1]
	v_mov_b32_e32 v151, v84
	v_and_b32_e32 v80, 0xffff0000, v39
	v_pk_fma_f32 v[146:147], v[76:77], v[148:149], v[146:147] op_sel:[1,0,0]
	v_mov_b32_e32 v153, v80
	v_pk_fma_f32 v[146:147], v[66:67], v[150:151], v[146:147] op_sel:[1,0,0]
	v_and_b32_e32 v85, 0xffff0000, v43
	v_pk_fma_f32 v[146:147], v[68:69], v[152:153], v[146:147] op_sel:[1,0,0]
	v_and_b32_e32 v81, 0xffff0000, v47
	v_pk_fma_f32 v[154:155], v[70:71], v[84:85], v[146:147] op_sel:[1,0,0]
	s_nop 0
	v_mul_f32_e32 v146, 0xbfb8aa3b, v154
	v_mul_f32_e32 v147, 0xbfb8aa3b, v155
	v_exp_f32_e32 v146, v146
	v_exp_f32_e32 v147, v147
	s_nop 0
	v_pk_add_f32 v[156:157], v[146:147], 1.0 op_sel_hi:[1,0]
	v_pk_fma_f32 v[146:147], v[74:75], v[148:149], v[72:73] op_sel:[1,0,1]
	s_nop 0
	v_pk_fma_f32 v[146:147], v[76:77], v[150:151], v[146:147] op_sel:[1,0,0]
	s_nop 0
	v_pk_fma_f32 v[146:147], v[66:67], v[152:153], v[146:147] op_sel:[1,0,0]
	s_nop 0
	v_pk_fma_f32 v[146:147], v[68:69], v[84:85], v[146:147] op_sel:[1,0,0]
	s_nop 0
	v_pk_fma_f32 v[150:151], v[70:71], v[80:81], v[146:147] op_sel:[1,0,0]
	s_nop 0
	v_mul_f32_e32 v146, 0xbfb8aa3b, v150
	v_mul_f32_e32 v147, 0xbfb8aa3b, v151
	v_exp_f32_e32 v146, v146
	v_exp_f32_e32 v147, v147
	s_nop 0
	v_pk_add_f32 v[152:153], v[146:147], 1.0 op_sel_hi:[1,0]
	v_rcp_f32_e32 v147, v157
	s_nop 0
	v_mul_f32_e32 v146, v155, v147
	v_rcp_f32_e32 v148, v156
	s_nop 0
	v_mul_f32_e32 v147, v154, v148
	v_rcp_f32_e32 v149, v153
	s_nop 0
	v_mul_f32_e32 v148, v151, v149
	v_rcp_f32_e32 v151, v152
	s_nop 0
	v_mul_f32_e32 v149, v150, v151
	v_lshlrev_b32_e32 v150, 16, v51
	v_lshlrev_b32_e32 v151, 16, v59
	v_lshlrev_b32_e32 v152, 16, v55
	v_lshlrev_b32_e32 v153, 16, v63
	v_pk_fma_f32 v[154:155], v[74:75], v[82:83], v[72:73] op_sel_hi:[0,1,0]
	v_pk_fma_f32 v[154:155], v[76:77], v[78:79], v[154:155] op_sel_hi:[0,1,1]
	v_pk_mov_b32 v[82:83], v[82:83], v[150:151] op_sel:[1,0]
	v_pk_mov_b32 v[156:157], v[78:79], v[152:153] op_sel:[1,0]
	v_pk_fma_f32 v[78:79], v[74:75], v[78:79], v[72:73] op_sel_hi:[0,1,0]
	v_pk_fma_f32 v[154:155], v[66:67], v[82:83], v[154:155] op_sel_hi:[0,1,1]
	v_pk_fma_f32 v[78:79], v[76:77], v[82:83], v[78:79] op_sel_hi:[0,1,1]
	v_pk_fma_f32 v[154:155], v[68:69], v[156:157], v[154:155] op_sel_hi:[0,1,1]
	v_pk_fma_f32 v[78:79], v[66:67], v[156:157], v[78:79] op_sel_hi:[0,1,1]
	v_pk_fma_f32 v[154:155], v[70:71], v[150:151], v[154:155] op_sel_hi:[0,1,1]
	v_pk_fma_f32 v[78:79], v[68:69], v[150:151], v[78:79] op_sel_hi:[0,1,1]
	v_mul_f32_e32 v158, 0xbfb8aa3b, v154
	v_mul_f32_e32 v159, 0xbfb8aa3b, v155
	v_pk_fma_f32 v[150:151], v[70:71], v[152:153], v[78:79] op_sel_hi:[0,1,1]
	v_exp_f32_e32 v158, v158
	v_exp_f32_e32 v159, v159
	v_mul_f32_e32 v78, 0xbfb8aa3b, v150
	v_mul_f32_e32 v79, 0xbfb8aa3b, v151
	v_exp_f32_e32 v78, v78
	v_exp_f32_e32 v79, v79
	v_pk_add_f32 v[158:159], v[158:159], 1.0 op_sel_hi:[1,0]
	v_pk_add_f32 v[152:153], v[78:79], 1.0 op_sel_hi:[1,0]
	v_rcp_f32_e32 v79, v159
	s_nop 0
	v_mul_f32_e32 v78, v155, v79
	v_rcp_f32_e32 v82, v158
	s_nop 0
	v_mul_f32_e32 v79, v154, v82
	v_rcp_f32_e32 v83, v153
	s_nop 0
	v_mul_f32_e32 v82, v151, v83
	v_rcp_f32_e32 v151, v152
	s_nop 0
	v_mul_f32_e32 v83, v150, v151
	v_and_b32_e32 v151, 0xffff0000, v59
	v_and_b32_e32 v150, 0xffff0000, v51
	v_pk_fma_f32 v[154:155], v[74:75], v[84:85], v[72:73] op_sel:[1,0,1]
	v_and_b32_e32 v153, 0xffff0000, v63
	v_and_b32_e32 v152, 0xffff0000, v55
	v_pk_fma_f32 v[154:155], v[76:77], v[80:81], v[154:155] op_sel:[1,0,0]
	v_pk_mov_b32 v[84:85], v[84:85], v[150:151] op_sel:[1,0]
	v_pk_fma_f32 v[72:73], v[74:75], v[80:81], v[72:73] op_sel:[1,0,1]
	v_pk_fma_f32 v[154:155], v[66:67], v[84:85], v[154:155] op_sel:[1,0,0]
	v_pk_mov_b32 v[156:157], v[80:81], v[152:153] op_sel:[1,0]
	v_pk_fma_f32 v[72:73], v[76:77], v[84:85], v[72:73] op_sel:[1,0,0]
	v_pk_fma_f32 v[154:155], v[68:69], v[156:157], v[154:155] op_sel:[1,0,0]
	v_pk_fma_f32 v[66:67], v[66:67], v[156:157], v[72:73] op_sel:[1,0,0]
	v_pk_fma_f32 v[154:155], v[70:71], v[150:151], v[154:155] op_sel:[1,0,0]
	v_pk_fma_f32 v[66:67], v[68:69], v[150:151], v[66:67] op_sel:[1,0,0]
	v_mul_f32_e32 v158, 0xbfb8aa3b, v154
	v_mul_f32_e32 v159, 0xbfb8aa3b, v155
	v_pk_fma_f32 v[70:71], v[70:71], v[152:153], v[66:67] op_sel:[1,0,0]
	v_exp_f32_e32 v158, v158
	v_exp_f32_e32 v159, v159
	v_mul_f32_e32 v66, 0xbfb8aa3b, v70
	v_mul_f32_e32 v67, 0xbfb8aa3b, v71
	v_exp_f32_e32 v66, v66
	v_exp_f32_e32 v67, v67
	v_pk_add_f32 v[158:159], v[158:159], 1.0 op_sel_hi:[1,0]
	v_pk_add_f32 v[72:73], v[66:67], 1.0 op_sel_hi:[1,0]
	v_rcp_f32_e32 v67, v159
	s_nop 0
	v_mul_f32_e32 v66, v155, v67
	v_rcp_f32_e32 v68, v158
	s_nop 0
	v_mul_f32_e32 v67, v154, v68
	v_rcp_f32_e32 v69, v73
	s_nop 0
	v_mul_f32_e32 v68, v71, v69
	v_rcp_f32_e32 v71, v72
	s_nop 0
	v_mul_f32_e32 v69, v70, v71
	s_and_saveexec_b64 s[58:59], s[8:9]
	s_cbranch_execz .LBB0_2478
	v_bfe_u32 v70, v107, 16, 1
	v_add3_u32 v70, v107, v70, s78
	v_bfe_u32 v71, v147, 16, 1
	v_lshrrev_b32_e32 v70, 16, v70
	v_add3_u32 v71, v147, v71, s78
	v_and_or_b32 v70, v71, s87, v70
	v_bfe_u32 v71, v145, 16, 1
	v_add3_u32 v71, v145, v71, s78
	v_bfe_u32 v72, v149, 16, 1
	v_lshrrev_b32_e32 v71, 16, v71
	v_add3_u32 v72, v149, v72, s78
	v_and_or_b32 v71, v72, s87, v71
	ds_write2_b32 v141, v70, v71 offset0:1 offset1:37
	v_bfe_u32 v70, v106, 16, 1
	v_add3_u32 v70, v106, v70, s78
	v_bfe_u32 v71, v146, 16, 1
	v_lshrrev_b32_e32 v70, 16, v70
	v_add3_u32 v71, v146, v71, s78
	v_and_or_b32 v70, v71, s87, v70
	v_bfe_u32 v71, v144, 16, 1
	v_add3_u32 v71, v144, v71, s78
	v_bfe_u32 v72, v148, 16, 1
	v_lshrrev_b32_e32 v71, 16, v71
	v_add3_u32 v72, v148, v72, s78
	v_and_or_b32 v71, v72, s87, v71
	ds_write2_b32 v141, v70, v71 offset0:73 offset1:109
	v_bfe_u32 v70, v79, 16, 1
	v_add3_u32 v70, v79, v70, s78
	v_bfe_u32 v71, v67, 16, 1
	v_lshrrev_b32_e32 v70, 16, v70
	v_add3_u32 v71, v67, v71, s78
	v_and_or_b32 v70, v71, s87, v70
	v_bfe_u32 v71, v83, 16, 1
	v_add3_u32 v71, v83, v71, s78
	v_bfe_u32 v72, v69, 16, 1
	v_lshrrev_b32_e32 v71, 16, v71
	v_add3_u32 v72, v69, v72, s78
	v_and_or_b32 v71, v72, s87, v71
	ds_write2_b32 v141, v70, v71 offset0:145 offset1:181
	v_bfe_u32 v70, v78, 16, 1
	v_add3_u32 v70, v78, v70, s78
	v_bfe_u32 v71, v66, 16, 1
	v_lshrrev_b32_e32 v70, 16, v70
	v_add3_u32 v71, v66, v71, s78
	v_and_or_b32 v70, v71, s87, v70
	v_bfe_u32 v71, v82, 16, 1
	v_add3_u32 v71, v82, v71, s78
	v_bfe_u32 v72, v68, 16, 1
	v_lshrrev_b32_e32 v71, 16, v71
	v_add3_u32 v72, v68, v72, s78
	v_and_or_b32 v71, v72, s87, v71
	ds_write2_b32 v141, v70, v71 offset0:217 offset1:253

.LBB0_2480:
	s_or_b64 exec, exec, s[58:59]
	ds_read2_b64 v[74:77], v1 offset0:98 offset1:194
	ds_read2_b64 v[66:69], v89 offset0:34 offset1:130
	ds_read2_b64 v[70:73], v143 offset0:98 offset1:194
	v_lshlrev_b32_e32 v106, 16, v24
	v_lshlrev_b32_e32 v80, 16, v20
	v_lshlrev_b32_e32 v144, 16, v32
	v_mov_b32_e32 v81, v106
	v_lshlrev_b32_e32 v84, 16, v16
	s_waitcnt lgkmcnt(0)
	v_pk_fma_f32 v[80:81], v[74:75], v[80:81], v[72:73] op_sel_hi:[0,1,0]
	v_mov_b32_e32 v85, v144
	v_lshlrev_b32_e32 v107, 16, v36
	v_pk_fma_f32 v[80:81], v[76:77], v[84:85], v[80:81] op_sel_hi:[0,1,1]
	v_lshlrev_b32_e32 v145, 16, v40
	v_pk_fma_f32 v[80:81], v[66:67], v[106:107], v[80:81] op_sel_hi:[0,1,1]
	v_pk_fma_f32 v[84:85], v[74:75], v[84:85], v[72:73] op_sel_hi:[0,1,0]
	v_lshlrev_b32_e32 v83, 16, v44
	v_mov_b32_e32 v82, v107
	v_pk_fma_f32 v[80:81], v[68:69], v[144:145], v[80:81] op_sel_hi:[0,1,1]
	v_pk_fma_f32 v[84:85], v[76:77], v[106:107], v[84:85] op_sel_hi:[0,1,1]
	v_pk_fma_f32 v[80:81], v[70:71], v[82:83], v[80:81] op_sel_hi:[0,1,1]
	v_pk_fma_f32 v[84:85], v[66:67], v[144:145], v[84:85] op_sel_hi:[0,1,1]
	v_lshlrev_b32_e32 v79, 16, v48
	v_mov_b32_e32 v78, v145
	v_mul_f32_e32 v147, 0xbfb8aa3b, v80
	v_pk_fma_f32 v[84:85], v[68:69], v[82:83], v[84:85] op_sel_hi:[0,1,1]
	v_exp_f32_e32 v154, v147
	v_mul_f32_e32 v147, 0xbfb8aa3b, v81
	v_pk_fma_f32 v[84:85], v[70:71], v[78:79], v[84:85] op_sel_hi:[0,1,1]
	v_exp_f32_e32 v155, v147
	v_mul_f32_e32 v106, 0xbfb8aa3b, v84
	v_mul_f32_e32 v107, 0xbfb8aa3b, v85
	v_exp_f32_e32 v106, v106
	v_exp_f32_e32 v107, v107
	v_pk_add_f32 v[154:155], v[154:155], 1.0 op_sel_hi:[1,0]
	v_and_b32_e32 v150, 0xffff0000, v24
	v_and_b32_e32 v146, 0xffff0000, v20
	v_pk_add_f32 v[156:157], v[106:107], 1.0 op_sel_hi:[1,0]
	v_rcp_f32_e32 v107, v155
	v_and_b32_e32 v152, 0xffff0000, v32
	v_and_b32_e32 v148, 0xffff0000, v16
	v_mov_b32_e32 v149, v152
	v_mul_f32_e32 v106, v81, v107
	v_rcp_f32_e32 v107, v154
	s_nop 0
	v_mul_f32_e32 v107, v80, v107
	v_rcp_f32_e32 v81, v157
	s_nop 0
	v_mul_f32_e32 v144, v85, v81
	v_rcp_f32_e32 v81, v156
	s_nop 0
	v_mul_f32_e32 v145, v84, v81
	v_mov_b32_e32 v147, v150
	v_and_b32_e32 v84, 0xffff0000, v36
	v_pk_fma_f32 v[146:147], v[74:75], v[146:147], v[72:73] op_sel:[1,0,1]
	v_mov_b32_e32 v151, v84
	v_and_b32_e32 v80, 0xffff0000, v40
	v_pk_fma_f32 v[146:147], v[76:77], v[148:149], v[146:147] op_sel:[1,0,0]
	v_mov_b32_e32 v153, v80
	v_pk_fma_f32 v[146:147], v[66:67], v[150:151], v[146:147] op_sel:[1,0,0]
	v_and_b32_e32 v85, 0xffff0000, v44
	v_pk_fma_f32 v[146:147], v[68:69], v[152:153], v[146:147] op_sel:[1,0,0]
	v_and_b32_e32 v81, 0xffff0000, v48
	v_pk_fma_f32 v[154:155], v[70:71], v[84:85], v[146:147] op_sel:[1,0,0]
	s_nop 0
	v_mul_f32_e32 v146, 0xbfb8aa3b, v154
	v_mul_f32_e32 v147, 0xbfb8aa3b, v155
	v_exp_f32_e32 v146, v146
	v_exp_f32_e32 v147, v147
	s_nop 0
	v_pk_add_f32 v[156:157], v[146:147], 1.0 op_sel_hi:[1,0]
	v_pk_fma_f32 v[146:147], v[74:75], v[148:149], v[72:73] op_sel:[1,0,1]
	s_nop 0
	v_pk_fma_f32 v[146:147], v[76:77], v[150:151], v[146:147] op_sel:[1,0,0]
	s_nop 0
	v_pk_fma_f32 v[146:147], v[66:67], v[152:153], v[146:147] op_sel:[1,0,0]
	s_nop 0
	v_pk_fma_f32 v[146:147], v[68:69], v[84:85], v[146:147] op_sel:[1,0,0]
	s_nop 0
	v_pk_fma_f32 v[150:151], v[70:71], v[80:81], v[146:147] op_sel:[1,0,0]
	s_nop 0
	v_mul_f32_e32 v146, 0xbfb8aa3b, v150
	v_mul_f32_e32 v147, 0xbfb8aa3b, v151
	v_exp_f32_e32 v146, v146
	v_exp_f32_e32 v147, v147
	s_nop 0
	v_pk_add_f32 v[152:153], v[146:147], 1.0 op_sel_hi:[1,0]
	v_rcp_f32_e32 v147, v157
	s_nop 0
	v_mul_f32_e32 v146, v155, v147
	v_rcp_f32_e32 v148, v156
	s_nop 0
	v_mul_f32_e32 v147, v154, v148
	v_rcp_f32_e32 v149, v153
	s_nop 0
	v_mul_f32_e32 v148, v151, v149
	v_rcp_f32_e32 v151, v152
	s_nop 0
	v_mul_f32_e32 v149, v150, v151
	v_lshlrev_b32_e32 v150, 16, v52
	v_lshlrev_b32_e32 v151, 16, v60
	v_lshlrev_b32_e32 v152, 16, v56
	v_lshlrev_b32_e32 v153, 16, v64
	v_pk_fma_f32 v[154:155], v[74:75], v[82:83], v[72:73] op_sel_hi:[0,1,0]
	v_pk_fma_f32 v[154:155], v[76:77], v[78:79], v[154:155] op_sel_hi:[0,1,1]
	v_pk_mov_b32 v[82:83], v[82:83], v[150:151] op_sel:[1,0]
	v_pk_mov_b32 v[156:157], v[78:79], v[152:153] op_sel:[1,0]
	v_pk_fma_f32 v[78:79], v[74:75], v[78:79], v[72:73] op_sel_hi:[0,1,0]
	v_pk_fma_f32 v[154:155], v[66:67], v[82:83], v[154:155] op_sel_hi:[0,1,1]
	v_pk_fma_f32 v[78:79], v[76:77], v[82:83], v[78:79] op_sel_hi:[0,1,1]
	v_pk_fma_f32 v[154:155], v[68:69], v[156:157], v[154:155] op_sel_hi:[0,1,1]
	v_pk_fma_f32 v[78:79], v[66:67], v[156:157], v[78:79] op_sel_hi:[0,1,1]
	v_pk_fma_f32 v[154:155], v[70:71], v[150:151], v[154:155] op_sel_hi:[0,1,1]
	v_pk_fma_f32 v[78:79], v[68:69], v[150:151], v[78:79] op_sel_hi:[0,1,1]
	v_mul_f32_e32 v158, 0xbfb8aa3b, v154
	v_mul_f32_e32 v159, 0xbfb8aa3b, v155
	v_pk_fma_f32 v[150:151], v[70:71], v[152:153], v[78:79] op_sel_hi:[0,1,1]
	v_exp_f32_e32 v158, v158
	v_exp_f32_e32 v159, v159
	v_mul_f32_e32 v78, 0xbfb8aa3b, v150
	v_mul_f32_e32 v79, 0xbfb8aa3b, v151
	v_exp_f32_e32 v78, v78
	v_exp_f32_e32 v79, v79
	v_pk_add_f32 v[158:159], v[158:159], 1.0 op_sel_hi:[1,0]
	v_pk_add_f32 v[152:153], v[78:79], 1.0 op_sel_hi:[1,0]
	v_rcp_f32_e32 v79, v159
	s_nop 0
	v_mul_f32_e32 v78, v155, v79
	v_rcp_f32_e32 v82, v158
	s_nop 0
	v_mul_f32_e32 v79, v154, v82
	v_rcp_f32_e32 v83, v153
	s_nop 0
	v_mul_f32_e32 v82, v151, v83
	v_rcp_f32_e32 v151, v152
	s_nop 0
	v_mul_f32_e32 v83, v150, v151
	v_and_b32_e32 v151, 0xffff0000, v60
	v_and_b32_e32 v150, 0xffff0000, v52
	v_pk_fma_f32 v[154:155], v[74:75], v[84:85], v[72:73] op_sel:[1,0,1]
	v_and_b32_e32 v153, 0xffff0000, v64
	v_and_b32_e32 v152, 0xffff0000, v56
	v_pk_fma_f32 v[154:155], v[76:77], v[80:81], v[154:155] op_sel:[1,0,0]
	v_pk_mov_b32 v[84:85], v[84:85], v[150:151] op_sel:[1,0]
	v_pk_fma_f32 v[72:73], v[74:75], v[80:81], v[72:73] op_sel:[1,0,1]
	v_pk_fma_f32 v[154:155], v[66:67], v[84:85], v[154:155] op_sel:[1,0,0]
	v_pk_mov_b32 v[156:157], v[80:81], v[152:153] op_sel:[1,0]
	v_pk_fma_f32 v[72:73], v[76:77], v[84:85], v[72:73] op_sel:[1,0,0]
	v_pk_fma_f32 v[154:155], v[68:69], v[156:157], v[154:155] op_sel:[1,0,0]
	v_pk_fma_f32 v[66:67], v[66:67], v[156:157], v[72:73] op_sel:[1,0,0]
	v_pk_fma_f32 v[154:155], v[70:71], v[150:151], v[154:155] op_sel:[1,0,0]
	v_pk_fma_f32 v[66:67], v[68:69], v[150:151], v[66:67] op_sel:[1,0,0]
	v_mul_f32_e32 v158, 0xbfb8aa3b, v154
	v_mul_f32_e32 v159, 0xbfb8aa3b, v155
	v_pk_fma_f32 v[70:71], v[70:71], v[152:153], v[66:67] op_sel:[1,0,0]
	v_exp_f32_e32 v158, v158
	v_exp_f32_e32 v159, v159
	v_mul_f32_e32 v66, 0xbfb8aa3b, v70
	v_mul_f32_e32 v67, 0xbfb8aa3b, v71
	v_exp_f32_e32 v66, v66
	v_exp_f32_e32 v67, v67
	v_pk_add_f32 v[158:159], v[158:159], 1.0 op_sel_hi:[1,0]
	v_pk_add_f32 v[72:73], v[66:67], 1.0 op_sel_hi:[1,0]
	v_rcp_f32_e32 v67, v159
	s_nop 0
	v_mul_f32_e32 v66, v155, v67
	v_rcp_f32_e32 v68, v158
	s_nop 0
	v_mul_f32_e32 v67, v154, v68
	v_rcp_f32_e32 v69, v73
	s_nop 0
	v_mul_f32_e32 v68, v71, v69
	v_rcp_f32_e32 v71, v72
	s_nop 0
	v_mul_f32_e32 v69, v70, v71
	s_and_saveexec_b64 s[58:59], s[8:9]
	s_cbranch_execz .LBB0_2482
	v_bfe_u32 v70, v107, 16, 1
	v_add3_u32 v70, v107, v70, s78
	v_bfe_u32 v71, v147, 16, 1
	v_lshrrev_b32_e32 v70, 16, v70
	v_add3_u32 v71, v147, v71, s78
	v_and_or_b32 v70, v71, s87, v70
	v_bfe_u32 v71, v145, 16, 1
	v_add3_u32 v71, v145, v71, s78
	v_bfe_u32 v72, v149, 16, 1
	v_lshrrev_b32_e32 v71, 16, v71
	v_add3_u32 v72, v149, v72, s78
	v_and_or_b32 v71, v72, s87, v71
	ds_write2_b32 v141, v70, v71 offset0:2 offset1:38
	v_bfe_u32 v70, v106, 16, 1
	v_add3_u32 v70, v106, v70, s78
	v_bfe_u32 v71, v146, 16, 1
	v_lshrrev_b32_e32 v70, 16, v70
	v_add3_u32 v71, v146, v71, s78
	v_and_or_b32 v70, v71, s87, v70
	v_bfe_u32 v71, v144, 16, 1
	v_add3_u32 v71, v144, v71, s78
	v_bfe_u32 v72, v148, 16, 1
	v_lshrrev_b32_e32 v71, 16, v71
	v_add3_u32 v72, v148, v72, s78
	v_and_or_b32 v71, v72, s87, v71
	ds_write2_b32 v141, v70, v71 offset0:74 offset1:110
	v_bfe_u32 v70, v79, 16, 1
	v_add3_u32 v70, v79, v70, s78
	v_bfe_u32 v71, v67, 16, 1
	v_lshrrev_b32_e32 v70, 16, v70
	v_add3_u32 v71, v67, v71, s78
	v_and_or_b32 v70, v71, s87, v70
	v_bfe_u32 v71, v83, 16, 1
	v_add3_u32 v71, v83, v71, s78
	v_bfe_u32 v72, v69, 16, 1
	v_lshrrev_b32_e32 v71, 16, v71
	v_add3_u32 v72, v69, v72, s78
	v_and_or_b32 v71, v72, s87, v71
	ds_write2_b32 v141, v70, v71 offset0:146 offset1:182
	v_bfe_u32 v70, v78, 16, 1
	v_add3_u32 v70, v78, v70, s78
	v_bfe_u32 v71, v66, 16, 1
	v_lshrrev_b32_e32 v70, 16, v70
	v_add3_u32 v71, v66, v71, s78
	v_and_or_b32 v70, v71, s87, v70
	v_bfe_u32 v71, v82, 16, 1
	v_add3_u32 v71, v82, v71, s78
	v_bfe_u32 v72, v68, 16, 1
	v_lshrrev_b32_e32 v71, 16, v71
	v_add3_u32 v72, v68, v72, s78
	v_and_or_b32 v71, v72, s87, v71
	ds_write2_b32 v141, v70, v71 offset0:218 offset1:254

.LBB0_2484:
	s_or_b64 exec, exec, s[58:59]
	ds_read2_b64 v[74:77], v1 offset0:99 offset1:195
	ds_read2_b64 v[66:69], v89 offset0:35 offset1:131
	ds_read2_b64 v[70:73], v143 offset0:99 offset1:195
	v_lshlrev_b32_e32 v106, 16, v25
	v_lshlrev_b32_e32 v80, 16, v21
	v_lshlrev_b32_e32 v150, 16, v33
	v_mov_b32_e32 v81, v106
	v_lshlrev_b32_e32 v84, 16, v17
	s_waitcnt lgkmcnt(0)
	v_pk_fma_f32 v[80:81], v[74:75], v[80:81], v[72:73] op_sel_hi:[0,1,0]
	v_mov_b32_e32 v85, v150
	v_lshlrev_b32_e32 v107, 16, v37
	v_pk_fma_f32 v[80:81], v[76:77], v[84:85], v[80:81] op_sel_hi:[0,1,1]
	v_lshlrev_b32_e32 v151, 16, v41
	v_pk_fma_f32 v[80:81], v[66:67], v[106:107], v[80:81] op_sel_hi:[0,1,1]
	v_lshlrev_b32_e32 v83, 16, v45
	v_mov_b32_e32 v82, v107
	v_pk_fma_f32 v[80:81], v[68:69], v[150:151], v[80:81] op_sel_hi:[0,1,1]
	v_pk_fma_f32 v[80:81], v[70:71], v[82:83], v[80:81] op_sel_hi:[0,1,1]
	v_mul_f32_e32 v1, 0xbfb8aa3b, v80
	v_pk_fma_f32 v[84:85], v[74:75], v[84:85], v[72:73] op_sel_hi:[0,1,0]
	v_exp_f32_e32 v154, v1
	v_mul_f32_e32 v1, 0xbfb8aa3b, v81
	v_pk_fma_f32 v[84:85], v[76:77], v[106:107], v[84:85] op_sel_hi:[0,1,1]
	v_exp_f32_e32 v155, v1
	v_pk_fma_f32 v[84:85], v[66:67], v[150:151], v[84:85] op_sel_hi:[0,1,1]
	v_lshlrev_b32_e32 v79, 16, v49
	v_mov_b32_e32 v78, v151
	v_pk_fma_f32 v[84:85], v[68:69], v[82:83], v[84:85] op_sel_hi:[0,1,1]
	v_pk_fma_f32 v[84:85], v[70:71], v[78:79], v[84:85] op_sel_hi:[0,1,1]
	v_mul_f32_e32 v1, 0xbfb8aa3b, v84
	v_pk_add_f32 v[154:155], v[154:155], 1.0 op_sel_hi:[1,0]
	v_exp_f32_e32 v106, v1
	v_mul_f32_e32 v1, 0xbfb8aa3b, v85
	v_exp_f32_e32 v107, v1
	v_rcp_f32_e32 v89, v155
	v_pk_add_f32 v[150:151], v[106:107], 1.0 op_sel_hi:[1,0]
	v_and_b32_e32 v148, 0xffff0000, v25
	v_and_b32_e32 v144, 0xffff0000, v21
	v_mul_f32_e32 v1, v81, v89
	v_rcp_f32_e32 v89, v154
	v_and_b32_e32 v152, 0xffff0000, v33
	v_mov_b32_e32 v145, v148
	v_and_b32_e32 v146, 0xffff0000, v17
	v_mul_f32_e32 v89, v80, v89
	v_rcp_f32_e32 v81, v151
	v_pk_fma_f32 v[144:145], v[74:75], v[144:145], v[72:73] op_sel:[1,0,1]
	v_mov_b32_e32 v147, v152
	v_pk_fma_f32 v[144:145], v[76:77], v[146:147], v[144:145] op_sel:[1,0,0]
	v_mul_f32_e32 v106, v85, v81
	v_rcp_f32_e32 v81, v150
	v_pk_fma_f32 v[146:147], v[74:75], v[146:147], v[72:73] op_sel:[1,0,1]
	v_mul_f32_e32 v107, v84, v81
	v_and_b32_e32 v84, 0xffff0000, v37
	v_mov_b32_e32 v149, v84
	v_and_b32_e32 v80, 0xffff0000, v41
	v_mov_b32_e32 v153, v80
	v_pk_fma_f32 v[144:145], v[66:67], v[148:149], v[144:145] op_sel:[1,0,0]
	v_and_b32_e32 v85, 0xffff0000, v45
	v_pk_fma_f32 v[144:145], v[68:69], v[152:153], v[144:145] op_sel:[1,0,0]
	v_pk_fma_f32 v[146:147], v[76:77], v[148:149], v[146:147] op_sel:[1,0,0]
	v_pk_fma_f32 v[144:145], v[70:71], v[84:85], v[144:145] op_sel:[1,0,0]
	v_pk_fma_f32 v[146:147], v[66:67], v[152:153], v[146:147] op_sel:[1,0,0]
	v_mul_f32_e32 v143, 0xbfb8aa3b, v144
	v_exp_f32_e32 v150, v143
	v_mul_f32_e32 v143, 0xbfb8aa3b, v145
	v_exp_f32_e32 v151, v143
	v_and_b32_e32 v81, 0xffff0000, v49
	v_pk_fma_f32 v[146:147], v[68:69], v[84:85], v[146:147] op_sel:[1,0,0]
	v_pk_add_f32 v[150:151], v[150:151], 1.0 op_sel_hi:[1,0]
	v_pk_fma_f32 v[146:147], v[70:71], v[80:81], v[146:147] op_sel:[1,0,0]
	s_nop 0
	v_mul_f32_e32 v143, 0xbfb8aa3b, v146
	v_exp_f32_e32 v148, v143
	v_mul_f32_e32 v143, 0xbfb8aa3b, v147
	v_exp_f32_e32 v149, v143
	v_rcp_f32_e32 v152, v151
	v_pk_add_f32 v[148:149], v[148:149], 1.0 op_sel_hi:[1,0]
	v_mul_f32_e32 v143, v145, v152
	v_rcp_f32_e32 v151, v150
	s_nop 0
	v_mul_f32_e32 v144, v144, v151
	v_rcp_f32_e32 v150, v149
	s_nop 0
	v_mul_f32_e32 v145, v147, v150
	v_rcp_f32_e32 v149, v148
	s_nop 0
	v_mul_f32_e32 v146, v146, v149
	v_lshlrev_b32_e32 v148, 16, v53
	v_lshlrev_b32_e32 v149, 16, v61
	v_pk_fma_f32 v[152:153], v[74:75], v[82:83], v[72:73] op_sel_hi:[0,1,0]
	v_lshlrev_b32_e32 v150, 16, v57
	v_lshlrev_b32_e32 v151, 16, v65
	v_pk_fma_f32 v[152:153], v[76:77], v[78:79], v[152:153] op_sel_hi:[0,1,1]
	v_pk_mov_b32 v[82:83], v[82:83], v[148:149] op_sel:[1,0]
	v_pk_mov_b32 v[154:155], v[78:79], v[150:151] op_sel:[1,0]
	v_pk_fma_f32 v[152:153], v[66:67], v[82:83], v[152:153] op_sel_hi:[0,1,1]
	v_pk_fma_f32 v[78:79], v[74:75], v[78:79], v[72:73] op_sel_hi:[0,1,0]
	v_pk_fma_f32 v[152:153], v[68:69], v[154:155], v[152:153] op_sel_hi:[0,1,1]
	v_pk_fma_f32 v[78:79], v[76:77], v[82:83], v[78:79] op_sel_hi:[0,1,1]
	v_pk_fma_f32 v[152:153], v[70:71], v[148:149], v[152:153] op_sel_hi:[0,1,1]
	v_pk_fma_f32 v[78:79], v[66:67], v[154:155], v[78:79] op_sel_hi:[0,1,1]
	v_mul_f32_e32 v147, 0xbfb8aa3b, v152
	v_pk_fma_f32 v[78:79], v[68:69], v[148:149], v[78:79] op_sel_hi:[0,1,1]
	v_exp_f32_e32 v156, v147
	v_mul_f32_e32 v147, 0xbfb8aa3b, v153
	v_pk_fma_f32 v[148:149], v[70:71], v[150:151], v[78:79] op_sel_hi:[0,1,1]
	v_exp_f32_e32 v157, v147
	v_mul_f32_e32 v78, 0xbfb8aa3b, v148
	v_mul_f32_e32 v79, 0xbfb8aa3b, v149
	v_exp_f32_e32 v78, v78
	v_exp_f32_e32 v79, v79
	v_pk_add_f32 v[156:157], v[156:157], 1.0 op_sel_hi:[1,0]
	v_pk_add_f32 v[150:151], v[78:79], 1.0 op_sel_hi:[1,0]
	v_rcp_f32_e32 v79, v157
	s_nop 0
	v_mul_f32_e32 v78, v153, v79
	v_rcp_f32_e32 v82, v156
	s_nop 0
	v_mul_f32_e32 v79, v152, v82
	v_rcp_f32_e32 v83, v151
	s_nop 0
	v_mul_f32_e32 v82, v149, v83
	v_rcp_f32_e32 v147, v150
	s_nop 0
	v_mul_f32_e32 v83, v148, v147
	v_and_b32_e32 v149, 0xffff0000, v61
	v_and_b32_e32 v148, 0xffff0000, v53
	v_pk_fma_f32 v[152:153], v[74:75], v[84:85], v[72:73] op_sel:[1,0,1]
	v_and_b32_e32 v151, 0xffff0000, v65
	v_and_b32_e32 v150, 0xffff0000, v57
	v_pk_fma_f32 v[152:153], v[76:77], v[80:81], v[152:153] op_sel:[1,0,0]
	v_pk_mov_b32 v[84:85], v[84:85], v[148:149] op_sel:[1,0]
	v_pk_mov_b32 v[154:155], v[80:81], v[150:151] op_sel:[1,0]
	v_pk_fma_f32 v[152:153], v[66:67], v[84:85], v[152:153] op_sel:[1,0,0]
	v_pk_fma_f32 v[72:73], v[74:75], v[80:81], v[72:73] op_sel:[1,0,1]
	v_pk_fma_f32 v[152:153], v[68:69], v[154:155], v[152:153] op_sel:[1,0,0]
	v_pk_fma_f32 v[72:73], v[76:77], v[84:85], v[72:73] op_sel:[1,0,0]
	v_pk_fma_f32 v[152:153], v[70:71], v[148:149], v[152:153] op_sel:[1,0,0]
	v_pk_fma_f32 v[66:67], v[66:67], v[154:155], v[72:73] op_sel:[1,0,0]
	v_mul_f32_e32 v147, 0xbfb8aa3b, v152
	v_pk_fma_f32 v[66:67], v[68:69], v[148:149], v[66:67] op_sel:[1,0,0]
	v_exp_f32_e32 v156, v147
	v_mul_f32_e32 v147, 0xbfb8aa3b, v153
	v_pk_fma_f32 v[70:71], v[70:71], v[150:151], v[66:67] op_sel:[1,0,0]
	v_exp_f32_e32 v157, v147
	v_mul_f32_e32 v66, 0xbfb8aa3b, v70
	v_mul_f32_e32 v67, 0xbfb8aa3b, v71
	v_exp_f32_e32 v66, v66
	v_exp_f32_e32 v67, v67
	v_pk_add_f32 v[156:157], v[156:157], 1.0 op_sel_hi:[1,0]
	v_pk_add_f32 v[72:73], v[66:67], 1.0 op_sel_hi:[1,0]
	v_rcp_f32_e32 v67, v157
	s_nop 0
	v_mul_f32_e32 v66, v153, v67
	v_rcp_f32_e32 v68, v156
	s_nop 0
	v_mul_f32_e32 v67, v152, v68
	v_rcp_f32_e32 v69, v73
	s_nop 0
	v_mul_f32_e32 v68, v71, v69
	v_rcp_f32_e32 v71, v72
	s_nop 0
	v_mul_f32_e32 v69, v70, v71
	s_and_saveexec_b64 s[58:59], s[8:9]
	s_cbranch_execz .LBB0_2486
	v_bfe_u32 v70, v89, 16, 1
	v_add3_u32 v70, v89, v70, s78
	v_bfe_u32 v71, v144, 16, 1
	v_lshrrev_b32_e32 v70, 16, v70
	v_add3_u32 v71, v144, v71, s78
	v_and_or_b32 v70, v71, s87, v70
	v_bfe_u32 v71, v107, 16, 1
	v_add3_u32 v71, v107, v71, s78
	v_bfe_u32 v72, v146, 16, 1
	v_lshrrev_b32_e32 v71, 16, v71
	v_add3_u32 v72, v146, v72, s78
	v_and_or_b32 v71, v72, s87, v71
	ds_write2_b32 v141, v70, v71 offset0:3 offset1:39
	v_bfe_u32 v70, v1, 16, 1
	v_add3_u32 v70, v1, v70, s78
	v_bfe_u32 v71, v143, 16, 1
	v_lshrrev_b32_e32 v70, 16, v70
	v_add3_u32 v71, v143, v71, s78
	v_and_or_b32 v70, v71, s87, v70
	v_bfe_u32 v71, v106, 16, 1
	v_add3_u32 v71, v106, v71, s78
	v_bfe_u32 v72, v145, 16, 1
	v_lshrrev_b32_e32 v71, 16, v71
	v_add3_u32 v72, v145, v72, s78
	v_and_or_b32 v71, v72, s87, v71
	ds_write2_b32 v141, v70, v71 offset0:75 offset1:111
	v_bfe_u32 v70, v79, 16, 1
	v_add3_u32 v70, v79, v70, s78
	v_bfe_u32 v71, v67, 16, 1
	v_lshrrev_b32_e32 v70, 16, v70
	v_add3_u32 v71, v67, v71, s78
	v_and_or_b32 v70, v71, s87, v70
	v_bfe_u32 v71, v83, 16, 1
	v_add3_u32 v71, v83, v71, s78
	v_bfe_u32 v72, v69, 16, 1
	v_lshrrev_b32_e32 v71, 16, v71
	v_add3_u32 v72, v69, v72, s78
	v_and_or_b32 v71, v72, s87, v71
	ds_write2_b32 v141, v70, v71 offset0:147 offset1:183
	v_bfe_u32 v70, v78, 16, 1
	v_add3_u32 v70, v78, v70, s78
	v_bfe_u32 v71, v66, 16, 1
	v_lshrrev_b32_e32 v70, 16, v70
	v_add3_u32 v71, v66, v71, s78
	v_and_or_b32 v70, v71, s87, v70
	v_bfe_u32 v71, v82, 16, 1
	v_add3_u32 v71, v82, v71, s78
	v_bfe_u32 v72, v68, 16, 1
	v_lshrrev_b32_e32 v71, 16, v71
	v_add3_u32 v72, v68, v72, s78
	v_and_or_b32 v71, v72, s87, v71
	ds_write2_b32 v141, v70, v71 offset0:219 offset1:255

.LBB0_2489:
	s_or_b64 exec, exec, s[0:1]
	v_add_u32_e32 v1, v113, v114
	s_waitcnt lgkmcnt(0)
	s_barrier
	s_add_i32 s98, s71, 64
	s_cmp_ge_u32 s98, s2
	s_cbranch_scc1 .Lssd1_pf_done
	s_and_saveexec_b64 s[100:101], s[4:5]
	s_xor_b64 s[100:101], exec, s[100:101]
	s_cbranch_execz .Lssd1_pf_conv
	v_add_u32_e32 v242, s71, v136
	v_add_u32_e32 v243, s84, v137
	v_cndmask_b32_e64 v242, v243, v242, s[6:7]
	v_add_u32_e32 v242, s33, v242
	v_mad_i64_i32 v[242:243], vcc, v242, s86, v[104:105]
	global_load_ushort v62, v[242:243], off offset:3328
.Lssd1_pf_conv:
	s_andn2_saveexec_b64 s[100:101], s[100:101]
	s_cbranch_execz .Lssd1_pf_end
	v_add_u32_e32 v242, s71, v110
	v_add_u32_e32 v243, s84, v135
	v_add_u32_e32 v244, 62, v242
	v_cmp_gt_u32_e32 vcc, s2, v244
	v_mov_b32_e32 v18, 0
	v_mov_b32_e32 v19, 0
	v_mov_b32_e32 v20, 0
	v_mov_b32_e32 v21, 0
	s_and_saveexec_b64 s[98:99], vcc
	s_cbranch_execz .Lssd1_pf_0
	v_subrev_u32_e32 v245, 63, v243
	v_cndmask_b32_e64 v244, v245, v244, s[6:7]
	v_add_u32_e32 v244, s33, v244
	v_mad_i64_i32 v[18:19], vcc, v244, s86, v[100:101]
	global_load_dwordx4 v[18:21], v[18:19], off
.Lssd1_pf_0:
	s_or_b64 exec, exec, s[98:99]
	v_add_u32_e32 v244, 63, v242
	v_cmp_gt_u32_e32 vcc, s2, v244
	v_mov_b32_e32 v14, 0
	v_mov_b32_e32 v15, 0
	v_mov_b32_e32 v16, 0
	v_mov_b32_e32 v17, 0
	s_and_saveexec_b64 s[98:99], vcc
	s_cbranch_execz .Lssd1_pf_1
	v_subrev_u32_e32 v245, 64, v243
	v_cndmask_b32_e64 v244, v245, v244, s[6:7]
	v_add_u32_e32 v244, s33, v244
	v_mad_i64_i32 v[14:15], vcc, v244, s86, v[100:101]
	global_load_dwordx4 v[14:17], v[14:15], off
.Lssd1_pf_1:
	s_or_b64 exec, exec, s[98:99]
	v_add_u32_e32 v244, 64, v242
	v_cmp_gt_u32_e32 vcc, s2, v244
	v_mov_b32_e32 v22, 0
	v_mov_b32_e32 v23, 0
	v_mov_b32_e32 v24, 0
	v_mov_b32_e32 v25, 0
	s_and_saveexec_b64 s[98:99], vcc
	s_cbranch_execz .Lssd1_pf_2
	v_subrev_u32_e32 v245, 65, v243
	v_cndmask_b32_e64 v244, v245, v244, s[6:7]
	v_add_u32_e32 v244, s33, v244
	v_mad_i64_i32 v[22:23], vcc, v244, s86, v[100:101]
	global_load_dwordx4 v[22:25], v[22:23], off
.Lssd1_pf_2:
	s_or_b64 exec, exec, s[98:99]
	v_add_u32_e32 v244, 65, v242
	v_cmp_gt_u32_e32 vcc, s2, v244
	v_mov_b32_e32 v30, 0
	v_mov_b32_e32 v31, 0
	v_mov_b32_e32 v32, 0
	v_mov_b32_e32 v33, 0
	s_and_saveexec_b64 s[98:99], vcc
	s_cbranch_execz .Lssd1_pf_3
	v_subrev_u32_e32 v245, 66, v243
	v_cndmask_b32_e64 v244, v245, v244, s[6:7]
	v_add_u32_e32 v244, s33, v244
	v_mad_i64_i32 v[30:31], vcc, v244, s86, v[100:101]
	global_load_dwordx4 v[30:33], v[30:31], off
.Lssd1_pf_3:
	s_or_b64 exec, exec, s[98:99]
	v_add_u32_e32 v244, 66, v242
	v_cmp_gt_u32_e32 vcc, s2, v244
	v_mov_b32_e32 v34, 0
	v_mov_b32_e32 v35, 0
	v_mov_b32_e32 v36, 0
	v_mov_b32_e32 v37, 0
	s_and_saveexec_b64 s[98:99], vcc
	s_cbranch_execz .Lssd1_pf_4
	v_subrev_u32_e32 v245, 67, v243
	v_cndmask_b32_e64 v244, v245, v244, s[6:7]
	v_add_u32_e32 v244, s33, v244
	v_mad_i64_i32 v[34:35], vcc, v244, s86, v[100:101]
	global_load_dwordx4 v[34:37], v[34:35], off
.Lssd1_pf_4:
	s_or_b64 exec, exec, s[98:99]
	v_add_u32_e32 v244, 67, v242
	v_cmp_gt_u32_e32 vcc, s2, v244
	v_mov_b32_e32 v38, 0
	v_mov_b32_e32 v39, 0
	v_mov_b32_e32 v40, 0
	v_mov_b32_e32 v41, 0
	s_and_saveexec_b64 s[98:99], vcc
	s_cbranch_execz .Lssd1_pf_5
	v_subrev_u32_e32 v245, 68, v243
	v_cndmask_b32_e64 v244, v245, v244, s[6:7]
	v_add_u32_e32 v244, s33, v244
	v_mad_i64_i32 v[38:39], vcc, v244, s86, v[100:101]
	global_load_dwordx4 v[38:41], v[38:39], off
.Lssd1_pf_5:
	s_or_b64 exec, exec, s[98:99]
	v_add_u32_e32 v244, 68, v242
	v_cmp_gt_u32_e32 vcc, s2, v244
	v_mov_b32_e32 v42, 0
	v_mov_b32_e32 v43, 0
	v_mov_b32_e32 v44, 0
	v_mov_b32_e32 v45, 0
	s_and_saveexec_b64 s[98:99], vcc
	s_cbranch_execz .Lssd1_pf_6
	v_subrev_u32_e32 v245, 69, v243
	v_cndmask_b32_e64 v244, v245, v244, s[6:7]
	v_add_u32_e32 v244, s33, v244
	v_mad_i64_i32 v[42:43], vcc, v244, s86, v[100:101]
	global_load_dwordx4 v[42:45], v[42:43], off
.Lssd1_pf_6:
	s_or_b64 exec, exec, s[98:99]
	v_add_u32_e32 v244, 69, v242
	v_cmp_gt_u32_e32 vcc, s2, v244
	v_mov_b32_e32 v46, 0
	v_mov_b32_e32 v47, 0
	v_mov_b32_e32 v48, 0
	v_mov_b32_e32 v49, 0
	s_and_saveexec_b64 s[98:99], vcc
	s_cbranch_execz .Lssd1_pf_7
	v_subrev_u32_e32 v245, 70, v243
	v_cndmask_b32_e64 v244, v245, v244, s[6:7]
	v_add_u32_e32 v244, s33, v244
	v_mad_i64_i32 v[46:47], vcc, v244, s86, v[100:101]
	global_load_dwordx4 v[46:49], v[46:47], off
.Lssd1_pf_7:
	s_or_b64 exec, exec, s[98:99]
	v_add_u32_e32 v244, 70, v242
	v_cmp_gt_u32_e32 vcc, s2, v244
	v_mov_b32_e32 v50, 0
	v_mov_b32_e32 v51, 0
	v_mov_b32_e32 v52, 0
	v_mov_b32_e32 v53, 0
	s_and_saveexec_b64 s[98:99], vcc
	s_cbranch_execz .Lssd1_pf_8
	v_subrev_u32_e32 v245, 71, v243
	v_cndmask_b32_e64 v244, v245, v244, s[6:7]
	v_add_u32_e32 v244, s33, v244
	v_mad_i64_i32 v[50:51], vcc, v244, s86, v[100:101]
	global_load_dwordx4 v[50:53], v[50:51], off
.Lssd1_pf_8:
	s_or_b64 exec, exec, s[98:99]
	v_add_u32_e32 v244, 71, v242
	v_cmp_gt_u32_e32 vcc, s2, v244
	v_mov_b32_e32 v54, 0
	v_mov_b32_e32 v55, 0
	v_mov_b32_e32 v56, 0
	v_mov_b32_e32 v57, 0
	s_and_saveexec_b64 s[98:99], vcc
	s_cbranch_execz .Lssd1_pf_9
	v_subrev_u32_e32 v245, 72, v243
	v_cndmask_b32_e64 v244, v245, v244, s[6:7]
	v_add_u32_e32 v244, s33, v244
	v_mad_i64_i32 v[54:55], vcc, v244, s86, v[100:101]
	global_load_dwordx4 v[54:57], v[54:55], off
.Lssd1_pf_9:
	s_or_b64 exec, exec, s[98:99]
	v_add_u32_e32 v244, 72, v242
	v_cmp_gt_u32_e32 vcc, s2, v244
	v_mov_b32_e32 v58, 0
	v_mov_b32_e32 v59, 0
	v_mov_b32_e32 v60, 0
	v_mov_b32_e32 v61, 0
	s_and_saveexec_b64 s[98:99], vcc
	s_cbranch_execz .Lssd1_pf_10
	v_subrev_u32_e32 v245, 73, v243
	v_cndmask_b32_e64 v244, v245, v244, s[6:7]
	v_add_u32_e32 v244, s33, v244
	v_mad_i64_i32 v[58:59], vcc, v244, s86, v[100:101]
	global_load_dwordx4 v[58:61], v[58:59], off
.Lssd1_pf_10:
	s_or_b64 exec, exec, s[98:99]
	v_add_u32_e32 v244, 73, v242
	v_cmp_gt_u32_e32 vcc, s2, v244
	v_mov_b32_e32 v62, 0
	v_mov_b32_e32 v63, 0
	v_mov_b32_e32 v64, 0
	v_mov_b32_e32 v65, 0
	s_and_saveexec_b64 s[98:99], vcc
	s_cbranch_execz .Lssd1_pf_11
	v_subrev_u32_e32 v245, 74, v243
	v_cndmask_b32_e64 v244, v245, v244, s[6:7]
	v_add_u32_e32 v244, s33, v244
	v_mad_i64_i32 v[62:63], vcc, v244, s86, v[100:101]
	global_load_dwordx4 v[62:65], v[62:63], off

.Lssd1_pf_done:
	ds_read_b128 v[70:73], v1
	ds_read_b128 v[66:69], v1 offset:64
	ds_read_b128 v[74:77], v142 offset:9216
	ds_read_b128 v[78:81], v142 offset:9280
	s_waitcnt lgkmcnt(1)
	v_mfma_f32_16x16x32_bf16 v[74:77], v[70:73], v[74:77], 0
	v_add_u32_e32 v89, 0xb400, v92
	s_add_i32 s73, s71, 64
	s_cmp_ge_u32 s73, s2
	s_waitcnt lgkmcnt(0)
	v_mfma_f32_16x16x32_bf16 v[144:147], v[66:69], v[78:81], v[74:77]
	ds_read_b128 v[78:81], v142 offset:11584
	s_nop 1
	ds_read_b128 v[74:77], v142 offset:11520
	s_waitcnt lgkmcnt(0)
	v_mfma_f32_16x16x32_bf16 v[74:77], v[70:73], v[74:77], 0
	v_mfma_f32_16x16x32_bf16 v[148:151], v[66:69], v[78:81], v[74:77]
	ds_read_b128 v[78:81], v142 offset:13888
	s_nop 5
	ds_read_b128 v[74:77], v142 offset:13824
	s_waitcnt lgkmcnt(0)
	v_mfma_f32_16x16x32_bf16 v[74:77], v[70:73], v[74:77], 0
	v_mfma_f32_16x16x32_bf16 v[82:85], v[66:69], v[78:81], v[74:77]
	ds_read_b128 v[78:81], v142 offset:16192
	s_nop 5
	ds_read_b128 v[74:77], v142 offset:16128
	s_waitcnt lgkmcnt(0)
	v_mfma_f32_16x16x32_bf16 v[74:77], v[70:73], v[74:77], 0
	v_mfma_f32_16x16x32_bf16 v[78:81], v[66:69], v[78:81], v[74:77]
	s_nop 6
	ds_read_b128 v[74:77], v140 offset:46080
	ds_read2_b32 v[106:107], v89 offset1:16
	ds_read2_b32 v[152:153], v89 offset0:64 offset1:80
	s_waitcnt lgkmcnt(1)
	v_sub_f32_e32 v143, v74, v106
	v_mul_f32_e32 v143, 0x3fb8aa3b, v143
	v_exp_f32_e32 v143, v143
	s_waitcnt lgkmcnt(0)
	v_mul_f32_e32 v143, v152, v143
	v_cndmask_b32_e64 v143, v143, 0, s[24:25]
	v_mul_f32_e32 v143, v144, v143
	v_bfe_u32 v144, v143, 16, 1
	v_add3_u32 v143, v143, v144, s78
	ds_write_b16_d16_hi v93, v143
	v_sub_f32_e32 v143, v75, v106
	v_mul_f32_e32 v143, 0x3fb8aa3b, v143
	v_exp_f32_e32 v143, v143
	s_nop 0
	v_mul_f32_e32 v143, v152, v143
	v_cndmask_b32_e64 v143, v143, 0, s[26:27]
	v_mul_f32_e32 v143, v145, v143
	v_bfe_u32 v144, v143, 16, 1
	v_add3_u32 v143, v143, v144, s78
	ds_write_b16_d16_hi v93, v143 offset:144
	v_sub_f32_e32 v143, v76, v106
	v_mul_f32_e32 v143, 0x3fb8aa3b, v143
	v_exp_f32_e32 v143, v143
	v_sub_f32_e32 v106, v77, v106
	v_mul_f32_e32 v106, 0x3fb8aa3b, v106
	v_exp_f32_e32 v106, v106
	v_mul_f32_e32 v143, v152, v143
	v_cndmask_b32_e64 v143, v143, 0, s[28:29]
	v_mul_f32_e32 v143, v146, v143
	v_mul_f32_e32 v106, v152, v106
	v_bfe_u32 v144, v143, 16, 1
	v_cndmask_b32_e64 v106, v106, 0, s[30:31]
	v_add3_u32 v143, v143, v144, s78
	v_mul_f32_e32 v106, v147, v106
	ds_write_b16_d16_hi v93, v143 offset:288
	v_bfe_u32 v143, v106, 16, 1
	v_add3_u32 v106, v106, v143, s78
	ds_write_b16_d16_hi v93, v106 offset:432
	v_sub_f32_e32 v106, v74, v107
	v_mul_f32_e32 v106, 0x3fb8aa3b, v106
	v_exp_f32_e32 v106, v106
	s_nop 0
	v_mul_f32_e32 v106, v153, v106
	v_cndmask_b32_e64 v106, v106, 0, s[34:35]
	v_mul_f32_e32 v106, v148, v106
	v_bfe_u32 v143, v106, 16, 1
	v_add3_u32 v106, v106, v143, s78
	ds_write_b16_d16_hi v93, v106 offset:32
	v_sub_f32_e32 v106, v75, v107
	v_mul_f32_e32 v106, 0x3fb8aa3b, v106
	v_exp_f32_e32 v106, v106
	s_nop 0
	v_mul_f32_e32 v106, v153, v106
	v_cndmask_b32_e64 v106, v106, 0, s[36:37]
	v_mul_f32_e32 v106, v149, v106
	v_bfe_u32 v143, v106, 16, 1
	v_add3_u32 v106, v106, v143, s78
	ds_write_b16_d16_hi v93, v106 offset:176
	v_sub_f32_e32 v106, v76, v107
	v_mul_f32_e32 v106, 0x3fb8aa3b, v106
	v_exp_f32_e32 v106, v106
	s_nop 0
	v_mul_f32_e32 v106, v153, v106
	v_cndmask_b32_e64 v106, v106, 0, s[38:39]
	v_mul_f32_e32 v106, v150, v106
	v_bfe_u32 v143, v106, 16, 1
	v_add3_u32 v106, v106, v143, s78
	ds_write_b16_d16_hi v93, v106 offset:320
	v_sub_f32_e32 v106, v77, v107
	v_mul_f32_e32 v106, 0x3fb8aa3b, v106
	v_exp_f32_e32 v106, v106
	s_nop 0
	v_mul_f32_e32 v106, v153, v106
	v_cndmask_b32_e64 v106, v106, 0, s[40:41]
	v_mul_f32_e32 v106, v151, v106
	v_bfe_u32 v107, v106, 16, 1
	v_add3_u32 v106, v106, v107, s78
	ds_write_b16_d16_hi v93, v106 offset:464
	ds_read2_b32 v[106:107], v89 offset0:32 offset1:48
	ds_read2_b32 v[144:145], v89 offset0:96 offset1:112
	s_waitcnt lgkmcnt(1)
	v_sub_f32_e32 v89, v74, v106
	v_mul_f32_e32 v89, 0x3fb8aa3b, v89
	v_exp_f32_e32 v89, v89
	s_waitcnt lgkmcnt(0)
	v_mul_f32_e32 v89, v144, v89
	v_cndmask_b32_e64 v89, v89, 0, s[42:43]
	v_mul_f32_e32 v82, v82, v89
	v_bfe_u32 v89, v82, 16, 1
	v_add3_u32 v82, v82, v89, s78
	ds_write_b16_d16_hi v93, v82 offset:64
	v_sub_f32_e32 v82, v75, v106
	v_mul_f32_e32 v82, 0x3fb8aa3b, v82
	v_exp_f32_e32 v82, v82
	s_nop 0
	v_mul_f32_e32 v82, v144, v82
	v_cndmask_b32_e64 v82, v82, 0, s[44:45]
	v_mul_f32_e32 v82, v83, v82
	v_bfe_u32 v83, v82, 16, 1
	v_add3_u32 v82, v82, v83, s78
	ds_write_b16_d16_hi v93, v82 offset:208
	v_sub_f32_e32 v82, v76, v106
	v_mul_f32_e32 v82, 0x3fb8aa3b, v82
	v_exp_f32_e32 v82, v82
	s_nop 0
	v_mul_f32_e32 v82, v144, v82
	v_cndmask_b32_e64 v82, v82, 0, s[46:47]
	v_mul_f32_e32 v82, v84, v82
	v_bfe_u32 v83, v82, 16, 1
	v_add3_u32 v82, v82, v83, s78
	ds_write_b16_d16_hi v93, v82 offset:352
	v_sub_f32_e32 v82, v77, v106
	v_mul_f32_e32 v82, 0x3fb8aa3b, v82
	v_exp_f32_e32 v82, v82
	s_nop 0
	v_mul_f32_e32 v82, v144, v82
	v_cndmask_b32_e64 v82, v82, 0, s[48:49]
	v_mul_f32_e32 v82, v85, v82
	v_bfe_u32 v83, v82, 16, 1
	v_add3_u32 v82, v82, v83, s78
	ds_write_b16_d16_hi v93, v82 offset:496
	v_sub_f32_e32 v82, v74, v107
	v_mul_f32_e32 v82, 0x3fb8aa3b, v82
	v_exp_f32_e32 v82, v82
	s_nop 0
	v_mul_f32_e32 v82, v145, v82
	v_cndmask_b32_e64 v82, v82, 0, s[50:51]
	v_mul_f32_e32 v78, v78, v82
	v_bfe_u32 v82, v78, 16, 1
	v_add3_u32 v78, v78, v82, s78
	ds_write_b16_d16_hi v93, v78 offset:96
	v_sub_f32_e32 v78, v75, v107
	v_mul_f32_e32 v78, 0x3fb8aa3b, v78
	v_exp_f32_e32 v78, v78
	s_nop 0
	v_mul_f32_e32 v78, v145, v78
	v_cndmask_b32_e64 v78, v78, 0, s[52:53]
	v_mul_f32_e32 v78, v79, v78
	v_bfe_u32 v79, v78, 16, 1
	v_add3_u32 v78, v78, v79, s78
	ds_write_b16_d16_hi v93, v78 offset:240
	v_sub_f32_e32 v78, v76, v107
	v_mul_f32_e32 v78, 0x3fb8aa3b, v78
	v_exp_f32_e32 v78, v78
	s_nop 0
	v_mul_f32_e32 v78, v145, v78
	v_cndmask_b32_e64 v78, v78, 0, s[54:55]
	v_mul_f32_e32 v78, v80, v78
	v_bfe_u32 v79, v78, 16, 1
	v_add3_u32 v78, v78, v79, s78
	ds_write_b16_d16_hi v93, v78 offset:384
	v_sub_f32_e32 v78, v77, v107
	v_mul_f32_e32 v78, 0x3fb8aa3b, v78
	v_exp_f32_e32 v78, v78
	s_nop 0
	v_mul_f32_e32 v78, v145, v78
	v_cndmask_b32_e64 v78, v78, 0, s[56:57]
	v_mul_f32_e32 v78, v81, v78
	v_bfe_u32 v79, v78, 16, 1
	v_add3_u32 v78, v78, v79, s78
	ds_write_b16_d16_hi v93, v78 offset:528
	ds_read_b128 v[78:81], v1
	ds_read_b128 v[82:85], v1 offset:64
	ds_read_b128 v[144:147], v142 offset:36864
	ds_read_b128 v[148:151], v142 offset:36928
	ds_read_b128 v[152:155], v142 offset:41536
	s_waitcnt lgkmcnt(2)
	v_mfma_f32_16x16x32_bf16 v[144:147], v[70:73], v[144:147], 0
	v_mul_f32_e32 v1, 0x3fb8aa3b, v74
	v_exp_f32_e32 v106, v1
	v_mul_f32_e32 v1, 0x3fb8aa3b, v75
	v_exp_f32_e32 v107, v1
	v_mul_f32_e32 v1, 0x3fb8aa3b, v76
	v_exp_f32_e32 v156, v1
	v_mul_f32_e32 v1, 0x3fb8aa3b, v77
	s_waitcnt lgkmcnt(1)
	v_mfma_f32_16x16x32_bf16 v[144:147], v[66:69], v[148:151], v[144:147]
	v_exp_f32_e32 v157, v1
	ds_read_b128 v[74:77], v142 offset:18432
	ds_read_b128 v[148:151], v142 offset:39232
	v_add_u32_e32 v1, s71, v138
	s_nop 3
	v_pk_mul_f32 v[144:145], v[106:107], v[144:145]
	v_pk_mul_f32 v[146:147], v[156:157], v[146:147]
	s_waitcnt lgkmcnt(1)
	s_nop 0
	v_mfma_f32_16x16x32_bf16 v[74:77], v[78:81], v[74:77], v[144:147]
	s_nop 2
	ds_read_b128 v[144:147], v142 offset:18496
	s_waitcnt lgkmcnt(0)
	v_mfma_f32_16x16x32_bf16 v[74:77], v[82:85], v[144:147], v[74:77]
	ds_read_b128 v[144:147], v142 offset:39168
	s_waitcnt lgkmcnt(0)
	v_mfma_f32_16x16x32_bf16 v[144:147], v[70:73], v[144:147], 0
	v_mfma_f32_16x16x32_bf16 v[144:147], v[66:69], v[148:151], v[144:147]
	ds_read_b128 v[148:151], v142 offset:20736
	s_nop 6
	v_pk_mul_f32 v[144:145], v[106:107], v[144:145]
	v_pk_mul_f32 v[146:147], v[156:157], v[146:147]
	s_waitcnt lgkmcnt(0)
	s_nop 0
	v_mfma_f32_16x16x32_bf16 v[144:147], v[78:81], v[148:151], v[144:147]
	ds_read_b128 v[148:151], v142 offset:20800
	s_waitcnt lgkmcnt(0)
	v_mfma_f32_16x16x32_bf16 v[144:147], v[82:85], v[148:151], v[144:147]
	ds_read_b128 v[148:151], v142 offset:41472
	s_waitcnt lgkmcnt(0)
	v_mfma_f32_16x16x32_bf16 v[148:151], v[70:73], v[148:151], 0
	v_mfma_f32_16x16x32_bf16 v[148:151], v[66:69], v[152:155], v[148:151]
	ds_read_b128 v[152:155], v142 offset:23040
	s_nop 6
	v_pk_mul_f32 v[148:149], v[106:107], v[148:149]
	v_pk_mul_f32 v[150:151], v[156:157], v[150:151]
	s_waitcnt lgkmcnt(0)
	s_nop 0
	v_mfma_f32_16x16x32_bf16 v[148:151], v[78:81], v[152:155], v[148:151]
	ds_read_b128 v[152:155], v142 offset:23104
	s_waitcnt lgkmcnt(0)
	v_mfma_f32_16x16x32_bf16 v[148:151], v[82:85], v[152:155], v[148:151]
	ds_read_b128 v[152:155], v142 offset:43776
	s_waitcnt lgkmcnt(0)
	v_mfma_f32_16x16x32_bf16 v[70:73], v[70:73], v[152:155], 0
	ds_read_b128 v[152:155], v142 offset:43840
	s_waitcnt lgkmcnt(0)
	v_mfma_f32_16x16x32_bf16 v[66:69], v[66:69], v[152:155], v[70:73]
	s_nop 4
	ds_read_b128 v[70:73], v142 offset:25344
	s_nop 1
	v_pk_mul_f32 v[66:67], v[106:107], v[66:67]
	v_pk_mul_f32 v[68:69], v[156:157], v[68:69]
	s_waitcnt lgkmcnt(0)
	s_nop 0
	v_mfma_f32_16x16x32_bf16 v[66:69], v[78:81], v[70:73], v[66:69]
	ds_read_b128 v[70:73], v142 offset:25408
	s_waitcnt lgkmcnt(0)
	v_mfma_f32_16x16x32_bf16 v[66:69], v[82:85], v[70:73], v[66:69]
	v_add_u32_e32 v70, s84, v139
	v_cndmask_b32_e64 v70, v70, v1, s[6:7]
	v_add_u32_e32 v70, s33, v70
	v_bfe_u32 v72, v74, 16, 1
	v_mad_i64_i32 v[70:71], s[0:1], v70, s72, v[102:103]
	v_add3_u32 v72, v74, v72, s78
	global_store_short_d16_hi v[70:71], v72, off offset:1024
	v_bfe_u32 v72, v144, 16, 1
	v_add3_u32 v72, v144, v72, s78
	global_store_short_d16_hi v[70:71], v72, off offset:1056
	v_bfe_u32 v72, v148, 16, 1
	v_add3_u32 v72, v148, v72, s78
	global_store_short_d16_hi v[70:71], v72, off offset:1088
	v_bfe_u32 v72, v66, 16, 1
	v_add3_u32 v66, v66, v72, s78
	global_store_short_d16_hi v[70:71], v66, off offset:1120
	v_add_u32_e32 v66, 1, v1
	v_xad_u32 v70, v1, -2, s2
	v_cndmask_b32_e64 v66, v70, v66, s[6:7]
	v_add_u32_e32 v66, s33, v66
	v_mad_i64_i32 v[70:71], s[0:1], v66, s72, v[102:103]
	v_bfe_u32 v66, v75, 16, 1
	v_add3_u32 v66, v75, v66, s78
	global_store_short_d16_hi v[70:71], v66, off offset:1024
	v_bfe_u32 v66, v145, 16, 1
	v_add3_u32 v66, v145, v66, s78
	global_store_short_d16_hi v[70:71], v66, off offset:1056
	v_bfe_u32 v66, v149, 16, 1
	v_add3_u32 v66, v149, v66, s78
	global_store_short_d16_hi v[70:71], v66, off offset:1088
	v_bfe_u32 v66, v67, 16, 1
	v_add3_u32 v66, v67, v66, s78
	global_store_short_d16_hi v[70:71], v66, off offset:1120
	v_add_u32_e32 v66, 2, v1
	v_xad_u32 v67, v1, -3, s2
	v_cndmask_b32_e64 v66, v67, v66, s[6:7]
	v_add_u32_e32 v66, s33, v66
	v_bfe_u32 v70, v76, 16, 1
	v_mad_i64_i32 v[66:67], s[0:1], v66, s72, v[102:103]
	v_add3_u32 v70, v76, v70, s78
	global_store_short_d16_hi v[66:67], v70, off offset:1024
	v_bfe_u32 v70, v146, 16, 1
	v_add3_u32 v70, v146, v70, s78
	global_store_short_d16_hi v[66:67], v70, off offset:1056
	v_bfe_u32 v70, v150, 16, 1
	v_add3_u32 v70, v150, v70, s78
	global_store_short_d16_hi v[66:67], v70, off offset:1088
	v_bfe_u32 v70, v68, 16, 1
	v_add3_u32 v68, v68, v70, s78
	global_store_short_d16_hi v[66:67], v68, off offset:1120
	v_add_u32_e32 v66, 3, v1
	v_xad_u32 v1, v1, -4, s2
	v_cndmask_b32_e64 v1, v1, v66, s[6:7]
	v_add_u32_e32 v1, s33, v1
	v_mad_i64_i32 v[66:67], s[0:1], v1, s72, v[102:103]
	v_bfe_u32 v1, v77, 16, 1
	v_add3_u32 v1, v77, v1, s78
	global_store_short_d16_hi v[66:67], v1, off offset:1024
	v_bfe_u32 v1, v147, 16, 1
	v_add3_u32 v1, v147, v1, s78
	global_store_short_d16_hi v[66:67], v1, off offset:1056
	v_bfe_u32 v1, v151, 16, 1
	v_add3_u32 v1, v151, v1, s78
	global_store_short_d16_hi v[66:67], v1, off offset:1088
	v_bfe_u32 v1, v69, 16, 1
	s_cselect_b64 s[0:1], -1, 0
	v_add3_u32 v1, v69, v1, s78
	s_and_b64 vcc, exec, s[0:1]
	global_store_short_d16_hi v[66:67], v1, off offset:1120

.LBB0_2532:
	s_lshl_b64 s[0:1], s[8:9], 1
	v_readlane_b32 s4, v241, 17
	v_readlane_b32 s5, v241, 18
	v_rcp_f32_e32 v7, v55
	s_add_i32 s18, s18, s16
	v_readlane_b32 s8, v241, 21
	v_readlane_b32 s9, v241, 22
	v_mul_f32_e32 v8, 1.0, v7
	s_add_u32 s0, s8, s0
	v_or_b32_e32 v1, v68, v47
	s_addc_u32 s1, s9, s1
	v_lshlrev_b32_e32 v4, 1, v45
	v_mov_b32_e32 v5, v0
	v_mul_f32_e32 v9, v8, v12
	v_add_u32_e32 v1, s18, v1
	v_lshl_add_u64 v[4:5], s[0:1], 0, v[4:5]
	s_movk_i32 s4, 0x300
	v_bfe_u32 v10, v9, 16, 1
	v_mad_i64_i32 v[6:7], s[0:1], v1, s4, v[4:5]
	v_add3_u32 v9, v9, v10, s78
	global_store_short_d16_hi v[6:7], v9, off
	v_mul_f32_e32 v9, v8, v16
	v_bfe_u32 v10, v9, 16, 1
	v_add3_u32 v9, v9, v10, s78
	global_store_short_d16_hi v[6:7], v9, off offset:32
	v_mul_f32_e32 v9, v8, v20
	v_bfe_u32 v10, v9, 16, 1
	v_add3_u32 v9, v9, v10, s78
	global_store_short_d16_hi v[6:7], v9, off offset:64
	v_rcp_f32_e32 v10, v54
	v_mul_f32_e32 v8, v8, v24
	v_bfe_u32 v11, v8, 16, 1
	v_add3_u32 v8, v8, v11, s78
	global_store_short_d16_hi v[6:7], v8, off offset:96
	v_mul_f32_e32 v8, 1.0, v10
	v_mul_f32_e32 v9, v8, v13
	v_add_u32_e32 v6, 1, v1
	v_bfe_u32 v10, v9, 16, 1
	v_mad_i64_i32 v[6:7], s[0:1], v6, s4, v[4:5]
	v_add3_u32 v9, v9, v10, s78
	global_store_short_d16_hi v[6:7], v9, off
	v_mul_f32_e32 v9, v8, v17
	v_bfe_u32 v10, v9, 16, 1
	v_add3_u32 v9, v9, v10, s78
	global_store_short_d16_hi v[6:7], v9, off offset:32
	v_mul_f32_e32 v9, v8, v21
	v_bfe_u32 v10, v9, 16, 1
	v_add3_u32 v9, v9, v10, s78
	global_store_short_d16_hi v[6:7], v9, off offset:64
	v_rcp_f32_e32 v10, v3
	v_mul_f32_e32 v8, v8, v25
	v_bfe_u32 v11, v8, 16, 1
	v_add3_u32 v8, v8, v11, s78
	global_store_short_d16_hi v[6:7], v8, off offset:96
	v_mul_f32_e32 v3, 1.0, v10
	v_mul_f32_e32 v8, v3, v14
	v_add_u32_e32 v6, 2, v1
	v_bfe_u32 v9, v8, 16, 1
	v_mad_i64_i32 v[6:7], s[0:1], v6, s4, v[4:5]
	v_add3_u32 v8, v8, v9, s78
	global_store_short_d16_hi v[6:7], v8, off
	v_mul_f32_e32 v8, v3, v18
	v_bfe_u32 v9, v8, 16, 1
	v_add3_u32 v8, v8, v9, s78
	global_store_short_d16_hi v[6:7], v8, off offset:32
	v_mul_f32_e32 v8, v3, v22
	v_bfe_u32 v9, v8, 16, 1
	v_add3_u32 v8, v8, v9, s78
	global_store_short_d16_hi v[6:7], v8, off offset:64
	v_rcp_f32_e32 v9, v2
	v_mul_f32_e32 v3, v3, v26
	v_bfe_u32 v10, v3, 16, 1
	v_add3_u32 v3, v3, v10, s78
	global_store_short_d16_hi v[6:7], v3, off offset:96
	v_mul_f32_e32 v6, 1.0, v9
	v_add_u32_e32 v1, 3, v1
	v_mad_i64_i32 v[2:3], s[0:1], v1, s4, v[4:5]
	v_mul_f32_e32 v1, v6, v15
	v_bfe_u32 v4, v1, 16, 1
	v_add3_u32 v1, v1, v4, s78
	global_store_short_d16_hi v[2:3], v1, off
	v_mul_f32_e32 v1, v6, v19
	v_bfe_u32 v4, v1, 16, 1
	v_add3_u32 v1, v1, v4, s78
	global_store_short_d16_hi v[2:3], v1, off offset:32
	v_mul_f32_e32 v1, v6, v23
	v_bfe_u32 v4, v1, 16, 1
	v_add3_u32 v1, v1, v4, s78
	global_store_short_d16_hi v[2:3], v1, off offset:64
	v_mul_f32_e32 v1, v6, v27
	v_bfe_u32 v4, v1, 16, 1
	v_add3_u32 v1, v1, v4, s78
	v_readlane_b32 s6, v241, 19
	v_readlane_b32 s7, v241, 20
	v_readlane_b32 s10, v241, 23
	v_readlane_b32 s11, v241, 24
	global_store_short_d16_hi v[2:3], v1, off offset:96
	s_barrier
	s_cbranch_execz .LBB0_2379
	s_branch .LBB0_2524

.LBB0_2833:
	v_lshl_add_u64 v[128:129], v[174:175], 0, v[176:177]
	v_lshl_add_u64 v[182:183], v[180:181], 0, v[176:177]
	global_load_dwordx4 v[112:115], v[128:129], off offset:2048
	global_load_dwordx4 v[116:119], v[182:183], off offset:1024
	global_load_dwordx4 v[120:123], v[182:183], off offset:1792
	global_load_dwordx4 v[124:127], v[128:129], off offset:1280
	s_waitcnt vmcnt(2)
	v_and_b32_e32 v135, 0xffff0000, v117
	v_lshlrev_b32_e32 v63, 16, v112
	s_waitcnt vmcnt(0)
	v_lshlrev_b32_e32 v69, 16, v125
	s_waitcnt lgkmcnt(0)
	v_lshlrev_b32_e32 v71, 16, v124
	v_lshlrev_b32_e32 v61, 16, v113
	v_and_b32_e32 v131, 0xffff0000, v113
	v_and_b32_e32 v130, 0xffff0000, v112
	v_and_b32_e32 v113, 0xffff0000, v115
	v_and_b32_e32 v112, 0xffff0000, v114
	v_mul_f32_e32 v77, v68, v63
	v_mul_f32_e32 v63, 0xbfb8aa3b, v71
	v_mul_f32_e32 v79, 0xbfb8aa3b, v69
	v_lshlrev_b32_e32 v138, 16, v122
	v_lshlrev_b32_e32 v139, 16, v123
	v_and_b32_e32 v133, 0xffff0000, v123
	v_and_b32_e32 v132, 0xffff0000, v122
	v_and_b32_e32 v73, 0xffff0000, v125
	v_and_b32_e32 v75, 0xffff0000, v124
	v_pk_mul_f32 v[122:123], v[154:155], v[112:113]
	v_exp_f32_e32 v112, v63
	v_exp_f32_e32 v113, v79
	v_mul_f32_e32 v124, 0xbfb8aa3b, v75
	v_mul_f32_e32 v125, 0xbfb8aa3b, v73
	v_exp_f32_e32 v124, v124
	v_exp_f32_e32 v125, v125
	v_pk_add_f32 v[112:113], v[112:113], 1.0 op_sel_hi:[1,0]
	v_lshlrev_b32_e32 v65, 16, v114
	v_lshlrev_b32_e32 v67, 16, v115
	v_lshlrev_b32_e32 v114, 16, v116
	v_lshlrev_b32_e32 v115, 16, v117
	v_and_b32_e32 v134, 0xffff0000, v116
	v_lshlrev_b32_e32 v136, 16, v118
	v_lshlrev_b32_e32 v137, 16, v119
	v_and_b32_e32 v117, 0xffff0000, v119
	v_and_b32_e32 v116, 0xffff0000, v118
	v_lshlrev_b32_e32 v118, 16, v120
	v_lshlrev_b32_e32 v119, 16, v121
	v_and_b32_e32 v121, 0xffff0000, v121
	v_and_b32_e32 v120, 0xffff0000, v120
	v_pk_add_f32 v[118:119], v[114:115], v[118:119]
	v_pk_add_f32 v[114:115], v[134:135], v[120:121]
	v_pk_add_f32 v[120:121], v[124:125], 1.0 op_sel_hi:[1,0]
	v_div_scale_f32 v124, s[6:7], v112, v112, v71
	v_rcp_f32_e32 v142, v113
	v_div_scale_f32 v134, s[8:9], v121, v121, v73
	v_rcp_f32_e32 v143, v124
	v_rcp_f32_e32 v144, v134
	v_fma_f32 v186, -v124, v143, 1.0
	v_div_scale_f32 v125, s[6:7], v71, v112, v71
	v_fma_f32 v187, -v134, v144, 1.0
	v_fmac_f32_e32 v143, v186, v143
	v_div_scale_f32 v135, s[8:9], v73, v121, v73
	v_fmac_f32_e32 v144, v187, v144
	v_mul_f32_e32 v186, v125, v143
	v_mul_f32_e32 v187, v135, v144
	v_fma_f32 v190, -v124, v186, v125
	v_div_scale_f32 v140, s[10:11], v120, v120, v75
	v_fma_f32 v191, -v134, v187, v135
	v_fmac_f32_e32 v186, v190, v143
	v_rcp_f32_e32 v184, v140
	v_fmac_f32_e32 v187, v191, v144
	v_fma_f32 v79, -v124, v186, v125
	v_mul_f32_e32 v125, v69, v142
	s_mov_b64 vcc, s[6:7]
	v_fma_f32 v134, -v134, v187, v135
	v_div_fmas_f32 v63, v79, v143, v186
	s_mov_b64 vcc, s[8:9]
	v_div_fixup_f32 v124, v63, v112, v71
	v_div_fmas_f32 v63, v134, v144, v187
	v_lshlrev_b32_e32 v71, 16, v126
	v_div_fixup_f32 v121, v63, v121, v73
	v_lshlrev_b32_e32 v69, 16, v127
	v_mul_f32_e32 v73, 0xbfb8aa3b, v71
	v_fma_f32 v188, -v140, v184, 1.0
	v_exp_f32_e32 v112, v73
	v_mul_f32_e32 v73, 0xbfb8aa3b, v69
	v_div_scale_f32 v141, s[10:11], v75, v120, v75
	v_fmac_f32_e32 v184, v188, v184
	v_exp_f32_e32 v113, v73
	v_mul_f32_e32 v188, v141, v184
	v_fma_f32 v192, -v140, v188, v141
	v_fmac_f32_e32 v188, v192, v184
	v_fma_f32 v63, -v140, v188, v141
	s_mov_b64 vcc, s[10:11]
	v_pk_add_f32 v[134:135], v[112:113], 1.0 op_sel_hi:[1,0]
	v_div_fmas_f32 v63, v63, v184, v188
	v_div_fixup_f32 v120, v63, v120, v75
	v_rcp_f32_e32 v75, v135
	v_cmp_gt_i32_e32 vcc, s2, v204
	v_and_b32_e32 v79, 0xffff0000, v127
	v_and_b32_e32 v140, 0xffff0000, v126
	v_cndmask_b32_e32 v63, v29, v31, vcc
	v_cndmask_b32_e32 v198, v41, v43, vcc
	v_or_b32_e32 v141, 2, v198
	v_and_b32_e32 v63, v63, v204
	v_cmp_lt_u32_e32 vcc, 1, v63
	v_cmp_lt_u32_e64 s[6:7], v63, v141
	s_and_b64 s[6:7], vcc, s[6:7]
	v_pk_add_f32 v[112:113], v[136:137], v[138:139]
	v_cndmask_b32_e64 v127, 0, -1, s[6:7]
	v_cndmask_b32_e64 v126, 0, v45, s[6:7]
	v_lshl_add_u64 v[126:127], v[128:129], 0, v[126:127]
	global_load_dwordx4 v[186:189], v[126:127], off offset:2048
	v_add_u32_e32 v126, 1, v63
	v_cmp_ne_u32_e64 s[8:9], 0, v63
	v_cmp_lt_u32_e64 s[10:11], v126, v141
	s_and_b64 s[8:9], s[8:9], s[10:11]
	v_cndmask_b32_e64 v127, 0, -1, s[8:9]
	v_cndmask_b32_e64 v126, 0, v47, s[8:9]
	v_lshl_add_u64 v[126:127], v[128:129], 0, v[126:127]
	global_load_dwordx4 v[190:193], v[126:127], off offset:2048
	v_rcp_f32_e32 v142, v134
	v_mul_f32_e32 v127, v69, v75
	v_pk_add_f32 v[116:117], v[116:117], v[132:133]
	v_mul_f32_e32 v75, 0xbfb8aa3b, v140
	v_exp_f32_e32 v136, v75
	v_mul_f32_e32 v75, 0xbfb8aa3b, v79
	v_exp_f32_e32 v137, v75
	v_add_u32_e32 v126, 3, v63
	v_cmp_lt_u32_e64 s[12:13], v126, v141
	v_mul_f32_e32 v126, v71, v142
	v_pk_add_f32 v[136:137], v[136:137], 1.0 op_sel_hi:[1,0]
	v_cndmask_b32_e64 v144, 0, v49, s[12:13]
	v_lshl_add_u64 v[138:139], v[128:129], 0, v[144:145]
	v_add_u32_e32 v73, 4, v63
	global_load_dwordx4 v[194:197], v[138:139], off offset:2048
	v_cmp_lt_u32_e64 s[10:11], v73, v141
	v_rcp_f32_e32 v71, v137
	v_mul_f32_e32 v61, v70, v61
	v_cndmask_b32_e64 v144, 0, v51, s[10:11]
	v_lshl_add_u64 v[128:129], v[128:129], 0, v[144:145]
	global_load_dwordx4 v[132:135], v[128:129], off offset:2048
	v_rcp_f32_e32 v128, v136
	v_mul_f32_e32 v141, v79, v71
	v_mul_f32_e32 v65, v44, v65
	v_mul_f32_e32 v140, v140, v128
	v_cmp_lt_u32_e32 vcc, v63, v198
	v_pk_mul_f32 v[130:131], v[166:167], v[130:131]
	v_mul_f32_e32 v67, v46, v67
	v_cndmask_b32_e32 v61, 0, v61, vcc
	v_cndmask_b32_e32 v65, 0, v65, vcc
	v_cndmask_b32_e32 v131, 0, v131, vcc
	v_cndmask_b32_e32 v130, 0, v130, vcc
	s_waitcnt vmcnt(3)
	v_lshlrev_b32_e32 v71, 16, v187
	v_mul_f32_e32 v71, v62, v71
	v_lshlrev_b32_e32 v73, 16, v186
	v_cndmask_b32_e64 v71, 0, v71, s[6:7]
	v_mul_f32_e32 v73, v60, v73
	v_add_f32_e32 v71, v58, v71
	v_cndmask_b32_e64 v73, 0, v73, s[6:7]
	v_add_f32_e32 v73, v56, v73
	v_and_b32_e32 v129, 0xffff0000, v187
	v_and_b32_e32 v128, 0xffff0000, v186
	v_pk_mul_f32 v[128:129], v[162:163], v[128:129]
	v_cndmask_b32_e32 v67, 0, v67, vcc
	v_cndmask_b32_e64 v129, 0, v129, s[6:7]
	v_cndmask_b32_e64 v128, 0, v128, s[6:7]
	s_waitcnt vmcnt(2)
	v_lshlrev_b32_e32 v75, 16, v191
	v_mul_f32_e32 v75, v66, v75
	v_lshlrev_b32_e32 v79, 16, v190
	v_cndmask_b32_e64 v75, 0, v75, s[8:9]
	v_mul_f32_e32 v79, v64, v79
	v_add_f32_e32 v71, v71, v75
	v_cndmask_b32_e64 v79, 0, v79, s[8:9]
	v_add_f32_e32 v61, v71, v61
	v_add_f32_e32 v73, v73, v79
	v_cndmask_b32_e32 v75, 0, v77, vcc
	v_add_f32_e32 v73, v73, v75
	v_lshlrev_b32_e32 v77, 16, v192
	v_and_b32_e32 v143, 0xffff0000, v191
	v_and_b32_e32 v142, 0xffff0000, v190
	v_mul_f32_e32 v77, v28, v77
	v_pk_mul_f32 v[142:143], v[164:165], v[142:143]
	v_lshlrev_b32_e32 v79, 16, v193
	v_cndmask_b32_e64 v77, 0, v77, s[8:9]
	v_pk_add_f32 v[128:129], v[160:161], v[128:129]
	v_cndmask_b32_e64 v143, 0, v143, s[8:9]
	v_cndmask_b32_e64 v142, 0, v142, s[8:9]
	v_pk_add_f32 v[128:129], v[128:129], v[142:143]
	v_cndmask_b32_e32 v123, 0, v123, vcc
	v_pk_add_f32 v[128:129], v[128:129], v[130:131]
	v_cndmask_b32_e32 v122, 0, v122, vcc
	v_add_u32_e32 v69, -1, v198
	v_lshl_add_u64 v[184:185], v[180:181], 0, v[172:173]
	s_waitcnt vmcnt(1)
	v_lshlrev_b32_e32 v71, 16, v195
	v_mul_f32_e32 v71, v74, v71
	v_lshlrev_b32_e32 v75, 16, v194
	v_cndmask_b32_e64 v71, 0, v71, s[12:13]
	v_mul_f32_e32 v75, v72, v75
	v_add_f32_e32 v61, v61, v71
	s_waitcnt vmcnt(0)
	v_lshlrev_b32_e32 v71, 16, v133
	v_cndmask_b32_e64 v75, 0, v75, s[12:13]
	v_mul_f32_e32 v71, v78, v71
	v_add_f32_e32 v73, v73, v75
	v_lshlrev_b32_e32 v75, 16, v132
	v_cndmask_b32_e64 v71, 0, v71, s[10:11]
	v_mul_f32_e32 v75, v76, v75
	v_add_f32_e32 v61, v61, v71
	v_lshlrev_b32_e32 v71, 16, v188
	v_cndmask_b32_e64 v75, 0, v75, s[10:11]
	v_mul_f32_e32 v71, v24, v71
	v_add_f32_e32 v73, v73, v75
	v_lshlrev_b32_e32 v75, 16, v189
	v_cndmask_b32_e64 v71, 0, v71, s[6:7]
	v_add_f32_e32 v71, v40, v71
	v_mul_f32_e32 v75, v26, v75
	v_cndmask_b32_e64 v75, 0, v75, s[6:7]
	v_add_f32_e32 v71, v71, v77
	v_mul_f32_e32 v77, v30, v79
	v_add_f32_e32 v75, v42, v75
	v_cndmask_b32_e64 v77, 0, v77, s[8:9]
	v_add_f32_e32 v65, v71, v65
	v_lshlrev_b32_e32 v71, 16, v196
	v_and_b32_e32 v131, 0xffff0000, v195
	v_and_b32_e32 v130, 0xffff0000, v194
	v_add_f32_e32 v75, v75, v77
	v_mul_f32_e32 v71, v48, v71
	v_pk_mul_f32 v[130:131], v[168:169], v[130:131]
	v_add_f32_e32 v67, v75, v67
	v_lshlrev_b32_e32 v75, 16, v197
	v_cndmask_b32_e64 v71, 0, v71, s[12:13]
	v_cndmask_b32_e64 v131, 0, v131, s[12:13]
	v_cndmask_b32_e64 v130, 0, v130, s[12:13]
	v_add_f32_e32 v65, v65, v71
	v_mul_f32_e32 v71, v50, v75
	v_pk_add_f32 v[128:129], v[128:129], v[130:131]
	v_and_b32_e32 v131, 0xffff0000, v133
	v_and_b32_e32 v130, 0xffff0000, v132
	v_cndmask_b32_e64 v71, 0, v71, s[12:13]
	v_pk_mul_f32 v[130:131], v[170:171], v[130:131]
	v_add_f32_e32 v67, v67, v71
	v_lshlrev_b32_e32 v71, 16, v134
	v_cndmask_b32_e64 v131, 0, v131, s[10:11]
	v_cndmask_b32_e64 v130, 0, v130, s[10:11]
	v_mul_f32_e32 v71, v52, v71
	v_pk_add_f32 v[128:129], v[128:129], v[130:131]
	v_and_b32_e32 v131, 0xffff0000, v189
	v_and_b32_e32 v130, 0xffff0000, v188
	v_lshlrev_b32_e32 v75, 16, v135
	v_cndmask_b32_e64 v71, 0, v71, s[10:11]
	v_pk_mul_f32 v[130:131], v[34:35], v[130:131]
	v_and_b32_e32 v133, 0xffff0000, v193
	v_and_b32_e32 v132, 0xffff0000, v192
	v_add_f32_e32 v65, v65, v71
	v_mul_f32_e32 v71, v54, v75
	v_cndmask_b32_e64 v131, 0, v131, s[6:7]
	v_cndmask_b32_e64 v130, 0, v130, s[6:7]
	v_pk_mul_f32 v[132:133], v[38:39], v[132:133]
	v_cndmask_b32_e64 v71, 0, v71, s[10:11]
	v_pk_add_f32 v[130:131], v[22:23], v[130:131]
	v_cndmask_b32_e64 v133, 0, v133, s[8:9]
	v_cndmask_b32_e64 v132, 0, v132, s[8:9]
	v_add_f32_e32 v67, v67, v71
	v_mul_f32_e32 v71, 0xbfb8aa3b, v73
	v_pk_add_f32 v[130:131], v[130:131], v[132:133]
	v_exp_f32_e32 v132, v71
	v_mul_f32_e32 v71, 0xbfb8aa3b, v61
	v_exp_f32_e32 v133, v71
	v_pk_add_f32 v[122:123], v[130:131], v[122:123]
	v_and_b32_e32 v131, 0xffff0000, v197
	v_and_b32_e32 v130, 0xffff0000, v196
	v_pk_mul_f32 v[130:131], v[156:157], v[130:131]
	v_mul_f32_e32 v71, 0xbfb8aa3b, v128
	v_cndmask_b32_e64 v131, 0, v131, s[12:13]
	v_cndmask_b32_e64 v130, 0, v130, s[12:13]
	v_pk_add_f32 v[122:123], v[122:123], v[130:131]
	v_and_b32_e32 v130, 0xffff0000, v134
	v_exp_f32_e32 v134, v71
	v_pk_add_f32 v[132:133], v[132:133], 1.0 op_sel_hi:[1,0]
	v_mul_f32_e32 v71, 0xbfb8aa3b, v129
	v_and_b32_e32 v131, 0xffff0000, v135
	v_exp_f32_e32 v135, v71
	v_rcp_f32_e32 v75, v133
	v_pk_mul_f32 v[130:131], v[158:159], v[130:131]
	v_cmp_lt_u32_e64 s[8:9], v63, v69
	v_cndmask_b32_e64 v131, 0, v131, s[10:11]
	v_cndmask_b32_e64 v130, 0, v130, s[10:11]
	v_pk_add_f32 v[142:143], v[122:123], v[130:131]
	v_rcp_f32_e32 v130, v132
	v_mul_f32_e32 v131, v61, v75
	v_pk_add_f32 v[122:123], v[134:135], 1.0 op_sel_hi:[1,0]
	v_mul_f32_e32 v130, v73, v130
	v_rcp_f32_e32 v71, v123
	v_pk_fma_f32 v[118:119], v[146:147], v[130:131], v[118:119]
	global_load_dwordx4 v[200:203], v[184:185], off
	global_load_dwordx4 v[206:209], v[184:185], off offset:512
	v_rcp_f32_e32 v79, v122
	v_mul_f32_e32 v61, v129, v71
	v_pk_mul_f32 v[186:187], v[118:119], v[124:125]
	v_mov_b32_e32 v119, v61
	v_mul_f32_e32 v118, v128, v79
	v_pk_fma_f32 v[114:115], v[146:147], v[118:119], v[114:115]
	v_mul_f32_e32 v71, 0xbfb8aa3b, v65
	v_pk_mul_f32 v[188:189], v[114:115], v[120:121]
	v_exp_f32_e32 v114, v71
	v_mul_f32_e32 v71, 0xbfb8aa3b, v67
	v_exp_f32_e32 v115, v71
	v_mul_f32_e32 v71, 0xbfb8aa3b, v142
	v_exp_f32_e32 v118, v71
	v_mul_f32_e32 v71, 0xbfb8aa3b, v143
	v_pk_add_f32 v[114:115], v[114:115], 1.0 op_sel_hi:[1,0]
	v_exp_f32_e32 v119, v71
	v_rcp_f32_e32 v75, v115
	v_pk_add_f32 v[118:119], v[118:119], 1.0 op_sel_hi:[1,0]
	v_lshl_add_u64 v[138:139], v[174:175], 0, v[172:173]
	v_cndmask_b32_e64 v144, 0, v49, s[8:9]
	v_rcp_f32_e32 v122, v114
	v_mul_f32_e32 v115, v67, v75
	v_lshl_add_u64 v[220:221], v[138:139], 0, v[144:145]
	v_mul_f32_e32 v114, v65, v122
	v_rcp_f32_e32 v67, v119
	v_cmp_eq_u32_e64 s[6:7], 0, v63
	v_pk_fma_f32 v[112:113], v[146:147], v[114:115], v[112:113]
	global_load_dwordx4 v[210:213], v[138:139], off offset:3872
	v_div_scale_f32 v65, s[10:11], v118, v118, v142
	v_cndmask_b32_e64 v121, -1, 0, s[6:7]
	v_cndmask_b32_e64 v120, v47, 0, s[6:7]
	v_rcp_f32_e32 v69, v65
	v_lshl_add_u64 v[218:219], v[138:139], 0, v[120:121]
	v_pk_mul_f32 v[190:191], v[112:113], v[126:127]
	global_load_dwordx4 v[112:115], v[138:139], off offset:3360
	global_load_dwordx4 v[120:123], v[218:219], off offset:3360
	global_load_dwordx4 v[124:127], v[220:221], off offset:3360
	v_mul_f32_e32 v119, v143, v67
	v_fma_f32 v63, -v65, v69, 1.0
	v_fmac_f32_e32 v69, v63, v69
	v_div_scale_f32 v63, vcc, v142, v118, v142
	v_mul_f32_e32 v67, v63, v69
	global_load_dwordx4 v[128:131], v[218:219], off offset:3872
	global_load_dwordx4 v[132:135], v[220:221], off offset:3872
	v_fma_f32 v75, -v65, v67, v63
	v_fmac_f32_e32 v67, v75, v69
	v_fma_f32 v63, -v65, v67, v63
	v_div_fmas_f32 v63, v63, v69, v67
	v_div_fixup_f32 v118, v63, v118, v142
	v_lshl_add_u64 v[136:137], v[178:179], 0, v[172:173]
	v_pk_fma_f32 v[116:117], v[146:147], v[118:119], v[116:117]
	global_load_dwordx4 v[214:217], v[136:137], off offset:1536
	v_pk_mul_f32 v[192:193], v[116:117], v[140:141]
	global_load_dwordx4 v[140:143], v[136:137], off offset:1024
	s_waitcnt vmcnt(9)
	v_and_b32_e32 v117, 0xffff0000, v201
	v_and_b32_e32 v116, 0xffff0000, v200
	s_waitcnt vmcnt(8)
	v_and_b32_e32 v119, 0xffff0000, v207
	v_and_b32_e32 v118, 0xffff0000, v206
	v_pk_add_f32 v[196:197], v[116:117], v[118:119]
	v_lshlrev_b32_e32 v117, 16, v201
	v_lshlrev_b32_e32 v116, 16, v200
	v_lshlrev_b32_e32 v119, 16, v207
	v_lshlrev_b32_e32 v118, 16, v206
	v_pk_add_f32 v[198:199], v[116:117], v[118:119]
	v_and_b32_e32 v117, 0xffff0000, v203
	v_and_b32_e32 v116, 0xffff0000, v202
	v_and_b32_e32 v119, 0xffff0000, v209
	v_and_b32_e32 v118, 0xffff0000, v208
	v_pk_add_f32 v[200:201], v[116:117], v[118:119]
	v_lshlrev_b32_e32 v117, 16, v203
	v_lshlrev_b32_e32 v116, 16, v202
	v_lshlrev_b32_e32 v119, 16, v209
	v_lshlrev_b32_e32 v118, 16, v208
	v_cndmask_b32_e64 v195, 0, 0.5, s[8:9]
	v_cndmask_b32_e64 v194, 0.5, 0, s[6:7]
	v_pk_add_f32 v[202:203], v[116:117], v[118:119]
	v_add_f32_e32 v69, 0, v198
	v_add_f32_e32 v69, v196, v69
	v_cndmask_b32_e64 v61, 0, v188, s[0:1]
	v_add_f32_e32 v69, v199, v69
	v_cndmask_b32_e64 v73, 0, v186, s[0:1]
	v_mul_f32_e32 v61, v61, v61
	v_add_f32_e32 v69, v197, v69
	v_cndmask_b32_e64 v77, 0, v187, s[0:1]
	v_add_f32_e32 v69, v202, v69
	v_fmac_f32_e32 v61, v73, v73
	v_cndmask_b32_e64 v79, 0, v189, s[0:1]
	v_add_f32_e32 v69, v200, v69
	v_fmac_f32_e32 v61, v77, v77
	v_cndmask_b32_e64 v71, 0, v190, s[0:1]
	v_add_f32_e32 v69, v203, v69
	v_fmac_f32_e32 v61, v79, v79
	v_cndmask_b32_e64 v63, 0, v192, s[0:1]
	v_add_f32_e32 v69, v201, v69
	v_fmac_f32_e32 v61, v71, v71
	v_fmac_f32_e32 v61, v63, v63
	v_add_f32_dpp v63, v69, v69 quad_perm:[1,0,3,2] row_mask:0xf bank_mask:0xf bound_ctrl:1
	s_waitcnt vmcnt(7)
	v_lshlrev_b32_e32 v230, 16, v212
	v_and_b32_e32 v231, 0xffff0000, v212
	v_lshlrev_b32_e32 v228, 16, v210
	v_and_b32_e32 v229, 0xffff0000, v210
	v_add_f32_dpp v63, v63, v63 quad_perm:[2,3,0,1] row_mask:0xf bank_mask:0xf bound_ctrl:1
	v_lshlrev_b32_e32 v210, 16, v211
	v_and_b32_e32 v211, 0xffff0000, v211
	v_add_f32_dpp v63, v63, v63 row_half_mirror row_mask:0xf bank_mask:0xf bound_ctrl:1
	v_mul_f32_e32 v144, 0x3c800000, v63
	v_cndmask_b32_e64 v65, 0, v191, s[0:1]
	v_cndmask_b32_e64 v67, 0, v193, s[0:1]
	v_fmac_f32_e32 v61, v65, v65
	v_fmac_f32_e32 v61, v67, v67
	v_mov_b32_e32 v67, 0
	s_waitcnt vmcnt(6)
	v_lshlrev_b32_e32 v206, 16, v112
	v_and_b32_e32 v207, 0xffff0000, v112
	v_lshlrev_b32_e32 v208, 16, v113
	v_and_b32_e32 v209, 0xffff0000, v113
	v_lshlrev_b32_e32 v222, 16, v114
	v_and_b32_e32 v223, 0xffff0000, v114
	v_lshlrev_b32_e32 v112, 16, v115
	v_and_b32_e32 v113, 0xffff0000, v115
	s_waitcnt vmcnt(5)
	v_and_b32_e32 v114, 0xffff0000, v123
	s_waitcnt vmcnt(4)
	v_lshlrev_b32_e32 v115, 16, v127
	v_and_b32_e32 v117, 0xffff0000, v127
	v_lshlrev_b32_e32 v116, 16, v123
	v_pk_mul_f32 v[114:115], v[194:195], v[114:115]
	v_and_b32_e32 v236, 0xffff0000, v120
	v_pk_fma_f32 v[114:115], v[194:195], v[116:117], v[114:115] op_sel:[0,0,1] op_sel_hi:[1,1,0]
	s_waitcnt vmcnt(2)
	v_and_b32_e32 v117, 0xffff0000, v135
	v_pk_add_f32 v[114:115], v[114:115], v[112:113] neg_lo:[0,1] neg_hi:[0,1]
	v_lshlrev_b32_e32 v116, 16, v131
	v_pk_fma_f32 v[224:225], v[106:107], v[114:115], v[112:113]
	v_and_b32_e32 v114, 0xffff0000, v131
	v_lshlrev_b32_e32 v115, 16, v135
	v_pk_mul_f32 v[114:115], v[194:195], v[114:115]
	v_lshlrev_b32_e32 v237, 16, v124
	v_lshlrev_b32_e32 v112, 16, v213
	v_and_b32_e32 v113, 0xffff0000, v213
	v_pk_fma_f32 v[114:115], v[194:195], v[116:117], v[114:115] op_sel:[0,0,1] op_sel_hi:[1,1,0]
	v_and_b32_e32 v239, 0xffff0000, v124
	v_lshlrev_b32_e32 v238, 16, v120
	v_pk_mul_f32 v[236:237], v[194:195], v[236:237]
	v_pk_add_f32 v[114:115], v[114:115], v[112:113] neg_lo:[0,1] neg_hi:[0,1]
	v_pk_fma_f32 v[236:237], v[194:195], v[238:239], v[236:237] op_sel:[0,0,1] op_sel_hi:[1,1,0]
	v_pk_fma_f32 v[212:213], v[110:111], v[114:115], v[112:113]
	v_add_co_u32_e32 v112, vcc, s2, v218
	v_pk_add_f32 v[236:237], v[236:237], v[206:207] neg_lo:[0,1] neg_hi:[0,1]
	s_nop 0
	v_addc_co_u32_e32 v113, vcc, 0, v219, vcc
	v_pk_fma_f32 v[206:207], v[96:97], v[236:237], v[206:207]
	v_and_b32_e32 v236, 0xffff0000, v128
	v_lshlrev_b32_e32 v237, 16, v132
	v_add_co_u32_e32 v116, vcc, s2, v220
	v_and_b32_e32 v239, 0xffff0000, v132
	v_lshlrev_b32_e32 v238, 16, v128
	v_pk_mul_f32 v[236:237], v[194:195], v[236:237]
	v_addc_co_u32_e32 v117, vcc, 0, v221, vcc
	s_waitcnt vmcnt(0)
	v_lshlrev_b32_e32 v220, 16, v142
	v_and_b32_e32 v221, 0xffff0000, v142
	v_lshlrev_b32_e32 v232, 16, v143
	v_and_b32_e32 v233, 0xffff0000, v143
	v_lshlrev_b32_e32 v142, 16, v214
	v_and_b32_e32 v143, 0xffff0000, v214
	v_pk_fma_f32 v[236:237], v[194:195], v[238:239], v[236:237] op_sel:[0,0,1] op_sel_hi:[1,1,0]
	v_lshlrev_b32_e32 v218, 16, v140
	v_and_b32_e32 v219, 0xffff0000, v140
	v_pk_add_f32 v[236:237], v[236:237], v[228:229] neg_lo:[0,1] neg_hi:[0,1]
	v_pk_add_f32 v[142:143], v[142:143], -1.0 op_sel_hi:[1,0]
	v_pk_fma_f32 v[228:229], v[100:101], v[236:237], v[228:229]
	v_pk_add_f32 v[218:219], v[218:219], -1.0 op_sel_hi:[1,0]
	v_pk_fma_f32 v[142:143], v[88:89], v[142:143], 1.0 op_sel_hi:[1,1,0]
	v_pk_fma_f32 v[218:219], v[88:89], v[218:219], 1.0 op_sel_hi:[1,1,0]
	v_pk_mul_f32 v[142:143], v[228:229], v[142:143]
	v_lshlrev_b32_e32 v124, 16, v121
	v_pk_fma_f32 v[142:143], v[228:229], v[218:219], v[142:143]
	v_lshlrev_b32_e32 v132, 16, v129
	v_pk_mul_f32 v[142:143], v[206:207], v[142:143]
	v_lshlrev_b32_e32 v214, 16, v215
	v_pk_mul_f32 v[142:143], v[92:93], v[142:143]
	v_and_b32_e32 v215, 0xffff0000, v215
	v_add_f32_e32 v63, 0, v142
	v_add_f32_e32 v63, v143, v63
	v_and_b32_e32 v142, 0xffff0000, v121
	v_lshlrev_b32_e32 v143, 16, v125
	v_and_b32_e32 v125, 0xffff0000, v125
	v_pk_mul_f32 v[120:121], v[194:195], v[142:143]
	v_lshlrev_b32_e32 v140, 16, v141
	v_pk_fma_f32 v[120:121], v[194:195], v[124:125], v[120:121] op_sel:[0,0,1] op_sel_hi:[1,1,0]
	v_and_b32_e32 v124, 0xffff0000, v129
	v_lshlrev_b32_e32 v125, 16, v133
	v_and_b32_e32 v133, 0xffff0000, v133
	v_pk_mul_f32 v[124:125], v[194:195], v[124:125]
	v_and_b32_e32 v141, 0xffff0000, v141
	v_pk_fma_f32 v[124:125], v[194:195], v[132:133], v[124:125] op_sel:[0,0,1] op_sel_hi:[1,1,0]
	v_pk_add_f32 v[132:133], v[214:215], -1.0 op_sel_hi:[1,0]
	v_pk_add_f32 v[124:125], v[124:125], v[210:211] neg_lo:[0,1] neg_hi:[0,1]
	v_pk_add_f32 v[128:129], v[140:141], -1.0 op_sel_hi:[1,0]
	v_pk_fma_f32 v[124:125], v[102:103], v[124:125], v[210:211]
	v_pk_fma_f32 v[132:133], v[90:91], v[132:133], 1.0 op_sel_hi:[1,1,0]
	v_pk_add_f32 v[120:121], v[120:121], v[208:209] neg_lo:[0,1] neg_hi:[0,1]
	v_pk_fma_f32 v[128:129], v[90:91], v[128:129], 1.0 op_sel_hi:[1,1,0]
	v_pk_mul_f32 v[132:133], v[124:125], v[132:133]
	v_pk_fma_f32 v[120:121], v[98:99], v[120:121], v[208:209]
	v_pk_fma_f32 v[124:125], v[124:125], v[128:129], v[132:133]
	global_load_dwordx4 v[112:115], v[112:113], off offset:288
	s_nop 0
	global_load_dwordx4 v[116:119], v[116:117], off offset:288
	v_pk_mul_f32 v[120:121], v[120:121], v[124:125]
	v_add_co_u32_e32 v124, vcc, s2, v138
	v_pk_mul_f32 v[120:121], v[94:95], v[120:121]
	s_nop 0
	v_addc_co_u32_e32 v125, vcc, 0, v139, vcc
	global_load_dwordx4 v[140:143], v[124:125], off offset:288
	s_nop 0
	global_load_dwordx4 v[136:139], v[136:137], off offset:2048
	v_add_f32_e32 v63, v120, v63
	v_add_f32_e32 v63, v121, v63
	v_and_b32_e32 v120, 0xffff0000, v122
	v_lshlrev_b32_e32 v121, 16, v126
	v_and_b32_e32 v123, 0xffff0000, v126
	v_lshlrev_b32_e32 v122, 16, v122
	v_pk_mul_f32 v[120:121], v[194:195], v[120:121]
	v_and_b32_e32 v125, 0xffff0000, v134
	v_pk_fma_f32 v[120:121], v[194:195], v[122:123], v[120:121] op_sel:[0,0,1] op_sel_hi:[1,1,0]
	v_and_b32_e32 v122, 0xffff0000, v130
	v_lshlrev_b32_e32 v123, 16, v134
	v_lshlrev_b32_e32 v124, 16, v130
	v_pk_mul_f32 v[122:123], v[194:195], v[122:123]
	v_lshlrev_b32_e32 v234, 16, v216
	v_and_b32_e32 v235, 0xffff0000, v216
	v_pk_fma_f32 v[122:123], v[194:195], v[124:125], v[122:123] op_sel:[0,0,1] op_sel_hi:[1,1,0]
	v_pk_add_f32 v[126:127], v[234:235], -1.0 op_sel_hi:[1,0]
	v_pk_add_f32 v[122:123], v[122:123], v[230:231] neg_lo:[0,1] neg_hi:[0,1]
	v_pk_add_f32 v[124:125], v[220:221], -1.0 op_sel_hi:[1,0]
	v_pk_fma_f32 v[122:123], v[108:109], v[122:123], v[230:231]
	v_pk_fma_f32 v[126:127], v[80:81], v[126:127], 1.0 op_sel_hi:[1,1,0]
	v_pk_add_f32 v[120:121], v[120:121], v[222:223] neg_lo:[0,1] neg_hi:[0,1]
	v_pk_fma_f32 v[124:125], v[80:81], v[124:125], 1.0 op_sel_hi:[1,1,0]
	v_pk_mul_f32 v[126:127], v[122:123], v[126:127]
	v_pk_fma_f32 v[120:121], v[104:105], v[120:121], v[222:223]
	v_pk_fma_f32 v[122:123], v[122:123], v[124:125], v[126:127]
	v_lshlrev_b32_e32 v216, 16, v217
	v_pk_mul_f32 v[120:121], v[120:121], v[122:123]
	v_and_b32_e32 v217, 0xffff0000, v217
	v_pk_mul_f32 v[120:121], v[84:85], v[120:121]
	v_pk_add_f32 v[122:123], v[216:217], -1.0 op_sel_hi:[1,0]
	v_add_f32_e32 v63, v120, v63
	v_add_f32_e32 v63, v121, v63
	v_pk_add_f32 v[120:121], v[232:233], -1.0 op_sel_hi:[1,0]
	v_pk_fma_f32 v[122:123], v[82:83], v[122:123], 1.0 op_sel_hi:[1,1,0]
	v_pk_fma_f32 v[120:121], v[82:83], v[120:121], 1.0 op_sel_hi:[1,1,0]
	v_pk_mul_f32 v[122:123], v[212:213], v[122:123]
	v_add_f32_dpp v61, v61, v61 row_ror:8 row_mask:0xf bank_mask:0xf bound_ctrl:1
	v_pk_fma_f32 v[120:121], v[212:213], v[120:121], v[122:123]
	v_cmp_lt_i32_e32 vcc, v53, v55
	v_pk_mul_f32 v[120:121], v[224:225], v[120:121]
	v_add_f32_dpp v61, v61, v61 row_ror:4 row_mask:0xf bank_mask:0xf bound_ctrl:1
	v_pk_mul_f32 v[120:121], v[86:87], v[120:121]
	v_cndmask_b32_e32 v69, v227, v53, vcc
	v_add_f32_e32 v63, v120, v63
	v_add_f32_dpp v61, v61, v61 row_ror:2 row_mask:0xf bank_mask:0xf bound_ctrl:1
	v_add_f32_e32 v63, v121, v63
	v_pk_add_f32 v[124:125], v[198:199], v[144:145] op_sel_hi:[1,0] neg_lo:[0,1] neg_hi:[0,1]
	v_pk_add_f32 v[120:121], v[196:197], v[144:145] op_sel_hi:[1,0] neg_lo:[0,1] neg_hi:[0,1]
	v_add_f32_dpp v61, v61, v61 row_ror:1 row_mask:0xf bank_mask:0xf bound_ctrl:1
	v_lshlrev_b32_e32 v69, 2, v69
	v_mov_b32_e32 v122, v124
	v_mov_b32_e32 v123, v120
	ds_bpermute_b32 v69, v69, v61
	v_add_f32_dpp v63, v63, v63 quad_perm:[1,0,3,2] row_mask:0xf bank_mask:0xf bound_ctrl:1
	v_pk_mul_f32 v[128:129], v[122:123], v[122:123]
	v_mov_b32_e32 v122, v121
	v_mov_b32_e32 v123, v125
	v_add_f32_dpp v65, v63, v63 quad_perm:[2,3,0,1] row_mask:0xf bank_mask:0xf bound_ctrl:1
	v_pk_mul_f32 v[130:131], v[122:123], v[122:123]
	v_pk_add_f32 v[126:127], v[202:203], v[144:145] op_sel_hi:[1,0] neg_lo:[0,1] neg_hi:[0,1]
	v_pk_add_f32 v[122:123], v[200:201], v[144:145] op_sel_hi:[1,0] neg_lo:[0,1] neg_hi:[0,1]
	v_add_f32_e32 v63, v128, v129
	v_mov_b32_e32 v132, v122
	v_mov_b32_e32 v133, v126
	v_add_f32_e32 v63, v131, v63
	v_pk_mul_f32 v[132:133], v[132:133], v[132:133]
	v_add_f32_e32 v63, v130, v63
	v_cmp_lt_i32_e32 vcc, v57, v55
	v_mov_b32_e32 v134, v123
	v_mov_b32_e32 v135, v127
	v_add_f32_e32 v63, v133, v63
	s_waitcnt lgkmcnt(0)
	v_add_f32_e32 v69, v61, v69
	v_cndmask_b32_e32 v61, v227, v57, vcc
	v_pk_mul_f32 v[134:135], v[134:135], v[134:135]
	v_add_f32_e32 v63, v132, v63
	v_lshlrev_b32_e32 v61, 2, v61
	v_add_f32_e32 v63, v135, v63
	ds_bpermute_b32 v71, v61, v69
	v_add_f32_e32 v63, v134, v63
	v_mov_b32_dpp v67, v65 row_half_mirror row_mask:0xf bank_mask:0xf
	s_nop 0
	v_add_f32_dpp v61, v63, v63 quad_perm:[1,0,3,2] row_mask:0xf bank_mask:0xf bound_ctrl:1
	v_mov_b32_e32 v63, 0
	s_nop 0
	v_add_f32_dpp v61, v61, v61 quad_perm:[2,3,0,1] row_mask:0xf bank_mask:0xf bound_ctrl:1
	s_nop 1
	v_mov_b32_dpp v63, v61 row_half_mirror row_mask:0xf bank_mask:0xf
	s_and_saveexec_b64 s[6:7], s[0:1]
	s_cbranch_execz .LBB0_2835
	s_waitcnt lgkmcnt(0)
	v_add_f32_e32 v69, v69, v71
	v_fmamk_f32 v69, v69, 0x3b2aaaab, v25
	v_mul_f32_e32 v71, 0x4b800000, v69
	v_cmp_gt_f32_e32 vcc, s22, v69
	s_nop 1
	v_cndmask_b32_e32 v69, v69, v71, vcc
	v_rsq_f32_e32 v69, v69
	s_nop 0
	v_mul_f32_e32 v71, 0x45800000, v69
	v_cndmask_b32_e32 v130, v69, v71, vcc
	v_pk_mul_f32 v[132:133], v[188:189], v[130:131] op_sel_hi:[1,0]
	v_pk_mul_f32 v[128:129], v[186:187], v[130:131] op_sel_hi:[1,0]
	v_pk_mul_f32 v[132:133], v[10:11], v[132:133]
	v_pk_mul_f32 v[128:129], v[36:37], v[128:129]
	v_and_b32_sdwa v73, v133, v59 dst_sel:DWORD dst_unused:UNUSED_PAD src0_sel:WORD_1 src1_sel:DWORD
	v_and_b32_sdwa v75, v132, v59 dst_sel:DWORD dst_unused:UNUSED_PAD src0_sel:WORD_1 src1_sel:DWORD
	v_and_b32_sdwa v69, v129, v59 dst_sel:DWORD dst_unused:UNUSED_PAD src0_sel:WORD_1 src1_sel:DWORD
	v_and_b32_sdwa v71, v128, v59 dst_sel:DWORD dst_unused:UNUSED_PAD src0_sel:WORD_1 src1_sel:DWORD
	v_add3_u32 v73, v133, v73, s23
	v_add3_u32 v75, v132, v75, s23
	v_pk_mul_f32 v[132:133], v[190:191], v[130:131] op_sel_hi:[1,0]
	v_pk_mul_f32 v[130:131], v[192:193], v[130:131] op_sel_hi:[1,0]
	v_add3_u32 v71, v128, v71, s23
	v_add3_u32 v69, v129, v69, s23
	v_and_b32_e32 v73, 0xffff0000, v73
	v_and_b32_e32 v75, 0xffff0000, v75
	v_pk_mul_f32 v[130:131], v[14:15], v[130:131]
	v_or_b32_sdwa v129, v73, v69 dst_sel:DWORD dst_unused:UNUSED_PAD src0_sel:DWORD src1_sel:WORD_1
	v_or_b32_sdwa v128, v75, v71 dst_sel:DWORD dst_unused:UNUSED_PAD src0_sel:DWORD src1_sel:WORD_1
	v_pk_mul_f32 v[132:133], v[32:33], v[132:133]
	v_and_b32_sdwa v73, v131, v59 dst_sel:DWORD dst_unused:UNUSED_PAD src0_sel:WORD_1 src1_sel:DWORD
	v_and_b32_sdwa v75, v130, v59 dst_sel:DWORD dst_unused:UNUSED_PAD src0_sel:WORD_1 src1_sel:DWORD
	v_and_b32_sdwa v69, v133, v59 dst_sel:DWORD dst_unused:UNUSED_PAD src0_sel:WORD_1 src1_sel:DWORD
	v_and_b32_sdwa v71, v132, v59 dst_sel:DWORD dst_unused:UNUSED_PAD src0_sel:WORD_1 src1_sel:DWORD
	v_add3_u32 v73, v131, v73, s23
	v_add3_u32 v75, v130, v75, s23
	v_add3_u32 v71, v132, v71, s23
	v_add3_u32 v69, v133, v69, s23
	v_and_b32_e32 v73, 0xffff0000, v73
	v_and_b32_e32 v75, 0xffff0000, v75
	v_or_b32_sdwa v131, v73, v69 dst_sel:DWORD dst_unused:UNUSED_PAD src0_sel:DWORD src1_sel:WORD_1
	v_or_b32_sdwa v130, v75, v71 dst_sel:DWORD dst_unused:UNUSED_PAD src0_sel:DWORD src1_sel:WORD_1
	global_store_dwordx4 v[182:183], v[128:131], off

.LBB0_3006:
	s_mul_i32 s51, s49, 0x6000
	s_waitcnt vmcnt(6)
	s_add_i32 s51, s29, s51
	s_mul_i32 s98, s50, 0x6000
	v_lshl_add_u64 v[196:197], v[136:137], 0, s[26:27]
	v_lshl_add_u64 v[198:199], v[134:135], 0, s[26:27]
	s_add_i32 s99, s51, s30
	s_waitcnt lgkmcnt(0)
	s_barrier
	v_add_u32_e32 v178, s98, v139
	v_add_u32_e32 v179, s98, v141
	ds_read_b128 v[162:165], v179
	ds_read_b128 v[146:149], v178
	ds_read_b128 v[166:169], v179 offset:1024
	ds_read_b128 v[170:173], v179 offset:2048
	ds_read_b128 v[174:177], v179 offset:3072
	ds_read_b128 v[150:153], v178 offset:1024
	ds_read_b128 v[154:157], v178 offset:2048
	ds_read_b128 v[158:161], v178 offset:3072
	ds_read_b128 v[180:183], v178 offset:4096
	ds_read_b128 v[184:187], v178 offset:5120
	ds_read_b128 v[188:191], v178 offset:6144
	ds_read_b128 v[192:195], v178 offset:7168
	v_lshl_add_u64 v[200:201], v[196:197], 0, s[18:19]
	s_mov_b32 m0, s51
	s_waitcnt lgkmcnt(10)
	v_mfma_f32_16x16x32_bf16 v[84:87], v[146:149], v[162:165], v[84:87]
	global_load_lds_dwordx4 v[200:201], off
	s_waitcnt lgkmcnt(9)
	v_mfma_f32_16x16x32_bf16 v[76:79], v[146:149], v[166:169], v[76:79]
	v_lshl_add_u64 v[200:201], v[196:197], 0, s[20:21]
	s_add_i32 m0, s51, 0x400
	s_waitcnt lgkmcnt(8)
	v_mfma_f32_16x16x32_bf16 v[68:71], v[146:149], v[170:173], v[68:71]
	global_load_lds_dwordx4 v[200:201], off
	s_waitcnt lgkmcnt(7)
	v_mfma_f32_16x16x32_bf16 v[60:63], v[146:149], v[174:177], v[60:63]
	v_lshl_add_u64 v[200:201], v[196:197], 0, s[22:23]
	s_add_i32 m0, s51, 0x800
	s_waitcnt lgkmcnt(6)
	v_mfma_f32_16x16x32_bf16 v[52:55], v[150:153], v[162:165], v[52:55]
	global_load_lds_dwordx4 v[200:201], off
	v_mfma_f32_16x16x32_bf16 v[44:47], v[150:153], v[166:169], v[44:47]
	v_mfma_f32_16x16x32_bf16 v[36:39], v[150:153], v[170:173], v[36:39]
	v_lshl_add_u64 v[200:201], v[196:197], 0, s[24:25]
	s_add_i32 m0, s51, 0xc00
	v_mfma_f32_16x16x32_bf16 v[32:35], v[150:153], v[174:177], v[32:35]
	global_load_lds_dwordx4 v[200:201], off
	s_waitcnt lgkmcnt(5)
	v_mfma_f32_16x16x32_bf16 v[28:31], v[154:157], v[162:165], v[28:31]
	v_lshl_add_u64 v[200:201], v[198:199], 0, s[18:19]
	s_add_i32 m0, s99, 0x4000
	v_mfma_f32_16x16x32_bf16 v[24:27], v[154:157], v[166:169], v[24:27]
	global_load_lds_dwordx4 v[200:201], off
	v_mfma_f32_16x16x32_bf16 v[20:23], v[154:157], v[170:173], v[20:23]
	v_lshl_add_u64 v[200:201], v[198:199], 0, s[20:21]
	s_add_i32 m0, s99, 0x4400
	v_mfma_f32_16x16x32_bf16 v[16:19], v[154:157], v[174:177], v[16:19]
	global_load_lds_dwordx4 v[200:201], off
	s_waitcnt lgkmcnt(4)
	v_mfma_f32_16x16x32_bf16 v[12:15], v[158:161], v[162:165], v[12:15]
	v_mfma_f32_16x16x32_bf16 v[8:11], v[158:161], v[166:169], v[8:11]
	v_mfma_f32_16x16x32_bf16 v[4:7], v[158:161], v[170:173], v[4:7]
	v_mfma_f32_16x16x32_bf16 v[0:3], v[158:161], v[174:177], v[0:3]
	s_waitcnt lgkmcnt(3)
	v_mfma_f32_16x16x32_bf16 v[124:127], v[180:183], v[162:165], v[124:127]
	v_mfma_f32_16x16x32_bf16 v[120:123], v[180:183], v[166:169], v[120:123]
	v_mfma_f32_16x16x32_bf16 v[116:119], v[180:183], v[170:173], v[116:119]
	v_mfma_f32_16x16x32_bf16 v[112:115], v[180:183], v[174:177], v[112:115]
	s_waitcnt lgkmcnt(2)
	v_mfma_f32_16x16x32_bf16 v[108:111], v[184:187], v[162:165], v[108:111]
	v_mfma_f32_16x16x32_bf16 v[104:107], v[184:187], v[166:169], v[104:107]
	v_mfma_f32_16x16x32_bf16 v[100:103], v[184:187], v[170:173], v[100:103]
	v_mfma_f32_16x16x32_bf16 v[96:99], v[184:187], v[174:177], v[96:99]
	s_waitcnt lgkmcnt(1)
	v_mfma_f32_16x16x32_bf16 v[92:95], v[188:191], v[162:165], v[92:95]
	v_mfma_f32_16x16x32_bf16 v[88:91], v[188:191], v[166:169], v[88:91]
	v_mfma_f32_16x16x32_bf16 v[80:83], v[188:191], v[170:173], v[80:83]
	v_mfma_f32_16x16x32_bf16 v[72:75], v[188:191], v[174:177], v[72:75]
	s_waitcnt lgkmcnt(0)
	v_mfma_f32_16x16x32_bf16 v[64:67], v[192:195], v[162:165], v[64:67]
	v_mfma_f32_16x16x32_bf16 v[56:59], v[192:195], v[166:169], v[56:59]
	v_mfma_f32_16x16x32_bf16 v[48:51], v[192:195], v[170:173], v[48:51]
	v_mfma_f32_16x16x32_bf16 v[40:43], v[192:195], v[174:177], v[40:43]
	s_add_i32 s51, s50, 1
	s_cmp_lg_u32 s50, 2
	s_cselect_b32 s50, s51, 0
	s_add_i32 s51, s49, 1
	s_cmp_lg_u32 s49, 2
	s_cselect_b32 s49, s51, 0
	s_add_u32 s26, s26, 64
	s_addc_u32 s27, s27, 0
	s_cmpk_eq_i32 s26, 0x780
	s_cbranch_scc0 .LBB0_3006
	s_waitcnt vmcnt(6)
	s_waitcnt lgkmcnt(0)
	s_barrier
	ds_read_b128 v[134:137], v139
	ds_read_b128 v[146:149], v139 offset:1024
	ds_read_b128 v[150:153], v139 offset:2048
	ds_read_b128 v[154:157], v139 offset:3072
	ds_read_b128 v[158:161], v141
	ds_read_b128 v[162:165], v141 offset:1024
	ds_read_b128 v[166:169], v141 offset:2048
	ds_read_b128 v[170:173], v141 offset:3072
	s_waitcnt lgkmcnt(0)
	s_nop 0
	v_mfma_f32_16x16x32_bf16 v[84:87], v[134:137], v[158:161], v[84:87]
	v_mfma_f32_16x16x32_bf16 v[76:79], v[134:137], v[162:165], v[76:79]
	v_mfma_f32_16x16x32_bf16 v[68:71], v[134:137], v[166:169], v[68:71]
	v_mfma_f32_16x16x32_bf16 v[60:63], v[134:137], v[170:173], v[60:63]
	v_mfma_f32_16x16x32_bf16 v[52:55], v[146:149], v[158:161], v[52:55]
	v_mfma_f32_16x16x32_bf16 v[44:47], v[146:149], v[162:165], v[44:47]
	v_mfma_f32_16x16x32_bf16 v[36:39], v[146:149], v[166:169], v[36:39]
	v_mfma_f32_16x16x32_bf16 v[32:35], v[146:149], v[170:173], v[32:35]
	v_mfma_f32_16x16x32_bf16 v[28:31], v[150:153], v[158:161], v[28:31]
	v_mfma_f32_16x16x32_bf16 v[24:27], v[150:153], v[162:165], v[24:27]
	v_mfma_f32_16x16x32_bf16 v[20:23], v[150:153], v[166:169], v[20:23]
	v_mfma_f32_16x16x32_bf16 v[16:19], v[150:153], v[170:173], v[16:19]
	v_mfma_f32_16x16x32_bf16 v[12:15], v[154:157], v[158:161], v[12:15]
	v_mfma_f32_16x16x32_bf16 v[8:11], v[154:157], v[162:165], v[8:11]
	v_mfma_f32_16x16x32_bf16 v[4:7], v[154:157], v[166:169], v[4:7]
	v_mfma_f32_16x16x32_bf16 v[0:3], v[154:157], v[170:173], v[0:3]
	ds_read_b128 v[134:137], v139 offset:4096
	ds_read_b128 v[146:149], v139 offset:5120
	ds_read_b128 v[150:153], v139 offset:6144
	ds_read_b128 v[154:157], v139 offset:7168
	s_waitcnt lgkmcnt(0)
	s_nop 0
	v_mfma_f32_16x16x32_bf16 v[124:127], v[134:137], v[158:161], v[124:127]
	v_mfma_f32_16x16x32_bf16 v[120:123], v[134:137], v[162:165], v[120:123]
	v_mfma_f32_16x16x32_bf16 v[174:177], v[134:137], v[166:169], v[116:119]
	v_mfma_f32_16x16x32_bf16 v[134:137], v[134:137], v[170:173], v[112:115]
	v_mfma_f32_16x16x32_bf16 v[178:181], v[146:149], v[158:161], v[108:111]
	v_mfma_f32_16x16x32_bf16 v[182:185], v[146:149], v[162:165], v[104:107]
	v_mfma_f32_16x16x32_bf16 v[186:189], v[146:149], v[166:169], v[100:103]
	v_mfma_f32_16x16x32_bf16 v[146:149], v[146:149], v[170:173], v[96:99]
	v_mfma_f32_16x16x32_bf16 v[190:193], v[150:153], v[158:161], v[92:95]
	v_mfma_f32_16x16x32_bf16 v[194:197], v[150:153], v[162:165], v[88:91]
	v_mfma_f32_16x16x32_bf16 v[198:201], v[150:153], v[166:169], v[80:83]
	v_mfma_f32_16x16x32_bf16 v[150:153], v[150:153], v[170:173], v[72:75]
	v_mfma_f32_16x16x32_bf16 v[158:161], v[154:157], v[158:161], v[64:67]
	v_mfma_f32_16x16x32_bf16 v[162:165], v[154:157], v[162:165], v[56:59]
	v_mfma_f32_16x16x32_bf16 v[166:169], v[154:157], v[166:169], v[48:51]
	v_mfma_f32_16x16x32_bf16 v[154:157], v[154:157], v[170:173], v[40:43]
	s_waitcnt vmcnt(0)
	s_waitcnt lgkmcnt(0)
	s_barrier
	ds_read_b128 v[40:43], v128
	ds_read_b128 v[48:51], v128 offset:1024
	ds_read_b128 v[56:59], v128 offset:2048
	ds_read_b128 v[170:173], v128 offset:3072
	ds_read_b128 v[202:205], v144
	ds_read_b128 v[206:209], v144 offset:1024
	ds_read_b128 v[210:213], v144 offset:2048
	ds_read_b128 v[214:217], v144 offset:3072
	s_waitcnt lgkmcnt(0)
	s_nop 0
	v_mfma_f32_16x16x32_bf16 v[222:225], v[40:43], v[206:209], v[76:79]
	v_mfma_f32_16x16x32_bf16 v[112:115], v[40:43], v[210:213], v[68:71]
	v_mfma_f32_16x16x32_bf16 v[72:75], v[170:173], v[202:205], v[12:15]
	v_mfma_f32_16x16x32_bf16 v[76:79], v[170:173], v[206:209], v[8:11]
	v_mfma_f32_16x16x32_bf16 v[64:67], v[170:173], v[210:213], v[4:7]
	v_mfma_f32_16x16x32_bf16 v[68:71], v[170:173], v[214:217], v[0:3]
	ds_read_b128 v[0:3], v128 offset:4096
	ds_read_b128 v[4:7], v128 offset:5120
	ds_read_b128 v[8:11], v128 offset:6144
	ds_read_b128 v[170:173], v128 offset:7168
	s_waitcnt lgkmcnt(0)
	v_mfma_f32_16x16x32_bf16 v[218:221], v[40:43], v[202:205], v[84:87]
	v_mfma_f32_16x16x32_bf16 v[116:119], v[40:43], v[214:217], v[60:63]
	v_mfma_f32_16x16x32_bf16 v[104:107], v[48:51], v[202:205], v[52:55]
	v_mfma_f32_16x16x32_bf16 v[108:111], v[48:51], v[206:209], v[44:47]
	v_mfma_f32_16x16x32_bf16 v[96:99], v[48:51], v[210:213], v[36:39]
	v_mfma_f32_16x16x32_bf16 v[100:103], v[48:51], v[214:217], v[32:35]
	v_mfma_f32_16x16x32_bf16 v[88:91], v[56:59], v[202:205], v[28:31]
	v_mfma_f32_16x16x32_bf16 v[92:95], v[56:59], v[206:209], v[24:27]
	v_mfma_f32_16x16x32_bf16 v[80:83], v[56:59], v[210:213], v[20:23]
	v_mfma_f32_16x16x32_bf16 v[84:87], v[56:59], v[214:217], v[16:19]
	v_mfma_f32_16x16x32_bf16 v[56:59], v[0:3], v[202:205], v[124:127]
	v_mfma_f32_16x16x32_bf16 v[60:63], v[0:3], v[206:209], v[120:123]
	v_mfma_f32_16x16x32_bf16 v[48:51], v[0:3], v[210:213], v[174:177]
	v_mfma_f32_16x16x32_bf16 v[52:55], v[0:3], v[214:217], v[134:137]
	v_mfma_f32_16x16x32_bf16 v[40:43], v[4:7], v[202:205], v[178:181]
	v_mfma_f32_16x16x32_bf16 v[44:47], v[4:7], v[206:209], v[182:185]
	v_mfma_f32_16x16x32_bf16 v[32:35], v[4:7], v[210:213], v[186:189]
	v_mfma_f32_16x16x32_bf16 v[36:39], v[4:7], v[214:217], v[146:149]
	v_mfma_f32_16x16x32_bf16 v[24:27], v[8:11], v[202:205], v[190:193]
	v_mfma_f32_16x16x32_bf16 v[28:31], v[8:11], v[206:209], v[194:197]
	v_mfma_f32_16x16x32_bf16 v[16:19], v[8:11], v[210:213], v[198:201]
	v_mfma_f32_16x16x32_bf16 v[20:23], v[8:11], v[214:217], v[150:153]
	v_mfma_f32_16x16x32_bf16 v[8:11], v[170:173], v[202:205], v[158:161]
	v_mfma_f32_16x16x32_bf16 v[12:15], v[170:173], v[206:209], v[162:165]
	v_mfma_f32_16x16x32_bf16 v[0:3], v[170:173], v[210:213], v[166:169]
	v_mfma_f32_16x16x32_bf16 v[4:7], v[170:173], v[214:217], v[154:157]
	v_mul_f32_e32 v121, 0xbfb8aa3b, v218
	v_exp_f32_e32 v121, v121
	v_or_b32_e32 v120, s48, v140
	v_ashrrev_i32_e32 v120, 1, v120
	v_or_b32_e32 v122, v120, v138
	v_add_f32_e32 v120, 1.0, v121
	v_rcp_f32_e32 v125, v120
	v_add_u32_e32 v124, s47, v145
	v_mov_b32_e32 v126, v124
	s_waitcnt lgkmcnt(0)
	v_mul_f32_e32 v120, v218, v125
	v_mul_f32_e32 v120, v222, v120
	v_mul_f32_e32 v134, 0xbfb8aa3b, v219
	v_bfe_u32 v121, v120, 16, 1
	v_exp_f32_e32 v134, v134
	s_barrier
	v_ashrrev_i32_e32 v123, 31, v122
	v_add3_u32 v125, v120, v121, s46
	v_mov_b64_e32 v[120:121], s[52:53]
	v_mad_i64_i32 v[126:127], s[26:27], v126, s45, v[120:121]
	v_lshlrev_b64 v[122:123], 1, v[122:123]
	v_lshl_add_u64 v[126:127], v[126:127], 0, v[122:123]
	global_store_short_d16_hi v[126:127], v125, off
	v_add_f32_e32 v125, 1.0, v134
	v_rcp_f32_e32 v127, v125
	v_or_b32_e32 v134, 1, v124
	v_mov_b32_e32 v135, v134
	v_mul_f32_e32 v125, v219, v127
	v_mul_f32_e32 v125, v223, v125
	v_bfe_u32 v126, v125, 16, 1
	v_add3_u32 v125, v125, v126, s46
	v_mul_f32_e32 v126, 0xbfb8aa3b, v220
	v_exp_f32_e32 v136, v126
	v_mad_i64_i32 v[126:127], s[26:27], v135, s45, v[120:121]
	v_lshl_add_u64 v[126:127], v[126:127], 0, v[122:123]
	global_store_short_d16_hi v[126:127], v125, off
	v_add_f32_e32 v125, 1.0, v136
	v_rcp_f32_e32 v127, v125
	v_or_b32_e32 v135, 2, v124
	v_mov_b32_e32 v136, v135
	v_mul_f32_e32 v125, v220, v127
	v_mul_f32_e32 v125, v224, v125
	v_bfe_u32 v126, v125, 16, 1
	v_add3_u32 v125, v125, v126, s46
	v_mul_f32_e32 v126, 0xbfb8aa3b, v221
	v_exp_f32_e32 v137, v126
	v_mad_i64_i32 v[126:127], s[26:27], v136, s45, v[120:121]
	v_lshl_add_u64 v[126:127], v[126:127], 0, v[122:123]
	global_store_short_d16_hi v[126:127], v125, off
	v_add_f32_e32 v125, 1.0, v137
	v_rcp_f32_e32 v127, v125
	v_or_b32_e32 v136, 3, v124
	v_mov_b32_e32 v137, v136
	v_mul_f32_e32 v125, v221, v127
	v_mul_f32_e32 v125, v225, v125
	v_bfe_u32 v126, v125, 16, 1
	v_add3_u32 v125, v125, v126, s46
	v_mul_f32_e32 v126, 0xbfb8aa3b, v112
	v_exp_f32_e32 v146, v126
	v_mad_i64_i32 v[126:127], s[26:27], v137, s45, v[120:121]
	v_lshl_add_u64 v[126:127], v[126:127], 0, v[122:123]
	v_add_f32_e32 v137, 1.0, v146
	v_rcp_f32_e32 v147, v137
	global_store_short_d16_hi v[126:127], v125, off
	v_mov_b32_e32 v125, v124
	v_mul_f32_e32 v112, v112, v147
	v_mul_f32_e32 v126, 0xbfb8aa3b, v113
	v_exp_f32_e32 v137, v126
	v_mul_f32_e32 v112, v116, v112
	v_bfe_u32 v116, v112, 16, 1
	v_add3_u32 v112, v112, v116, s46
	v_add_f32_e32 v116, 1.0, v137
	v_mad_i64_i32 v[126:127], s[26:27], v125, s45, v[120:121]
	v_rcp_f32_e32 v137, v116
	v_lshl_add_u64 v[126:127], v[126:127], 0, v[122:123]
	global_store_short_d16_hi v[126:127], v112, off offset:32
	v_mul_f32_e32 v112, v113, v137
	v_mul_f32_e32 v116, 0xbfb8aa3b, v114
	v_exp_f32_e32 v116, v116
	v_mul_f32_e32 v112, v117, v112
	v_bfe_u32 v113, v112, 16, 1
	v_add3_u32 v117, v112, v113, s46
	v_add_f32_e32 v116, 1.0, v116
	v_rcp_f32_e32 v126, v116
	v_mad_i64_i32 v[112:113], s[26:27], v134, s45, v[120:121]
	v_lshl_add_u64 v[112:113], v[112:113], 0, v[122:123]
	global_store_short_d16_hi v[112:113], v117, off offset:32
	v_mul_f32_e32 v112, v114, v126
	v_mul_f32_e32 v114, 0xbfb8aa3b, v115
	v_exp_f32_e32 v114, v114
	v_mul_f32_e32 v112, v118, v112
	v_bfe_u32 v113, v112, 16, 1
	v_add_f32_e32 v114, 1.0, v114
	v_rcp_f32_e32 v118, v114
	v_add3_u32 v116, v112, v113, s46
	v_mad_i64_i32 v[112:113], s[26:27], v135, s45, v[120:121]
	v_lshl_add_u64 v[112:113], v[112:113], 0, v[122:123]
	global_store_short_d16_hi v[112:113], v116, off offset:32
	v_mul_f32_e32 v112, v115, v118
	v_mul_f32_e32 v112, v119, v112
	v_bfe_u32 v113, v112, 16, 1
	v_add3_u32 v114, v112, v113, s46
	v_mul_f32_e32 v112, 0xbfb8aa3b, v104
	v_exp_f32_e32 v115, v112
	s_nop 0
	v_mad_i64_i32 v[112:113], s[26:27], v136, s45, v[120:121]
	v_lshl_add_u64 v[112:113], v[112:113], 0, v[122:123]
	global_store_short_d16_hi v[112:113], v114, off offset:32
	v_add_f32_e32 v112, 1.0, v115
	v_rcp_f32_e32 v114, v112
	v_or_b32_e32 v115, 16, v124
	v_mov_b32_e32 v116, v115
	v_mul_f32_e32 v104, v104, v114
	v_mul_f32_e32 v104, v108, v104
	v_bfe_u32 v108, v104, 16, 1
	v_add3_u32 v104, v104, v108, s46
	v_mul_f32_e32 v108, 0xbfb8aa3b, v105
	v_exp_f32_e32 v108, v108
	v_mad_i64_i32 v[112:113], s[26:27], v116, s45, v[120:121]
	v_lshl_add_u64 v[112:113], v[112:113], 0, v[122:123]
	global_store_short_d16_hi v[112:113], v104, off
	v_add_f32_e32 v104, 1.0, v108
	v_rcp_f32_e32 v112, v104
	v_or_b32_e32 v113, 17, v124
	v_mov_b32_e32 v114, v113
	v_mul_f32_e32 v104, v105, v112
	v_mul_f32_e32 v104, v109, v104
	v_bfe_u32 v105, v104, 16, 1
	v_add3_u32 v108, v104, v105, s46
	v_mul_f32_e32 v104, 0xbfb8aa3b, v106
	v_exp_f32_e32 v109, v104
	v_mad_i64_i32 v[104:105], s[26:27], v114, s45, v[120:121]
	v_lshl_add_u64 v[104:105], v[104:105], 0, v[122:123]
	global_store_short_d16_hi v[104:105], v108, off
	v_add_f32_e32 v104, 1.0, v109
	v_rcp_f32_e32 v108, v104
	v_or_b32_e32 v109, 18, v124
	v_mov_b32_e32 v112, v109
	v_mul_f32_e32 v104, v106, v108
	v_mul_f32_e32 v104, v110, v104
	v_bfe_u32 v105, v104, 16, 1
	v_add3_u32 v106, v104, v105, s46
	v_mul_f32_e32 v104, 0xbfb8aa3b, v107
	v_exp_f32_e32 v108, v104
	v_mad_i64_i32 v[104:105], s[26:27], v112, s45, v[120:121]
	v_lshl_add_u64 v[104:105], v[104:105], 0, v[122:123]
	global_store_short_d16_hi v[104:105], v106, off
	v_add_f32_e32 v104, 1.0, v108
	v_rcp_f32_e32 v106, v104
	v_or_b32_e32 v108, 19, v124
	v_mov_b32_e32 v110, v108
	v_mul_f32_e32 v104, v107, v106
	v_mul_f32_e32 v106, 0xbfb8aa3b, v96
	v_exp_f32_e32 v106, v106
	v_mul_f32_e32 v104, v111, v104
	v_bfe_u32 v105, v104, 16, 1
	v_add_f32_e32 v106, 1.0, v106
	v_add3_u32 v107, v104, v105, s46
	v_mad_i64_i32 v[104:105], s[26:27], v110, s45, v[120:121]
	v_rcp_f32_e32 v111, v106
	v_lshl_add_u64 v[104:105], v[104:105], 0, v[122:123]
	global_store_short_d16_hi v[104:105], v107, off
	v_mul_f32_e32 v96, v96, v111
	v_mul_f32_e32 v104, 0xbfb8aa3b, v97
	v_exp_f32_e32 v106, v104
	v_mul_f32_e32 v96, v100, v96
	v_bfe_u32 v100, v96, 16, 1
	v_add3_u32 v96, v96, v100, s46
	v_add_f32_e32 v100, 1.0, v106
	v_rcp_f32_e32 v107, v100
	v_mad_i64_i32 v[104:105], s[26:27], v115, s45, v[120:121]
	v_lshl_add_u64 v[104:105], v[104:105], 0, v[122:123]
	global_store_short_d16_hi v[104:105], v96, off offset:32
	v_mul_f32_e32 v96, v97, v107
	v_mul_f32_e32 v100, 0xbfb8aa3b, v98
	v_exp_f32_e32 v100, v100
	v_mul_f32_e32 v96, v101, v96
	v_bfe_u32 v97, v96, 16, 1
	v_add_f32_e32 v100, 1.0, v100
	v_rcp_f32_e32 v105, v100
	v_add3_u32 v101, v96, v97, s46
	v_mad_i64_i32 v[96:97], s[26:27], v113, s45, v[120:121]
	v_lshl_add_u64 v[96:97], v[96:97], 0, v[122:123]
	global_store_short_d16_hi v[96:97], v101, off offset:32
	v_mul_f32_e32 v96, v98, v105
	v_mul_f32_e32 v98, 0xbfb8aa3b, v99
	v_exp_f32_e32 v98, v98
	v_mul_f32_e32 v96, v102, v96
	v_bfe_u32 v97, v96, 16, 1
	v_add_f32_e32 v98, 1.0, v98
	v_rcp_f32_e32 v102, v98
	v_add3_u32 v100, v96, v97, s46
	v_mad_i64_i32 v[96:97], s[26:27], v109, s45, v[120:121]
	v_lshl_add_u64 v[96:97], v[96:97], 0, v[122:123]
	global_store_short_d16_hi v[96:97], v100, off offset:32
	v_mul_f32_e32 v96, v99, v102
	v_mul_f32_e32 v96, v103, v96
	v_bfe_u32 v97, v96, 16, 1
	v_add3_u32 v98, v96, v97, s46
	v_mul_f32_e32 v96, 0xbfb8aa3b, v88
	v_exp_f32_e32 v99, v96
	s_nop 0
	v_mad_i64_i32 v[96:97], s[26:27], v108, s45, v[120:121]
	v_lshl_add_u64 v[96:97], v[96:97], 0, v[122:123]
	global_store_short_d16_hi v[96:97], v98, off offset:32
	v_add_f32_e32 v96, 1.0, v99
	v_rcp_f32_e32 v98, v96
	v_or_b32_e32 v99, 32, v124
	v_mov_b32_e32 v100, v99
	v_mul_f32_e32 v88, v88, v98
	v_mul_f32_e32 v88, v92, v88
	v_bfe_u32 v92, v88, 16, 1
	v_add3_u32 v88, v88, v92, s46
	v_mul_f32_e32 v92, 0xbfb8aa3b, v89
	v_exp_f32_e32 v92, v92
	v_mad_i64_i32 v[96:97], s[26:27], v100, s45, v[120:121]
	v_lshl_add_u64 v[96:97], v[96:97], 0, v[122:123]
	global_store_short_d16_hi v[96:97], v88, off
	v_add_f32_e32 v88, 1.0, v92
	v_rcp_f32_e32 v96, v88
	v_or_b32_e32 v97, 33, v124
	v_mov_b32_e32 v98, v97
	v_mul_f32_e32 v88, v89, v96
	v_mul_f32_e32 v88, v93, v88
	v_bfe_u32 v89, v88, 16, 1
	v_add3_u32 v92, v88, v89, s46
	v_mul_f32_e32 v88, 0xbfb8aa3b, v90
	v_exp_f32_e32 v93, v88
	v_mad_i64_i32 v[88:89], s[26:27], v98, s45, v[120:121]
	v_lshl_add_u64 v[88:89], v[88:89], 0, v[122:123]
	global_store_short_d16_hi v[88:89], v92, off
	v_add_f32_e32 v88, 1.0, v93
	v_rcp_f32_e32 v92, v88
	v_or_b32_e32 v93, 34, v124
	v_mov_b32_e32 v96, v93
	v_mul_f32_e32 v88, v90, v92
	v_mul_f32_e32 v88, v94, v88
	v_bfe_u32 v89, v88, 16, 1
	v_add3_u32 v90, v88, v89, s46
	v_mul_f32_e32 v88, 0xbfb8aa3b, v91
	v_exp_f32_e32 v92, v88
	v_mad_i64_i32 v[88:89], s[26:27], v96, s45, v[120:121]
	v_lshl_add_u64 v[88:89], v[88:89], 0, v[122:123]
	global_store_short_d16_hi v[88:89], v90, off
	v_add_f32_e32 v88, 1.0, v92
	v_rcp_f32_e32 v90, v88
	v_or_b32_e32 v92, 35, v124
	v_mov_b32_e32 v94, v92
	v_mul_f32_e32 v88, v91, v90
	v_mul_f32_e32 v90, 0xbfb8aa3b, v80
	v_exp_f32_e32 v90, v90
	v_mul_f32_e32 v88, v95, v88
	v_bfe_u32 v89, v88, 16, 1
	v_add_f32_e32 v90, 1.0, v90
	v_add3_u32 v91, v88, v89, s46
	v_mad_i64_i32 v[88:89], s[26:27], v94, s45, v[120:121]
	v_rcp_f32_e32 v95, v90
	v_lshl_add_u64 v[88:89], v[88:89], 0, v[122:123]
	global_store_short_d16_hi v[88:89], v91, off
	v_mul_f32_e32 v80, v80, v95
	v_mul_f32_e32 v88, 0xbfb8aa3b, v81
	v_exp_f32_e32 v90, v88
	v_mul_f32_e32 v80, v84, v80
	v_bfe_u32 v84, v80, 16, 1
	v_add3_u32 v80, v80, v84, s46
	v_add_f32_e32 v84, 1.0, v90
	v_rcp_f32_e32 v91, v84
	v_mad_i64_i32 v[88:89], s[26:27], v99, s45, v[120:121]
	v_lshl_add_u64 v[88:89], v[88:89], 0, v[122:123]
	global_store_short_d16_hi v[88:89], v80, off offset:32
	v_mul_f32_e32 v80, v81, v91
	v_mul_f32_e32 v84, 0xbfb8aa3b, v82
	v_exp_f32_e32 v84, v84
	v_mul_f32_e32 v80, v85, v80
	v_bfe_u32 v81, v80, 16, 1
	v_add_f32_e32 v84, 1.0, v84
	v_rcp_f32_e32 v89, v84
	v_add3_u32 v85, v80, v81, s46
	v_mad_i64_i32 v[80:81], s[26:27], v97, s45, v[120:121]
	v_lshl_add_u64 v[80:81], v[80:81], 0, v[122:123]
	global_store_short_d16_hi v[80:81], v85, off offset:32
	v_mul_f32_e32 v80, v82, v89
	v_mul_f32_e32 v82, 0xbfb8aa3b, v83
	v_exp_f32_e32 v82, v82
	v_mul_f32_e32 v80, v86, v80
	v_bfe_u32 v81, v80, 16, 1
	v_add_f32_e32 v82, 1.0, v82
	v_rcp_f32_e32 v86, v82
	v_add3_u32 v84, v80, v81, s46
	v_mad_i64_i32 v[80:81], s[26:27], v93, s45, v[120:121]
	v_lshl_add_u64 v[80:81], v[80:81], 0, v[122:123]
	global_store_short_d16_hi v[80:81], v84, off offset:32
	v_mul_f32_e32 v80, v83, v86
	v_mul_f32_e32 v80, v87, v80
	v_bfe_u32 v81, v80, 16, 1
	v_add3_u32 v82, v80, v81, s46
	v_mul_f32_e32 v80, 0xbfb8aa3b, v72
	v_exp_f32_e32 v83, v80
	s_nop 0
	v_mad_i64_i32 v[80:81], s[26:27], v92, s45, v[120:121]
	v_lshl_add_u64 v[80:81], v[80:81], 0, v[122:123]
	global_store_short_d16_hi v[80:81], v82, off offset:32
	v_add_f32_e32 v80, 1.0, v83
	v_rcp_f32_e32 v82, v80
	v_or_b32_e32 v83, 48, v124
	v_mov_b32_e32 v84, v83
	v_mul_f32_e32 v72, v72, v82
	v_mul_f32_e32 v72, v76, v72
	v_bfe_u32 v76, v72, 16, 1
	v_add3_u32 v72, v72, v76, s46
	v_mul_f32_e32 v76, 0xbfb8aa3b, v73
	v_exp_f32_e32 v76, v76
	v_mad_i64_i32 v[80:81], s[26:27], v84, s45, v[120:121]
	v_lshl_add_u64 v[80:81], v[80:81], 0, v[122:123]
	global_store_short_d16_hi v[80:81], v72, off
	v_add_f32_e32 v72, 1.0, v76
	v_rcp_f32_e32 v80, v72
	v_or_b32_e32 v81, 49, v124
	v_mov_b32_e32 v82, v81
	v_mul_f32_e32 v72, v73, v80
	v_mul_f32_e32 v72, v77, v72
	v_bfe_u32 v73, v72, 16, 1
	v_add3_u32 v76, v72, v73, s46
	v_mul_f32_e32 v72, 0xbfb8aa3b, v74
	v_exp_f32_e32 v77, v72
	v_mad_i64_i32 v[72:73], s[26:27], v82, s45, v[120:121]
	v_lshl_add_u64 v[72:73], v[72:73], 0, v[122:123]
	global_store_short_d16_hi v[72:73], v76, off
	v_add_f32_e32 v72, 1.0, v77
	v_rcp_f32_e32 v76, v72
	v_or_b32_e32 v77, 50, v124
	v_mov_b32_e32 v80, v77
	v_mul_f32_e32 v72, v74, v76
	v_mul_f32_e32 v72, v78, v72
	v_bfe_u32 v73, v72, 16, 1
	v_add3_u32 v74, v72, v73, s46
	v_mul_f32_e32 v72, 0xbfb8aa3b, v75
	v_exp_f32_e32 v76, v72
	v_mad_i64_i32 v[72:73], s[26:27], v80, s45, v[120:121]
	v_lshl_add_u64 v[72:73], v[72:73], 0, v[122:123]
	global_store_short_d16_hi v[72:73], v74, off
	v_add_f32_e32 v72, 1.0, v76
	v_rcp_f32_e32 v74, v72
	v_or_b32_e32 v76, 51, v124
	v_mov_b32_e32 v78, v76
	v_mul_f32_e32 v72, v75, v74
	v_mul_f32_e32 v74, 0xbfb8aa3b, v64
	v_exp_f32_e32 v74, v74
	v_mul_f32_e32 v72, v79, v72
	v_bfe_u32 v73, v72, 16, 1
	v_add_f32_e32 v74, 1.0, v74
	v_add3_u32 v75, v72, v73, s46
	v_mad_i64_i32 v[72:73], s[26:27], v78, s45, v[120:121]
	v_rcp_f32_e32 v79, v74
	v_lshl_add_u64 v[72:73], v[72:73], 0, v[122:123]
	global_store_short_d16_hi v[72:73], v75, off
	v_mul_f32_e32 v64, v64, v79
	v_mul_f32_e32 v72, 0xbfb8aa3b, v65
	v_exp_f32_e32 v74, v72
	v_mul_f32_e32 v64, v68, v64
	v_bfe_u32 v68, v64, 16, 1
	v_add3_u32 v64, v64, v68, s46
	v_add_f32_e32 v68, 1.0, v74
	v_rcp_f32_e32 v75, v68
	v_mad_i64_i32 v[72:73], s[26:27], v83, s45, v[120:121]
	v_lshl_add_u64 v[72:73], v[72:73], 0, v[122:123]
	global_store_short_d16_hi v[72:73], v64, off offset:32
	v_mul_f32_e32 v64, v65, v75
	v_mul_f32_e32 v68, 0xbfb8aa3b, v66
	v_exp_f32_e32 v68, v68
	v_mul_f32_e32 v64, v69, v64
	v_bfe_u32 v65, v64, 16, 1
	v_add_f32_e32 v68, 1.0, v68
	v_rcp_f32_e32 v73, v68
	v_add3_u32 v69, v64, v65, s46
	v_mad_i64_i32 v[64:65], s[26:27], v81, s45, v[120:121]
	v_lshl_add_u64 v[64:65], v[64:65], 0, v[122:123]
	global_store_short_d16_hi v[64:65], v69, off offset:32
	v_mul_f32_e32 v64, v66, v73
	v_mul_f32_e32 v66, 0xbfb8aa3b, v67
	v_exp_f32_e32 v66, v66
	v_mul_f32_e32 v64, v70, v64
	v_bfe_u32 v65, v64, 16, 1
	v_add_f32_e32 v66, 1.0, v66
	v_rcp_f32_e32 v70, v66
	v_add3_u32 v68, v64, v65, s46
	v_mad_i64_i32 v[64:65], s[26:27], v77, s45, v[120:121]
	v_lshl_add_u64 v[64:65], v[64:65], 0, v[122:123]
	global_store_short_d16_hi v[64:65], v68, off offset:32
	v_mul_f32_e32 v64, v67, v70
	v_mul_f32_e32 v64, v71, v64
	v_bfe_u32 v65, v64, 16, 1
	v_add3_u32 v66, v64, v65, s46
	v_mad_i64_i32 v[64:65], s[26:27], v76, s45, v[120:121]
	v_lshl_add_u64 v[64:65], v[64:65], 0, v[122:123]
	global_store_short_d16_hi v[64:65], v66, off offset:32
	v_mul_f32_e32 v64, 0xbfb8aa3b, v56
	v_exp_f32_e32 v64, v64
	v_or_b32_e32 v66, 64, v124
	v_mov_b32_e32 v65, v66
	v_add_f32_e32 v64, 1.0, v64
	v_rcp_f32_e32 v68, v64
	s_add_i32 s2, s2, s3
	v_mul_f32_e32 v56, v56, v68
	v_mul_f32_e32 v56, v60, v56
	v_bfe_u32 v60, v56, 16, 1
	v_add3_u32 v56, v56, v60, s46
	v_mul_f32_e32 v60, 0xbfb8aa3b, v57
	v_exp_f32_e32 v60, v60
	v_mad_i64_i32 v[64:65], s[26:27], v65, s45, v[120:121]
	v_lshl_add_u64 v[64:65], v[64:65], 0, v[122:123]
	global_store_short_d16_hi v[64:65], v56, off
	v_add_f32_e32 v56, 1.0, v60
	v_rcp_f32_e32 v64, v56
	v_or_b32_e32 v65, 0x41, v124
	v_mov_b32_e32 v67, v65
	v_mul_f32_e32 v56, v57, v64
	v_mul_f32_e32 v56, v61, v56
	v_bfe_u32 v57, v56, 16, 1
	v_add3_u32 v60, v56, v57, s46
	v_mul_f32_e32 v56, 0xbfb8aa3b, v58
	v_exp_f32_e32 v61, v56
	v_mad_i64_i32 v[56:57], s[26:27], v67, s45, v[120:121]
	v_lshl_add_u64 v[56:57], v[56:57], 0, v[122:123]
	global_store_short_d16_hi v[56:57], v60, off
	v_add_f32_e32 v56, 1.0, v61
	v_rcp_f32_e32 v60, v56
	v_or_b32_e32 v61, 0x42, v124
	v_mov_b32_e32 v64, v61
	v_mul_f32_e32 v56, v58, v60
	v_mul_f32_e32 v56, v62, v56
	v_bfe_u32 v57, v56, 16, 1
	v_add3_u32 v58, v56, v57, s46
	v_mul_f32_e32 v56, 0xbfb8aa3b, v59
	v_exp_f32_e32 v60, v56
	v_mad_i64_i32 v[56:57], s[26:27], v64, s45, v[120:121]
	v_lshl_add_u64 v[56:57], v[56:57], 0, v[122:123]
	global_store_short_d16_hi v[56:57], v58, off
	v_add_f32_e32 v56, 1.0, v60
	v_rcp_f32_e32 v58, v56
	v_or_b32_e32 v60, 0x43, v124
	v_mov_b32_e32 v62, v60
	v_mul_f32_e32 v56, v59, v58
	v_mul_f32_e32 v58, 0xbfb8aa3b, v48
	v_exp_f32_e32 v58, v58
	v_mul_f32_e32 v56, v63, v56
	v_bfe_u32 v57, v56, 16, 1
	v_add_f32_e32 v58, 1.0, v58
	v_add3_u32 v59, v56, v57, s46
	v_mad_i64_i32 v[56:57], s[26:27], v62, s45, v[120:121]
	v_rcp_f32_e32 v63, v58
	v_lshl_add_u64 v[56:57], v[56:57], 0, v[122:123]
	global_store_short_d16_hi v[56:57], v59, off
	v_mul_f32_e32 v48, v48, v63
	v_mul_f32_e32 v56, 0xbfb8aa3b, v49
	v_exp_f32_e32 v58, v56
	v_mul_f32_e32 v48, v52, v48
	v_bfe_u32 v52, v48, 16, 1
	v_add3_u32 v48, v48, v52, s46
	v_add_f32_e32 v52, 1.0, v58
	v_rcp_f32_e32 v59, v52
	v_mad_i64_i32 v[56:57], s[26:27], v66, s45, v[120:121]
	v_lshl_add_u64 v[56:57], v[56:57], 0, v[122:123]
	global_store_short_d16_hi v[56:57], v48, off offset:32
	v_mul_f32_e32 v48, v49, v59
	v_mul_f32_e32 v52, 0xbfb8aa3b, v50
	v_exp_f32_e32 v52, v52
	v_mul_f32_e32 v48, v53, v48
	v_bfe_u32 v49, v48, 16, 1
	v_add_f32_e32 v52, 1.0, v52
	v_rcp_f32_e32 v57, v52
	v_add3_u32 v53, v48, v49, s46
	v_mad_i64_i32 v[48:49], s[26:27], v65, s45, v[120:121]
	v_lshl_add_u64 v[48:49], v[48:49], 0, v[122:123]
	global_store_short_d16_hi v[48:49], v53, off offset:32
	v_mul_f32_e32 v48, v50, v57
	v_mul_f32_e32 v50, 0xbfb8aa3b, v51
	v_exp_f32_e32 v50, v50
	v_mul_f32_e32 v48, v54, v48
	v_bfe_u32 v49, v48, 16, 1
	v_add_f32_e32 v50, 1.0, v50
	v_rcp_f32_e32 v54, v50
	v_add3_u32 v52, v48, v49, s46
	v_mad_i64_i32 v[48:49], s[26:27], v61, s45, v[120:121]
	v_lshl_add_u64 v[48:49], v[48:49], 0, v[122:123]
	global_store_short_d16_hi v[48:49], v52, off offset:32
	v_mul_f32_e32 v48, v51, v54
	v_mul_f32_e32 v48, v55, v48
	v_bfe_u32 v49, v48, 16, 1
	v_add3_u32 v50, v48, v49, s46
	v_mul_f32_e32 v48, 0xbfb8aa3b, v40
	v_exp_f32_e32 v51, v48
	s_add_i32 s31, s31, s33
	v_mad_i64_i32 v[48:49], s[26:27], v60, s45, v[120:121]
	v_lshl_add_u64 v[48:49], v[48:49], 0, v[122:123]
	global_store_short_d16_hi v[48:49], v50, off offset:32
	v_add_f32_e32 v48, 1.0, v51
	v_rcp_f32_e32 v50, v48
	v_or_b32_e32 v51, 0x50, v124
	v_mov_b32_e32 v52, v51
	v_mul_f32_e32 v40, v40, v50
	v_mul_f32_e32 v40, v44, v40
	v_bfe_u32 v44, v40, 16, 1
	v_add3_u32 v40, v40, v44, s46
	v_mul_f32_e32 v44, 0xbfb8aa3b, v41
	v_exp_f32_e32 v44, v44
	v_mad_i64_i32 v[48:49], s[26:27], v52, s45, v[120:121]
	v_lshl_add_u64 v[48:49], v[48:49], 0, v[122:123]
	global_store_short_d16_hi v[48:49], v40, off
	v_add_f32_e32 v40, 1.0, v44
	v_rcp_f32_e32 v48, v40
	v_or_b32_e32 v49, 0x51, v124
	v_mov_b32_e32 v50, v49
	v_mul_f32_e32 v40, v41, v48
	v_mul_f32_e32 v40, v45, v40
	v_bfe_u32 v41, v40, 16, 1
	v_add3_u32 v44, v40, v41, s46
	v_mul_f32_e32 v40, 0xbfb8aa3b, v42
	v_exp_f32_e32 v45, v40
	v_mad_i64_i32 v[40:41], s[26:27], v50, s45, v[120:121]
	v_lshl_add_u64 v[40:41], v[40:41], 0, v[122:123]
	global_store_short_d16_hi v[40:41], v44, off
	v_add_f32_e32 v40, 1.0, v45
	v_rcp_f32_e32 v44, v40
	v_or_b32_e32 v45, 0x52, v124
	v_mov_b32_e32 v48, v45
	v_mul_f32_e32 v40, v42, v44
	v_mul_f32_e32 v40, v46, v40
	v_bfe_u32 v41, v40, 16, 1
	v_add3_u32 v42, v40, v41, s46
	v_mul_f32_e32 v40, 0xbfb8aa3b, v43
	v_exp_f32_e32 v44, v40
	v_mad_i64_i32 v[40:41], s[26:27], v48, s45, v[120:121]
	v_lshl_add_u64 v[40:41], v[40:41], 0, v[122:123]
	global_store_short_d16_hi v[40:41], v42, off
	v_add_f32_e32 v40, 1.0, v44
	v_rcp_f32_e32 v42, v40
	v_or_b32_e32 v44, 0x53, v124
	v_mov_b32_e32 v46, v44
	v_mul_f32_e32 v40, v43, v42
	v_mul_f32_e32 v42, 0xbfb8aa3b, v32
	v_exp_f32_e32 v42, v42
	v_mul_f32_e32 v40, v47, v40
	v_bfe_u32 v41, v40, 16, 1
	v_add_f32_e32 v42, 1.0, v42
	v_add3_u32 v43, v40, v41, s46
	v_mad_i64_i32 v[40:41], s[26:27], v46, s45, v[120:121]
	v_rcp_f32_e32 v47, v42
	v_lshl_add_u64 v[40:41], v[40:41], 0, v[122:123]
	global_store_short_d16_hi v[40:41], v43, off
	v_mul_f32_e32 v32, v32, v47
	v_mul_f32_e32 v40, 0xbfb8aa3b, v33
	v_exp_f32_e32 v42, v40
	v_mul_f32_e32 v32, v36, v32
	v_bfe_u32 v36, v32, 16, 1
	v_add3_u32 v32, v32, v36, s46
	v_add_f32_e32 v36, 1.0, v42
	v_rcp_f32_e32 v43, v36
	v_mad_i64_i32 v[40:41], s[26:27], v51, s45, v[120:121]
	v_lshl_add_u64 v[40:41], v[40:41], 0, v[122:123]
	global_store_short_d16_hi v[40:41], v32, off offset:32
	v_mul_f32_e32 v32, v33, v43
	v_mul_f32_e32 v36, 0xbfb8aa3b, v34
	v_exp_f32_e32 v36, v36
	v_mul_f32_e32 v32, v37, v32
	v_bfe_u32 v33, v32, 16, 1
	v_add_f32_e32 v36, 1.0, v36
	v_rcp_f32_e32 v41, v36
	v_add3_u32 v37, v32, v33, s46
	v_mad_i64_i32 v[32:33], s[26:27], v49, s45, v[120:121]
	v_lshl_add_u64 v[32:33], v[32:33], 0, v[122:123]
	global_store_short_d16_hi v[32:33], v37, off offset:32
	v_mul_f32_e32 v32, v34, v41
	v_mul_f32_e32 v34, 0xbfb8aa3b, v35
	v_exp_f32_e32 v34, v34
	v_mul_f32_e32 v32, v38, v32
	v_bfe_u32 v33, v32, 16, 1
	v_add_f32_e32 v34, 1.0, v34
	v_rcp_f32_e32 v38, v34
	v_add3_u32 v36, v32, v33, s46
	v_mad_i64_i32 v[32:33], s[26:27], v45, s45, v[120:121]
	v_lshl_add_u64 v[32:33], v[32:33], 0, v[122:123]
	global_store_short_d16_hi v[32:33], v36, off offset:32
	v_mul_f32_e32 v32, v35, v38
	v_mul_f32_e32 v32, v39, v32
	v_bfe_u32 v33, v32, 16, 1
	v_add3_u32 v34, v32, v33, s46
	v_mul_f32_e32 v32, 0xbfb8aa3b, v24
	v_exp_f32_e32 v35, v32
	s_xor_b64 s[0:1], s[0:1], s[4:5]
	v_mad_i64_i32 v[32:33], s[26:27], v44, s45, v[120:121]
	v_lshl_add_u64 v[32:33], v[32:33], 0, v[122:123]
	global_store_short_d16_hi v[32:33], v34, off offset:32
	v_add_f32_e32 v32, 1.0, v35
	v_rcp_f32_e32 v34, v32
	v_or_b32_e32 v35, 0x60, v124
	v_mov_b32_e32 v36, v35
	v_mul_f32_e32 v24, v24, v34
	v_mul_f32_e32 v24, v28, v24
	v_bfe_u32 v28, v24, 16, 1
	v_add3_u32 v24, v24, v28, s46
	v_mul_f32_e32 v28, 0xbfb8aa3b, v25
	v_exp_f32_e32 v28, v28
	v_mad_i64_i32 v[32:33], s[26:27], v36, s45, v[120:121]
	v_lshl_add_u64 v[32:33], v[32:33], 0, v[122:123]
	global_store_short_d16_hi v[32:33], v24, off
	v_add_f32_e32 v24, 1.0, v28
	v_rcp_f32_e32 v32, v24
	v_or_b32_e32 v33, 0x61, v124
	v_mov_b32_e32 v34, v33
	v_mul_f32_e32 v24, v25, v32
	v_mul_f32_e32 v24, v29, v24
	v_bfe_u32 v25, v24, 16, 1
	v_add3_u32 v28, v24, v25, s46
	v_mul_f32_e32 v24, 0xbfb8aa3b, v26
	v_exp_f32_e32 v29, v24
	v_mad_i64_i32 v[24:25], s[26:27], v34, s45, v[120:121]
	v_lshl_add_u64 v[24:25], v[24:25], 0, v[122:123]
	global_store_short_d16_hi v[24:25], v28, off
	v_add_f32_e32 v24, 1.0, v29
	v_rcp_f32_e32 v28, v24
	v_or_b32_e32 v29, 0x62, v124
	v_mov_b32_e32 v32, v29
	v_mul_f32_e32 v24, v26, v28
	v_mul_f32_e32 v24, v30, v24
	v_bfe_u32 v25, v24, 16, 1
	v_add3_u32 v26, v24, v25, s46
	v_mul_f32_e32 v24, 0xbfb8aa3b, v27
	v_exp_f32_e32 v28, v24
	v_mad_i64_i32 v[24:25], s[26:27], v32, s45, v[120:121]
	v_lshl_add_u64 v[24:25], v[24:25], 0, v[122:123]
	global_store_short_d16_hi v[24:25], v26, off
	v_add_f32_e32 v24, 1.0, v28
	v_rcp_f32_e32 v26, v24
	v_or_b32_e32 v28, 0x63, v124
	v_mov_b32_e32 v30, v28
	v_mul_f32_e32 v24, v27, v26
	v_mul_f32_e32 v26, 0xbfb8aa3b, v16
	v_exp_f32_e32 v26, v26
	v_mul_f32_e32 v24, v31, v24
	v_bfe_u32 v25, v24, 16, 1
	v_add_f32_e32 v26, 1.0, v26
	v_add3_u32 v27, v24, v25, s46
	v_mad_i64_i32 v[24:25], s[26:27], v30, s45, v[120:121]
	v_rcp_f32_e32 v31, v26
	v_lshl_add_u64 v[24:25], v[24:25], 0, v[122:123]
	global_store_short_d16_hi v[24:25], v27, off
	v_mul_f32_e32 v16, v16, v31
	v_mul_f32_e32 v24, 0xbfb8aa3b, v17
	v_exp_f32_e32 v26, v24
	v_mul_f32_e32 v16, v20, v16
	v_bfe_u32 v20, v16, 16, 1
	v_add3_u32 v16, v16, v20, s46
	v_add_f32_e32 v20, 1.0, v26
	v_rcp_f32_e32 v27, v20
	v_mad_i64_i32 v[24:25], s[26:27], v35, s45, v[120:121]
	v_lshl_add_u64 v[24:25], v[24:25], 0, v[122:123]
	global_store_short_d16_hi v[24:25], v16, off offset:32
	v_mul_f32_e32 v16, v17, v27
	v_mul_f32_e32 v20, 0xbfb8aa3b, v18
	v_exp_f32_e32 v20, v20
	v_mul_f32_e32 v16, v21, v16
	v_bfe_u32 v17, v16, 16, 1
	v_add_f32_e32 v20, 1.0, v20
	v_rcp_f32_e32 v25, v20
	v_add3_u32 v21, v16, v17, s46
	v_mad_i64_i32 v[16:17], s[26:27], v33, s45, v[120:121]
	v_lshl_add_u64 v[16:17], v[16:17], 0, v[122:123]
	global_store_short_d16_hi v[16:17], v21, off offset:32
	v_mul_f32_e32 v16, v18, v25
	v_mul_f32_e32 v18, 0xbfb8aa3b, v19
	v_exp_f32_e32 v18, v18
	v_mul_f32_e32 v16, v22, v16
	v_bfe_u32 v17, v16, 16, 1
	v_add_f32_e32 v18, 1.0, v18
	v_rcp_f32_e32 v22, v18
	v_add3_u32 v20, v16, v17, s46
	v_mad_i64_i32 v[16:17], s[26:27], v29, s45, v[120:121]
	v_lshl_add_u64 v[16:17], v[16:17], 0, v[122:123]
	global_store_short_d16_hi v[16:17], v20, off offset:32
	v_mul_f32_e32 v16, v19, v22
	v_mul_f32_e32 v16, v23, v16
	v_bfe_u32 v17, v16, 16, 1
	v_add3_u32 v18, v16, v17, s46
	v_mul_f32_e32 v16, 0xbfb8aa3b, v8
	v_exp_f32_e32 v19, v16
	s_cmpk_gt_i32 s2, 0x1b7
	v_mad_i64_i32 v[16:17], s[26:27], v28, s45, v[120:121]
	v_lshl_add_u64 v[16:17], v[16:17], 0, v[122:123]
	global_store_short_d16_hi v[16:17], v18, off offset:32
	v_add_f32_e32 v16, 1.0, v19
	v_rcp_f32_e32 v18, v16
	v_or_b32_e32 v19, 0x70, v124
	v_mov_b32_e32 v20, v19
	v_mul_f32_e32 v8, v8, v18
	v_mul_f32_e32 v8, v12, v8
	v_bfe_u32 v12, v8, 16, 1
	v_add3_u32 v8, v8, v12, s46
	v_mul_f32_e32 v12, 0xbfb8aa3b, v9
	v_exp_f32_e32 v12, v12
	v_mad_i64_i32 v[16:17], s[26:27], v20, s45, v[120:121]
	v_lshl_add_u64 v[16:17], v[16:17], 0, v[122:123]
	global_store_short_d16_hi v[16:17], v8, off
	v_add_f32_e32 v8, 1.0, v12
	v_rcp_f32_e32 v16, v8
	v_or_b32_e32 v17, 0x71, v124
	v_mov_b32_e32 v18, v17
	v_mul_f32_e32 v8, v9, v16
	v_mul_f32_e32 v8, v13, v8
	v_bfe_u32 v9, v8, 16, 1
	v_add3_u32 v12, v8, v9, s46
	v_mul_f32_e32 v8, 0xbfb8aa3b, v10
	v_exp_f32_e32 v13, v8
	v_mad_i64_i32 v[8:9], s[26:27], v18, s45, v[120:121]
	v_lshl_add_u64 v[8:9], v[8:9], 0, v[122:123]
	global_store_short_d16_hi v[8:9], v12, off
	v_add_f32_e32 v8, 1.0, v13
	v_rcp_f32_e32 v12, v8
	v_or_b32_e32 v13, 0x72, v124
	v_mov_b32_e32 v16, v13
	v_mul_f32_e32 v8, v10, v12
	v_mul_f32_e32 v8, v14, v8
	v_bfe_u32 v9, v8, 16, 1
	v_add3_u32 v10, v8, v9, s46
	v_mul_f32_e32 v8, 0xbfb8aa3b, v11
	v_exp_f32_e32 v12, v8
	v_mad_i64_i32 v[8:9], s[26:27], v16, s45, v[120:121]
	v_lshl_add_u64 v[8:9], v[8:9], 0, v[122:123]
	global_store_short_d16_hi v[8:9], v10, off
	v_add_f32_e32 v8, 1.0, v12
	v_rcp_f32_e32 v10, v8
	v_or_b32_e32 v12, 0x73, v124
	v_mov_b32_e32 v14, v12
	v_mul_f32_e32 v8, v11, v10
	v_mul_f32_e32 v10, 0xbfb8aa3b, v0
	v_exp_f32_e32 v10, v10
	v_mul_f32_e32 v8, v15, v8
	v_bfe_u32 v9, v8, 16, 1
	v_add_f32_e32 v10, 1.0, v10
	v_add3_u32 v11, v8, v9, s46
	v_mad_i64_i32 v[8:9], s[26:27], v14, s45, v[120:121]
	v_rcp_f32_e32 v15, v10
	v_lshl_add_u64 v[8:9], v[8:9], 0, v[122:123]
	global_store_short_d16_hi v[8:9], v11, off
	v_mul_f32_e32 v0, v0, v15
	v_mul_f32_e32 v8, 0xbfb8aa3b, v1
	v_exp_f32_e32 v10, v8
	v_mul_f32_e32 v0, v4, v0
	v_bfe_u32 v4, v0, 16, 1
	v_add3_u32 v0, v0, v4, s46
	v_add_f32_e32 v4, 1.0, v10
	v_rcp_f32_e32 v11, v4
	v_mad_i64_i32 v[8:9], s[26:27], v19, s45, v[120:121]
	v_lshl_add_u64 v[8:9], v[8:9], 0, v[122:123]
	global_store_short_d16_hi v[8:9], v0, off offset:32
	v_mul_f32_e32 v0, v1, v11
	v_mul_f32_e32 v4, 0xbfb8aa3b, v2
	v_exp_f32_e32 v4, v4
	v_mul_f32_e32 v0, v5, v0
	v_bfe_u32 v1, v0, 16, 1
	v_add_f32_e32 v4, 1.0, v4
	v_rcp_f32_e32 v9, v4
	v_add3_u32 v5, v0, v1, s46
	v_mad_i64_i32 v[0:1], s[26:27], v17, s45, v[120:121]
	v_lshl_add_u64 v[0:1], v[0:1], 0, v[122:123]
	global_store_short_d16_hi v[0:1], v5, off offset:32
	v_mul_f32_e32 v0, v2, v9
	v_mul_f32_e32 v2, 0xbfb8aa3b, v3
	v_exp_f32_e32 v2, v2
	v_mul_f32_e32 v0, v6, v0
	v_bfe_u32 v1, v0, 16, 1
	v_add_f32_e32 v2, 1.0, v2
	v_rcp_f32_e32 v6, v2
	v_add3_u32 v4, v0, v1, s46
	v_mad_i64_i32 v[0:1], s[26:27], v13, s45, v[120:121]
	v_lshl_add_u64 v[0:1], v[0:1], 0, v[122:123]
	global_store_short_d16_hi v[0:1], v4, off offset:32
	v_mul_f32_e32 v0, v3, v6
	v_mul_f32_e32 v0, v7, v0
	v_bfe_u32 v1, v0, 16, 1
	v_add3_u32 v2, v0, v1, s46
	v_mad_i64_i32 v[0:1], s[26:27], v12, s45, v[120:121]
	v_lshl_add_u64 v[0:1], v[0:1], 0, v[122:123]
	global_store_short_d16_hi v[0:1], v2, off offset:32
	s_cbranch_scc0 .LBB0_3005

	.amdhsa_kernel _Z6k_mega1P
		.amdhsa_group_segment_fixed_size 73748
		.amdhsa_private_segment_fixed_size 0
		.amdhsa_kernarg_size 688
		.amdhsa_user_sgpr_count 2
		.amdhsa_user_sgpr_dispatch_ptr 0
		.amdhsa_user_sgpr_queue_ptr 0
		.amdhsa_user_sgpr_kernarg_segment_ptr 1
		.amdhsa_user_sgpr_dispatch_id 0
		.amdhsa_user_sgpr_kernarg_preload_length 0
		.amdhsa_user_sgpr_kernarg_preload_offset 0
		.amdhsa_user_sgpr_private_segment_size 0
		.amdhsa_uses_dynamic_stack 0
		.amdhsa_enable_private_segment 0
		.amdhsa_system_sgpr_workgroup_id_x 1
		.amdhsa_system_sgpr_workgroup_id_y 0
		.amdhsa_system_sgpr_workgroup_id_z 0
		.amdhsa_system_sgpr_workgroup_info 0
		.amdhsa_system_vgpr_workitem_id 2
		.amdhsa_next_free_vgpr 248
		.amdhsa_next_free_sgpr 102
		.amdhsa_accum_offset 248
		.amdhsa_reserve_vcc 1
		.amdhsa_float_round_mode_32 0
		.amdhsa_float_round_mode_16_64 0
		.amdhsa_float_denorm_mode_32 3
		.amdhsa_float_denorm_mode_16_64 3
		.amdhsa_dx10_clamp 1
		.amdhsa_ieee_mode 1
		.amdhsa_fp16_overflow 0
		.amdhsa_tg_split 0
		.amdhsa_exception_fp_ieee_invalid_op 0
		.amdhsa_exception_fp_denorm_src 0
		.amdhsa_exception_fp_ieee_div_zero 0
		.amdhsa_exception_fp_ieee_overflow 0
		.amdhsa_exception_fp_ieee_underflow 0
		.amdhsa_exception_fp_ieee_inexact 0
		.amdhsa_exception_int_div_zero 0
	.end_amdhsa_kernel

amdhsa.kernels:
  - .agpr_count:     0
    .args:
      - .offset:         0
        .size:           432
        .value_kind:     by_value
      - .offset:         432
        .size:           4
        .value_kind:     hidden_block_count_x
      - .offset:         436
        .size:           4
        .value_kind:     hidden_block_count_y
      - .offset:         440
        .size:           4
        .value_kind:     hidden_block_count_z
      - .offset:         444
        .size:           2
        .value_kind:     hidden_group_size_x
      - .offset:         446
        .size:           2
        .value_kind:     hidden_group_size_y
      - .offset:         448
        .size:           2
        .value_kind:     hidden_group_size_z
      - .offset:         450
        .size:           2
        .value_kind:     hidden_remainder_x
      - .offset:         452
        .size:           2
        .value_kind:     hidden_remainder_y
      - .offset:         454
        .size:           2
        .value_kind:     hidden_remainder_z
      - .offset:         472
        .size:           8
        .value_kind:     hidden_global_offset_x
      - .offset:         480
        .size:           8
        .value_kind:     hidden_global_offset_y
      - .offset:         488
        .size:           8
        .value_kind:     hidden_global_offset_z
      - .offset:         496
        .size:           2
        .value_kind:     hidden_grid_dims
      - .offset:         520
        .size:           8
        .value_kind:     hidden_multigrid_sync_arg
    .group_segment_fixed_size: 73748
    .kernarg_segment_align: 8
    .kernarg_segment_size: 688
    .language:       OpenCL C
    .language_version:
      - 2
      - 0
    .max_flat_workgroup_size: 256
    .name:           _Z6k_mega1P
    .private_segment_fixed_size: 0
    .sgpr_count:     108
    .sgpr_spill_count: 133
    .symbol:         _Z6k_mega1P.kd
    .uniform_work_group_size: 1
    .uses_dynamic_stack: false
    .vgpr_count:     248
    .vgpr_spill_count: 0
    .wavefront_size: 64
